# GEMM K-loops: one static s_setprio 1 for waves 4-7 per tile loop and no per-phase flips (the guide's recipe), on top of barrier relocation + mixer wave priorities
# speedup vs baseline: 1.0070x; 1.0034x over previous
; #define PG8_STAGE(bufoff, gbase, voff) do { _Pragma("unroll") for (int _i = 0; _i < 2; ++_i) \
;         __builtin_amdgcn_global_load_lds((const unsigned*)((const char*)(gbase) + (voff)[_i]), (LAS unsigned*)(lds + (bufoff) + ldsw + _i * 8192), 16, 0, 0); } while (0)
; #define PG8_WAIT_V(n) asm volatile("s_waitcnt vmcnt(" #n ")" ::: "memory")
; #define PG8_BAR __builtin_amdgcn_s_barrier()
; template <class Epi, bool ALIGN_EPI = PG8_ALIGN>
; __device__ __forceinline__ void gemm_phase(LAS unsigned char* lds, const Gemm g, const StaticOrder& S, const Epi& E) {
;     ...
;     f32x4 acc[2][2][4][2];
; #pragma unroll
;     for (int a = 0; a < 2; ++a)
; #pragma unroll
;         for (int b = 0; b < 2; ++b)
; #pragma unroll
;             for (int m = 0; m < 4; ++m)
; #pragma unroll
;                 for (int n = 0; n < 2; ++n) acc[a][b][m][n] = (f32x4){0.f, 0.f, 0.f, 0.f};
;     bf16x8 At[4][2], B0[2][2], B1[2][2];
;     const char* cA = (const char*)g.A + (size_t)cur.pm * tstepA; const char* cB = (const char*)g.Bt + (size_t)cur.pn * tstepB;
;     PG8_STAGE(PG8_SB(0, 0), cB, voffB); PG8_STAGE(PG8_SB(0, 1), cB + hstepB, voffB); PG8_STAGE(PG8_SA(0, 0), cA, voffA); PG8_STAGE(PG8_SA(0, 1), cA + hstepA, voffA);
;     if (wr == 1) PG8_BAR;
;     PG8_WAIT_V(2); PG8_BAR;
;     PG8_STAGE(PG8_SB(1, 0), cB + kstep, voffB); PG8_STAGE(PG8_SA(1, 0), cA + kstep, voffA); PG8_STAGE(PG8_SB(1, 1), cB + hstepB + kstep, voffB);
;     PG8_WAIT_V(6); PG8_BAR;
;     for (;;) {
;         const bool has_next = S.next(ui + 1, nxt);
;         const char* nA = has_next ? (const char*)g.A + (size_t)nxt.pm * tstepA : cA; const char* nB = has_next ? (const char*)g.Bt + (size_t)nxt.pn * tstepB : cB;
.LBB0_217:
	s_ashr_i32 s15, s14, 31
	s_lshl_b64 s[40:41], s[14:15], 20
	s_add_u32 s40, s58, s40
	v_mov_b32_e32 v127, 0
	s_addc_u32 s41, s59, s41
	s_andn2_b64 vcc, exec, s[10:11]
	v_mov_b32_e32 v126, v127
	v_mov_b32_e32 v125, v127
	v_mov_b32_e32 v124, v127
	v_mov_b32_e32 v119, v127
	v_mov_b32_e32 v118, v127
	v_mov_b32_e32 v117, v127
	v_mov_b32_e32 v116, v127
	v_mov_b32_e32 v111, v127
	v_mov_b32_e32 v110, v127
	v_mov_b32_e32 v109, v127
	v_mov_b32_e32 v108, v127
	v_mov_b32_e32 v103, v127
	v_mov_b32_e32 v102, v127
	v_mov_b32_e32 v101, v127
	v_mov_b32_e32 v100, v127
	v_mov_b32_e32 v95, v127
	v_mov_b32_e32 v94, v127
	v_mov_b32_e32 v93, v127
	v_mov_b32_e32 v92, v127
	v_mov_b32_e32 v87, v127
	v_mov_b32_e32 v86, v127
	v_mov_b32_e32 v85, v127
	v_mov_b32_e32 v84, v127
	v_mov_b32_e32 v79, v127
	v_mov_b32_e32 v78, v127
	v_mov_b32_e32 v77, v127
	v_mov_b32_e32 v76, v127
	v_mov_b32_e32 v71, v127
	v_mov_b32_e32 v70, v127
	v_mov_b32_e32 v69, v127
	v_mov_b32_e32 v68, v127
	v_mov_b32_e32 v123, v127
	v_mov_b32_e32 v122, v127
	v_mov_b32_e32 v121, v127
	v_mov_b32_e32 v120, v127
	v_mov_b32_e32 v115, v127
	v_mov_b32_e32 v114, v127
	v_mov_b32_e32 v113, v127
	v_mov_b32_e32 v112, v127
	v_mov_b32_e32 v107, v127
	v_mov_b32_e32 v106, v127
	v_mov_b32_e32 v105, v127
	v_mov_b32_e32 v104, v127
	v_mov_b32_e32 v99, v127
	v_mov_b32_e32 v98, v127
	v_mov_b32_e32 v97, v127
	v_mov_b32_e32 v96, v127
	v_mov_b32_e32 v91, v127
	v_mov_b32_e32 v90, v127
	v_mov_b32_e32 v89, v127
	v_mov_b32_e32 v88, v127
	v_mov_b32_e32 v83, v127
	v_mov_b32_e32 v82, v127
	v_mov_b32_e32 v81, v127
	v_mov_b32_e32 v80, v127
	v_mov_b32_e32 v75, v127
	v_mov_b32_e32 v74, v127
	v_mov_b32_e32 v73, v127
	v_mov_b32_e32 v72, v127
	v_mov_b32_e32 v67, v127
	v_mov_b32_e32 v66, v127
	v_mov_b32_e32 v65, v127
	v_mov_b32_e32 v64, v127
	v_mov_b32_e32 v63, v127
	v_mov_b32_e32 v62, v127
	v_mov_b32_e32 v61, v127
	v_mov_b32_e32 v60, v127
	v_mov_b32_e32 v55, v127
	v_mov_b32_e32 v54, v127
	v_mov_b32_e32 v53, v127
	v_mov_b32_e32 v52, v127
	v_mov_b32_e32 v47, v127
	v_mov_b32_e32 v46, v127
	v_mov_b32_e32 v45, v127
	v_mov_b32_e32 v44, v127
	v_mov_b32_e32 v39, v127
	v_mov_b32_e32 v38, v127
	v_mov_b32_e32 v37, v127
	v_mov_b32_e32 v36, v127
	v_mov_b32_e32 v31, v127
	v_mov_b32_e32 v30, v127
	v_mov_b32_e32 v29, v127
	v_mov_b32_e32 v28, v127
	v_mov_b32_e32 v23, v127
	v_mov_b32_e32 v22, v127
	v_mov_b32_e32 v21, v127
	v_mov_b32_e32 v20, v127
	v_mov_b32_e32 v15, v127
	v_mov_b32_e32 v14, v127
	v_mov_b32_e32 v13, v127
	v_mov_b32_e32 v12, v127
	v_mov_b32_e32 v7, v127
	v_mov_b32_e32 v6, v127
	v_mov_b32_e32 v5, v127
	v_mov_b32_e32 v4, v127
	v_mov_b32_e32 v59, v127
	v_mov_b32_e32 v58, v127
	v_mov_b32_e32 v57, v127
	v_mov_b32_e32 v56, v127
	v_mov_b32_e32 v51, v127
	v_mov_b32_e32 v50, v127
	v_mov_b32_e32 v49, v127
	v_mov_b32_e32 v48, v127
	v_mov_b32_e32 v43, v127
	v_mov_b32_e32 v42, v127
	v_mov_b32_e32 v41, v127
	v_mov_b32_e32 v40, v127
	v_mov_b32_e32 v35, v127
	v_mov_b32_e32 v34, v127
	v_mov_b32_e32 v33, v127
	v_mov_b32_e32 v32, v127
	v_mov_b32_e32 v27, v127
	v_mov_b32_e32 v26, v127
	v_mov_b32_e32 v25, v127
	v_mov_b32_e32 v24, v127
	v_mov_b32_e32 v19, v127
	v_mov_b32_e32 v18, v127
	v_mov_b32_e32 v17, v127
	v_mov_b32_e32 v16, v127
	v_mov_b32_e32 v11, v127
	v_mov_b32_e32 v10, v127
	v_mov_b32_e32 v9, v127
	v_mov_b32_e32 v8, v127
	v_mov_b32_e32 v3, v127
	v_mov_b32_e32 v2, v127
	v_mov_b32_e32 v1, v127
	v_mov_b32_e32 v0, v127
	s_cbranch_vccnz .LBB0_220
	s_and_b64 s[2:3], s[2:3], exec
	s_cselect_b32 s15, s41, s37
	s_cselect_b32 s34, s40, s36
	s_add_u32 s2, s36, 0x80080
	s_addc_u32 s3, s37, 0
	s_add_u32 s36, s24, 0x100
	v_mov_b32_e32 v0, 0
	s_addc_u32 s37, s25, 0
	s_mov_b32 s24, 0
	v_mov_b32_e32 v1, v0
	v_mov_b32_e32 v2, v0
	v_mov_b32_e32 v3, v0
	v_mov_b32_e32 v8, v0
	v_mov_b32_e32 v9, v0
	v_mov_b32_e32 v10, v0
	v_mov_b32_e32 v11, v0
	v_mov_b32_e32 v16, v0
	v_mov_b32_e32 v17, v0
	v_mov_b32_e32 v18, v0
	v_mov_b32_e32 v19, v0
	v_mov_b32_e32 v24, v0
	v_mov_b32_e32 v25, v0
	v_mov_b32_e32 v26, v0
	v_mov_b32_e32 v27, v0
	v_mov_b32_e32 v32, v0
	v_mov_b32_e32 v33, v0
	v_mov_b32_e32 v34, v0
	v_mov_b32_e32 v35, v0
	v_mov_b32_e32 v40, v0
	v_mov_b32_e32 v41, v0
	v_mov_b32_e32 v42, v0
	v_mov_b32_e32 v43, v0
	v_mov_b32_e32 v48, v0
	v_mov_b32_e32 v49, v0
	v_mov_b32_e32 v50, v0
	v_mov_b32_e32 v51, v0
	v_mov_b32_e32 v56, v0
	v_mov_b32_e32 v57, v0
	v_mov_b32_e32 v58, v0
	v_mov_b32_e32 v59, v0
	v_mov_b32_e32 v4, v0
	v_mov_b32_e32 v5, v0
	v_mov_b32_e32 v6, v0
	v_mov_b32_e32 v7, v0
	v_mov_b32_e32 v12, v0
	v_mov_b32_e32 v13, v0
	v_mov_b32_e32 v14, v0
	v_mov_b32_e32 v15, v0
	v_mov_b32_e32 v20, v0
	v_mov_b32_e32 v21, v0
	v_mov_b32_e32 v22, v0
	v_mov_b32_e32 v23, v0
	v_mov_b32_e32 v28, v0
	v_mov_b32_e32 v29, v0
	v_mov_b32_e32 v30, v0
	v_mov_b32_e32 v31, v0
	v_mov_b32_e32 v36, v0
	v_mov_b32_e32 v37, v0
	v_mov_b32_e32 v38, v0
	v_mov_b32_e32 v39, v0
	v_mov_b32_e32 v44, v0
	v_mov_b32_e32 v45, v0
	v_mov_b32_e32 v46, v0
	v_mov_b32_e32 v47, v0
	v_mov_b32_e32 v52, v0
	v_mov_b32_e32 v53, v0
	v_mov_b32_e32 v54, v0
	v_mov_b32_e32 v55, v0
	v_mov_b32_e32 v60, v0
	v_mov_b32_e32 v61, v0
	v_mov_b32_e32 v62, v0
	v_mov_b32_e32 v63, v0
	v_mov_b32_e32 v64, v0
	v_mov_b32_e32 v65, v0
	v_mov_b32_e32 v66, v0
	v_mov_b32_e32 v67, v0
	v_mov_b32_e32 v72, v0
	v_mov_b32_e32 v73, v0
	v_mov_b32_e32 v74, v0
	v_mov_b32_e32 v75, v0
	v_mov_b32_e32 v80, v0
	v_mov_b32_e32 v81, v0
	v_mov_b32_e32 v82, v0
	v_mov_b32_e32 v83, v0
	v_mov_b32_e32 v88, v0
	v_mov_b32_e32 v89, v0
	v_mov_b32_e32 v90, v0
	v_mov_b32_e32 v91, v0
	v_mov_b32_e32 v96, v0
	v_mov_b32_e32 v97, v0
	v_mov_b32_e32 v98, v0
	v_mov_b32_e32 v99, v0
	v_mov_b32_e32 v104, v0
	v_mov_b32_e32 v105, v0
	v_mov_b32_e32 v106, v0
	v_mov_b32_e32 v107, v0
	v_mov_b32_e32 v112, v0
	v_mov_b32_e32 v113, v0
	v_mov_b32_e32 v114, v0
	v_mov_b32_e32 v115, v0
	v_mov_b32_e32 v120, v0
	v_mov_b32_e32 v121, v0
	v_mov_b32_e32 v122, v0
	v_mov_b32_e32 v123, v0
	v_mov_b32_e32 v68, v0
	v_mov_b32_e32 v69, v0
	v_mov_b32_e32 v70, v0
	v_mov_b32_e32 v71, v0
	v_mov_b32_e32 v76, v0
	v_mov_b32_e32 v77, v0
	v_mov_b32_e32 v78, v0
	v_mov_b32_e32 v79, v0
	v_mov_b32_e32 v84, v0
	v_mov_b32_e32 v85, v0
	v_mov_b32_e32 v86, v0
	v_mov_b32_e32 v87, v0
	v_mov_b32_e32 v92, v0
	v_mov_b32_e32 v93, v0
	v_mov_b32_e32 v94, v0
	v_mov_b32_e32 v95, v0
	v_mov_b32_e32 v100, v0
	v_mov_b32_e32 v101, v0
	v_mov_b32_e32 v102, v0
	v_mov_b32_e32 v103, v0
	v_mov_b32_e32 v108, v0
	v_mov_b32_e32 v109, v0
	v_mov_b32_e32 v110, v0
	v_mov_b32_e32 v111, v0
	v_mov_b32_e32 v116, v0
	v_mov_b32_e32 v117, v0
	v_mov_b32_e32 v118, v0
	v_mov_b32_e32 v119, v0
	v_mov_b32_e32 v124, v0
	v_mov_b32_e32 v125, v0
	v_mov_b32_e32 v126, v0
	v_mov_b32_e32 v127, v0
	v_readfirstlane_b32 s100, v238
	s_cmp_lt_u32 s100, 0x100
	s_cbranch_scc1 .Lgp_219
	s_setprio 1
; #define PG8_STAGE(bufoff, gbase, voff) do { _Pragma("unroll") for (int _i = 0; _i < 2; ++_i) \
;         __builtin_amdgcn_global_load_lds((const unsigned*)((const char*)(gbase) + (voff)[_i]), (LAS unsigned*)(lds + (bufoff) + ldsw + _i * 8192), 16, 0, 0); } while (0)
; #define PG8_LDA(dst, b, h) do { _Pragma("unroll") for (int m = 0; m < 4; ++m) _Pragma("unroll") for (int k = 0; k < 2; ++k) dst[m][k] = *(const LAS bf16x8*)(lds + PG8_SA(b, h) + aoff + m * 2048 + k * 1024); } while (0)
; #define PG8_LDB(dst, b, h) do { _Pragma("unroll") for (int n = 0; n < 2; ++n) _Pragma("unroll") for (int k = 0; k < 2; ++k) dst[n][k] = *(const LAS bf16x8*)(lds + PG8_SB(b, h) + boff + n * 2048 + k * 1024); } while (0)
; #define PG8_MMA(ai, bj, At, Bt) do { __builtin_amdgcn_s_setprio(1); _Pragma("unroll") for (int m = 0; m < 4; ++m) _Pragma("unroll") for (int n = 0; n < 2; ++n) _Pragma("unroll") for (int k = 0; k < 2; ++k) \
;         acc[ai][bj][m][n] = __builtin_amdgcn_mfma_f32_16x16x32_bf16(Bt[n][k], At[m][k], acc[ai][bj][m][n], 0, 0, 0); __builtin_amdgcn_s_setprio(0); } while (0)
; #define PG8_WAIT_V(n) asm volatile("s_waitcnt vmcnt(" #n ")" ::: "memory")
; #define PG8_WAIT_L(n) asm volatile("s_waitcnt lgkmcnt(" #n ")" ::: "memory")
; #define PG8_BAR __builtin_amdgcn_s_barrier()
; #define PG8_SCHED __builtin_amdgcn_sched_barrier(0)
; template <class Epi, bool ALIGN_EPI = PG8_ALIGN>
; __device__ __forceinline__ void gemm_phase(LAS unsigned char* lds, const Gemm g, const StaticOrder& S, const Epi& E) {
;     ...
;         for (int t = 0; t < nt; t += 2) {
;             const bool last = (t == nt - 2);
;             const char* a1 = cA + (size_t)(t + 1) * kstep;
;             const char* a2 = last ? nA : cA + (size_t)(t + 2) * kstep; const char* b2 = last ? nB : cB + (size_t)(t + 2) * kstep;
;             const char* a3 = a2 + kstep; const char* b3 = b2 + kstep;
;             PG8_LDB(B0, 0, 0); PG8_LDB(B1, 0, 1); PG8_SCHED; PG8_LDA(At, 0, 0); PG8_STAGE(PG8_SA(1, 1), a1 + hstepA, voffA);
;             PG8_WAIT_V(8); PG8_WAIT_L(0); PG8_BAR; PG8_MMA(0, 0, At, B0); PG8_MMA(0, 1, At, B1); PG8_BAR; PG8_SCHED;
;             PG8_LDA(At, 0, 1); PG8_STAGE(PG8_SB(0, 0), b2, voffB); PG8_STAGE(PG8_SB(0, 1), b2 + hstepB, voffB); PG8_STAGE(PG8_SA(0, 0), a2, voffA);
;             PG8_WAIT_V(8); PG8_WAIT_L(0); PG8_BAR; PG8_MMA(1, 0, At, B0); PG8_MMA(1, 1, At, B1); PG8_BAR; PG8_SCHED;
.Lgp_219:
.LBB0_219:
	s_add_i32 s49, s24, 2
	s_add_u32 s20, s2, 0xfff80080
	s_addc_u32 s21, s3, -1
	s_add_i32 s22, 16, 0x10000
	s_cmp_eq_u32 s46, s24
	s_cselect_b32 s25, s15, s21
	s_cselect_b32 s24, s34, s20
	s_cselect_b32 s51, s17, s37
	s_cselect_b32 s50, s16, s36
	s_add_i32 s20, 16, 0x14000
	v_add_u32_e32 v154, s22, v139
	v_add_u32_e32 v170, s20, v139
	ds_read_b128 v[142:145], v154
	ds_read_b128 v[146:149], v154 offset:1024
	ds_read_b128 v[150:153], v154 offset:2048
	ds_read_b128 v[154:157], v154 offset:3072
	ds_read_b128 v[158:161], v170
	ds_read_b128 v[162:165], v170 offset:1024
	ds_read_b128 v[166:169], v170 offset:2048
	ds_read_b128 v[170:173], v170 offset:3072
	v_lshl_add_u64 v[174:175], s[2:3], 0, v[134:135]
	s_add_i32 m0, s29, 0xc000
	ds_read_b128 v[184:187], v141
	ds_read_b128 v[188:191], v141 offset:1024
	ds_read_b128 v[192:195], v141 offset:2048
	ds_read_b128 v[196:199], v141 offset:3072
	ds_read_b128 v[200:203], v141 offset:4096
	ds_read_b128 v[204:207], v141 offset:5120
	ds_read_b128 v[208:211], v141 offset:6144
	ds_read_b128 v[212:215], v141 offset:7168
	global_load_lds_dwordx4 v[174:175], off
	v_lshl_add_u64 v[174:175], s[2:3], 0, v[136:137]
	s_add_i32 m0, s29, 0xe000
	s_nop 0
	global_load_lds_dwordx4 v[174:175], off
	s_waitcnt vmcnt(8)
	s_waitcnt lgkmcnt(0)
	s_barrier
	s_waitcnt lgkmcnt(0)
	v_mfma_f32_16x16x32_bf16 v[124:127], v[142:145], v[184:187], v[124:127]
	v_mfma_f32_16x16x32_bf16 v[116:119], v[150:153], v[184:187], v[116:119]
	v_mfma_f32_16x16x32_bf16 v[108:111], v[142:145], v[192:195], v[108:111]
	v_mfma_f32_16x16x32_bf16 v[100:103], v[150:153], v[192:195], v[100:103]
	v_mfma_f32_16x16x32_bf16 v[92:95], v[142:145], v[200:203], v[92:95]
	v_mfma_f32_16x16x32_bf16 v[84:87], v[150:153], v[200:203], v[84:87]
	v_mfma_f32_16x16x32_bf16 v[76:79], v[142:145], v[208:211], v[76:79]
	v_mfma_f32_16x16x32_bf16 v[68:71], v[150:153], v[208:211], v[68:71]
	v_mfma_f32_16x16x32_bf16 v[124:127], v[146:149], v[188:191], v[124:127]
	v_mfma_f32_16x16x32_bf16 v[116:119], v[154:157], v[188:191], v[116:119]
	v_mfma_f32_16x16x32_bf16 v[108:111], v[146:149], v[196:199], v[108:111]
	v_mfma_f32_16x16x32_bf16 v[100:103], v[154:157], v[196:199], v[100:103]
	v_mfma_f32_16x16x32_bf16 v[92:95], v[146:149], v[204:207], v[92:95]
	v_mfma_f32_16x16x32_bf16 v[84:87], v[154:157], v[204:207], v[84:87]
	v_mfma_f32_16x16x32_bf16 v[76:79], v[146:149], v[212:215], v[76:79]
	v_mfma_f32_16x16x32_bf16 v[68:71], v[154:157], v[212:215], v[68:71]
	v_mfma_f32_16x16x32_bf16 v[120:123], v[158:161], v[184:187], v[120:123]
	v_mfma_f32_16x16x32_bf16 v[112:115], v[166:169], v[184:187], v[112:115]
	v_mfma_f32_16x16x32_bf16 v[104:107], v[158:161], v[192:195], v[104:107]
	v_mfma_f32_16x16x32_bf16 v[96:99], v[166:169], v[192:195], v[96:99]
	v_mfma_f32_16x16x32_bf16 v[88:91], v[158:161], v[200:203], v[88:91]
	v_mfma_f32_16x16x32_bf16 v[80:83], v[166:169], v[200:203], v[80:83]
	v_mfma_f32_16x16x32_bf16 v[72:75], v[158:161], v[208:211], v[72:75]
	v_mfma_f32_16x16x32_bf16 v[64:67], v[166:169], v[208:211], v[64:67]
	v_mfma_f32_16x16x32_bf16 v[120:123], v[162:165], v[188:191], v[120:123]
	v_mfma_f32_16x16x32_bf16 v[112:115], v[170:173], v[188:191], v[112:115]
	v_mfma_f32_16x16x32_bf16 v[104:107], v[162:165], v[196:199], v[104:107]
	v_mfma_f32_16x16x32_bf16 v[96:99], v[170:173], v[196:199], v[96:99]
	v_mfma_f32_16x16x32_bf16 v[88:91], v[162:165], v[204:207], v[88:91]
	v_mfma_f32_16x16x32_bf16 v[80:83], v[170:173], v[204:207], v[80:83]
	v_mfma_f32_16x16x32_bf16 v[72:75], v[162:165], v[212:215], v[72:75]
	v_mfma_f32_16x16x32_bf16 v[64:67], v[170:173], v[212:215], v[64:67]
	s_barrier
	s_add_i32 s21, s22, s18
	v_lshl_add_u64 v[174:175], s[50:51], 0, v[176:177]
	s_mov_b32 m0, s21
	ds_read_b128 v[184:187], v141 offset:16384
	ds_read_b128 v[188:191], v141 offset:17408
	ds_read_b128 v[192:195], v141 offset:18432
	ds_read_b128 v[196:199], v141 offset:19456
	ds_read_b128 v[200:203], v141 offset:20480
	ds_read_b128 v[204:207], v141 offset:21504
	ds_read_b128 v[208:211], v141 offset:22528
	ds_read_b128 v[212:215], v141 offset:23552
	global_load_lds_dwordx4 v[174:175], off
	s_add_i32 m0, s21, 0x2000
	v_lshl_add_u64 v[216:217], s[50:51], 0, v[128:129]
	s_add_u32 s50, s50, s4
	s_addc_u32 s51, s51, s5
	s_add_i32 s20, s20, s18
	global_load_lds_dwordx4 v[216:217], off
	v_lshl_add_u64 v[218:219], s[50:51], 0, v[176:177]
	s_mov_b32 m0, s20
	v_lshl_add_u64 v[220:221], s[50:51], 0, v[128:129]
	global_load_lds_dwordx4 v[218:219], off
	s_add_i32 m0, s20, 0x2000
	v_lshl_add_u64 v[222:223], s[24:25], 0, v[132:133]
	global_load_lds_dwordx4 v[220:221], off
	s_mov_b32 m0, s29
	v_lshl_add_u64 v[224:225], s[24:25], 0, v[130:131]
	global_load_lds_dwordx4 v[222:223], off
	s_mov_b32 m0, s30
	s_nop 0
	global_load_lds_dwordx4 v[224:225], off
	s_waitcnt vmcnt(8)
	s_waitcnt lgkmcnt(0)
	s_barrier
; #define PG8_STAGE(bufoff, gbase, voff) do { _Pragma("unroll") for (int _i = 0; _i < 2; ++_i) \
;         __builtin_amdgcn_global_load_lds((const unsigned*)((const char*)(gbase) + (voff)[_i]), (LAS unsigned*)(lds + (bufoff) + ldsw + _i * 8192), 16, 0, 0); } while (0)
; #define PG8_LDA(dst, b, h) do { _Pragma("unroll") for (int m = 0; m < 4; ++m) _Pragma("unroll") for (int k = 0; k < 2; ++k) dst[m][k] = *(const LAS bf16x8*)(lds + PG8_SA(b, h) + aoff + m * 2048 + k * 1024); } while (0)
; #define PG8_LDB(dst, b, h) do { _Pragma("unroll") for (int n = 0; n < 2; ++n) _Pragma("unroll") for (int k = 0; k < 2; ++k) dst[n][k] = *(const LAS bf16x8*)(lds + PG8_SB(b, h) + boff + n * 2048 + k * 1024); } while (0)
; #define PG8_MMA(ai, bj, At, Bt) do { __builtin_amdgcn_s_setprio(1); _Pragma("unroll") for (int m = 0; m < 4; ++m) _Pragma("unroll") for (int n = 0; n < 2; ++n) _Pragma("unroll") for (int k = 0; k < 2; ++k) \
;         acc[ai][bj][m][n] = __builtin_amdgcn_mfma_f32_16x16x32_bf16(Bt[n][k], At[m][k], acc[ai][bj][m][n], 0, 0, 0); __builtin_amdgcn_s_setprio(0); } while (0)
; #define PG8_WAIT_V(n) asm volatile("s_waitcnt vmcnt(" #n ")" ::: "memory")
; #define PG8_WAIT_L(n) asm volatile("s_waitcnt lgkmcnt(" #n ")" ::: "memory")
; #define PG8_BAR __builtin_amdgcn_s_barrier()
; #define PG8_SCHED __builtin_amdgcn_sched_barrier(0)
; template <class Epi, bool ALIGN_EPI = PG8_ALIGN>
; __device__ __forceinline__ void gemm_phase(LAS unsigned char* lds, const Gemm g, const StaticOrder& S, const Epi& E) {
;     ...
;             PG8_WAIT_V(8); PG8_WAIT_L(0); PG8_BAR; PG8_MMA(1, 0, At, B0); PG8_MMA(1, 1, At, B1); PG8_BAR; PG8_SCHED;
;             PG8_LDB(B0, 1, 0); PG8_LDB(B1, 1, 1); PG8_SCHED; PG8_LDA(At, 1, 0); PG8_STAGE(PG8_SA(0, 1), a2 + hstepA, voffA);
;             PG8_WAIT_V(8); PG8_WAIT_L(0); PG8_BAR; PG8_MMA(0, 0, At, B0); PG8_MMA(0, 1, At, B1); PG8_BAR; PG8_SCHED;
	s_waitcnt lgkmcnt(0)
	v_mfma_f32_16x16x32_bf16 v[60:63], v[142:145], v[184:187], v[60:63]
	v_mfma_f32_16x16x32_bf16 v[52:55], v[150:153], v[184:187], v[52:55]
	v_mfma_f32_16x16x32_bf16 v[44:47], v[142:145], v[192:195], v[44:47]
	v_mfma_f32_16x16x32_bf16 v[36:39], v[150:153], v[192:195], v[36:39]
	v_mfma_f32_16x16x32_bf16 v[28:31], v[142:145], v[200:203], v[28:31]
	v_mfma_f32_16x16x32_bf16 v[20:23], v[150:153], v[200:203], v[20:23]
	v_mfma_f32_16x16x32_bf16 v[12:15], v[142:145], v[208:211], v[12:15]
	v_mfma_f32_16x16x32_bf16 v[4:7], v[150:153], v[208:211], v[4:7]
	v_mfma_f32_16x16x32_bf16 v[60:63], v[146:149], v[188:191], v[60:63]
	v_mfma_f32_16x16x32_bf16 v[52:55], v[154:157], v[188:191], v[52:55]
	v_mfma_f32_16x16x32_bf16 v[44:47], v[146:149], v[196:199], v[44:47]
	v_mfma_f32_16x16x32_bf16 v[36:39], v[154:157], v[196:199], v[36:39]
	v_mfma_f32_16x16x32_bf16 v[28:31], v[146:149], v[204:207], v[28:31]
	v_mfma_f32_16x16x32_bf16 v[20:23], v[154:157], v[204:207], v[20:23]
	v_mfma_f32_16x16x32_bf16 v[12:15], v[146:149], v[212:215], v[12:15]
	v_mfma_f32_16x16x32_bf16 v[4:7], v[154:157], v[212:215], v[4:7]
	v_mfma_f32_16x16x32_bf16 v[56:59], v[158:161], v[184:187], v[56:59]
	v_mfma_f32_16x16x32_bf16 v[48:51], v[166:169], v[184:187], v[48:51]
	v_mfma_f32_16x16x32_bf16 v[40:43], v[158:161], v[192:195], v[40:43]
	v_mfma_f32_16x16x32_bf16 v[32:35], v[166:169], v[192:195], v[32:35]
	v_mfma_f32_16x16x32_bf16 v[24:27], v[158:161], v[200:203], v[24:27]
	v_mfma_f32_16x16x32_bf16 v[16:19], v[166:169], v[200:203], v[16:19]
	v_mfma_f32_16x16x32_bf16 v[8:11], v[158:161], v[208:211], v[8:11]
	v_mfma_f32_16x16x32_bf16 v[0:3], v[166:169], v[208:211], v[0:3]
	v_mfma_f32_16x16x32_bf16 v[56:59], v[162:165], v[188:191], v[56:59]
	v_mfma_f32_16x16x32_bf16 v[48:51], v[170:173], v[188:191], v[48:51]
	v_mfma_f32_16x16x32_bf16 v[40:43], v[162:165], v[196:199], v[40:43]
	v_mfma_f32_16x16x32_bf16 v[32:35], v[170:173], v[196:199], v[32:35]
	v_mfma_f32_16x16x32_bf16 v[24:27], v[162:165], v[204:207], v[24:27]
	v_mfma_f32_16x16x32_bf16 v[16:19], v[170:173], v[204:207], v[16:19]
	v_mfma_f32_16x16x32_bf16 v[8:11], v[162:165], v[212:215], v[8:11]
	v_mfma_f32_16x16x32_bf16 v[0:3], v[170:173], v[212:215], v[0:3]
	s_barrier
	s_add_i32 s20, 16, 0x18000
	s_add_i32 s21, 16, 0x1c000
	v_add_u32_e32 v154, s20, v139
	v_add_u32_e32 v170, s21, v139
	ds_read_b128 v[142:145], v154
	ds_read_b128 v[146:149], v154 offset:1024
	ds_read_b128 v[150:153], v154 offset:2048
	ds_read_b128 v[154:157], v154 offset:3072
	ds_read_b128 v[158:161], v170
	ds_read_b128 v[162:165], v170 offset:1024
	ds_read_b128 v[166:169], v170 offset:2048
	ds_read_b128 v[170:173], v170 offset:3072
	s_add_u32 s24, s24, 0x80000
	s_addc_u32 s25, s25, 0
	s_mov_b32 m0, s31
	v_lshl_add_u64 v[226:227], s[24:25], 0, v[132:133]
	ds_read_b128 v[184:187], v141 offset:32768
	ds_read_b128 v[188:191], v141 offset:33792
	ds_read_b128 v[192:195], v141 offset:34816
	ds_read_b128 v[196:199], v141 offset:35840
	ds_read_b128 v[200:203], v141 offset:36864
	ds_read_b128 v[204:207], v141 offset:37888
	ds_read_b128 v[208:211], v141 offset:38912
	ds_read_b128 v[212:215], v141 offset:39936
	global_load_lds_dwordx4 v[226:227], off
	v_lshl_add_u64 v[226:227], s[24:25], 0, v[130:131]
	s_mov_b32 m0, s42
	s_nop 0
	global_load_lds_dwordx4 v[226:227], off
	s_waitcnt vmcnt(8)
	s_waitcnt lgkmcnt(0)
	s_barrier
	s_waitcnt lgkmcnt(0)
	v_mfma_f32_16x16x32_bf16 v[124:127], v[142:145], v[184:187], v[124:127]
	v_mfma_f32_16x16x32_bf16 v[116:119], v[150:153], v[184:187], v[116:119]
	v_mfma_f32_16x16x32_bf16 v[108:111], v[142:145], v[192:195], v[108:111]
	v_mfma_f32_16x16x32_bf16 v[100:103], v[150:153], v[192:195], v[100:103]
	v_mfma_f32_16x16x32_bf16 v[92:95], v[142:145], v[200:203], v[92:95]
	v_mfma_f32_16x16x32_bf16 v[84:87], v[150:153], v[200:203], v[84:87]
	v_mfma_f32_16x16x32_bf16 v[76:79], v[142:145], v[208:211], v[76:79]
	v_mfma_f32_16x16x32_bf16 v[68:71], v[150:153], v[208:211], v[68:71]
	v_mfma_f32_16x16x32_bf16 v[124:127], v[146:149], v[188:191], v[124:127]
	v_mfma_f32_16x16x32_bf16 v[116:119], v[154:157], v[188:191], v[116:119]
	v_mfma_f32_16x16x32_bf16 v[108:111], v[146:149], v[196:199], v[108:111]
	v_mfma_f32_16x16x32_bf16 v[100:103], v[154:157], v[196:199], v[100:103]
	v_mfma_f32_16x16x32_bf16 v[92:95], v[146:149], v[204:207], v[92:95]
	v_mfma_f32_16x16x32_bf16 v[84:87], v[154:157], v[204:207], v[84:87]
	v_mfma_f32_16x16x32_bf16 v[76:79], v[146:149], v[212:215], v[76:79]
	v_mfma_f32_16x16x32_bf16 v[68:71], v[154:157], v[212:215], v[68:71]
	v_mfma_f32_16x16x32_bf16 v[120:123], v[158:161], v[184:187], v[120:123]
	v_mfma_f32_16x16x32_bf16 v[112:115], v[166:169], v[184:187], v[112:115]
	v_mfma_f32_16x16x32_bf16 v[104:107], v[158:161], v[192:195], v[104:107]
	v_mfma_f32_16x16x32_bf16 v[96:99], v[166:169], v[192:195], v[96:99]
	v_mfma_f32_16x16x32_bf16 v[88:91], v[158:161], v[200:203], v[88:91]
	v_mfma_f32_16x16x32_bf16 v[80:83], v[166:169], v[200:203], v[80:83]
	v_mfma_f32_16x16x32_bf16 v[72:75], v[158:161], v[208:211], v[72:75]
	v_mfma_f32_16x16x32_bf16 v[64:67], v[166:169], v[208:211], v[64:67]
	v_mfma_f32_16x16x32_bf16 v[120:123], v[162:165], v[188:191], v[120:123]
	v_mfma_f32_16x16x32_bf16 v[112:115], v[170:173], v[188:191], v[112:115]
	v_mfma_f32_16x16x32_bf16 v[104:107], v[162:165], v[196:199], v[104:107]
	v_mfma_f32_16x16x32_bf16 v[96:99], v[170:173], v[196:199], v[96:99]
	v_mfma_f32_16x16x32_bf16 v[88:91], v[162:165], v[204:207], v[88:91]
	v_mfma_f32_16x16x32_bf16 v[80:83], v[170:173], v[204:207], v[80:83]
	v_mfma_f32_16x16x32_bf16 v[72:75], v[162:165], v[212:215], v[72:75]
	v_mfma_f32_16x16x32_bf16 v[64:67], v[170:173], v[212:215], v[64:67]
	s_barrier
; #define PG8_STAGE(bufoff, gbase, voff) do { _Pragma("unroll") for (int _i = 0; _i < 2; ++_i) \
;         __builtin_amdgcn_global_load_lds((const unsigned*)((const char*)(gbase) + (voff)[_i]), (LAS unsigned*)(lds + (bufoff) + ldsw + _i * 8192), 16, 0, 0); } while (0)
; #define PG8_LDA(dst, b, h) do { _Pragma("unroll") for (int m = 0; m < 4; ++m) _Pragma("unroll") for (int k = 0; k < 2; ++k) dst[m][k] = *(const LAS bf16x8*)(lds + PG8_SA(b, h) + aoff + m * 2048 + k * 1024); } while (0)
; #define PG8_MMA(ai, bj, At, Bt) do { __builtin_amdgcn_s_setprio(1); _Pragma("unroll") for (int m = 0; m < 4; ++m) _Pragma("unroll") for (int n = 0; n < 2; ++n) _Pragma("unroll") for (int k = 0; k < 2; ++k) \
;         acc[ai][bj][m][n] = __builtin_amdgcn_mfma_f32_16x16x32_bf16(Bt[n][k], At[m][k], acc[ai][bj][m][n], 0, 0, 0); __builtin_amdgcn_s_setprio(0); } while (0)
; #define PG8_WAIT_V(n) asm volatile("s_waitcnt vmcnt(" #n ")" ::: "memory")
; #define PG8_WAIT_L(n) asm volatile("s_waitcnt lgkmcnt(" #n ")" ::: "memory")
; #define PG8_BAR __builtin_amdgcn_s_barrier()
; #define PG8_SCHED __builtin_amdgcn_sched_barrier(0)
; template <class Epi, bool ALIGN_EPI = PG8_ALIGN>
; __device__ __forceinline__ void gemm_phase(LAS unsigned char* lds, const Gemm g, const StaticOrder& S, const Epi& E) {
;     ...
;             PG8_LDA(At, 1, 1); PG8_STAGE(PG8_SB(1, 0), b3, voffB); PG8_STAGE(PG8_SB(1, 1), b3 + hstepB, voffB); PG8_STAGE(PG8_SA(1, 0), a3, voffA);
;             PG8_WAIT_V(8); PG8_WAIT_L(0); PG8_BAR; PG8_MMA(1, 0, At, B0); PG8_MMA(1, 1, At, B1); PG8_BAR; PG8_SCHED;
;         }
	s_add_i32 s20, s20, s18
	v_lshl_add_u64 v[174:175], v[174:175], 0, s[0:1]
	s_mov_b32 m0, s20
	ds_read_b128 v[184:187], v141 offset:49152
	ds_read_b128 v[188:191], v141 offset:50176
	ds_read_b128 v[192:195], v141 offset:51200
	ds_read_b128 v[196:199], v141 offset:52224
	ds_read_b128 v[200:203], v141 offset:53248
	ds_read_b128 v[204:207], v141 offset:54272
	ds_read_b128 v[208:211], v141 offset:55296
	ds_read_b128 v[212:215], v141 offset:56320
	global_load_lds_dwordx4 v[174:175], off
	v_lshl_add_u64 v[174:175], v[216:217], 0, s[0:1]
	s_add_i32 m0, s20, 0x2000
	s_add_i32 s20, s21, s18
	global_load_lds_dwordx4 v[174:175], off
	v_lshl_add_u64 v[174:175], v[218:219], 0, s[0:1]
	s_mov_b32 m0, s20
	s_nop 0
	global_load_lds_dwordx4 v[174:175], off
	v_lshl_add_u64 v[174:175], v[220:221], 0, s[0:1]
	s_add_i32 m0, s20, 0x2000
	s_nop 0
	global_load_lds_dwordx4 v[174:175], off
	v_lshl_add_u64 v[174:175], v[222:223], 0, s[0:1]
	s_mov_b32 m0, s43
	s_nop 0
	global_load_lds_dwordx4 v[174:175], off
	v_lshl_add_u64 v[174:175], v[224:225], 0, s[0:1]
	s_mov_b32 m0, s44
	s_nop 0
	global_load_lds_dwordx4 v[174:175], off
	s_waitcnt vmcnt(8)
	s_waitcnt lgkmcnt(0)
	s_barrier
	s_waitcnt lgkmcnt(0)
	v_mfma_f32_16x16x32_bf16 v[60:63], v[142:145], v[184:187], v[60:63]
	v_mfma_f32_16x16x32_bf16 v[52:55], v[150:153], v[184:187], v[52:55]
	v_mfma_f32_16x16x32_bf16 v[44:47], v[142:145], v[192:195], v[44:47]
	v_mfma_f32_16x16x32_bf16 v[36:39], v[150:153], v[192:195], v[36:39]
	v_mfma_f32_16x16x32_bf16 v[28:31], v[142:145], v[200:203], v[28:31]
	v_mfma_f32_16x16x32_bf16 v[20:23], v[150:153], v[200:203], v[20:23]
	v_mfma_f32_16x16x32_bf16 v[12:15], v[142:145], v[208:211], v[12:15]
	v_mfma_f32_16x16x32_bf16 v[4:7], v[150:153], v[208:211], v[4:7]
	v_mfma_f32_16x16x32_bf16 v[60:63], v[146:149], v[188:191], v[60:63]
	v_mfma_f32_16x16x32_bf16 v[52:55], v[154:157], v[188:191], v[52:55]
	v_mfma_f32_16x16x32_bf16 v[44:47], v[146:149], v[196:199], v[44:47]
	v_mfma_f32_16x16x32_bf16 v[36:39], v[154:157], v[196:199], v[36:39]
	v_mfma_f32_16x16x32_bf16 v[28:31], v[146:149], v[204:207], v[28:31]
	v_mfma_f32_16x16x32_bf16 v[20:23], v[154:157], v[204:207], v[20:23]
	v_mfma_f32_16x16x32_bf16 v[12:15], v[146:149], v[212:215], v[12:15]
	v_mfma_f32_16x16x32_bf16 v[4:7], v[154:157], v[212:215], v[4:7]
	v_mfma_f32_16x16x32_bf16 v[56:59], v[158:161], v[184:187], v[56:59]
	v_mfma_f32_16x16x32_bf16 v[48:51], v[166:169], v[184:187], v[48:51]
	v_mfma_f32_16x16x32_bf16 v[40:43], v[158:161], v[192:195], v[40:43]
	v_mfma_f32_16x16x32_bf16 v[32:35], v[166:169], v[192:195], v[32:35]
	v_mfma_f32_16x16x32_bf16 v[24:27], v[158:161], v[200:203], v[24:27]
	v_mfma_f32_16x16x32_bf16 v[16:19], v[166:169], v[200:203], v[16:19]
	v_mfma_f32_16x16x32_bf16 v[8:11], v[158:161], v[208:211], v[8:11]
	v_mfma_f32_16x16x32_bf16 v[0:3], v[166:169], v[208:211], v[0:3]
	v_mfma_f32_16x16x32_bf16 v[56:59], v[162:165], v[188:191], v[56:59]
	v_mfma_f32_16x16x32_bf16 v[48:51], v[170:173], v[188:191], v[48:51]
	v_mfma_f32_16x16x32_bf16 v[40:43], v[162:165], v[196:199], v[40:43]
	v_mfma_f32_16x16x32_bf16 v[32:35], v[170:173], v[196:199], v[32:35]
	v_mfma_f32_16x16x32_bf16 v[24:27], v[162:165], v[204:207], v[24:27]
	v_mfma_f32_16x16x32_bf16 v[16:19], v[170:173], v[204:207], v[16:19]
	v_mfma_f32_16x16x32_bf16 v[8:11], v[162:165], v[212:215], v[8:11]
	v_mfma_f32_16x16x32_bf16 v[0:3], v[170:173], v[212:215], v[0:3]
	s_barrier
	s_add_u32 s2, s2, 0x100
	s_addc_u32 s3, s3, 0
	s_add_u32 s36, s36, 0x100
	s_addc_u32 s37, s37, 0
	s_cmp_ge_i32 s49, s45
	s_mov_b32 s24, s49
	s_cbranch_scc0 .LBB0_219
	s_setprio 0

; template <class Epi, bool ALIGN_EPI = PG8_ALIGN>
; __device__ __forceinline__ void gemm_phase(LAS unsigned char* lds, const Gemm g, const StaticOrder& S, const Epi& E) {
;     ...
;     f32x4 acc[2][2][4][2];
; #pragma unroll
;     for (int a = 0; a < 2; ++a)
; #pragma unroll
;         for (int b = 0; b < 2; ++b)
; #pragma unroll
;             for (int m = 0; m < 4; ++m)
; #pragma unroll
;                 for (int n = 0; n < 2; ++n) acc[a][b][m][n] = (f32x4){0.f, 0.f, 0.f, 0.f};
;     ...
;         const bool has_next = S.next(ui + 1, nxt);
;         const char* nA = has_next ? (const char*)g.A + (size_t)nxt.pm * tstepA : cA; const char* nB = has_next ? (const char*)g.Bt + (size_t)nxt.pn * tstepB : cB;
;         for (int t = 0; t < nt; t += 2) {
.LBB0_293:
	v_mov_b32_e32 v127, 0
	s_andn2_b64 vcc, exec, s[12:13]
	v_mov_b32_e32 v126, 0
	v_mov_b32_e32 v125, 0
	v_mov_b32_e32 v124, 0
	v_mov_b32_e32 v123, 0
	v_mov_b32_e32 v122, 0
	v_mov_b32_e32 v121, 0
	v_mov_b32_e32 v120, 0
	v_mov_b32_e32 v101, 0
	v_mov_b32_e32 v100, 0
	v_mov_b32_e32 v103, 0
	v_mov_b32_e32 v102, 0
	v_mov_b32_e32 v109, 0
	v_mov_b32_e32 v108, 0
	v_mov_b32_e32 v111, 0
	v_mov_b32_e32 v110, 0
	v_mov_b32_e32 v85, 0
	v_mov_b32_e32 v84, 0
	v_mov_b32_e32 v87, 0
	v_mov_b32_e32 v86, 0
	v_mov_b32_e32 v93, 0
	v_mov_b32_e32 v92, 0
	v_mov_b32_e32 v95, 0
	v_mov_b32_e32 v94, 0
	v_mov_b32_e32 v73, 0
	v_mov_b32_e32 v72, 0
	v_mov_b32_e32 v75, 0
	v_mov_b32_e32 v74, 0
	v_mov_b32_e32 v77, 0
	v_mov_b32_e32 v76, 0
	v_mov_b32_e32 v79, 0
	v_mov_b32_e32 v78, 0
	v_mov_b32_e32 v139, 0
	v_mov_b32_e32 v138, 0
	v_mov_b32_e32 v141, 0
	v_mov_b32_e32 v140, 0
	v_mov_b32_e32 v143, 0
	v_mov_b32_e32 v142, 0
	v_mov_b32_e32 v145, 0
	v_mov_b32_e32 v144, 0
	v_mov_b32_e32 v113, 0
	v_mov_b32_e32 v112, 0
	v_mov_b32_e32 v115, 0
	v_mov_b32_e32 v114, 0
	v_mov_b32_e32 v117, 0
	v_mov_b32_e32 v116, 0
	v_mov_b32_e32 v119, 0
	v_mov_b32_e32 v118, 0
	v_mov_b32_e32 v97, 0
	v_mov_b32_e32 v96, 0
	v_mov_b32_e32 v99, 0
	v_mov_b32_e32 v98, 0
	v_mov_b32_e32 v105, 0
	v_mov_b32_e32 v104, 0
	v_mov_b32_e32 v107, 0
	v_mov_b32_e32 v106, 0
	v_mov_b32_e32 v71, 0
	v_mov_b32_e32 v70, 0
	v_mov_b32_e32 v69, 0
	v_mov_b32_e32 v68, 0
	v_mov_b32_e32 v67, 0
	v_mov_b32_e32 v66, 0
	v_mov_b32_e32 v65, 0
	v_mov_b32_e32 v64, 0
	v_mov_b32_e32 v63, 0
	v_mov_b32_e32 v62, 0
	v_mov_b32_e32 v61, 0
	v_mov_b32_e32 v60, 0
	v_mov_b32_e32 v59, 0
	v_mov_b32_e32 v58, 0
	v_mov_b32_e32 v57, 0
	v_mov_b32_e32 v56, 0
	v_mov_b32_e32 v37, 0
	v_mov_b32_e32 v36, 0
	v_mov_b32_e32 v39, 0
	v_mov_b32_e32 v38, 0
	v_mov_b32_e32 v45, 0
	v_mov_b32_e32 v44, 0
	v_mov_b32_e32 v47, 0
	v_mov_b32_e32 v46, 0
	v_mov_b32_e32 v21, 0
	v_mov_b32_e32 v20, 0
	v_mov_b32_e32 v23, 0
	v_mov_b32_e32 v22, 0
	v_mov_b32_e32 v29, 0
	v_mov_b32_e32 v28, 0
	v_mov_b32_e32 v31, 0
	v_mov_b32_e32 v30, 0
	v_mov_b32_e32 v9, 0
	v_mov_b32_e32 v8, 0
	v_mov_b32_e32 v11, 0
	v_mov_b32_e32 v10, 0
	v_mov_b32_e32 v13, 0
	v_mov_b32_e32 v12, 0
	v_mov_b32_e32 v15, 0
	v_mov_b32_e32 v14, 0
	v_mov_b32_e32 v81, 0
	v_mov_b32_e32 v80, 0
	v_mov_b32_e32 v83, 0
	v_mov_b32_e32 v82, 0
	v_mov_b32_e32 v89, 0
	v_mov_b32_e32 v88, 0
	v_mov_b32_e32 v91, 0
	v_mov_b32_e32 v90, 0
	v_mov_b32_e32 v49, 0
	v_mov_b32_e32 v48, 0
	v_mov_b32_e32 v51, 0
	v_mov_b32_e32 v50, 0
	v_mov_b32_e32 v53, 0
	v_mov_b32_e32 v52, 0
	v_mov_b32_e32 v55, 0
	v_mov_b32_e32 v54, 0
	v_mov_b32_e32 v33, 0
	v_mov_b32_e32 v32, 0
	v_mov_b32_e32 v35, 0
	v_mov_b32_e32 v34, 0
	v_mov_b32_e32 v41, 0
	v_mov_b32_e32 v40, 0
	v_mov_b32_e32 v43, 0
	v_mov_b32_e32 v42, 0
	v_mov_b32_e32 v7, 0
	v_mov_b32_e32 v6, 0
	v_mov_b32_e32 v5, 0
	v_mov_b32_e32 v4, 0
	v_mov_b32_e32 v3, 0
	v_mov_b32_e32 v2, 0
	v_mov_b32_e32 v1, 0
	v_mov_b32_e32 v0, 0
	s_cbranch_vccnz .LBB0_297
	s_add_u32 s51, s36, 0x100
	v_mov_b32_e32 v0, 0
	s_addc_u32 s52, s37, 0
	s_mov_b32 s38, 0
	v_mov_b32_e32 v1, v0
	v_mov_b32_e32 v2, v0
	v_mov_b32_e32 v3, v0
	v_mov_b32_e32 v4, v0
	v_mov_b32_e32 v5, v0
	v_mov_b32_e32 v6, v0
	v_mov_b32_e32 v7, v0
	v_mov_b32_e32 v8, v0
	v_mov_b32_e32 v9, v0
	v_mov_b32_e32 v10, v0
	v_mov_b32_e32 v11, v0
	v_mov_b32_e32 v12, v0
	v_mov_b32_e32 v13, v0
	v_mov_b32_e32 v14, v0
	v_mov_b32_e32 v15, v0
	v_mov_b32_e32 v20, v0
	v_mov_b32_e32 v21, v0
	v_mov_b32_e32 v22, v0
	v_mov_b32_e32 v23, v0
	v_mov_b32_e32 v28, v0
	v_mov_b32_e32 v29, v0
	v_mov_b32_e32 v30, v0
	v_mov_b32_e32 v31, v0
	v_mov_b32_e32 v36, v0
	v_mov_b32_e32 v37, v0
	v_mov_b32_e32 v38, v0
	v_mov_b32_e32 v39, v0
	v_mov_b32_e32 v44, v0
	v_mov_b32_e32 v45, v0
	v_mov_b32_e32 v46, v0
	v_mov_b32_e32 v47, v0
	v_mov_b32_e32 v16, v0
	v_mov_b32_e32 v17, v0
	v_mov_b32_e32 v18, v0
	v_mov_b32_e32 v19, v0
	v_mov_b32_e32 v24, v0
	v_mov_b32_e32 v25, v0
	v_mov_b32_e32 v26, v0
	v_mov_b32_e32 v27, v0
	v_mov_b32_e32 v32, v0
	v_mov_b32_e32 v33, v0
	v_mov_b32_e32 v34, v0
	v_mov_b32_e32 v35, v0
	v_mov_b32_e32 v40, v0
	v_mov_b32_e32 v41, v0
	v_mov_b32_e32 v42, v0
	v_mov_b32_e32 v43, v0
	v_mov_b32_e32 v48, v0
	v_mov_b32_e32 v49, v0
	v_mov_b32_e32 v50, v0
	v_mov_b32_e32 v51, v0
	v_mov_b32_e32 v52, v0
	v_mov_b32_e32 v53, v0
	v_mov_b32_e32 v54, v0
	v_mov_b32_e32 v55, v0
	v_mov_b32_e32 v56, v0
	v_mov_b32_e32 v57, v0
	v_mov_b32_e32 v58, v0
	v_mov_b32_e32 v59, v0
	v_mov_b32_e32 v60, v0
	v_mov_b32_e32 v61, v0
	v_mov_b32_e32 v62, v0
	v_mov_b32_e32 v63, v0
	v_mov_b32_e32 v64, v0
	v_mov_b32_e32 v65, v0
	v_mov_b32_e32 v66, v0
	v_mov_b32_e32 v67, v0
	v_mov_b32_e32 v68, v0
	v_mov_b32_e32 v69, v0
	v_mov_b32_e32 v70, v0
	v_mov_b32_e32 v71, v0
	v_mov_b32_e32 v72, v0
	v_mov_b32_e32 v73, v0
	v_mov_b32_e32 v74, v0
	v_mov_b32_e32 v75, v0
	v_mov_b32_e32 v76, v0
	v_mov_b32_e32 v77, v0
	v_mov_b32_e32 v78, v0
	v_mov_b32_e32 v79, v0
	v_mov_b32_e32 v84, v0
	v_mov_b32_e32 v85, v0
	v_mov_b32_e32 v86, v0
	v_mov_b32_e32 v87, v0
	v_mov_b32_e32 v92, v0
	v_mov_b32_e32 v93, v0
	v_mov_b32_e32 v94, v0
	v_mov_b32_e32 v95, v0
	v_mov_b32_e32 v100, v0
	v_mov_b32_e32 v101, v0
	v_mov_b32_e32 v102, v0
	v_mov_b32_e32 v103, v0
	v_mov_b32_e32 v108, v0
	v_mov_b32_e32 v109, v0
	v_mov_b32_e32 v110, v0
	v_mov_b32_e32 v111, v0
	v_mov_b32_e32 v80, v0
	v_mov_b32_e32 v81, v0
	v_mov_b32_e32 v82, v0
	v_mov_b32_e32 v83, v0
	v_mov_b32_e32 v88, v0
	v_mov_b32_e32 v89, v0
	v_mov_b32_e32 v90, v0
	v_mov_b32_e32 v91, v0
	v_mov_b32_e32 v96, v0
	v_mov_b32_e32 v97, v0
	v_mov_b32_e32 v98, v0
	v_mov_b32_e32 v99, v0
	v_mov_b32_e32 v104, v0
	v_mov_b32_e32 v105, v0
	v_mov_b32_e32 v106, v0
	v_mov_b32_e32 v107, v0
	v_mov_b32_e32 v112, v0
	v_mov_b32_e32 v113, v0
	v_mov_b32_e32 v114, v0
	v_mov_b32_e32 v115, v0
	v_mov_b32_e32 v116, v0
	v_mov_b32_e32 v117, v0
	v_mov_b32_e32 v118, v0
	v_mov_b32_e32 v119, v0
	v_mov_b32_e32 v120, v0
	v_mov_b32_e32 v121, v0
	v_mov_b32_e32 v122, v0
	v_mov_b32_e32 v123, v0
	v_mov_b32_e32 v124, v0
	v_mov_b32_e32 v125, v0
	v_mov_b32_e32 v126, v0
	v_mov_b32_e32 v127, v0
	v_readfirstlane_b32 s100, v238
	s_cmp_lt_u32 s100, 0x100
	s_cbranch_scc1 .Lgp_295
	s_setprio 1
; #define PG8_STAGE(bufoff, gbase, voff) do { _Pragma("unroll") for (int _i = 0; _i < 2; ++_i) \
;         __builtin_amdgcn_global_load_lds((const unsigned*)((const char*)(gbase) + (voff)[_i]), (LAS unsigned*)(lds + (bufoff) + ldsw + _i * 8192), 16, 0, 0); } while (0)
; #define PG8_LDA(dst, b, h) do { _Pragma("unroll") for (int m = 0; m < 4; ++m) _Pragma("unroll") for (int k = 0; k < 2; ++k) dst[m][k] = *(const LAS bf16x8*)(lds + PG8_SA(b, h) + aoff + m * 2048 + k * 1024); } while (0)
; #define PG8_LDB(dst, b, h) do { _Pragma("unroll") for (int n = 0; n < 2; ++n) _Pragma("unroll") for (int k = 0; k < 2; ++k) dst[n][k] = *(const LAS bf16x8*)(lds + PG8_SB(b, h) + boff + n * 2048 + k * 1024); } while (0)
; #define PG8_MMA(ai, bj, At, Bt) do { __builtin_amdgcn_s_setprio(1); _Pragma("unroll") for (int m = 0; m < 4; ++m) _Pragma("unroll") for (int n = 0; n < 2; ++n) _Pragma("unroll") for (int k = 0; k < 2; ++k) \
;         acc[ai][bj][m][n] = __builtin_amdgcn_mfma_f32_16x16x32_bf16(Bt[n][k], At[m][k], acc[ai][bj][m][n], 0, 0, 0); __builtin_amdgcn_s_setprio(0); } while (0)
; #define PG8_BAR __builtin_amdgcn_s_barrier()
; template <class Epi, bool ALIGN_EPI = PG8_ALIGN>
; __device__ __forceinline__ void gemm_phase(LAS unsigned char* lds, const Gemm g, const StaticOrder& S, const Epi& E) {
;     ...
;         const bool has_next = S.next(ui + 1, nxt);
;         const char* nA = has_next ? (const char*)g.A + (size_t)nxt.pm * tstepA : cA; const char* nB = has_next ? (const char*)g.Bt + (size_t)nxt.pn * tstepB : cB;
;         for (int t = 0; t < nt; t += 2) {
;             const bool last = (t == nt - 2);
;             const char* a1 = cA + (size_t)(t + 1) * kstep;
;             const char* a2 = last ? nA : cA + (size_t)(t + 2) * kstep; const char* b2 = last ? nB : cB + (size_t)(t + 2) * kstep;
;             const char* a3 = a2 + kstep; const char* b3 = b2 + kstep;
;             PG8_LDB(B0, 0, 0); PG8_LDB(B1, 0, 1); PG8_SCHED; PG8_LDA(At, 0, 0); PG8_STAGE(PG8_SA(1, 1), a1 + hstepA, voffA);
;             PG8_WAIT_V(8); PG8_WAIT_L(0); PG8_BAR; PG8_MMA(0, 0, At, B0); PG8_MMA(0, 1, At, B1); PG8_BAR; PG8_SCHED;
;             PG8_LDA(At, 0, 1); PG8_STAGE(PG8_SB(0, 0), b2, voffB); PG8_STAGE(PG8_SB(0, 1), b2 + hstepB, voffB); PG8_STAGE(PG8_SA(0, 0), a2, voffA);
;             PG8_WAIT_V(8); PG8_WAIT_L(0); PG8_BAR; PG8_MMA(1, 0, At, B0); PG8_MMA(1, 1, At, B1); PG8_BAR; PG8_SCHED;
.Lgp_295:
.LBB0_295:
	s_add_i32 s53, s38, 2
	s_add_u32 s36, s24, 0x100
	s_addc_u32 s37, s25, 0
	s_add_i32 s20, 16, 0x10000
	s_cmp_eq_u32 s26, s38
	s_cselect_b32 s39, s3, s37
	s_cselect_b32 s38, s2, s36
	s_cselect_b32 s55, s17, s52
	s_cselect_b32 s54, s16, s51
	s_add_i32 s21, 16, 0x14000
	v_add_u32_e32 v154, s20, v147
	v_add_u32_e32 v170, s21, v147
	ds_read_b128 v[138:141], v154
	ds_read_b128 v[142:145], v154 offset:1024
	ds_read_b128 v[150:153], v154 offset:2048
	ds_read_b128 v[154:157], v154 offset:3072
	ds_read_b128 v[158:161], v170
	ds_read_b128 v[162:165], v170 offset:1024
	ds_read_b128 v[166:169], v170 offset:2048
	ds_read_b128 v[170:173], v170 offset:3072
	v_lshl_add_u64 v[174:175], s[24:25], 0, v[134:135]
	s_add_i32 m0, s31, 0xc000
	ds_read_b128 v[184:187], v149
	ds_read_b128 v[188:191], v149 offset:1024
	ds_read_b128 v[192:195], v149 offset:2048
	ds_read_b128 v[196:199], v149 offset:3072
	ds_read_b128 v[200:203], v149 offset:4096
	ds_read_b128 v[204:207], v149 offset:5120
	ds_read_b128 v[208:211], v149 offset:6144
	ds_read_b128 v[212:215], v149 offset:7168
	global_load_lds_dwordx4 v[174:175], off
	v_lshl_add_u64 v[174:175], s[24:25], 0, v[136:137]
	s_add_i32 m0, s31, 0xe000
	s_nop 0
	global_load_lds_dwordx4 v[174:175], off
	s_waitcnt vmcnt(8)
	s_waitcnt lgkmcnt(0)
	s_barrier
	s_waitcnt lgkmcnt(0)
	v_mfma_f32_16x16x32_bf16 v[124:127], v[138:141], v[184:187], v[124:127]
	v_mfma_f32_16x16x32_bf16 v[120:123], v[150:153], v[184:187], v[120:123]
	v_mfma_f32_16x16x32_bf16 v[116:119], v[138:141], v[192:195], v[116:119]
	v_mfma_f32_16x16x32_bf16 v[112:115], v[150:153], v[192:195], v[112:115]
	v_mfma_f32_16x16x32_bf16 v[104:107], v[138:141], v[200:203], v[104:107]
	v_mfma_f32_16x16x32_bf16 v[96:99], v[150:153], v[200:203], v[96:99]
	v_mfma_f32_16x16x32_bf16 v[88:91], v[138:141], v[208:211], v[88:91]
	v_mfma_f32_16x16x32_bf16 v[80:83], v[150:153], v[208:211], v[80:83]
	v_mfma_f32_16x16x32_bf16 v[124:127], v[142:145], v[188:191], v[124:127]
	v_mfma_f32_16x16x32_bf16 v[120:123], v[154:157], v[188:191], v[120:123]
	v_mfma_f32_16x16x32_bf16 v[116:119], v[142:145], v[196:199], v[116:119]
	v_mfma_f32_16x16x32_bf16 v[112:115], v[154:157], v[196:199], v[112:115]
	v_mfma_f32_16x16x32_bf16 v[104:107], v[142:145], v[204:207], v[104:107]
	v_mfma_f32_16x16x32_bf16 v[96:99], v[154:157], v[204:207], v[96:99]
	v_mfma_f32_16x16x32_bf16 v[88:91], v[142:145], v[212:215], v[88:91]
	v_mfma_f32_16x16x32_bf16 v[80:83], v[154:157], v[212:215], v[80:83]
	v_mfma_f32_16x16x32_bf16 v[108:111], v[158:161], v[184:187], v[108:111]
	v_mfma_f32_16x16x32_bf16 v[100:103], v[166:169], v[184:187], v[100:103]
	v_mfma_f32_16x16x32_bf16 v[92:95], v[158:161], v[192:195], v[92:95]
	v_mfma_f32_16x16x32_bf16 v[84:87], v[166:169], v[192:195], v[84:87]
	v_mfma_f32_16x16x32_bf16 v[76:79], v[158:161], v[200:203], v[76:79]
	v_mfma_f32_16x16x32_bf16 v[72:75], v[166:169], v[200:203], v[72:75]
	v_mfma_f32_16x16x32_bf16 v[68:71], v[158:161], v[208:211], v[68:71]
	v_mfma_f32_16x16x32_bf16 v[64:67], v[166:169], v[208:211], v[64:67]
	v_mfma_f32_16x16x32_bf16 v[108:111], v[162:165], v[188:191], v[108:111]
	v_mfma_f32_16x16x32_bf16 v[100:103], v[170:173], v[188:191], v[100:103]
	v_mfma_f32_16x16x32_bf16 v[92:95], v[162:165], v[196:199], v[92:95]
	v_mfma_f32_16x16x32_bf16 v[84:87], v[170:173], v[196:199], v[84:87]
	v_mfma_f32_16x16x32_bf16 v[76:79], v[162:165], v[204:207], v[76:79]
	v_mfma_f32_16x16x32_bf16 v[72:75], v[170:173], v[204:207], v[72:75]
	v_mfma_f32_16x16x32_bf16 v[68:71], v[162:165], v[212:215], v[68:71]
	v_mfma_f32_16x16x32_bf16 v[64:67], v[170:173], v[212:215], v[64:67]
	s_barrier
	s_add_i32 s20, s20, s18
	v_lshl_add_u64 v[174:175], s[54:55], 0, v[176:177]
	s_mov_b32 m0, s20
	ds_read_b128 v[184:187], v149 offset:16384
	ds_read_b128 v[188:191], v149 offset:17408
	ds_read_b128 v[192:195], v149 offset:18432
	ds_read_b128 v[196:199], v149 offset:19456
	ds_read_b128 v[200:203], v149 offset:20480
	ds_read_b128 v[204:207], v149 offset:21504
	ds_read_b128 v[208:211], v149 offset:22528
	ds_read_b128 v[212:215], v149 offset:23552
	global_load_lds_dwordx4 v[174:175], off
	s_add_i32 m0, s20, 0x2000
	s_add_u32 s24, s54, s6
	v_lshl_add_u64 v[216:217], s[54:55], 0, v[128:129]
	s_addc_u32 s25, s55, s7
	s_add_i32 s20, s21, s18
	global_load_lds_dwordx4 v[216:217], off
	v_lshl_add_u64 v[218:219], s[24:25], 0, v[176:177]
	s_mov_b32 m0, s20
	v_lshl_add_u64 v[220:221], s[24:25], 0, v[128:129]
	global_load_lds_dwordx4 v[218:219], off
	s_add_i32 m0, s20, 0x2000
	v_lshl_add_u64 v[222:223], s[38:39], 0, v[132:133]
	global_load_lds_dwordx4 v[220:221], off
	s_mov_b32 m0, s31
	v_lshl_add_u64 v[224:225], s[38:39], 0, v[130:131]
	global_load_lds_dwordx4 v[222:223], off
	s_mov_b32 m0, s40
	s_nop 0
	global_load_lds_dwordx4 v[224:225], off
	s_waitcnt vmcnt(8)
	s_waitcnt lgkmcnt(0)
	s_barrier
; #define PG8_STAGE(bufoff, gbase, voff) do { _Pragma("unroll") for (int _i = 0; _i < 2; ++_i) \
;         __builtin_amdgcn_global_load_lds((const unsigned*)((const char*)(gbase) + (voff)[_i]), (LAS unsigned*)(lds + (bufoff) + ldsw + _i * 8192), 16, 0, 0); } while (0)
; #define PG8_LDA(dst, b, h) do { _Pragma("unroll") for (int m = 0; m < 4; ++m) _Pragma("unroll") for (int k = 0; k < 2; ++k) dst[m][k] = *(const LAS bf16x8*)(lds + PG8_SA(b, h) + aoff + m * 2048 + k * 1024); } while (0)
; #define PG8_LDB(dst, b, h) do { _Pragma("unroll") for (int n = 0; n < 2; ++n) _Pragma("unroll") for (int k = 0; k < 2; ++k) dst[n][k] = *(const LAS bf16x8*)(lds + PG8_SB(b, h) + boff + n * 2048 + k * 1024); } while (0)
; #define PG8_MMA(ai, bj, At, Bt) do { __builtin_amdgcn_s_setprio(1); _Pragma("unroll") for (int m = 0; m < 4; ++m) _Pragma("unroll") for (int n = 0; n < 2; ++n) _Pragma("unroll") for (int k = 0; k < 2; ++k) \
;         acc[ai][bj][m][n] = __builtin_amdgcn_mfma_f32_16x16x32_bf16(Bt[n][k], At[m][k], acc[ai][bj][m][n], 0, 0, 0); __builtin_amdgcn_s_setprio(0); } while (0)
; #define PG8_WAIT_V(n) asm volatile("s_waitcnt vmcnt(" #n ")" ::: "memory")
; #define PG8_WAIT_L(n) asm volatile("s_waitcnt lgkmcnt(" #n ")" ::: "memory")
; #define PG8_BAR __builtin_amdgcn_s_barrier()
; #define PG8_SCHED __builtin_amdgcn_sched_barrier(0)
; template <class Epi, bool ALIGN_EPI = PG8_ALIGN>
; __device__ __forceinline__ void gemm_phase(LAS unsigned char* lds, const Gemm g, const StaticOrder& S, const Epi& E) {
;     ...
;             PG8_WAIT_V(8); PG8_WAIT_L(0); PG8_BAR; PG8_MMA(1, 0, At, B0); PG8_MMA(1, 1, At, B1); PG8_BAR; PG8_SCHED;
;             PG8_LDB(B0, 1, 0); PG8_LDB(B1, 1, 1); PG8_SCHED; PG8_LDA(At, 1, 0); PG8_STAGE(PG8_SA(0, 1), a2 + hstepA, voffA);
;             PG8_WAIT_V(8); PG8_WAIT_L(0); PG8_BAR; PG8_MMA(0, 0, At, B0); PG8_MMA(0, 1, At, B1); PG8_BAR; PG8_SCHED;
;             PG8_LDA(At, 1, 1); PG8_STAGE(PG8_SB(1, 0), b3, voffB); PG8_STAGE(PG8_SB(1, 1), b3 + hstepB, voffB); PG8_STAGE(PG8_SA(1, 0), a3, voffA);
;             PG8_WAIT_V(8); PG8_WAIT_L(0); PG8_BAR; PG8_MMA(1, 0, At, B0); PG8_MMA(1, 1, At, B1); PG8_BAR; PG8_SCHED;
	s_waitcnt lgkmcnt(0)
	v_mfma_f32_16x16x32_bf16 v[60:63], v[138:141], v[184:187], v[60:63]
	v_mfma_f32_16x16x32_bf16 v[56:59], v[150:153], v[184:187], v[56:59]
	v_mfma_f32_16x16x32_bf16 v[52:55], v[138:141], v[192:195], v[52:55]
	v_mfma_f32_16x16x32_bf16 v[48:51], v[150:153], v[192:195], v[48:51]
	v_mfma_f32_16x16x32_bf16 v[40:43], v[138:141], v[200:203], v[40:43]
	v_mfma_f32_16x16x32_bf16 v[32:35], v[150:153], v[200:203], v[32:35]
	v_mfma_f32_16x16x32_bf16 v[24:27], v[138:141], v[208:211], v[24:27]
	v_mfma_f32_16x16x32_bf16 v[16:19], v[150:153], v[208:211], v[16:19]
	v_mfma_f32_16x16x32_bf16 v[60:63], v[142:145], v[188:191], v[60:63]
	v_mfma_f32_16x16x32_bf16 v[56:59], v[154:157], v[188:191], v[56:59]
	v_mfma_f32_16x16x32_bf16 v[52:55], v[142:145], v[196:199], v[52:55]
	v_mfma_f32_16x16x32_bf16 v[48:51], v[154:157], v[196:199], v[48:51]
	v_mfma_f32_16x16x32_bf16 v[40:43], v[142:145], v[204:207], v[40:43]
	v_mfma_f32_16x16x32_bf16 v[32:35], v[154:157], v[204:207], v[32:35]
	v_mfma_f32_16x16x32_bf16 v[24:27], v[142:145], v[212:215], v[24:27]
	v_mfma_f32_16x16x32_bf16 v[16:19], v[154:157], v[212:215], v[16:19]
	v_mfma_f32_16x16x32_bf16 v[44:47], v[158:161], v[184:187], v[44:47]
	v_mfma_f32_16x16x32_bf16 v[36:39], v[166:169], v[184:187], v[36:39]
	v_mfma_f32_16x16x32_bf16 v[28:31], v[158:161], v[192:195], v[28:31]
	v_mfma_f32_16x16x32_bf16 v[20:23], v[166:169], v[192:195], v[20:23]
	v_mfma_f32_16x16x32_bf16 v[12:15], v[158:161], v[200:203], v[12:15]
	v_mfma_f32_16x16x32_bf16 v[8:11], v[166:169], v[200:203], v[8:11]
	v_mfma_f32_16x16x32_bf16 v[4:7], v[158:161], v[208:211], v[4:7]
	v_mfma_f32_16x16x32_bf16 v[0:3], v[166:169], v[208:211], v[0:3]
	v_mfma_f32_16x16x32_bf16 v[44:47], v[162:165], v[188:191], v[44:47]
	v_mfma_f32_16x16x32_bf16 v[36:39], v[170:173], v[188:191], v[36:39]
	v_mfma_f32_16x16x32_bf16 v[28:31], v[162:165], v[196:199], v[28:31]
	v_mfma_f32_16x16x32_bf16 v[20:23], v[170:173], v[196:199], v[20:23]
	v_mfma_f32_16x16x32_bf16 v[12:15], v[162:165], v[204:207], v[12:15]
	v_mfma_f32_16x16x32_bf16 v[8:11], v[170:173], v[204:207], v[8:11]
	v_mfma_f32_16x16x32_bf16 v[4:7], v[162:165], v[212:215], v[4:7]
	v_mfma_f32_16x16x32_bf16 v[0:3], v[170:173], v[212:215], v[0:3]
	s_barrier
	s_add_i32 s20, 16, 0x18000
	s_add_i32 s21, 16, 0x1c000
	v_add_u32_e32 v154, s20, v147
	v_add_u32_e32 v170, s21, v147
	ds_read_b128 v[138:141], v154
	ds_read_b128 v[142:145], v154 offset:1024
	ds_read_b128 v[150:153], v154 offset:2048
	ds_read_b128 v[154:157], v154 offset:3072
	ds_read_b128 v[158:161], v170
	ds_read_b128 v[162:165], v170 offset:1024
	ds_read_b128 v[166:169], v170 offset:2048
	ds_read_b128 v[170:173], v170 offset:3072
	s_add_u32 s24, s38, 0x160000
	s_addc_u32 s25, s39, 0
	s_mov_b32 m0, s41
	v_lshl_add_u64 v[226:227], s[24:25], 0, v[132:133]
	ds_read_b128 v[184:187], v149 offset:32768
	ds_read_b128 v[188:191], v149 offset:33792
	ds_read_b128 v[192:195], v149 offset:34816
	ds_read_b128 v[196:199], v149 offset:35840
	ds_read_b128 v[200:203], v149 offset:36864
	ds_read_b128 v[204:207], v149 offset:37888
	ds_read_b128 v[208:211], v149 offset:38912
	ds_read_b128 v[212:215], v149 offset:39936
	global_load_lds_dwordx4 v[226:227], off
	v_lshl_add_u64 v[226:227], s[24:25], 0, v[130:131]
	s_mov_b32 m0, s44
	s_nop 0
	global_load_lds_dwordx4 v[226:227], off
	s_waitcnt vmcnt(8)
	s_waitcnt lgkmcnt(0)
	s_barrier
	s_waitcnt lgkmcnt(0)
	v_mfma_f32_16x16x32_bf16 v[124:127], v[138:141], v[184:187], v[124:127]
	v_mfma_f32_16x16x32_bf16 v[120:123], v[150:153], v[184:187], v[120:123]
	v_mfma_f32_16x16x32_bf16 v[116:119], v[138:141], v[192:195], v[116:119]
	v_mfma_f32_16x16x32_bf16 v[112:115], v[150:153], v[192:195], v[112:115]
	v_mfma_f32_16x16x32_bf16 v[104:107], v[138:141], v[200:203], v[104:107]
	v_mfma_f32_16x16x32_bf16 v[96:99], v[150:153], v[200:203], v[96:99]
	v_mfma_f32_16x16x32_bf16 v[88:91], v[138:141], v[208:211], v[88:91]
	v_mfma_f32_16x16x32_bf16 v[80:83], v[150:153], v[208:211], v[80:83]
	v_mfma_f32_16x16x32_bf16 v[124:127], v[142:145], v[188:191], v[124:127]
	v_mfma_f32_16x16x32_bf16 v[120:123], v[154:157], v[188:191], v[120:123]
	v_mfma_f32_16x16x32_bf16 v[116:119], v[142:145], v[196:199], v[116:119]
	v_mfma_f32_16x16x32_bf16 v[112:115], v[154:157], v[196:199], v[112:115]
	v_mfma_f32_16x16x32_bf16 v[104:107], v[142:145], v[204:207], v[104:107]
	v_mfma_f32_16x16x32_bf16 v[96:99], v[154:157], v[204:207], v[96:99]
	v_mfma_f32_16x16x32_bf16 v[88:91], v[142:145], v[212:215], v[88:91]
	v_mfma_f32_16x16x32_bf16 v[80:83], v[154:157], v[212:215], v[80:83]
	v_mfma_f32_16x16x32_bf16 v[108:111], v[158:161], v[184:187], v[108:111]
	v_mfma_f32_16x16x32_bf16 v[100:103], v[166:169], v[184:187], v[100:103]
	v_mfma_f32_16x16x32_bf16 v[92:95], v[158:161], v[192:195], v[92:95]
	v_mfma_f32_16x16x32_bf16 v[84:87], v[166:169], v[192:195], v[84:87]
	v_mfma_f32_16x16x32_bf16 v[76:79], v[158:161], v[200:203], v[76:79]
	v_mfma_f32_16x16x32_bf16 v[72:75], v[166:169], v[200:203], v[72:75]
	v_mfma_f32_16x16x32_bf16 v[68:71], v[158:161], v[208:211], v[68:71]
	v_mfma_f32_16x16x32_bf16 v[64:67], v[166:169], v[208:211], v[64:67]
	v_mfma_f32_16x16x32_bf16 v[108:111], v[162:165], v[188:191], v[108:111]
	v_mfma_f32_16x16x32_bf16 v[100:103], v[170:173], v[188:191], v[100:103]
	v_mfma_f32_16x16x32_bf16 v[92:95], v[162:165], v[196:199], v[92:95]
	v_mfma_f32_16x16x32_bf16 v[84:87], v[170:173], v[196:199], v[84:87]
	v_mfma_f32_16x16x32_bf16 v[76:79], v[162:165], v[204:207], v[76:79]
	v_mfma_f32_16x16x32_bf16 v[72:75], v[170:173], v[204:207], v[72:75]
	v_mfma_f32_16x16x32_bf16 v[68:71], v[162:165], v[212:215], v[68:71]
	v_mfma_f32_16x16x32_bf16 v[64:67], v[170:173], v[212:215], v[64:67]
	s_barrier
; #define PG8_STAGE(bufoff, gbase, voff) do { _Pragma("unroll") for (int _i = 0; _i < 2; ++_i) \
;         __builtin_amdgcn_global_load_lds((const unsigned*)((const char*)(gbase) + (voff)[_i]), (LAS unsigned*)(lds + (bufoff) + ldsw + _i * 8192), 16, 0, 0); } while (0)
; #define PG8_LDA(dst, b, h) do { _Pragma("unroll") for (int m = 0; m < 4; ++m) _Pragma("unroll") for (int k = 0; k < 2; ++k) dst[m][k] = *(const LAS bf16x8*)(lds + PG8_SA(b, h) + aoff + m * 2048 + k * 1024); } while (0)
; #define PG8_LDB(dst, b, h) do { _Pragma("unroll") for (int n = 0; n < 2; ++n) _Pragma("unroll") for (int k = 0; k < 2; ++k) dst[n][k] = *(const LAS bf16x8*)(lds + PG8_SB(b, h) + boff + n * 2048 + k * 1024); } while (0)
; #define PG8_MMA(ai, bj, At, Bt) do { __builtin_amdgcn_s_setprio(1); _Pragma("unroll") for (int m = 0; m < 4; ++m) _Pragma("unroll") for (int n = 0; n < 2; ++n) _Pragma("unroll") for (int k = 0; k < 2; ++k) \
;         acc[ai][bj][m][n] = __builtin_amdgcn_mfma_f32_16x16x32_bf16(Bt[n][k], At[m][k], acc[ai][bj][m][n], 0, 0, 0); __builtin_amdgcn_s_setprio(0); } while (0)
; #define PG8_WAIT_V(n) asm volatile("s_waitcnt vmcnt(" #n ")" ::: "memory")
; #define PG8_WAIT_L(n) asm volatile("s_waitcnt lgkmcnt(" #n ")" ::: "memory")
; #define PG8_BAR __builtin_amdgcn_s_barrier()
; #define PG8_SCHED __builtin_amdgcn_sched_barrier(0)
; template <class Epi, bool ALIGN_EPI = PG8_ALIGN>
; __device__ __forceinline__ void gemm_phase(LAS unsigned char* lds, const Gemm g, const StaticOrder& S, const Epi& E) {
;     ...
;             PG8_LDB(B0, 1, 0); PG8_LDB(B1, 1, 1); PG8_SCHED; PG8_LDA(At, 1, 0); PG8_STAGE(PG8_SA(0, 1), a2 + hstepA, voffA);
;             PG8_WAIT_V(8); PG8_WAIT_L(0); PG8_BAR; PG8_MMA(0, 0, At, B0); PG8_MMA(0, 1, At, B1); PG8_BAR; PG8_SCHED;
;             PG8_LDA(At, 1, 1); PG8_STAGE(PG8_SB(1, 0), b3, voffB); PG8_STAGE(PG8_SB(1, 1), b3 + hstepB, voffB); PG8_STAGE(PG8_SA(1, 0), a3, voffA);
;             PG8_WAIT_V(8); PG8_WAIT_L(0); PG8_BAR; PG8_MMA(1, 0, At, B0); PG8_MMA(1, 1, At, B1); PG8_BAR; PG8_SCHED;
;         }
	s_add_i32 s20, s20, s18
	v_lshl_add_u64 v[174:175], v[174:175], 0, s[0:1]
	s_mov_b32 m0, s20
	ds_read_b128 v[184:187], v149 offset:49152
	ds_read_b128 v[188:191], v149 offset:50176
	ds_read_b128 v[192:195], v149 offset:51200
	ds_read_b128 v[196:199], v149 offset:52224
	ds_read_b128 v[200:203], v149 offset:53248
	ds_read_b128 v[204:207], v149 offset:54272
	ds_read_b128 v[208:211], v149 offset:55296
	ds_read_b128 v[212:215], v149 offset:56320
	global_load_lds_dwordx4 v[174:175], off
	v_lshl_add_u64 v[174:175], v[216:217], 0, s[0:1]
	s_add_i32 m0, s20, 0x2000
	s_add_i32 s20, s21, s18
	global_load_lds_dwordx4 v[174:175], off
	v_lshl_add_u64 v[174:175], v[218:219], 0, s[0:1]
	s_mov_b32 m0, s20
	s_nop 0
	global_load_lds_dwordx4 v[174:175], off
	v_lshl_add_u64 v[174:175], v[220:221], 0, s[0:1]
	s_add_i32 m0, s20, 0x2000
	s_nop 0
	global_load_lds_dwordx4 v[174:175], off
	v_lshl_add_u64 v[174:175], v[222:223], 0, s[0:1]
	s_mov_b32 m0, s45
	s_nop 0
	global_load_lds_dwordx4 v[174:175], off
	v_lshl_add_u64 v[174:175], v[224:225], 0, s[0:1]
	s_mov_b32 m0, s46
	s_nop 0
	global_load_lds_dwordx4 v[174:175], off
	s_waitcnt vmcnt(8)
	s_waitcnt lgkmcnt(0)
	s_barrier
	s_waitcnt lgkmcnt(0)
	v_mfma_f32_16x16x32_bf16 v[60:63], v[138:141], v[184:187], v[60:63]
	v_mfma_f32_16x16x32_bf16 v[56:59], v[150:153], v[184:187], v[56:59]
	v_mfma_f32_16x16x32_bf16 v[52:55], v[138:141], v[192:195], v[52:55]
	v_mfma_f32_16x16x32_bf16 v[48:51], v[150:153], v[192:195], v[48:51]
	v_mfma_f32_16x16x32_bf16 v[40:43], v[138:141], v[200:203], v[40:43]
	v_mfma_f32_16x16x32_bf16 v[32:35], v[150:153], v[200:203], v[32:35]
	v_mfma_f32_16x16x32_bf16 v[24:27], v[138:141], v[208:211], v[24:27]
	v_mfma_f32_16x16x32_bf16 v[16:19], v[150:153], v[208:211], v[16:19]
	v_mfma_f32_16x16x32_bf16 v[60:63], v[142:145], v[188:191], v[60:63]
	v_mfma_f32_16x16x32_bf16 v[56:59], v[154:157], v[188:191], v[56:59]
	v_mfma_f32_16x16x32_bf16 v[52:55], v[142:145], v[196:199], v[52:55]
	v_mfma_f32_16x16x32_bf16 v[48:51], v[154:157], v[196:199], v[48:51]
	v_mfma_f32_16x16x32_bf16 v[40:43], v[142:145], v[204:207], v[40:43]
	v_mfma_f32_16x16x32_bf16 v[32:35], v[154:157], v[204:207], v[32:35]
	v_mfma_f32_16x16x32_bf16 v[24:27], v[142:145], v[212:215], v[24:27]
	v_mfma_f32_16x16x32_bf16 v[16:19], v[154:157], v[212:215], v[16:19]
	v_mfma_f32_16x16x32_bf16 v[44:47], v[158:161], v[184:187], v[44:47]
	v_mfma_f32_16x16x32_bf16 v[36:39], v[166:169], v[184:187], v[36:39]
	v_mfma_f32_16x16x32_bf16 v[28:31], v[158:161], v[192:195], v[28:31]
	v_mfma_f32_16x16x32_bf16 v[20:23], v[166:169], v[192:195], v[20:23]
	v_mfma_f32_16x16x32_bf16 v[12:15], v[158:161], v[200:203], v[12:15]
	v_mfma_f32_16x16x32_bf16 v[8:11], v[166:169], v[200:203], v[8:11]
	v_mfma_f32_16x16x32_bf16 v[4:7], v[158:161], v[208:211], v[4:7]
	v_mfma_f32_16x16x32_bf16 v[0:3], v[166:169], v[208:211], v[0:3]
	v_mfma_f32_16x16x32_bf16 v[44:47], v[162:165], v[188:191], v[44:47]
	v_mfma_f32_16x16x32_bf16 v[36:39], v[170:173], v[188:191], v[36:39]
	v_mfma_f32_16x16x32_bf16 v[28:31], v[162:165], v[196:199], v[28:31]
	v_mfma_f32_16x16x32_bf16 v[20:23], v[170:173], v[196:199], v[20:23]
	v_mfma_f32_16x16x32_bf16 v[12:15], v[162:165], v[204:207], v[12:15]
	v_mfma_f32_16x16x32_bf16 v[8:11], v[170:173], v[204:207], v[8:11]
	v_mfma_f32_16x16x32_bf16 v[4:7], v[162:165], v[212:215], v[4:7]
	v_mfma_f32_16x16x32_bf16 v[0:3], v[170:173], v[212:215], v[0:3]
	s_barrier
	s_add_u32 s51, s51, 0x100
	s_addc_u32 s52, s52, 0
	s_cmp_ge_i32 s53, s47
	s_mov_b64 s[24:25], s[36:37]
	s_mov_b32 s38, s53
	s_cbranch_scc0 .LBB0_295
; __device__ __forceinline__ unsigned cvt_pk(float lo, float hi) { f32x2_t v = {lo, hi}; bf16x2_t b = __builtin_convertvector(v, bf16x2_t); return __builtin_bit_cast(unsigned, b); }
;     __device__ __forceinline__ void operator()(const f32x4 (&acc)[2][2][4][2], const Unit& u, int wr, int wc, int fr, int fq) const {
;         const int row0 = u.pm * BM + wr * 64 + fr, col0 = u.pn * BM + wc * 32 + 8 * fq;
;         float scv[2][4];
; #pragma unroll
;         for (int ai = 0; ai < 2; ++ai)
; #pragma unroll
;             for (int m = 0; m < 4; ++m) scv[ai][m] = rs ? rs[(size_t)(row0 + ai * HALF + m * 16) * rs_stride] * cs : cs;
; #pragma unroll
;         for (int ai = 0; ai < 2; ++ai)
; #pragma unroll
;             for (int m = 0; m < 4; ++m) {
;                 const int row = row0 + ai * HALF + m * 16; const float sc = scv[ai][m];
;                 bf16_t* rowp = O + (size_t)row * ldc + col0;
; #pragma unroll
;                 for (int bj = 0; bj < 2; ++bj) { const f32x4 v0 = acc[ai][bj][m][0] * sc, v1 = acc[ai][bj][m][1] * sc;
;                     u32x4 w; w.x = cvt_pk(v0[0], v0[1]); w.y = cvt_pk(v0[2], v0[3]); w.z = cvt_pk(v1[0], v1[1]); w.w = cvt_pk(v1[2], v1[3]);
	s_setprio 0
	v_pk_mul_f32 v[126:127], v[126:127], 0.5 op_sel_hi:[1,0]
	v_pk_mul_f32 v[124:125], v[124:125], 0.5 op_sel_hi:[1,0]
	v_pk_mul_f32 v[122:123], v[122:123], 0.5 op_sel_hi:[1,0]
	v_pk_mul_f32 v[120:121], v[120:121], 0.5 op_sel_hi:[1,0]
	v_pk_mul_f32 v[138:139], v[110:111], 0.5 op_sel_hi:[1,0]
	v_pk_mul_f32 v[140:141], v[108:109], 0.5 op_sel_hi:[1,0]
	v_pk_mul_f32 v[142:143], v[102:103], 0.5 op_sel_hi:[1,0]
	v_pk_mul_f32 v[144:145], v[100:101], 0.5 op_sel_hi:[1,0]
	v_pk_mul_f32 v[100:101], v[118:119], 0.5 op_sel_hi:[1,0]
	v_pk_mul_f32 v[102:103], v[116:117], 0.5 op_sel_hi:[1,0]
	v_pk_mul_f32 v[108:109], v[114:115], 0.5 op_sel_hi:[1,0]
	v_pk_mul_f32 v[110:111], v[112:113], 0.5 op_sel_hi:[1,0]
	v_pk_mul_f32 v[112:113], v[94:95], 0.5 op_sel_hi:[1,0]
	v_pk_mul_f32 v[114:115], v[92:93], 0.5 op_sel_hi:[1,0]
	v_pk_mul_f32 v[116:117], v[86:87], 0.5 op_sel_hi:[1,0]
	v_pk_mul_f32 v[118:119], v[84:85], 0.5 op_sel_hi:[1,0]
	v_pk_mul_f32 v[84:85], v[106:107], 0.5 op_sel_hi:[1,0]
	v_pk_mul_f32 v[86:87], v[104:105], 0.5 op_sel_hi:[1,0]
	v_pk_mul_f32 v[92:93], v[98:99], 0.5 op_sel_hi:[1,0]
	v_pk_mul_f32 v[94:95], v[96:97], 0.5 op_sel_hi:[1,0]
	v_pk_mul_f32 v[96:97], v[78:79], 0.5 op_sel_hi:[1,0]
	v_pk_mul_f32 v[98:99], v[76:77], 0.5 op_sel_hi:[1,0]
	v_pk_mul_f32 v[104:105], v[74:75], 0.5 op_sel_hi:[1,0]
	v_pk_mul_f32 v[106:107], v[72:73], 0.5 op_sel_hi:[1,0]
	v_pk_mul_f32 v[72:73], v[90:91], 0.5 op_sel_hi:[1,0]
	v_pk_mul_f32 v[74:75], v[88:89], 0.5 op_sel_hi:[1,0]
	v_pk_mul_f32 v[76:77], v[82:83], 0.5 op_sel_hi:[1,0]
	v_pk_mul_f32 v[78:79], v[80:81], 0.5 op_sel_hi:[1,0]
	v_pk_mul_f32 v[70:71], v[70:71], 0.5 op_sel_hi:[1,0]
	v_pk_mul_f32 v[68:69], v[68:69], 0.5 op_sel_hi:[1,0]
	v_pk_mul_f32 v[66:67], v[66:67], 0.5 op_sel_hi:[1,0]
	v_pk_mul_f32 v[64:65], v[64:65], 0.5 op_sel_hi:[1,0]
	v_pk_mul_f32 v[62:63], v[62:63], 0.5 op_sel_hi:[1,0]
	v_pk_mul_f32 v[60:61], v[60:61], 0.5 op_sel_hi:[1,0]
	v_pk_mul_f32 v[58:59], v[58:59], 0.5 op_sel_hi:[1,0]
	v_pk_mul_f32 v[56:57], v[56:57], 0.5 op_sel_hi:[1,0]
	v_pk_mul_f32 v[80:81], v[46:47], 0.5 op_sel_hi:[1,0]
	v_pk_mul_f32 v[82:83], v[44:45], 0.5 op_sel_hi:[1,0]
	v_pk_mul_f32 v[88:89], v[38:39], 0.5 op_sel_hi:[1,0]
	v_pk_mul_f32 v[90:91], v[36:37], 0.5 op_sel_hi:[1,0]
	v_pk_mul_f32 v[36:37], v[54:55], 0.5 op_sel_hi:[1,0]
	v_pk_mul_f32 v[38:39], v[52:53], 0.5 op_sel_hi:[1,0]
	v_pk_mul_f32 v[44:45], v[50:51], 0.5 op_sel_hi:[1,0]
	v_pk_mul_f32 v[46:47], v[48:49], 0.5 op_sel_hi:[1,0]
	v_pk_mul_f32 v[48:49], v[30:31], 0.5 op_sel_hi:[1,0]
	v_pk_mul_f32 v[50:51], v[28:29], 0.5 op_sel_hi:[1,0]
	v_pk_mul_f32 v[52:53], v[22:23], 0.5 op_sel_hi:[1,0]
	v_pk_mul_f32 v[54:55], v[20:21], 0.5 op_sel_hi:[1,0]
	v_pk_mul_f32 v[20:21], v[42:43], 0.5 op_sel_hi:[1,0]
	v_pk_mul_f32 v[22:23], v[40:41], 0.5 op_sel_hi:[1,0]
	v_pk_mul_f32 v[28:29], v[34:35], 0.5 op_sel_hi:[1,0]
	v_pk_mul_f32 v[30:31], v[32:33], 0.5 op_sel_hi:[1,0]
	v_pk_mul_f32 v[32:33], v[14:15], 0.5 op_sel_hi:[1,0]
	v_pk_mul_f32 v[34:35], v[12:13], 0.5 op_sel_hi:[1,0]
	v_pk_mul_f32 v[40:41], v[10:11], 0.5 op_sel_hi:[1,0]
	v_pk_mul_f32 v[42:43], v[8:9], 0.5 op_sel_hi:[1,0]
	v_pk_mul_f32 v[8:9], v[26:27], 0.5 op_sel_hi:[1,0]
	v_pk_mul_f32 v[10:11], v[24:25], 0.5 op_sel_hi:[1,0]
	v_pk_mul_f32 v[12:13], v[18:19], 0.5 op_sel_hi:[1,0]
	v_pk_mul_f32 v[14:15], v[16:17], 0.5 op_sel_hi:[1,0]
	v_pk_mul_f32 v[6:7], v[6:7], 0.5 op_sel_hi:[1,0]
	v_pk_mul_f32 v[4:5], v[4:5], 0.5 op_sel_hi:[1,0]
	v_pk_mul_f32 v[2:3], v[2:3], 0.5 op_sel_hi:[1,0]
	v_pk_mul_f32 v[0:1], v[0:1], 0.5 op_sel_hi:[1,0]

; #define PG8_STAGE(bufoff, gbase, voff) do { _Pragma("unroll") for (int _i = 0; _i < 2; ++_i) \
;         __builtin_amdgcn_global_load_lds((const unsigned*)((const char*)(gbase) + (voff)[_i]), (LAS unsigned*)(lds + (bufoff) + ldsw + _i * 8192), 16, 0, 0); } while (0)
; #define PG8_WAIT_V(n) asm volatile("s_waitcnt vmcnt(" #n ")" ::: "memory")
; #define PG8_BAR __builtin_amdgcn_s_barrier()
; template <class Epi, bool ALIGN_EPI = PG8_ALIGN>
; __device__ __forceinline__ void gemm_phase(LAS unsigned char* lds, const Gemm g, const StaticOrder& S, const Epi& E) {
;     ...
;     f32x4 acc[2][2][4][2];
; #pragma unroll
;     for (int a = 0; a < 2; ++a)
; #pragma unroll
;         for (int b = 0; b < 2; ++b)
; #pragma unroll
;             for (int m = 0; m < 4; ++m)
; #pragma unroll
;                 for (int n = 0; n < 2; ++n) acc[a][b][m][n] = (f32x4){0.f, 0.f, 0.f, 0.f};
;     bf16x8 At[4][2], B0[2][2], B1[2][2];
;     const char* cA = (const char*)g.A + (size_t)cur.pm * tstepA; const char* cB = (const char*)g.Bt + (size_t)cur.pn * tstepB;
;     PG8_STAGE(PG8_SB(0, 0), cB, voffB); PG8_STAGE(PG8_SB(0, 1), cB + hstepB, voffB); PG8_STAGE(PG8_SA(0, 0), cA, voffA); PG8_STAGE(PG8_SA(0, 1), cA + hstepA, voffA);
;     if (wr == 1) PG8_BAR;
;     PG8_WAIT_V(2); PG8_BAR;
;     PG8_STAGE(PG8_SB(1, 0), cB + kstep, voffB); PG8_STAGE(PG8_SA(1, 0), cA + kstep, voffA); PG8_STAGE(PG8_SB(1, 1), cB + hstepB + kstep, voffB);
;     PG8_WAIT_V(6); PG8_BAR;
;     for (;;) {
;         const bool has_next = S.next(ui + 1, nxt);
;         const char* nA = has_next ? (const char*)g.A + (size_t)nxt.pm * tstepA : cA; const char* nB = has_next ? (const char*)g.Bt + (size_t)nxt.pn * tstepB : cB;
.LBB0_456:
	s_ashr_i32 s17, s16, 31
	s_lshl_b64 s[36:37], s[16:17], 20
	s_add_u32 s36, s58, s36
	v_mov_b32_e32 v123, 0
	s_addc_u32 s37, s59, s37
	s_andn2_b64 vcc, exec, s[12:13]
	v_mov_b32_e32 v122, v123
	v_mov_b32_e32 v121, v123
	v_mov_b32_e32 v120, v123
	v_mov_b32_e32 v127, v123
	v_mov_b32_e32 v126, v123
	v_mov_b32_e32 v125, v123
	v_mov_b32_e32 v124, v123
	v_mov_b32_e32 v111, v123
	v_mov_b32_e32 v110, v123
	v_mov_b32_e32 v109, v123
	v_mov_b32_e32 v108, v123
	v_mov_b32_e32 v107, v123
	v_mov_b32_e32 v106, v123
	v_mov_b32_e32 v105, v123
	v_mov_b32_e32 v104, v123
	v_mov_b32_e32 v95, v123
	v_mov_b32_e32 v94, v123
	v_mov_b32_e32 v93, v123
	v_mov_b32_e32 v92, v123
	v_mov_b32_e32 v91, v123
	v_mov_b32_e32 v90, v123
	v_mov_b32_e32 v89, v123
	v_mov_b32_e32 v88, v123
	v_mov_b32_e32 v79, v123
	v_mov_b32_e32 v78, v123
	v_mov_b32_e32 v77, v123
	v_mov_b32_e32 v76, v123
	v_mov_b32_e32 v75, v123
	v_mov_b32_e32 v74, v123
	v_mov_b32_e32 v73, v123
	v_mov_b32_e32 v72, v123
	v_mov_b32_e32 v119, v123
	v_mov_b32_e32 v118, v123
	v_mov_b32_e32 v117, v123
	v_mov_b32_e32 v116, v123
	v_mov_b32_e32 v115, v123
	v_mov_b32_e32 v114, v123
	v_mov_b32_e32 v113, v123
	v_mov_b32_e32 v112, v123
	v_mov_b32_e32 v103, v123
	v_mov_b32_e32 v102, v123
	v_mov_b32_e32 v101, v123
	v_mov_b32_e32 v100, v123
	v_mov_b32_e32 v99, v123
	v_mov_b32_e32 v98, v123
	v_mov_b32_e32 v97, v123
	v_mov_b32_e32 v96, v123
	v_mov_b32_e32 v87, v123
	v_mov_b32_e32 v86, v123
	v_mov_b32_e32 v85, v123
	v_mov_b32_e32 v84, v123
	v_mov_b32_e32 v83, v123
	v_mov_b32_e32 v82, v123
	v_mov_b32_e32 v81, v123
	v_mov_b32_e32 v80, v123
	v_mov_b32_e32 v71, v123
	v_mov_b32_e32 v70, v123
	v_mov_b32_e32 v69, v123
	v_mov_b32_e32 v68, v123
	v_mov_b32_e32 v67, v123
	v_mov_b32_e32 v66, v123
	v_mov_b32_e32 v65, v123
	v_mov_b32_e32 v64, v123
	v_mov_b32_e32 v63, v123
	v_mov_b32_e32 v62, v123
	v_mov_b32_e32 v61, v123
	v_mov_b32_e32 v60, v123
	v_mov_b32_e32 v59, v123
	v_mov_b32_e32 v58, v123
	v_mov_b32_e32 v57, v123
	v_mov_b32_e32 v56, v123
	v_mov_b32_e32 v47, v123
	v_mov_b32_e32 v46, v123
	v_mov_b32_e32 v45, v123
	v_mov_b32_e32 v44, v123
	v_mov_b32_e32 v43, v123
	v_mov_b32_e32 v42, v123
	v_mov_b32_e32 v41, v123
	v_mov_b32_e32 v40, v123
	v_mov_b32_e32 v31, v123
	v_mov_b32_e32 v30, v123
	v_mov_b32_e32 v29, v123
	v_mov_b32_e32 v28, v123
	v_mov_b32_e32 v27, v123
	v_mov_b32_e32 v26, v123
	v_mov_b32_e32 v25, v123
	v_mov_b32_e32 v24, v123
	v_mov_b32_e32 v15, v123
	v_mov_b32_e32 v14, v123
	v_mov_b32_e32 v13, v123
	v_mov_b32_e32 v12, v123
	v_mov_b32_e32 v11, v123
	v_mov_b32_e32 v10, v123
	v_mov_b32_e32 v9, v123
	v_mov_b32_e32 v8, v123
	v_mov_b32_e32 v55, v123
	v_mov_b32_e32 v54, v123
	v_mov_b32_e32 v53, v123
	v_mov_b32_e32 v52, v123
	v_mov_b32_e32 v51, v123
	v_mov_b32_e32 v50, v123
	v_mov_b32_e32 v49, v123
	v_mov_b32_e32 v48, v123
	v_mov_b32_e32 v39, v123
	v_mov_b32_e32 v38, v123
	v_mov_b32_e32 v37, v123
	v_mov_b32_e32 v36, v123
	v_mov_b32_e32 v35, v123
	v_mov_b32_e32 v34, v123
	v_mov_b32_e32 v33, v123
	v_mov_b32_e32 v32, v123
	v_mov_b32_e32 v23, v123
	v_mov_b32_e32 v22, v123
	v_mov_b32_e32 v21, v123
	v_mov_b32_e32 v20, v123
	v_mov_b32_e32 v19, v123
	v_mov_b32_e32 v18, v123
	v_mov_b32_e32 v17, v123
	v_mov_b32_e32 v16, v123
	v_mov_b32_e32 v7, v123
	v_mov_b32_e32 v6, v123
	v_mov_b32_e32 v5, v123
	v_mov_b32_e32 v4, v123
	v_mov_b32_e32 v3, v123
	v_mov_b32_e32 v2, v123
	v_mov_b32_e32 v1, v123
	v_mov_b32_e32 v0, v123
	s_cbranch_vccnz .LBB0_459
	s_and_b64 s[4:5], s[4:5], exec
	s_cselect_b32 s17, s37, s41
	s_cselect_b32 s50, s36, s40
	s_add_u32 s4, s40, 0x80080
	s_addc_u32 s5, s41, 0
	s_add_u32 s40, s38, 0x100
	v_mov_b32_e32 v0, 0
	s_addc_u32 s41, s39, 0
	s_mov_b32 s38, 0
	v_mov_b32_e32 v1, v0
	v_mov_b32_e32 v2, v0
	v_mov_b32_e32 v3, v0
	v_mov_b32_e32 v4, v0
	v_mov_b32_e32 v5, v0
	v_mov_b32_e32 v6, v0
	v_mov_b32_e32 v7, v0
	v_mov_b32_e32 v16, v0
	v_mov_b32_e32 v17, v0
	v_mov_b32_e32 v18, v0
	v_mov_b32_e32 v19, v0
	v_mov_b32_e32 v20, v0
	v_mov_b32_e32 v21, v0
	v_mov_b32_e32 v22, v0
	v_mov_b32_e32 v23, v0
	v_mov_b32_e32 v32, v0
	v_mov_b32_e32 v33, v0
	v_mov_b32_e32 v34, v0
	v_mov_b32_e32 v35, v0
	v_mov_b32_e32 v36, v0
	v_mov_b32_e32 v37, v0
	v_mov_b32_e32 v38, v0
	v_mov_b32_e32 v39, v0
	v_mov_b32_e32 v48, v0
	v_mov_b32_e32 v49, v0
	v_mov_b32_e32 v50, v0
	v_mov_b32_e32 v51, v0
	v_mov_b32_e32 v52, v0
	v_mov_b32_e32 v53, v0
	v_mov_b32_e32 v54, v0
	v_mov_b32_e32 v55, v0
	v_mov_b32_e32 v8, v0
	v_mov_b32_e32 v9, v0
	v_mov_b32_e32 v10, v0
	v_mov_b32_e32 v11, v0
	v_mov_b32_e32 v12, v0
	v_mov_b32_e32 v13, v0
	v_mov_b32_e32 v14, v0
	v_mov_b32_e32 v15, v0
	v_mov_b32_e32 v24, v0
	v_mov_b32_e32 v25, v0
	v_mov_b32_e32 v26, v0
	v_mov_b32_e32 v27, v0
	v_mov_b32_e32 v28, v0
	v_mov_b32_e32 v29, v0
	v_mov_b32_e32 v30, v0
	v_mov_b32_e32 v31, v0
	v_mov_b32_e32 v40, v0
	v_mov_b32_e32 v41, v0
	v_mov_b32_e32 v42, v0
	v_mov_b32_e32 v43, v0
	v_mov_b32_e32 v44, v0
	v_mov_b32_e32 v45, v0
	v_mov_b32_e32 v46, v0
	v_mov_b32_e32 v47, v0
	v_mov_b32_e32 v56, v0
	v_mov_b32_e32 v57, v0
	v_mov_b32_e32 v58, v0
	v_mov_b32_e32 v59, v0
	v_mov_b32_e32 v60, v0
	v_mov_b32_e32 v61, v0
	v_mov_b32_e32 v62, v0
	v_mov_b32_e32 v63, v0
	v_mov_b32_e32 v64, v0
	v_mov_b32_e32 v65, v0
	v_mov_b32_e32 v66, v0
	v_mov_b32_e32 v67, v0
	v_mov_b32_e32 v68, v0
	v_mov_b32_e32 v69, v0
	v_mov_b32_e32 v70, v0
	v_mov_b32_e32 v71, v0
	v_mov_b32_e32 v80, v0
	v_mov_b32_e32 v81, v0
	v_mov_b32_e32 v82, v0
	v_mov_b32_e32 v83, v0
	v_mov_b32_e32 v84, v0
	v_mov_b32_e32 v85, v0
	v_mov_b32_e32 v86, v0
	v_mov_b32_e32 v87, v0
	v_mov_b32_e32 v96, v0
	v_mov_b32_e32 v97, v0
	v_mov_b32_e32 v98, v0
	v_mov_b32_e32 v99, v0
	v_mov_b32_e32 v100, v0
	v_mov_b32_e32 v101, v0
	v_mov_b32_e32 v102, v0
	v_mov_b32_e32 v103, v0
	v_mov_b32_e32 v112, v0
	v_mov_b32_e32 v113, v0
	v_mov_b32_e32 v114, v0
	v_mov_b32_e32 v115, v0
	v_mov_b32_e32 v116, v0
	v_mov_b32_e32 v117, v0
	v_mov_b32_e32 v118, v0
	v_mov_b32_e32 v119, v0
	v_mov_b32_e32 v72, v0
	v_mov_b32_e32 v73, v0
	v_mov_b32_e32 v74, v0
	v_mov_b32_e32 v75, v0
	v_mov_b32_e32 v76, v0
	v_mov_b32_e32 v77, v0
	v_mov_b32_e32 v78, v0
	v_mov_b32_e32 v79, v0
	v_mov_b32_e32 v88, v0
	v_mov_b32_e32 v89, v0
	v_mov_b32_e32 v90, v0
	v_mov_b32_e32 v91, v0
	v_mov_b32_e32 v92, v0
	v_mov_b32_e32 v93, v0
	v_mov_b32_e32 v94, v0
	v_mov_b32_e32 v95, v0
	v_mov_b32_e32 v104, v0
	v_mov_b32_e32 v105, v0
	v_mov_b32_e32 v106, v0
	v_mov_b32_e32 v107, v0
	v_mov_b32_e32 v108, v0
	v_mov_b32_e32 v109, v0
	v_mov_b32_e32 v110, v0
	v_mov_b32_e32 v111, v0
	v_mov_b32_e32 v124, v0
	v_mov_b32_e32 v125, v0
	v_mov_b32_e32 v126, v0
	v_mov_b32_e32 v127, v0
	v_mov_b32_e32 v120, v0
	v_mov_b32_e32 v121, v0
	v_mov_b32_e32 v122, v0
	v_mov_b32_e32 v123, v0
	v_readfirstlane_b32 s100, v238
	s_cmp_lt_u32 s100, 0x100
	s_cbranch_scc1 .Lgp_458
	s_setprio 1
; #define PG8_STAGE(bufoff, gbase, voff) do { _Pragma("unroll") for (int _i = 0; _i < 2; ++_i) \
;         __builtin_amdgcn_global_load_lds((const unsigned*)((const char*)(gbase) + (voff)[_i]), (LAS unsigned*)(lds + (bufoff) + ldsw + _i * 8192), 16, 0, 0); } while (0)
; #define PG8_LDA(dst, b, h) do { _Pragma("unroll") for (int m = 0; m < 4; ++m) _Pragma("unroll") for (int k = 0; k < 2; ++k) dst[m][k] = *(const LAS bf16x8*)(lds + PG8_SA(b, h) + aoff + m * 2048 + k * 1024); } while (0)
; #define PG8_LDB(dst, b, h) do { _Pragma("unroll") for (int n = 0; n < 2; ++n) _Pragma("unroll") for (int k = 0; k < 2; ++k) dst[n][k] = *(const LAS bf16x8*)(lds + PG8_SB(b, h) + boff + n * 2048 + k * 1024); } while (0)
; #define PG8_MMA(ai, bj, At, Bt) do { __builtin_amdgcn_s_setprio(1); _Pragma("unroll") for (int m = 0; m < 4; ++m) _Pragma("unroll") for (int n = 0; n < 2; ++n) _Pragma("unroll") for (int k = 0; k < 2; ++k) \
;         acc[ai][bj][m][n] = __builtin_amdgcn_mfma_f32_16x16x32_bf16(Bt[n][k], At[m][k], acc[ai][bj][m][n], 0, 0, 0); __builtin_amdgcn_s_setprio(0); } while (0)
; #define PG8_BAR __builtin_amdgcn_s_barrier()
; template <class Epi, bool ALIGN_EPI = PG8_ALIGN>
; __device__ __forceinline__ void gemm_phase(LAS unsigned char* lds, const Gemm g, const StaticOrder& S, const Epi& E) {
;     ...
;         const bool has_next = S.next(ui + 1, nxt);
;         const char* nA = has_next ? (const char*)g.A + (size_t)nxt.pm * tstepA : cA; const char* nB = has_next ? (const char*)g.Bt + (size_t)nxt.pn * tstepB : cB;
;         for (int t = 0; t < nt; t += 2) {
;             const bool last = (t == nt - 2);
;             const char* a1 = cA + (size_t)(t + 1) * kstep;
;             const char* a2 = last ? nA : cA + (size_t)(t + 2) * kstep; const char* b2 = last ? nB : cB + (size_t)(t + 2) * kstep;
;             const char* a3 = a2 + kstep; const char* b3 = b2 + kstep;
;             PG8_LDB(B0, 0, 0); PG8_LDB(B1, 0, 1); PG8_SCHED; PG8_LDA(At, 0, 0); PG8_STAGE(PG8_SA(1, 1), a1 + hstepA, voffA);
;             PG8_WAIT_V(8); PG8_WAIT_L(0); PG8_BAR; PG8_MMA(0, 0, At, B0); PG8_MMA(0, 1, At, B1); PG8_BAR; PG8_SCHED;
;             PG8_LDA(At, 0, 1); PG8_STAGE(PG8_SB(0, 0), b2, voffB); PG8_STAGE(PG8_SB(0, 1), b2 + hstepB, voffB); PG8_STAGE(PG8_SA(0, 0), a2, voffA);
;             PG8_WAIT_V(8); PG8_WAIT_L(0); PG8_BAR; PG8_MMA(1, 0, At, B0); PG8_MMA(1, 1, At, B1); PG8_BAR; PG8_SCHED;
.Lgp_458:
.LBB0_458:
	s_add_i32 s51, s38, 2
	s_add_u32 s20, s4, 0xfff80080
	s_addc_u32 s21, s5, -1
	s_add_i32 s22, 16, 0x10000
	s_cmp_eq_u32 s45, s38
	s_cselect_b32 s39, s17, s21
	s_cselect_b32 s38, s50, s20
	s_cselect_b32 s53, s25, s41
	s_cselect_b32 s52, s24, s40
	s_add_i32 s20, 16, 0x14000
	v_add_u32_e32 v154, s22, v139
	v_add_u32_e32 v170, s20, v139
	ds_read_b128 v[142:145], v154
	ds_read_b128 v[146:149], v154 offset:1024
	ds_read_b128 v[150:153], v154 offset:2048
	ds_read_b128 v[154:157], v154 offset:3072
	ds_read_b128 v[158:161], v170
	ds_read_b128 v[162:165], v170 offset:1024
	ds_read_b128 v[166:169], v170 offset:2048
	ds_read_b128 v[170:173], v170 offset:3072
	v_lshl_add_u64 v[174:175], s[4:5], 0, v[134:135]
	s_add_i32 m0, s29, 0xc000
	ds_read_b128 v[184:187], v141
	ds_read_b128 v[188:191], v141 offset:1024
	ds_read_b128 v[192:195], v141 offset:2048
	ds_read_b128 v[196:199], v141 offset:3072
	ds_read_b128 v[200:203], v141 offset:4096
	ds_read_b128 v[204:207], v141 offset:5120
	ds_read_b128 v[208:211], v141 offset:6144
	ds_read_b128 v[212:215], v141 offset:7168
	global_load_lds_dwordx4 v[174:175], off
	v_lshl_add_u64 v[174:175], s[4:5], 0, v[136:137]
	s_add_i32 m0, s29, 0xe000
	s_nop 0
	global_load_lds_dwordx4 v[174:175], off
	s_waitcnt vmcnt(8)
	s_waitcnt lgkmcnt(0)
	s_barrier
	s_waitcnt lgkmcnt(0)
	v_mfma_f32_16x16x32_bf16 v[120:123], v[142:145], v[184:187], v[120:123]
	v_mfma_f32_16x16x32_bf16 v[124:127], v[150:153], v[184:187], v[124:127]
	v_mfma_f32_16x16x32_bf16 v[108:111], v[142:145], v[192:195], v[108:111]
	v_mfma_f32_16x16x32_bf16 v[104:107], v[150:153], v[192:195], v[104:107]
	v_mfma_f32_16x16x32_bf16 v[92:95], v[142:145], v[200:203], v[92:95]
	v_mfma_f32_16x16x32_bf16 v[88:91], v[150:153], v[200:203], v[88:91]
	v_mfma_f32_16x16x32_bf16 v[76:79], v[142:145], v[208:211], v[76:79]
	v_mfma_f32_16x16x32_bf16 v[72:75], v[150:153], v[208:211], v[72:75]
	v_mfma_f32_16x16x32_bf16 v[120:123], v[146:149], v[188:191], v[120:123]
	v_mfma_f32_16x16x32_bf16 v[124:127], v[154:157], v[188:191], v[124:127]
	v_mfma_f32_16x16x32_bf16 v[108:111], v[146:149], v[196:199], v[108:111]
	v_mfma_f32_16x16x32_bf16 v[104:107], v[154:157], v[196:199], v[104:107]
	v_mfma_f32_16x16x32_bf16 v[92:95], v[146:149], v[204:207], v[92:95]
	v_mfma_f32_16x16x32_bf16 v[88:91], v[154:157], v[204:207], v[88:91]
	v_mfma_f32_16x16x32_bf16 v[76:79], v[146:149], v[212:215], v[76:79]
	v_mfma_f32_16x16x32_bf16 v[72:75], v[154:157], v[212:215], v[72:75]
	v_mfma_f32_16x16x32_bf16 v[116:119], v[158:161], v[184:187], v[116:119]
	v_mfma_f32_16x16x32_bf16 v[112:115], v[166:169], v[184:187], v[112:115]
	v_mfma_f32_16x16x32_bf16 v[100:103], v[158:161], v[192:195], v[100:103]
	v_mfma_f32_16x16x32_bf16 v[96:99], v[166:169], v[192:195], v[96:99]
	v_mfma_f32_16x16x32_bf16 v[84:87], v[158:161], v[200:203], v[84:87]
	v_mfma_f32_16x16x32_bf16 v[80:83], v[166:169], v[200:203], v[80:83]
	v_mfma_f32_16x16x32_bf16 v[68:71], v[158:161], v[208:211], v[68:71]
	v_mfma_f32_16x16x32_bf16 v[64:67], v[166:169], v[208:211], v[64:67]
	v_mfma_f32_16x16x32_bf16 v[116:119], v[162:165], v[188:191], v[116:119]
	v_mfma_f32_16x16x32_bf16 v[112:115], v[170:173], v[188:191], v[112:115]
	v_mfma_f32_16x16x32_bf16 v[100:103], v[162:165], v[196:199], v[100:103]
	v_mfma_f32_16x16x32_bf16 v[96:99], v[170:173], v[196:199], v[96:99]
	v_mfma_f32_16x16x32_bf16 v[84:87], v[162:165], v[204:207], v[84:87]
	v_mfma_f32_16x16x32_bf16 v[80:83], v[170:173], v[204:207], v[80:83]
	v_mfma_f32_16x16x32_bf16 v[68:71], v[162:165], v[212:215], v[68:71]
	v_mfma_f32_16x16x32_bf16 v[64:67], v[170:173], v[212:215], v[64:67]
	s_barrier
	s_add_i32 s21, s22, s18
	v_lshl_add_u64 v[174:175], s[52:53], 0, v[176:177]
	s_mov_b32 m0, s21
	ds_read_b128 v[184:187], v141 offset:16384
	ds_read_b128 v[188:191], v141 offset:17408
	ds_read_b128 v[192:195], v141 offset:18432
	ds_read_b128 v[196:199], v141 offset:19456
	ds_read_b128 v[200:203], v141 offset:20480
	ds_read_b128 v[204:207], v141 offset:21504
	ds_read_b128 v[208:211], v141 offset:22528
	ds_read_b128 v[212:215], v141 offset:23552
	global_load_lds_dwordx4 v[174:175], off
	s_add_i32 m0, s21, 0x2000
	v_lshl_add_u64 v[216:217], s[52:53], 0, v[128:129]
	s_add_u32 s52, s52, s6
	s_addc_u32 s53, s53, s7
	s_add_i32 s20, s20, s18
	global_load_lds_dwordx4 v[216:217], off
	v_lshl_add_u64 v[218:219], s[52:53], 0, v[176:177]
	s_mov_b32 m0, s20
	v_lshl_add_u64 v[220:221], s[52:53], 0, v[128:129]
	global_load_lds_dwordx4 v[218:219], off
	s_add_i32 m0, s20, 0x2000
	v_lshl_add_u64 v[222:223], s[38:39], 0, v[132:133]
	global_load_lds_dwordx4 v[220:221], off
	s_mov_b32 m0, s29
	v_lshl_add_u64 v[224:225], s[38:39], 0, v[130:131]
	global_load_lds_dwordx4 v[222:223], off
	s_mov_b32 m0, s30
	s_nop 0
	global_load_lds_dwordx4 v[224:225], off
	s_waitcnt vmcnt(8)
	s_waitcnt lgkmcnt(0)
	s_barrier
; #define PG8_STAGE(bufoff, gbase, voff) do { _Pragma("unroll") for (int _i = 0; _i < 2; ++_i) \
;         __builtin_amdgcn_global_load_lds((const unsigned*)((const char*)(gbase) + (voff)[_i]), (LAS unsigned*)(lds + (bufoff) + ldsw + _i * 8192), 16, 0, 0); } while (0)
; #define PG8_LDA(dst, b, h) do { _Pragma("unroll") for (int m = 0; m < 4; ++m) _Pragma("unroll") for (int k = 0; k < 2; ++k) dst[m][k] = *(const LAS bf16x8*)(lds + PG8_SA(b, h) + aoff + m * 2048 + k * 1024); } while (0)
; #define PG8_LDB(dst, b, h) do { _Pragma("unroll") for (int n = 0; n < 2; ++n) _Pragma("unroll") for (int k = 0; k < 2; ++k) dst[n][k] = *(const LAS bf16x8*)(lds + PG8_SB(b, h) + boff + n * 2048 + k * 1024); } while (0)
; #define PG8_MMA(ai, bj, At, Bt) do { __builtin_amdgcn_s_setprio(1); _Pragma("unroll") for (int m = 0; m < 4; ++m) _Pragma("unroll") for (int n = 0; n < 2; ++n) _Pragma("unroll") for (int k = 0; k < 2; ++k) \
;         acc[ai][bj][m][n] = __builtin_amdgcn_mfma_f32_16x16x32_bf16(Bt[n][k], At[m][k], acc[ai][bj][m][n], 0, 0, 0); __builtin_amdgcn_s_setprio(0); } while (0)
; #define PG8_WAIT_V(n) asm volatile("s_waitcnt vmcnt(" #n ")" ::: "memory")
; #define PG8_WAIT_L(n) asm volatile("s_waitcnt lgkmcnt(" #n ")" ::: "memory")
; #define PG8_BAR __builtin_amdgcn_s_barrier()
; #define PG8_SCHED __builtin_amdgcn_sched_barrier(0)
; template <class Epi, bool ALIGN_EPI = PG8_ALIGN>
; __device__ __forceinline__ void gemm_phase(LAS unsigned char* lds, const Gemm g, const StaticOrder& S, const Epi& E) {
;     ...
;             PG8_WAIT_V(8); PG8_WAIT_L(0); PG8_BAR; PG8_MMA(1, 0, At, B0); PG8_MMA(1, 1, At, B1); PG8_BAR; PG8_SCHED;
;             PG8_LDB(B0, 1, 0); PG8_LDB(B1, 1, 1); PG8_SCHED; PG8_LDA(At, 1, 0); PG8_STAGE(PG8_SA(0, 1), a2 + hstepA, voffA);
;             PG8_WAIT_V(8); PG8_WAIT_L(0); PG8_BAR; PG8_MMA(0, 0, At, B0); PG8_MMA(0, 1, At, B1); PG8_BAR; PG8_SCHED;
;             PG8_LDA(At, 1, 1); PG8_STAGE(PG8_SB(1, 0), b3, voffB); PG8_STAGE(PG8_SB(1, 1), b3 + hstepB, voffB); PG8_STAGE(PG8_SA(1, 0), a3, voffA);
;             PG8_WAIT_V(8); PG8_WAIT_L(0); PG8_BAR; PG8_MMA(1, 0, At, B0); PG8_MMA(1, 1, At, B1); PG8_BAR; PG8_SCHED;
	s_waitcnt lgkmcnt(0)
	v_mfma_f32_16x16x32_bf16 v[60:63], v[142:145], v[184:187], v[60:63]
	v_mfma_f32_16x16x32_bf16 v[56:59], v[150:153], v[184:187], v[56:59]
	v_mfma_f32_16x16x32_bf16 v[44:47], v[142:145], v[192:195], v[44:47]
	v_mfma_f32_16x16x32_bf16 v[40:43], v[150:153], v[192:195], v[40:43]
	v_mfma_f32_16x16x32_bf16 v[28:31], v[142:145], v[200:203], v[28:31]
	v_mfma_f32_16x16x32_bf16 v[24:27], v[150:153], v[200:203], v[24:27]
	v_mfma_f32_16x16x32_bf16 v[12:15], v[142:145], v[208:211], v[12:15]
	v_mfma_f32_16x16x32_bf16 v[8:11], v[150:153], v[208:211], v[8:11]
	v_mfma_f32_16x16x32_bf16 v[60:63], v[146:149], v[188:191], v[60:63]
	v_mfma_f32_16x16x32_bf16 v[56:59], v[154:157], v[188:191], v[56:59]
	v_mfma_f32_16x16x32_bf16 v[44:47], v[146:149], v[196:199], v[44:47]
	v_mfma_f32_16x16x32_bf16 v[40:43], v[154:157], v[196:199], v[40:43]
	v_mfma_f32_16x16x32_bf16 v[28:31], v[146:149], v[204:207], v[28:31]
	v_mfma_f32_16x16x32_bf16 v[24:27], v[154:157], v[204:207], v[24:27]
	v_mfma_f32_16x16x32_bf16 v[12:15], v[146:149], v[212:215], v[12:15]
	v_mfma_f32_16x16x32_bf16 v[8:11], v[154:157], v[212:215], v[8:11]
	v_mfma_f32_16x16x32_bf16 v[52:55], v[158:161], v[184:187], v[52:55]
	v_mfma_f32_16x16x32_bf16 v[48:51], v[166:169], v[184:187], v[48:51]
	v_mfma_f32_16x16x32_bf16 v[36:39], v[158:161], v[192:195], v[36:39]
	v_mfma_f32_16x16x32_bf16 v[32:35], v[166:169], v[192:195], v[32:35]
	v_mfma_f32_16x16x32_bf16 v[20:23], v[158:161], v[200:203], v[20:23]
	v_mfma_f32_16x16x32_bf16 v[16:19], v[166:169], v[200:203], v[16:19]
	v_mfma_f32_16x16x32_bf16 v[4:7], v[158:161], v[208:211], v[4:7]
	v_mfma_f32_16x16x32_bf16 v[0:3], v[166:169], v[208:211], v[0:3]
	v_mfma_f32_16x16x32_bf16 v[52:55], v[162:165], v[188:191], v[52:55]
	v_mfma_f32_16x16x32_bf16 v[48:51], v[170:173], v[188:191], v[48:51]
	v_mfma_f32_16x16x32_bf16 v[36:39], v[162:165], v[196:199], v[36:39]
	v_mfma_f32_16x16x32_bf16 v[32:35], v[170:173], v[196:199], v[32:35]
	v_mfma_f32_16x16x32_bf16 v[20:23], v[162:165], v[204:207], v[20:23]
	v_mfma_f32_16x16x32_bf16 v[16:19], v[170:173], v[204:207], v[16:19]
	v_mfma_f32_16x16x32_bf16 v[4:7], v[162:165], v[212:215], v[4:7]
	v_mfma_f32_16x16x32_bf16 v[0:3], v[170:173], v[212:215], v[0:3]
	s_barrier
	s_add_i32 s20, 16, 0x18000
	s_add_i32 s21, 16, 0x1c000
	v_add_u32_e32 v154, s20, v139
	v_add_u32_e32 v170, s21, v139
	ds_read_b128 v[142:145], v154
	ds_read_b128 v[146:149], v154 offset:1024
	ds_read_b128 v[150:153], v154 offset:2048
	ds_read_b128 v[154:157], v154 offset:3072
	ds_read_b128 v[158:161], v170
	ds_read_b128 v[162:165], v170 offset:1024
	ds_read_b128 v[166:169], v170 offset:2048
	ds_read_b128 v[170:173], v170 offset:3072
	s_add_u32 s38, s38, 0x80000
	s_addc_u32 s39, s39, 0
	s_mov_b32 m0, s31
	v_lshl_add_u64 v[226:227], s[38:39], 0, v[132:133]
	ds_read_b128 v[184:187], v141 offset:32768
	ds_read_b128 v[188:191], v141 offset:33792
	ds_read_b128 v[192:195], v141 offset:34816
	ds_read_b128 v[196:199], v141 offset:35840
	ds_read_b128 v[200:203], v141 offset:36864
	ds_read_b128 v[204:207], v141 offset:37888
	ds_read_b128 v[208:211], v141 offset:38912
	ds_read_b128 v[212:215], v141 offset:39936
	global_load_lds_dwordx4 v[226:227], off
	v_lshl_add_u64 v[226:227], s[38:39], 0, v[130:131]
	s_mov_b32 m0, s42
	s_nop 0
	global_load_lds_dwordx4 v[226:227], off
	s_waitcnt vmcnt(8)
	s_waitcnt lgkmcnt(0)
	s_barrier
	s_waitcnt lgkmcnt(0)
	v_mfma_f32_16x16x32_bf16 v[120:123], v[142:145], v[184:187], v[120:123]
	v_mfma_f32_16x16x32_bf16 v[124:127], v[150:153], v[184:187], v[124:127]
	v_mfma_f32_16x16x32_bf16 v[108:111], v[142:145], v[192:195], v[108:111]
	v_mfma_f32_16x16x32_bf16 v[104:107], v[150:153], v[192:195], v[104:107]
	v_mfma_f32_16x16x32_bf16 v[92:95], v[142:145], v[200:203], v[92:95]
	v_mfma_f32_16x16x32_bf16 v[88:91], v[150:153], v[200:203], v[88:91]
	v_mfma_f32_16x16x32_bf16 v[76:79], v[142:145], v[208:211], v[76:79]
	v_mfma_f32_16x16x32_bf16 v[72:75], v[150:153], v[208:211], v[72:75]
	v_mfma_f32_16x16x32_bf16 v[120:123], v[146:149], v[188:191], v[120:123]
	v_mfma_f32_16x16x32_bf16 v[124:127], v[154:157], v[188:191], v[124:127]
	v_mfma_f32_16x16x32_bf16 v[108:111], v[146:149], v[196:199], v[108:111]
	v_mfma_f32_16x16x32_bf16 v[104:107], v[154:157], v[196:199], v[104:107]
	v_mfma_f32_16x16x32_bf16 v[92:95], v[146:149], v[204:207], v[92:95]
	v_mfma_f32_16x16x32_bf16 v[88:91], v[154:157], v[204:207], v[88:91]
	v_mfma_f32_16x16x32_bf16 v[76:79], v[146:149], v[212:215], v[76:79]
	v_mfma_f32_16x16x32_bf16 v[72:75], v[154:157], v[212:215], v[72:75]
	v_mfma_f32_16x16x32_bf16 v[116:119], v[158:161], v[184:187], v[116:119]
	v_mfma_f32_16x16x32_bf16 v[112:115], v[166:169], v[184:187], v[112:115]
	v_mfma_f32_16x16x32_bf16 v[100:103], v[158:161], v[192:195], v[100:103]
	v_mfma_f32_16x16x32_bf16 v[96:99], v[166:169], v[192:195], v[96:99]
	v_mfma_f32_16x16x32_bf16 v[84:87], v[158:161], v[200:203], v[84:87]
	v_mfma_f32_16x16x32_bf16 v[80:83], v[166:169], v[200:203], v[80:83]
	v_mfma_f32_16x16x32_bf16 v[68:71], v[158:161], v[208:211], v[68:71]
	v_mfma_f32_16x16x32_bf16 v[64:67], v[166:169], v[208:211], v[64:67]
	v_mfma_f32_16x16x32_bf16 v[116:119], v[162:165], v[188:191], v[116:119]
	v_mfma_f32_16x16x32_bf16 v[112:115], v[170:173], v[188:191], v[112:115]
	v_mfma_f32_16x16x32_bf16 v[100:103], v[162:165], v[196:199], v[100:103]
	v_mfma_f32_16x16x32_bf16 v[96:99], v[170:173], v[196:199], v[96:99]
	v_mfma_f32_16x16x32_bf16 v[84:87], v[162:165], v[204:207], v[84:87]
	v_mfma_f32_16x16x32_bf16 v[80:83], v[170:173], v[204:207], v[80:83]
	v_mfma_f32_16x16x32_bf16 v[68:71], v[162:165], v[212:215], v[68:71]
	v_mfma_f32_16x16x32_bf16 v[64:67], v[170:173], v[212:215], v[64:67]
	s_barrier
; #define PG8_STAGE(bufoff, gbase, voff) do { _Pragma("unroll") for (int _i = 0; _i < 2; ++_i) \
;         __builtin_amdgcn_global_load_lds((const unsigned*)((const char*)(gbase) + (voff)[_i]), (LAS unsigned*)(lds + (bufoff) + ldsw + _i * 8192), 16, 0, 0); } while (0)
; #define PG8_LDA(dst, b, h) do { _Pragma("unroll") for (int m = 0; m < 4; ++m) _Pragma("unroll") for (int k = 0; k < 2; ++k) dst[m][k] = *(const LAS bf16x8*)(lds + PG8_SA(b, h) + aoff + m * 2048 + k * 1024); } while (0)
; #define PG8_LDB(dst, b, h) do { _Pragma("unroll") for (int n = 0; n < 2; ++n) _Pragma("unroll") for (int k = 0; k < 2; ++k) dst[n][k] = *(const LAS bf16x8*)(lds + PG8_SB(b, h) + boff + n * 2048 + k * 1024); } while (0)
; #define PG8_MMA(ai, bj, At, Bt) do { __builtin_amdgcn_s_setprio(1); _Pragma("unroll") for (int m = 0; m < 4; ++m) _Pragma("unroll") for (int n = 0; n < 2; ++n) _Pragma("unroll") for (int k = 0; k < 2; ++k) \
;         acc[ai][bj][m][n] = __builtin_amdgcn_mfma_f32_16x16x32_bf16(Bt[n][k], At[m][k], acc[ai][bj][m][n], 0, 0, 0); __builtin_amdgcn_s_setprio(0); } while (0)
; #define PG8_WAIT_V(n) asm volatile("s_waitcnt vmcnt(" #n ")" ::: "memory")
; #define PG8_WAIT_L(n) asm volatile("s_waitcnt lgkmcnt(" #n ")" ::: "memory")
; #define PG8_BAR __builtin_amdgcn_s_barrier()
; #define PG8_SCHED __builtin_amdgcn_sched_barrier(0)
; template <class Epi, bool ALIGN_EPI = PG8_ALIGN>
; __device__ __forceinline__ void gemm_phase(LAS unsigned char* lds, const Gemm g, const StaticOrder& S, const Epi& E) {
;     ...
;             PG8_LDB(B0, 1, 0); PG8_LDB(B1, 1, 1); PG8_SCHED; PG8_LDA(At, 1, 0); PG8_STAGE(PG8_SA(0, 1), a2 + hstepA, voffA);
;             PG8_WAIT_V(8); PG8_WAIT_L(0); PG8_BAR; PG8_MMA(0, 0, At, B0); PG8_MMA(0, 1, At, B1); PG8_BAR; PG8_SCHED;
;             PG8_LDA(At, 1, 1); PG8_STAGE(PG8_SB(1, 0), b3, voffB); PG8_STAGE(PG8_SB(1, 1), b3 + hstepB, voffB); PG8_STAGE(PG8_SA(1, 0), a3, voffA);
;             PG8_WAIT_V(8); PG8_WAIT_L(0); PG8_BAR; PG8_MMA(1, 0, At, B0); PG8_MMA(1, 1, At, B1); PG8_BAR; PG8_SCHED;
;         }
	s_add_i32 s20, s20, s18
	v_lshl_add_u64 v[174:175], v[174:175], 0, s[0:1]
	s_mov_b32 m0, s20
	ds_read_b128 v[184:187], v141 offset:49152
	ds_read_b128 v[188:191], v141 offset:50176
	ds_read_b128 v[192:195], v141 offset:51200
	ds_read_b128 v[196:199], v141 offset:52224
	ds_read_b128 v[200:203], v141 offset:53248
	ds_read_b128 v[204:207], v141 offset:54272
	ds_read_b128 v[208:211], v141 offset:55296
	ds_read_b128 v[212:215], v141 offset:56320
	global_load_lds_dwordx4 v[174:175], off
	v_lshl_add_u64 v[174:175], v[216:217], 0, s[0:1]
	s_add_i32 m0, s20, 0x2000
	s_add_i32 s20, s21, s18
	global_load_lds_dwordx4 v[174:175], off
	v_lshl_add_u64 v[174:175], v[218:219], 0, s[0:1]
	s_mov_b32 m0, s20
	s_nop 0
	global_load_lds_dwordx4 v[174:175], off
	v_lshl_add_u64 v[174:175], v[220:221], 0, s[0:1]
	s_add_i32 m0, s20, 0x2000
	s_nop 0
	global_load_lds_dwordx4 v[174:175], off
	v_lshl_add_u64 v[174:175], v[222:223], 0, s[0:1]
	s_mov_b32 m0, s34
	s_nop 0
	global_load_lds_dwordx4 v[174:175], off
	v_lshl_add_u64 v[174:175], v[224:225], 0, s[0:1]
	s_mov_b32 m0, s43
	s_nop 0
	global_load_lds_dwordx4 v[174:175], off
	s_waitcnt vmcnt(8)
	s_waitcnt lgkmcnt(0)
	s_barrier
	s_waitcnt lgkmcnt(0)
	v_mfma_f32_16x16x32_bf16 v[60:63], v[142:145], v[184:187], v[60:63]
	v_mfma_f32_16x16x32_bf16 v[56:59], v[150:153], v[184:187], v[56:59]
	v_mfma_f32_16x16x32_bf16 v[44:47], v[142:145], v[192:195], v[44:47]
	v_mfma_f32_16x16x32_bf16 v[40:43], v[150:153], v[192:195], v[40:43]
	v_mfma_f32_16x16x32_bf16 v[28:31], v[142:145], v[200:203], v[28:31]
	v_mfma_f32_16x16x32_bf16 v[24:27], v[150:153], v[200:203], v[24:27]
	v_mfma_f32_16x16x32_bf16 v[12:15], v[142:145], v[208:211], v[12:15]
	v_mfma_f32_16x16x32_bf16 v[8:11], v[150:153], v[208:211], v[8:11]
	v_mfma_f32_16x16x32_bf16 v[60:63], v[146:149], v[188:191], v[60:63]
	v_mfma_f32_16x16x32_bf16 v[56:59], v[154:157], v[188:191], v[56:59]
	v_mfma_f32_16x16x32_bf16 v[44:47], v[146:149], v[196:199], v[44:47]
	v_mfma_f32_16x16x32_bf16 v[40:43], v[154:157], v[196:199], v[40:43]
	v_mfma_f32_16x16x32_bf16 v[28:31], v[146:149], v[204:207], v[28:31]
	v_mfma_f32_16x16x32_bf16 v[24:27], v[154:157], v[204:207], v[24:27]
	v_mfma_f32_16x16x32_bf16 v[12:15], v[146:149], v[212:215], v[12:15]
	v_mfma_f32_16x16x32_bf16 v[8:11], v[154:157], v[212:215], v[8:11]
	v_mfma_f32_16x16x32_bf16 v[52:55], v[158:161], v[184:187], v[52:55]
	v_mfma_f32_16x16x32_bf16 v[48:51], v[166:169], v[184:187], v[48:51]
	v_mfma_f32_16x16x32_bf16 v[36:39], v[158:161], v[192:195], v[36:39]
	v_mfma_f32_16x16x32_bf16 v[32:35], v[166:169], v[192:195], v[32:35]
	v_mfma_f32_16x16x32_bf16 v[20:23], v[158:161], v[200:203], v[20:23]
	v_mfma_f32_16x16x32_bf16 v[16:19], v[166:169], v[200:203], v[16:19]
	v_mfma_f32_16x16x32_bf16 v[4:7], v[158:161], v[208:211], v[4:7]
	v_mfma_f32_16x16x32_bf16 v[0:3], v[166:169], v[208:211], v[0:3]
	v_mfma_f32_16x16x32_bf16 v[52:55], v[162:165], v[188:191], v[52:55]
	v_mfma_f32_16x16x32_bf16 v[48:51], v[170:173], v[188:191], v[48:51]
	v_mfma_f32_16x16x32_bf16 v[36:39], v[162:165], v[196:199], v[36:39]
	v_mfma_f32_16x16x32_bf16 v[32:35], v[170:173], v[196:199], v[32:35]
	v_mfma_f32_16x16x32_bf16 v[20:23], v[162:165], v[204:207], v[20:23]
	v_mfma_f32_16x16x32_bf16 v[16:19], v[170:173], v[204:207], v[16:19]
	v_mfma_f32_16x16x32_bf16 v[4:7], v[162:165], v[212:215], v[4:7]
	v_mfma_f32_16x16x32_bf16 v[0:3], v[170:173], v[212:215], v[0:3]
	s_barrier
	s_add_u32 s4, s4, 0x100
	s_addc_u32 s5, s5, 0
	s_add_u32 s40, s40, 0x100
	s_addc_u32 s41, s41, 0
	s_cmp_ge_i32 s51, s44
	s_mov_b32 s38, s51
	s_cbranch_scc0 .LBB0_458
	s_setprio 0

; #define PG8_STAGE(bufoff, gbase, voff) do { _Pragma("unroll") for (int _i = 0; _i < 2; ++_i) \
;         __builtin_amdgcn_global_load_lds((const unsigned*)((const char*)(gbase) + (voff)[_i]), (LAS unsigned*)(lds + (bufoff) + ldsw + _i * 8192), 16, 0, 0); } while (0)
; #define PG8_WAIT_V(n) asm volatile("s_waitcnt vmcnt(" #n ")" ::: "memory")
; #define PG8_BAR __builtin_amdgcn_s_barrier()
; template <class Epi, bool ALIGN_EPI = PG8_ALIGN>
; __device__ __forceinline__ void gemm_phase(LAS unsigned char* lds, const Gemm g, const StaticOrder& S, const Epi& E) {
;     ...
;     f32x4 acc[2][2][4][2];
; #pragma unroll
;     for (int a = 0; a < 2; ++a)
; #pragma unroll
;         for (int b = 0; b < 2; ++b)
; #pragma unroll
;             for (int m = 0; m < 4; ++m)
; #pragma unroll
;                 for (int n = 0; n < 2; ++n) acc[a][b][m][n] = (f32x4){0.f, 0.f, 0.f, 0.f};
;     bf16x8 At[4][2], B0[2][2], B1[2][2];
;     const char* cA = (const char*)g.A + (size_t)cur.pm * tstepA; const char* cB = (const char*)g.Bt + (size_t)cur.pn * tstepB;
;     PG8_STAGE(PG8_SB(0, 0), cB, voffB); PG8_STAGE(PG8_SB(0, 1), cB + hstepB, voffB); PG8_STAGE(PG8_SA(0, 0), cA, voffA); PG8_STAGE(PG8_SA(0, 1), cA + hstepA, voffA);
;     if (wr == 1) PG8_BAR;
;     PG8_WAIT_V(2); PG8_BAR;
;     PG8_STAGE(PG8_SB(1, 0), cB + kstep, voffB); PG8_STAGE(PG8_SA(1, 0), cA + kstep, voffA); PG8_STAGE(PG8_SB(1, 1), cB + hstepB + kstep, voffB);
;     PG8_WAIT_V(6); PG8_BAR;
;     for (;;) {
;         const bool has_next = S.next(ui + 1, nxt);
;         const char* nA = has_next ? (const char*)g.A + (size_t)nxt.pm * tstepA : cA; const char* nB = has_next ? (const char*)g.Bt + (size_t)nxt.pn * tstepB : cB;
.LBB0_479:
	s_ashr_i32 s17, s16, 31
	s_lshl_b64 s[36:37], s[16:17], 17
	s_add_u32 s36, s18, s36
	v_mov_b32_e32 v123, 0
	s_addc_u32 s37, s29, s37
	s_andn2_b64 vcc, exec, s[12:13]
	v_mov_b32_e32 v122, v123
	v_mov_b32_e32 v121, v123
	v_mov_b32_e32 v120, v123
	v_mov_b32_e32 v127, v123
	v_mov_b32_e32 v126, v123
	v_mov_b32_e32 v125, v123
	v_mov_b32_e32 v124, v123
	v_mov_b32_e32 v111, v123
	v_mov_b32_e32 v110, v123
	v_mov_b32_e32 v109, v123
	v_mov_b32_e32 v108, v123
	v_mov_b32_e32 v107, v123
	v_mov_b32_e32 v106, v123
	v_mov_b32_e32 v105, v123
	v_mov_b32_e32 v104, v123
	v_mov_b32_e32 v95, v123
	v_mov_b32_e32 v94, v123
	v_mov_b32_e32 v93, v123
	v_mov_b32_e32 v92, v123
	v_mov_b32_e32 v91, v123
	v_mov_b32_e32 v90, v123
	v_mov_b32_e32 v89, v123
	v_mov_b32_e32 v88, v123
	v_mov_b32_e32 v79, v123
	v_mov_b32_e32 v78, v123
	v_mov_b32_e32 v77, v123
	v_mov_b32_e32 v76, v123
	v_mov_b32_e32 v75, v123
	v_mov_b32_e32 v74, v123
	v_mov_b32_e32 v73, v123
	v_mov_b32_e32 v72, v123
	v_mov_b32_e32 v119, v123
	v_mov_b32_e32 v118, v123
	v_mov_b32_e32 v117, v123
	v_mov_b32_e32 v116, v123
	v_mov_b32_e32 v115, v123
	v_mov_b32_e32 v114, v123
	v_mov_b32_e32 v113, v123
	v_mov_b32_e32 v112, v123
	v_mov_b32_e32 v103, v123
	v_mov_b32_e32 v102, v123
	v_mov_b32_e32 v101, v123
	v_mov_b32_e32 v100, v123
	v_mov_b32_e32 v99, v123
	v_mov_b32_e32 v98, v123
	v_mov_b32_e32 v97, v123
	v_mov_b32_e32 v96, v123
	v_mov_b32_e32 v87, v123
	v_mov_b32_e32 v86, v123
	v_mov_b32_e32 v85, v123
	v_mov_b32_e32 v84, v123
	v_mov_b32_e32 v83, v123
	v_mov_b32_e32 v82, v123
	v_mov_b32_e32 v81, v123
	v_mov_b32_e32 v80, v123
	v_mov_b32_e32 v71, v123
	v_mov_b32_e32 v70, v123
	v_mov_b32_e32 v69, v123
	v_mov_b32_e32 v68, v123
	v_mov_b32_e32 v67, v123
	v_mov_b32_e32 v66, v123
	v_mov_b32_e32 v65, v123
	v_mov_b32_e32 v64, v123
	v_mov_b32_e32 v63, v123
	v_mov_b32_e32 v62, v123
	v_mov_b32_e32 v61, v123
	v_mov_b32_e32 v60, v123
	v_mov_b32_e32 v59, v123
	v_mov_b32_e32 v58, v123
	v_mov_b32_e32 v57, v123
	v_mov_b32_e32 v56, v123
	v_mov_b32_e32 v47, v123
	v_mov_b32_e32 v46, v123
	v_mov_b32_e32 v45, v123
	v_mov_b32_e32 v44, v123
	v_mov_b32_e32 v43, v123
	v_mov_b32_e32 v42, v123
	v_mov_b32_e32 v41, v123
	v_mov_b32_e32 v40, v123
	v_mov_b32_e32 v31, v123
	v_mov_b32_e32 v30, v123
	v_mov_b32_e32 v29, v123
	v_mov_b32_e32 v28, v123
	v_mov_b32_e32 v27, v123
	v_mov_b32_e32 v26, v123
	v_mov_b32_e32 v25, v123
	v_mov_b32_e32 v24, v123
	v_mov_b32_e32 v15, v123
	v_mov_b32_e32 v14, v123
	v_mov_b32_e32 v13, v123
	v_mov_b32_e32 v12, v123
	v_mov_b32_e32 v11, v123
	v_mov_b32_e32 v10, v123
	v_mov_b32_e32 v9, v123
	v_mov_b32_e32 v8, v123
	v_mov_b32_e32 v55, v123
	v_mov_b32_e32 v54, v123
	v_mov_b32_e32 v53, v123
	v_mov_b32_e32 v52, v123
	v_mov_b32_e32 v51, v123
	v_mov_b32_e32 v50, v123
	v_mov_b32_e32 v49, v123
	v_mov_b32_e32 v48, v123
	v_mov_b32_e32 v39, v123
	v_mov_b32_e32 v38, v123
	v_mov_b32_e32 v37, v123
	v_mov_b32_e32 v36, v123
	v_mov_b32_e32 v35, v123
	v_mov_b32_e32 v34, v123
	v_mov_b32_e32 v33, v123
	v_mov_b32_e32 v32, v123
	v_mov_b32_e32 v23, v123
	v_mov_b32_e32 v22, v123
	v_mov_b32_e32 v21, v123
	v_mov_b32_e32 v20, v123
	v_mov_b32_e32 v19, v123
	v_mov_b32_e32 v18, v123
	v_mov_b32_e32 v17, v123
	v_mov_b32_e32 v16, v123
	v_mov_b32_e32 v7, v123
	v_mov_b32_e32 v6, v123
	v_mov_b32_e32 v5, v123
	v_mov_b32_e32 v4, v123
	v_mov_b32_e32 v3, v123
	v_mov_b32_e32 v2, v123
	v_mov_b32_e32 v1, v123
	v_mov_b32_e32 v0, v123
	s_cbranch_vccnz .LBB0_482
	s_and_b64 s[4:5], s[4:5], exec
	s_cselect_b32 s17, s37, s41
	s_cselect_b32 s52, s36, s40
	s_add_u32 s4, s40, 0x10080
	s_addc_u32 s5, s41, 0
	s_add_u32 s40, s38, 0x100
	v_mov_b32_e32 v0, 0
	s_addc_u32 s41, s39, 0
	s_mov_b32 s38, 0
	v_mov_b32_e32 v1, v0
	v_mov_b32_e32 v2, v0
	v_mov_b32_e32 v3, v0
	v_mov_b32_e32 v4, v0
	v_mov_b32_e32 v5, v0
	v_mov_b32_e32 v6, v0
	v_mov_b32_e32 v7, v0
	v_mov_b32_e32 v16, v0
	v_mov_b32_e32 v17, v0
	v_mov_b32_e32 v18, v0
	v_mov_b32_e32 v19, v0
	v_mov_b32_e32 v20, v0
	v_mov_b32_e32 v21, v0
	v_mov_b32_e32 v22, v0
	v_mov_b32_e32 v23, v0
	v_mov_b32_e32 v32, v0
	v_mov_b32_e32 v33, v0
	v_mov_b32_e32 v34, v0
	v_mov_b32_e32 v35, v0
	v_mov_b32_e32 v36, v0
	v_mov_b32_e32 v37, v0
	v_mov_b32_e32 v38, v0
	v_mov_b32_e32 v39, v0
	v_mov_b32_e32 v48, v0
	v_mov_b32_e32 v49, v0
	v_mov_b32_e32 v50, v0
	v_mov_b32_e32 v51, v0
	v_mov_b32_e32 v52, v0
	v_mov_b32_e32 v53, v0
	v_mov_b32_e32 v54, v0
	v_mov_b32_e32 v55, v0
	v_mov_b32_e32 v8, v0
	v_mov_b32_e32 v9, v0
	v_mov_b32_e32 v10, v0
	v_mov_b32_e32 v11, v0
	v_mov_b32_e32 v12, v0
	v_mov_b32_e32 v13, v0
	v_mov_b32_e32 v14, v0
	v_mov_b32_e32 v15, v0
	v_mov_b32_e32 v24, v0
	v_mov_b32_e32 v25, v0
	v_mov_b32_e32 v26, v0
	v_mov_b32_e32 v27, v0
	v_mov_b32_e32 v28, v0
	v_mov_b32_e32 v29, v0
	v_mov_b32_e32 v30, v0
	v_mov_b32_e32 v31, v0
	v_mov_b32_e32 v40, v0
	v_mov_b32_e32 v41, v0
	v_mov_b32_e32 v42, v0
	v_mov_b32_e32 v43, v0
	v_mov_b32_e32 v44, v0
	v_mov_b32_e32 v45, v0
	v_mov_b32_e32 v46, v0
	v_mov_b32_e32 v47, v0
	v_mov_b32_e32 v56, v0
	v_mov_b32_e32 v57, v0
	v_mov_b32_e32 v58, v0
	v_mov_b32_e32 v59, v0
	v_mov_b32_e32 v60, v0
	v_mov_b32_e32 v61, v0
	v_mov_b32_e32 v62, v0
	v_mov_b32_e32 v63, v0
	v_mov_b32_e32 v64, v0
	v_mov_b32_e32 v65, v0
	v_mov_b32_e32 v66, v0
	v_mov_b32_e32 v67, v0
	v_mov_b32_e32 v68, v0
	v_mov_b32_e32 v69, v0
	v_mov_b32_e32 v70, v0
	v_mov_b32_e32 v71, v0
	v_mov_b32_e32 v80, v0
	v_mov_b32_e32 v81, v0
	v_mov_b32_e32 v82, v0
	v_mov_b32_e32 v83, v0
	v_mov_b32_e32 v84, v0
	v_mov_b32_e32 v85, v0
	v_mov_b32_e32 v86, v0
	v_mov_b32_e32 v87, v0
	v_mov_b32_e32 v96, v0
	v_mov_b32_e32 v97, v0
	v_mov_b32_e32 v98, v0
	v_mov_b32_e32 v99, v0
	v_mov_b32_e32 v100, v0
	v_mov_b32_e32 v101, v0
	v_mov_b32_e32 v102, v0
	v_mov_b32_e32 v103, v0
	v_mov_b32_e32 v112, v0
	v_mov_b32_e32 v113, v0
	v_mov_b32_e32 v114, v0
	v_mov_b32_e32 v115, v0
	v_mov_b32_e32 v116, v0
	v_mov_b32_e32 v117, v0
	v_mov_b32_e32 v118, v0
	v_mov_b32_e32 v119, v0
	v_mov_b32_e32 v72, v0
	v_mov_b32_e32 v73, v0
	v_mov_b32_e32 v74, v0
	v_mov_b32_e32 v75, v0
	v_mov_b32_e32 v76, v0
	v_mov_b32_e32 v77, v0
	v_mov_b32_e32 v78, v0
	v_mov_b32_e32 v79, v0
	v_mov_b32_e32 v88, v0
	v_mov_b32_e32 v89, v0
	v_mov_b32_e32 v90, v0
	v_mov_b32_e32 v91, v0
	v_mov_b32_e32 v92, v0
	v_mov_b32_e32 v93, v0
	v_mov_b32_e32 v94, v0
	v_mov_b32_e32 v95, v0
	v_mov_b32_e32 v104, v0
	v_mov_b32_e32 v105, v0
	v_mov_b32_e32 v106, v0
	v_mov_b32_e32 v107, v0
	v_mov_b32_e32 v108, v0
	v_mov_b32_e32 v109, v0
	v_mov_b32_e32 v110, v0
	v_mov_b32_e32 v111, v0
	v_mov_b32_e32 v124, v0
	v_mov_b32_e32 v125, v0
	v_mov_b32_e32 v126, v0
	v_mov_b32_e32 v127, v0
	v_mov_b32_e32 v120, v0
	v_mov_b32_e32 v121, v0
	v_mov_b32_e32 v122, v0
	v_mov_b32_e32 v123, v0
	v_readfirstlane_b32 s100, v238
	s_cmp_lt_u32 s100, 0x100
	s_cbranch_scc1 .Lgp_481
	s_setprio 1
; #define PG8_STAGE(bufoff, gbase, voff) do { _Pragma("unroll") for (int _i = 0; _i < 2; ++_i) \
;         __builtin_amdgcn_global_load_lds((const unsigned*)((const char*)(gbase) + (voff)[_i]), (LAS unsigned*)(lds + (bufoff) + ldsw + _i * 8192), 16, 0, 0); } while (0)
; #define PG8_LDA(dst, b, h) do { _Pragma("unroll") for (int m = 0; m < 4; ++m) _Pragma("unroll") for (int k = 0; k < 2; ++k) dst[m][k] = *(const LAS bf16x8*)(lds + PG8_SA(b, h) + aoff + m * 2048 + k * 1024); } while (0)
; #define PG8_LDB(dst, b, h) do { _Pragma("unroll") for (int n = 0; n < 2; ++n) _Pragma("unroll") for (int k = 0; k < 2; ++k) dst[n][k] = *(const LAS bf16x8*)(lds + PG8_SB(b, h) + boff + n * 2048 + k * 1024); } while (0)
; #define PG8_MMA(ai, bj, At, Bt) do { __builtin_amdgcn_s_setprio(1); _Pragma("unroll") for (int m = 0; m < 4; ++m) _Pragma("unroll") for (int n = 0; n < 2; ++n) _Pragma("unroll") for (int k = 0; k < 2; ++k) \
;         acc[ai][bj][m][n] = __builtin_amdgcn_mfma_f32_16x16x32_bf16(Bt[n][k], At[m][k], acc[ai][bj][m][n], 0, 0, 0); __builtin_amdgcn_s_setprio(0); } while (0)
; #define PG8_BAR __builtin_amdgcn_s_barrier()
; template <class Epi, bool ALIGN_EPI = PG8_ALIGN>
; __device__ __forceinline__ void gemm_phase(LAS unsigned char* lds, const Gemm g, const StaticOrder& S, const Epi& E) {
;     ...
;         const bool has_next = S.next(ui + 1, nxt);
;         const char* nA = has_next ? (const char*)g.A + (size_t)nxt.pm * tstepA : cA; const char* nB = has_next ? (const char*)g.Bt + (size_t)nxt.pn * tstepB : cB;
;         for (int t = 0; t < nt; t += 2) {
;             const bool last = (t == nt - 2);
;             const char* a1 = cA + (size_t)(t + 1) * kstep;
;             const char* a2 = last ? nA : cA + (size_t)(t + 2) * kstep; const char* b2 = last ? nB : cB + (size_t)(t + 2) * kstep;
;             const char* a3 = a2 + kstep; const char* b3 = b2 + kstep;
;             PG8_LDB(B0, 0, 0); PG8_LDB(B1, 0, 1); PG8_SCHED; PG8_LDA(At, 0, 0); PG8_STAGE(PG8_SA(1, 1), a1 + hstepA, voffA);
;             PG8_WAIT_V(8); PG8_WAIT_L(0); PG8_BAR; PG8_MMA(0, 0, At, B0); PG8_MMA(0, 1, At, B1); PG8_BAR; PG8_SCHED;
;             PG8_LDA(At, 0, 1); PG8_STAGE(PG8_SB(0, 0), b2, voffB); PG8_STAGE(PG8_SB(0, 1), b2 + hstepB, voffB); PG8_STAGE(PG8_SA(0, 0), a2, voffA);
;             PG8_WAIT_V(8); PG8_WAIT_L(0); PG8_BAR; PG8_MMA(1, 0, At, B0); PG8_MMA(1, 1, At, B1); PG8_BAR; PG8_SCHED;
.Lgp_481:
.LBB0_481:
	s_add_i32 s53, s38, 2
	s_add_u32 s20, s4, 0xffff0080
	s_addc_u32 s21, s5, -1
	s_add_i32 s22, 16, 0x10000
	s_cmp_eq_u32 s47, s38
	s_cselect_b32 s39, s17, s21
	s_cselect_b32 s38, s52, s20
	s_cselect_b32 s55, s25, s41
	s_cselect_b32 s54, s24, s40
	s_add_i32 s20, 16, 0x14000
	v_add_u32_e32 v154, s22, v139
	v_add_u32_e32 v170, s20, v139
	ds_read_b128 v[142:145], v154
	ds_read_b128 v[146:149], v154 offset:1024
	ds_read_b128 v[150:153], v154 offset:2048
	ds_read_b128 v[154:157], v154 offset:3072
	ds_read_b128 v[158:161], v170
	ds_read_b128 v[162:165], v170 offset:1024
	ds_read_b128 v[166:169], v170 offset:2048
	ds_read_b128 v[170:173], v170 offset:3072
	v_lshl_add_u64 v[174:175], s[4:5], 0, v[134:135]
	s_add_i32 m0, s26, 0xc000
	ds_read_b128 v[184:187], v141
	ds_read_b128 v[188:191], v141 offset:1024
	ds_read_b128 v[192:195], v141 offset:2048
	ds_read_b128 v[196:199], v141 offset:3072
	ds_read_b128 v[200:203], v141 offset:4096
	ds_read_b128 v[204:207], v141 offset:5120
	ds_read_b128 v[208:211], v141 offset:6144
	ds_read_b128 v[212:215], v141 offset:7168
	global_load_lds_dwordx4 v[174:175], off
	v_lshl_add_u64 v[174:175], s[4:5], 0, v[136:137]
	s_add_i32 m0, s26, 0xe000
	s_nop 0
	global_load_lds_dwordx4 v[174:175], off
	s_waitcnt vmcnt(8)
	s_waitcnt lgkmcnt(0)
	s_barrier
	s_waitcnt lgkmcnt(0)
	v_mfma_f32_16x16x32_bf16 v[120:123], v[142:145], v[184:187], v[120:123]
	v_mfma_f32_16x16x32_bf16 v[124:127], v[150:153], v[184:187], v[124:127]
	v_mfma_f32_16x16x32_bf16 v[108:111], v[142:145], v[192:195], v[108:111]
	v_mfma_f32_16x16x32_bf16 v[104:107], v[150:153], v[192:195], v[104:107]
	v_mfma_f32_16x16x32_bf16 v[92:95], v[142:145], v[200:203], v[92:95]
	v_mfma_f32_16x16x32_bf16 v[88:91], v[150:153], v[200:203], v[88:91]
	v_mfma_f32_16x16x32_bf16 v[76:79], v[142:145], v[208:211], v[76:79]
	v_mfma_f32_16x16x32_bf16 v[72:75], v[150:153], v[208:211], v[72:75]
	v_mfma_f32_16x16x32_bf16 v[120:123], v[146:149], v[188:191], v[120:123]
	v_mfma_f32_16x16x32_bf16 v[124:127], v[154:157], v[188:191], v[124:127]
	v_mfma_f32_16x16x32_bf16 v[108:111], v[146:149], v[196:199], v[108:111]
	v_mfma_f32_16x16x32_bf16 v[104:107], v[154:157], v[196:199], v[104:107]
	v_mfma_f32_16x16x32_bf16 v[92:95], v[146:149], v[204:207], v[92:95]
	v_mfma_f32_16x16x32_bf16 v[88:91], v[154:157], v[204:207], v[88:91]
	v_mfma_f32_16x16x32_bf16 v[76:79], v[146:149], v[212:215], v[76:79]
	v_mfma_f32_16x16x32_bf16 v[72:75], v[154:157], v[212:215], v[72:75]
	v_mfma_f32_16x16x32_bf16 v[116:119], v[158:161], v[184:187], v[116:119]
	v_mfma_f32_16x16x32_bf16 v[112:115], v[166:169], v[184:187], v[112:115]
	v_mfma_f32_16x16x32_bf16 v[100:103], v[158:161], v[192:195], v[100:103]
	v_mfma_f32_16x16x32_bf16 v[96:99], v[166:169], v[192:195], v[96:99]
	v_mfma_f32_16x16x32_bf16 v[84:87], v[158:161], v[200:203], v[84:87]
	v_mfma_f32_16x16x32_bf16 v[80:83], v[166:169], v[200:203], v[80:83]
	v_mfma_f32_16x16x32_bf16 v[68:71], v[158:161], v[208:211], v[68:71]
	v_mfma_f32_16x16x32_bf16 v[64:67], v[166:169], v[208:211], v[64:67]
	v_mfma_f32_16x16x32_bf16 v[116:119], v[162:165], v[188:191], v[116:119]
	v_mfma_f32_16x16x32_bf16 v[112:115], v[170:173], v[188:191], v[112:115]
	v_mfma_f32_16x16x32_bf16 v[100:103], v[162:165], v[196:199], v[100:103]
	v_mfma_f32_16x16x32_bf16 v[96:99], v[170:173], v[196:199], v[96:99]
	v_mfma_f32_16x16x32_bf16 v[84:87], v[162:165], v[204:207], v[84:87]
	v_mfma_f32_16x16x32_bf16 v[80:83], v[170:173], v[204:207], v[80:83]
	v_mfma_f32_16x16x32_bf16 v[68:71], v[162:165], v[212:215], v[68:71]
	v_mfma_f32_16x16x32_bf16 v[64:67], v[170:173], v[212:215], v[64:67]
	s_barrier
	s_add_i32 s21, s22, s42
	v_lshl_add_u64 v[174:175], s[54:55], 0, v[176:177]
	s_mov_b32 m0, s21
	ds_read_b128 v[184:187], v141 offset:16384
	ds_read_b128 v[188:191], v141 offset:17408
	ds_read_b128 v[192:195], v141 offset:18432
	ds_read_b128 v[196:199], v141 offset:19456
	ds_read_b128 v[200:203], v141 offset:20480
	ds_read_b128 v[204:207], v141 offset:21504
	ds_read_b128 v[208:211], v141 offset:22528
	ds_read_b128 v[212:215], v141 offset:23552
	global_load_lds_dwordx4 v[174:175], off
	s_add_i32 m0, s21, 0x2000
	v_lshl_add_u64 v[216:217], s[54:55], 0, v[128:129]
	s_add_u32 s54, s54, s6
	s_addc_u32 s55, s55, s7
	s_add_i32 s20, s20, s42
	global_load_lds_dwordx4 v[216:217], off
	v_lshl_add_u64 v[218:219], s[54:55], 0, v[176:177]
	s_mov_b32 m0, s20
	v_lshl_add_u64 v[220:221], s[54:55], 0, v[128:129]
	global_load_lds_dwordx4 v[218:219], off
	s_add_i32 m0, s20, 0x2000
	v_lshl_add_u64 v[222:223], s[38:39], 0, v[132:133]
	global_load_lds_dwordx4 v[220:221], off
	s_mov_b32 m0, s26
	v_lshl_add_u64 v[224:225], s[38:39], 0, v[130:131]
	global_load_lds_dwordx4 v[222:223], off
	s_mov_b32 m0, s27
	s_nop 0
	global_load_lds_dwordx4 v[224:225], off
	s_waitcnt vmcnt(8)
	s_waitcnt lgkmcnt(0)
	s_barrier
; #define PG8_STAGE(bufoff, gbase, voff) do { _Pragma("unroll") for (int _i = 0; _i < 2; ++_i) \
;         __builtin_amdgcn_global_load_lds((const unsigned*)((const char*)(gbase) + (voff)[_i]), (LAS unsigned*)(lds + (bufoff) + ldsw + _i * 8192), 16, 0, 0); } while (0)
; #define PG8_LDA(dst, b, h) do { _Pragma("unroll") for (int m = 0; m < 4; ++m) _Pragma("unroll") for (int k = 0; k < 2; ++k) dst[m][k] = *(const LAS bf16x8*)(lds + PG8_SA(b, h) + aoff + m * 2048 + k * 1024); } while (0)
; #define PG8_LDB(dst, b, h) do { _Pragma("unroll") for (int n = 0; n < 2; ++n) _Pragma("unroll") for (int k = 0; k < 2; ++k) dst[n][k] = *(const LAS bf16x8*)(lds + PG8_SB(b, h) + boff + n * 2048 + k * 1024); } while (0)
; #define PG8_MMA(ai, bj, At, Bt) do { __builtin_amdgcn_s_setprio(1); _Pragma("unroll") for (int m = 0; m < 4; ++m) _Pragma("unroll") for (int n = 0; n < 2; ++n) _Pragma("unroll") for (int k = 0; k < 2; ++k) \
;         acc[ai][bj][m][n] = __builtin_amdgcn_mfma_f32_16x16x32_bf16(Bt[n][k], At[m][k], acc[ai][bj][m][n], 0, 0, 0); __builtin_amdgcn_s_setprio(0); } while (0)
; #define PG8_WAIT_V(n) asm volatile("s_waitcnt vmcnt(" #n ")" ::: "memory")
; #define PG8_WAIT_L(n) asm volatile("s_waitcnt lgkmcnt(" #n ")" ::: "memory")
; #define PG8_BAR __builtin_amdgcn_s_barrier()
; #define PG8_SCHED __builtin_amdgcn_sched_barrier(0)
; template <class Epi, bool ALIGN_EPI = PG8_ALIGN>
; __device__ __forceinline__ void gemm_phase(LAS unsigned char* lds, const Gemm g, const StaticOrder& S, const Epi& E) {
;     ...
;             PG8_WAIT_V(8); PG8_WAIT_L(0); PG8_BAR; PG8_MMA(1, 0, At, B0); PG8_MMA(1, 1, At, B1); PG8_BAR; PG8_SCHED;
;             PG8_LDB(B0, 1, 0); PG8_LDB(B1, 1, 1); PG8_SCHED; PG8_LDA(At, 1, 0); PG8_STAGE(PG8_SA(0, 1), a2 + hstepA, voffA);
;             PG8_WAIT_V(8); PG8_WAIT_L(0); PG8_BAR; PG8_MMA(0, 0, At, B0); PG8_MMA(0, 1, At, B1); PG8_BAR; PG8_SCHED;
;             PG8_LDA(At, 1, 1); PG8_STAGE(PG8_SB(1, 0), b3, voffB); PG8_STAGE(PG8_SB(1, 1), b3 + hstepB, voffB); PG8_STAGE(PG8_SA(1, 0), a3, voffA);
;             PG8_WAIT_V(8); PG8_WAIT_L(0); PG8_BAR; PG8_MMA(1, 0, At, B0); PG8_MMA(1, 1, At, B1); PG8_BAR; PG8_SCHED;
	s_waitcnt lgkmcnt(0)
	v_mfma_f32_16x16x32_bf16 v[60:63], v[142:145], v[184:187], v[60:63]
	v_mfma_f32_16x16x32_bf16 v[56:59], v[150:153], v[184:187], v[56:59]
	v_mfma_f32_16x16x32_bf16 v[44:47], v[142:145], v[192:195], v[44:47]
	v_mfma_f32_16x16x32_bf16 v[40:43], v[150:153], v[192:195], v[40:43]
	v_mfma_f32_16x16x32_bf16 v[28:31], v[142:145], v[200:203], v[28:31]
	v_mfma_f32_16x16x32_bf16 v[24:27], v[150:153], v[200:203], v[24:27]
	v_mfma_f32_16x16x32_bf16 v[12:15], v[142:145], v[208:211], v[12:15]
	v_mfma_f32_16x16x32_bf16 v[8:11], v[150:153], v[208:211], v[8:11]
	v_mfma_f32_16x16x32_bf16 v[60:63], v[146:149], v[188:191], v[60:63]
	v_mfma_f32_16x16x32_bf16 v[56:59], v[154:157], v[188:191], v[56:59]
	v_mfma_f32_16x16x32_bf16 v[44:47], v[146:149], v[196:199], v[44:47]
	v_mfma_f32_16x16x32_bf16 v[40:43], v[154:157], v[196:199], v[40:43]
	v_mfma_f32_16x16x32_bf16 v[28:31], v[146:149], v[204:207], v[28:31]
	v_mfma_f32_16x16x32_bf16 v[24:27], v[154:157], v[204:207], v[24:27]
	v_mfma_f32_16x16x32_bf16 v[12:15], v[146:149], v[212:215], v[12:15]
	v_mfma_f32_16x16x32_bf16 v[8:11], v[154:157], v[212:215], v[8:11]
	v_mfma_f32_16x16x32_bf16 v[52:55], v[158:161], v[184:187], v[52:55]
	v_mfma_f32_16x16x32_bf16 v[48:51], v[166:169], v[184:187], v[48:51]
	v_mfma_f32_16x16x32_bf16 v[36:39], v[158:161], v[192:195], v[36:39]
	v_mfma_f32_16x16x32_bf16 v[32:35], v[166:169], v[192:195], v[32:35]
	v_mfma_f32_16x16x32_bf16 v[20:23], v[158:161], v[200:203], v[20:23]
	v_mfma_f32_16x16x32_bf16 v[16:19], v[166:169], v[200:203], v[16:19]
	v_mfma_f32_16x16x32_bf16 v[4:7], v[158:161], v[208:211], v[4:7]
	v_mfma_f32_16x16x32_bf16 v[0:3], v[166:169], v[208:211], v[0:3]
	v_mfma_f32_16x16x32_bf16 v[52:55], v[162:165], v[188:191], v[52:55]
	v_mfma_f32_16x16x32_bf16 v[48:51], v[170:173], v[188:191], v[48:51]
	v_mfma_f32_16x16x32_bf16 v[36:39], v[162:165], v[196:199], v[36:39]
	v_mfma_f32_16x16x32_bf16 v[32:35], v[170:173], v[196:199], v[32:35]
	v_mfma_f32_16x16x32_bf16 v[20:23], v[162:165], v[204:207], v[20:23]
	v_mfma_f32_16x16x32_bf16 v[16:19], v[170:173], v[204:207], v[16:19]
	v_mfma_f32_16x16x32_bf16 v[4:7], v[162:165], v[212:215], v[4:7]
	v_mfma_f32_16x16x32_bf16 v[0:3], v[170:173], v[212:215], v[0:3]
	s_barrier
	s_add_i32 s20, 16, 0x18000
	s_add_i32 s21, 16, 0x1c000
	v_add_u32_e32 v154, s20, v139
	v_add_u32_e32 v170, s21, v139
	ds_read_b128 v[142:145], v154
	ds_read_b128 v[146:149], v154 offset:1024
	ds_read_b128 v[150:153], v154 offset:2048
	ds_read_b128 v[154:157], v154 offset:3072
	ds_read_b128 v[158:161], v170
	ds_read_b128 v[162:165], v170 offset:1024
	ds_read_b128 v[166:169], v170 offset:2048
	ds_read_b128 v[170:173], v170 offset:3072
	s_add_u32 s38, s38, 0x10000
	s_addc_u32 s39, s39, 0
	s_mov_b32 m0, s43
	v_lshl_add_u64 v[226:227], s[38:39], 0, v[132:133]
	ds_read_b128 v[184:187], v141 offset:32768
	ds_read_b128 v[188:191], v141 offset:33792
	ds_read_b128 v[192:195], v141 offset:34816
	ds_read_b128 v[196:199], v141 offset:35840
	ds_read_b128 v[200:203], v141 offset:36864
	ds_read_b128 v[204:207], v141 offset:37888
	ds_read_b128 v[208:211], v141 offset:38912
	ds_read_b128 v[212:215], v141 offset:39936
	global_load_lds_dwordx4 v[226:227], off
	v_lshl_add_u64 v[226:227], s[38:39], 0, v[130:131]
	s_mov_b32 m0, s44
	s_nop 0
	global_load_lds_dwordx4 v[226:227], off
	s_waitcnt vmcnt(8)
	s_waitcnt lgkmcnt(0)
	s_barrier
	s_waitcnt lgkmcnt(0)
	v_mfma_f32_16x16x32_bf16 v[120:123], v[142:145], v[184:187], v[120:123]
	v_mfma_f32_16x16x32_bf16 v[124:127], v[150:153], v[184:187], v[124:127]
	v_mfma_f32_16x16x32_bf16 v[108:111], v[142:145], v[192:195], v[108:111]
	v_mfma_f32_16x16x32_bf16 v[104:107], v[150:153], v[192:195], v[104:107]
	v_mfma_f32_16x16x32_bf16 v[92:95], v[142:145], v[200:203], v[92:95]
	v_mfma_f32_16x16x32_bf16 v[88:91], v[150:153], v[200:203], v[88:91]
	v_mfma_f32_16x16x32_bf16 v[76:79], v[142:145], v[208:211], v[76:79]
	v_mfma_f32_16x16x32_bf16 v[72:75], v[150:153], v[208:211], v[72:75]
	v_mfma_f32_16x16x32_bf16 v[120:123], v[146:149], v[188:191], v[120:123]
	v_mfma_f32_16x16x32_bf16 v[124:127], v[154:157], v[188:191], v[124:127]
	v_mfma_f32_16x16x32_bf16 v[108:111], v[146:149], v[196:199], v[108:111]
	v_mfma_f32_16x16x32_bf16 v[104:107], v[154:157], v[196:199], v[104:107]
	v_mfma_f32_16x16x32_bf16 v[92:95], v[146:149], v[204:207], v[92:95]
	v_mfma_f32_16x16x32_bf16 v[88:91], v[154:157], v[204:207], v[88:91]
	v_mfma_f32_16x16x32_bf16 v[76:79], v[146:149], v[212:215], v[76:79]
	v_mfma_f32_16x16x32_bf16 v[72:75], v[154:157], v[212:215], v[72:75]
	v_mfma_f32_16x16x32_bf16 v[116:119], v[158:161], v[184:187], v[116:119]
	v_mfma_f32_16x16x32_bf16 v[112:115], v[166:169], v[184:187], v[112:115]
	v_mfma_f32_16x16x32_bf16 v[100:103], v[158:161], v[192:195], v[100:103]
	v_mfma_f32_16x16x32_bf16 v[96:99], v[166:169], v[192:195], v[96:99]
	v_mfma_f32_16x16x32_bf16 v[84:87], v[158:161], v[200:203], v[84:87]
	v_mfma_f32_16x16x32_bf16 v[80:83], v[166:169], v[200:203], v[80:83]
	v_mfma_f32_16x16x32_bf16 v[68:71], v[158:161], v[208:211], v[68:71]
	v_mfma_f32_16x16x32_bf16 v[64:67], v[166:169], v[208:211], v[64:67]
	v_mfma_f32_16x16x32_bf16 v[116:119], v[162:165], v[188:191], v[116:119]
	v_mfma_f32_16x16x32_bf16 v[112:115], v[170:173], v[188:191], v[112:115]
	v_mfma_f32_16x16x32_bf16 v[100:103], v[162:165], v[196:199], v[100:103]
	v_mfma_f32_16x16x32_bf16 v[96:99], v[170:173], v[196:199], v[96:99]
	v_mfma_f32_16x16x32_bf16 v[84:87], v[162:165], v[204:207], v[84:87]
	v_mfma_f32_16x16x32_bf16 v[80:83], v[170:173], v[204:207], v[80:83]
	v_mfma_f32_16x16x32_bf16 v[68:71], v[162:165], v[212:215], v[68:71]
	v_mfma_f32_16x16x32_bf16 v[64:67], v[170:173], v[212:215], v[64:67]
	s_barrier
; #define PG8_STAGE(bufoff, gbase, voff) do { _Pragma("unroll") for (int _i = 0; _i < 2; ++_i) \
;         __builtin_amdgcn_global_load_lds((const unsigned*)((const char*)(gbase) + (voff)[_i]), (LAS unsigned*)(lds + (bufoff) + ldsw + _i * 8192), 16, 0, 0); } while (0)
; #define PG8_LDA(dst, b, h) do { _Pragma("unroll") for (int m = 0; m < 4; ++m) _Pragma("unroll") for (int k = 0; k < 2; ++k) dst[m][k] = *(const LAS bf16x8*)(lds + PG8_SA(b, h) + aoff + m * 2048 + k * 1024); } while (0)
; #define PG8_LDB(dst, b, h) do { _Pragma("unroll") for (int n = 0; n < 2; ++n) _Pragma("unroll") for (int k = 0; k < 2; ++k) dst[n][k] = *(const LAS bf16x8*)(lds + PG8_SB(b, h) + boff + n * 2048 + k * 1024); } while (0)
; #define PG8_MMA(ai, bj, At, Bt) do { __builtin_amdgcn_s_setprio(1); _Pragma("unroll") for (int m = 0; m < 4; ++m) _Pragma("unroll") for (int n = 0; n < 2; ++n) _Pragma("unroll") for (int k = 0; k < 2; ++k) \
;         acc[ai][bj][m][n] = __builtin_amdgcn_mfma_f32_16x16x32_bf16(Bt[n][k], At[m][k], acc[ai][bj][m][n], 0, 0, 0); __builtin_amdgcn_s_setprio(0); } while (0)
; #define PG8_WAIT_V(n) asm volatile("s_waitcnt vmcnt(" #n ")" ::: "memory")
; #define PG8_WAIT_L(n) asm volatile("s_waitcnt lgkmcnt(" #n ")" ::: "memory")
; #define PG8_BAR __builtin_amdgcn_s_barrier()
; #define PG8_SCHED __builtin_amdgcn_sched_barrier(0)
; template <class Epi, bool ALIGN_EPI = PG8_ALIGN>
; __device__ __forceinline__ void gemm_phase(LAS unsigned char* lds, const Gemm g, const StaticOrder& S, const Epi& E) {
;     ...
;             PG8_LDB(B0, 1, 0); PG8_LDB(B1, 1, 1); PG8_SCHED; PG8_LDA(At, 1, 0); PG8_STAGE(PG8_SA(0, 1), a2 + hstepA, voffA);
;             PG8_WAIT_V(8); PG8_WAIT_L(0); PG8_BAR; PG8_MMA(0, 0, At, B0); PG8_MMA(0, 1, At, B1); PG8_BAR; PG8_SCHED;
;             PG8_LDA(At, 1, 1); PG8_STAGE(PG8_SB(1, 0), b3, voffB); PG8_STAGE(PG8_SB(1, 1), b3 + hstepB, voffB); PG8_STAGE(PG8_SA(1, 0), a3, voffA);
;             PG8_WAIT_V(8); PG8_WAIT_L(0); PG8_BAR; PG8_MMA(1, 0, At, B0); PG8_MMA(1, 1, At, B1); PG8_BAR; PG8_SCHED;
;         }
	s_add_i32 s20, s20, s42
	v_lshl_add_u64 v[174:175], v[174:175], 0, s[0:1]
	s_mov_b32 m0, s20
	ds_read_b128 v[184:187], v141 offset:49152
	ds_read_b128 v[188:191], v141 offset:50176
	ds_read_b128 v[192:195], v141 offset:51200
	ds_read_b128 v[196:199], v141 offset:52224
	ds_read_b128 v[200:203], v141 offset:53248
	ds_read_b128 v[204:207], v141 offset:54272
	ds_read_b128 v[208:211], v141 offset:55296
	ds_read_b128 v[212:215], v141 offset:56320
	global_load_lds_dwordx4 v[174:175], off
	v_lshl_add_u64 v[174:175], v[216:217], 0, s[0:1]
	s_add_i32 m0, s20, 0x2000
	s_add_i32 s20, s21, s42
	global_load_lds_dwordx4 v[174:175], off
	v_lshl_add_u64 v[174:175], v[218:219], 0, s[0:1]
	s_mov_b32 m0, s20
	s_nop 0
	global_load_lds_dwordx4 v[174:175], off
	v_lshl_add_u64 v[174:175], v[220:221], 0, s[0:1]
	s_add_i32 m0, s20, 0x2000
	s_nop 0
	global_load_lds_dwordx4 v[174:175], off
	v_lshl_add_u64 v[174:175], v[222:223], 0, s[0:1]
	s_mov_b32 m0, s45
	s_nop 0
	global_load_lds_dwordx4 v[174:175], off
	v_lshl_add_u64 v[174:175], v[224:225], 0, s[0:1]
	s_mov_b32 m0, s46
	s_nop 0
	global_load_lds_dwordx4 v[174:175], off
	s_waitcnt vmcnt(8)
	s_waitcnt lgkmcnt(0)
	s_barrier
	s_waitcnt lgkmcnt(0)
	v_mfma_f32_16x16x32_bf16 v[60:63], v[142:145], v[184:187], v[60:63]
	v_mfma_f32_16x16x32_bf16 v[56:59], v[150:153], v[184:187], v[56:59]
	v_mfma_f32_16x16x32_bf16 v[44:47], v[142:145], v[192:195], v[44:47]
	v_mfma_f32_16x16x32_bf16 v[40:43], v[150:153], v[192:195], v[40:43]
	v_mfma_f32_16x16x32_bf16 v[28:31], v[142:145], v[200:203], v[28:31]
	v_mfma_f32_16x16x32_bf16 v[24:27], v[150:153], v[200:203], v[24:27]
	v_mfma_f32_16x16x32_bf16 v[12:15], v[142:145], v[208:211], v[12:15]
	v_mfma_f32_16x16x32_bf16 v[8:11], v[150:153], v[208:211], v[8:11]
	v_mfma_f32_16x16x32_bf16 v[60:63], v[146:149], v[188:191], v[60:63]
	v_mfma_f32_16x16x32_bf16 v[56:59], v[154:157], v[188:191], v[56:59]
	v_mfma_f32_16x16x32_bf16 v[44:47], v[146:149], v[196:199], v[44:47]
	v_mfma_f32_16x16x32_bf16 v[40:43], v[154:157], v[196:199], v[40:43]
	v_mfma_f32_16x16x32_bf16 v[28:31], v[146:149], v[204:207], v[28:31]
	v_mfma_f32_16x16x32_bf16 v[24:27], v[154:157], v[204:207], v[24:27]
	v_mfma_f32_16x16x32_bf16 v[12:15], v[146:149], v[212:215], v[12:15]
	v_mfma_f32_16x16x32_bf16 v[8:11], v[154:157], v[212:215], v[8:11]
	v_mfma_f32_16x16x32_bf16 v[52:55], v[158:161], v[184:187], v[52:55]
	v_mfma_f32_16x16x32_bf16 v[48:51], v[166:169], v[184:187], v[48:51]
	v_mfma_f32_16x16x32_bf16 v[36:39], v[158:161], v[192:195], v[36:39]
	v_mfma_f32_16x16x32_bf16 v[32:35], v[166:169], v[192:195], v[32:35]
	v_mfma_f32_16x16x32_bf16 v[20:23], v[158:161], v[200:203], v[20:23]
	v_mfma_f32_16x16x32_bf16 v[16:19], v[166:169], v[200:203], v[16:19]
	v_mfma_f32_16x16x32_bf16 v[4:7], v[158:161], v[208:211], v[4:7]
	v_mfma_f32_16x16x32_bf16 v[0:3], v[166:169], v[208:211], v[0:3]
	v_mfma_f32_16x16x32_bf16 v[52:55], v[162:165], v[188:191], v[52:55]
	v_mfma_f32_16x16x32_bf16 v[48:51], v[170:173], v[188:191], v[48:51]
	v_mfma_f32_16x16x32_bf16 v[36:39], v[162:165], v[196:199], v[36:39]
	v_mfma_f32_16x16x32_bf16 v[32:35], v[170:173], v[196:199], v[32:35]
	v_mfma_f32_16x16x32_bf16 v[20:23], v[162:165], v[204:207], v[20:23]
	v_mfma_f32_16x16x32_bf16 v[16:19], v[170:173], v[204:207], v[16:19]
	v_mfma_f32_16x16x32_bf16 v[4:7], v[162:165], v[212:215], v[4:7]
	v_mfma_f32_16x16x32_bf16 v[0:3], v[170:173], v[212:215], v[0:3]
	s_barrier
	s_add_u32 s4, s4, 0x100
	s_addc_u32 s5, s5, 0
	s_add_u32 s40, s40, 0x100
	s_addc_u32 s41, s41, 0
	s_cmp_ge_i32 s53, s34
	s_mov_b32 s38, s53
	s_cbranch_scc0 .LBB0_481
	s_setprio 0

; #define PG8_STAGE(bufoff, gbase, voff) do { _Pragma("unroll") for (int _i = 0; _i < 2; ++_i) \
;         __builtin_amdgcn_global_load_lds((const unsigned*)((const char*)(gbase) + (voff)[_i]), (LAS unsigned*)(lds + (bufoff) + ldsw + _i * 8192), 16, 0, 0); } while (0)
; #define PG8_WAIT_V(n) asm volatile("s_waitcnt vmcnt(" #n ")" ::: "memory")
; #define PG8_BAR __builtin_amdgcn_s_barrier()
; template <class Epi, bool ALIGN_EPI = PG8_ALIGN>
; __device__ __forceinline__ void gemm_phase(LAS unsigned char* lds, const Gemm g, const StaticOrder& S, const Epi& E) {
;     ...
;     f32x4 acc[2][2][4][2];
; #pragma unroll
;     for (int a = 0; a < 2; ++a)
; #pragma unroll
;         for (int b = 0; b < 2; ++b)
; #pragma unroll
;             for (int m = 0; m < 4; ++m)
; #pragma unroll
;                 for (int n = 0; n < 2; ++n) acc[a][b][m][n] = (f32x4){0.f, 0.f, 0.f, 0.f};
;     bf16x8 At[4][2], B0[2][2], B1[2][2];
;     const char* cA = (const char*)g.A + (size_t)cur.pm * tstepA; const char* cB = (const char*)g.Bt + (size_t)cur.pn * tstepB;
;     PG8_STAGE(PG8_SB(0, 0), cB, voffB); PG8_STAGE(PG8_SB(0, 1), cB + hstepB, voffB); PG8_STAGE(PG8_SA(0, 0), cA, voffA); PG8_STAGE(PG8_SA(0, 1), cA + hstepA, voffA);
;     if (wr == 1) PG8_BAR;
;     PG8_WAIT_V(2); PG8_BAR;
;     PG8_STAGE(PG8_SB(1, 0), cB + kstep, voffB); PG8_STAGE(PG8_SA(1, 0), cA + kstep, voffA); PG8_STAGE(PG8_SB(1, 1), cB + hstepB + kstep, voffB);
;     PG8_WAIT_V(6); PG8_BAR;
;     for (;;) {
;         const bool has_next = S.next(ui + 1, nxt);
;         const char* nA = has_next ? (const char*)g.A + (size_t)nxt.pm * tstepA : cA; const char* nB = has_next ? (const char*)g.Bt + (size_t)nxt.pn * tstepB : cB;
.LBB0_640:
	v_mov_b32_e32 v123, 0
	s_andn2_b64 vcc, exec, s[12:13]
	v_mov_b32_e32 v122, v123
	v_mov_b32_e32 v121, v123
	v_mov_b32_e32 v120, v123
	v_mov_b32_e32 v127, v123
	v_mov_b32_e32 v126, v123
	v_mov_b32_e32 v125, v123
	v_mov_b32_e32 v124, v123
	v_mov_b32_e32 v111, v123
	v_mov_b32_e32 v110, v123
	v_mov_b32_e32 v109, v123
	v_mov_b32_e32 v108, v123
	v_mov_b32_e32 v107, v123
	v_mov_b32_e32 v106, v123
	v_mov_b32_e32 v105, v123
	v_mov_b32_e32 v104, v123
	v_mov_b32_e32 v95, v123
	v_mov_b32_e32 v94, v123
	v_mov_b32_e32 v93, v123
	v_mov_b32_e32 v92, v123
	v_mov_b32_e32 v91, v123
	v_mov_b32_e32 v90, v123
	v_mov_b32_e32 v89, v123
	v_mov_b32_e32 v88, v123
	v_mov_b32_e32 v79, v123
	v_mov_b32_e32 v78, v123
	v_mov_b32_e32 v77, v123
	v_mov_b32_e32 v76, v123
	v_mov_b32_e32 v75, v123
	v_mov_b32_e32 v74, v123
	v_mov_b32_e32 v73, v123
	v_mov_b32_e32 v72, v123
	v_mov_b32_e32 v119, v123
	v_mov_b32_e32 v118, v123
	v_mov_b32_e32 v117, v123
	v_mov_b32_e32 v116, v123
	v_mov_b32_e32 v115, v123
	v_mov_b32_e32 v114, v123
	v_mov_b32_e32 v113, v123
	v_mov_b32_e32 v112, v123
	v_mov_b32_e32 v103, v123
	v_mov_b32_e32 v102, v123
	v_mov_b32_e32 v101, v123
	v_mov_b32_e32 v100, v123
	v_mov_b32_e32 v99, v123
	v_mov_b32_e32 v98, v123
	v_mov_b32_e32 v97, v123
	v_mov_b32_e32 v96, v123
	v_mov_b32_e32 v87, v123
	v_mov_b32_e32 v86, v123
	v_mov_b32_e32 v85, v123
	v_mov_b32_e32 v84, v123
	v_mov_b32_e32 v83, v123
	v_mov_b32_e32 v82, v123
	v_mov_b32_e32 v81, v123
	v_mov_b32_e32 v80, v123
	v_mov_b32_e32 v71, v123
	v_mov_b32_e32 v70, v123
	v_mov_b32_e32 v69, v123
	v_mov_b32_e32 v68, v123
	v_mov_b32_e32 v67, v123
	v_mov_b32_e32 v66, v123
	v_mov_b32_e32 v65, v123
	v_mov_b32_e32 v64, v123
	v_mov_b32_e32 v63, v123
	v_mov_b32_e32 v62, v123
	v_mov_b32_e32 v61, v123
	v_mov_b32_e32 v60, v123
	v_mov_b32_e32 v59, v123
	v_mov_b32_e32 v58, v123
	v_mov_b32_e32 v57, v123
	v_mov_b32_e32 v56, v123
	v_mov_b32_e32 v47, v123
	v_mov_b32_e32 v46, v123
	v_mov_b32_e32 v45, v123
	v_mov_b32_e32 v44, v123
	v_mov_b32_e32 v43, v123
	v_mov_b32_e32 v42, v123
	v_mov_b32_e32 v41, v123
	v_mov_b32_e32 v40, v123
	v_mov_b32_e32 v31, v123
	v_mov_b32_e32 v30, v123
	v_mov_b32_e32 v29, v123
	v_mov_b32_e32 v28, v123
	v_mov_b32_e32 v27, v123
	v_mov_b32_e32 v26, v123
	v_mov_b32_e32 v25, v123
	v_mov_b32_e32 v24, v123
	v_mov_b32_e32 v15, v123
	v_mov_b32_e32 v14, v123
	v_mov_b32_e32 v13, v123
	v_mov_b32_e32 v12, v123
	v_mov_b32_e32 v11, v123
	v_mov_b32_e32 v10, v123
	v_mov_b32_e32 v9, v123
	v_mov_b32_e32 v8, v123
	v_mov_b32_e32 v55, v123
	v_mov_b32_e32 v54, v123
	v_mov_b32_e32 v53, v123
	v_mov_b32_e32 v52, v123
	v_mov_b32_e32 v51, v123
	v_mov_b32_e32 v50, v123
	v_mov_b32_e32 v49, v123
	v_mov_b32_e32 v48, v123
	v_mov_b32_e32 v39, v123
	v_mov_b32_e32 v38, v123
	v_mov_b32_e32 v37, v123
	v_mov_b32_e32 v36, v123
	v_mov_b32_e32 v35, v123
	v_mov_b32_e32 v34, v123
	v_mov_b32_e32 v33, v123
	v_mov_b32_e32 v32, v123
	v_mov_b32_e32 v23, v123
	v_mov_b32_e32 v22, v123
	v_mov_b32_e32 v21, v123
	v_mov_b32_e32 v20, v123
	v_mov_b32_e32 v19, v123
	v_mov_b32_e32 v18, v123
	v_mov_b32_e32 v17, v123
	v_mov_b32_e32 v16, v123
	v_mov_b32_e32 v7, v123
	v_mov_b32_e32 v6, v123
	v_mov_b32_e32 v5, v123
	v_mov_b32_e32 v4, v123
	v_mov_b32_e32 v3, v123
	v_mov_b32_e32 v2, v123
	v_mov_b32_e32 v1, v123
	v_mov_b32_e32 v0, v123
	s_cbranch_vccnz .LBB0_643
	s_add_u32 s51, s36, 0x100
	v_mov_b32_e32 v0, 0
	s_addc_u32 s52, s37, 0
	s_mov_b32 s38, 0
	v_mov_b32_e32 v1, v0
	v_mov_b32_e32 v2, v0
	v_mov_b32_e32 v3, v0
	v_mov_b32_e32 v4, v0
	v_mov_b32_e32 v5, v0
	v_mov_b32_e32 v6, v0
	v_mov_b32_e32 v7, v0
	v_mov_b32_e32 v16, v0
	v_mov_b32_e32 v17, v0
	v_mov_b32_e32 v18, v0
	v_mov_b32_e32 v19, v0
	v_mov_b32_e32 v20, v0
	v_mov_b32_e32 v21, v0
	v_mov_b32_e32 v22, v0
	v_mov_b32_e32 v23, v0
	v_mov_b32_e32 v32, v0
	v_mov_b32_e32 v33, v0
	v_mov_b32_e32 v34, v0
	v_mov_b32_e32 v35, v0
	v_mov_b32_e32 v36, v0
	v_mov_b32_e32 v37, v0
	v_mov_b32_e32 v38, v0
	v_mov_b32_e32 v39, v0
	v_mov_b32_e32 v48, v0
	v_mov_b32_e32 v49, v0
	v_mov_b32_e32 v50, v0
	v_mov_b32_e32 v51, v0
	v_mov_b32_e32 v52, v0
	v_mov_b32_e32 v53, v0
	v_mov_b32_e32 v54, v0
	v_mov_b32_e32 v55, v0
	v_mov_b32_e32 v8, v0
	v_mov_b32_e32 v9, v0
	v_mov_b32_e32 v10, v0
	v_mov_b32_e32 v11, v0
	v_mov_b32_e32 v12, v0
	v_mov_b32_e32 v13, v0
	v_mov_b32_e32 v14, v0
	v_mov_b32_e32 v15, v0
	v_mov_b32_e32 v24, v0
	v_mov_b32_e32 v25, v0
	v_mov_b32_e32 v26, v0
	v_mov_b32_e32 v27, v0
	v_mov_b32_e32 v28, v0
	v_mov_b32_e32 v29, v0
	v_mov_b32_e32 v30, v0
	v_mov_b32_e32 v31, v0
	v_mov_b32_e32 v40, v0
	v_mov_b32_e32 v41, v0
	v_mov_b32_e32 v42, v0
	v_mov_b32_e32 v43, v0
	v_mov_b32_e32 v44, v0
	v_mov_b32_e32 v45, v0
	v_mov_b32_e32 v46, v0
	v_mov_b32_e32 v47, v0
	v_mov_b32_e32 v56, v0
	v_mov_b32_e32 v57, v0
	v_mov_b32_e32 v58, v0
	v_mov_b32_e32 v59, v0
	v_mov_b32_e32 v60, v0
	v_mov_b32_e32 v61, v0
	v_mov_b32_e32 v62, v0
	v_mov_b32_e32 v63, v0
	v_mov_b32_e32 v64, v0
	v_mov_b32_e32 v65, v0
	v_mov_b32_e32 v66, v0
	v_mov_b32_e32 v67, v0
	v_mov_b32_e32 v68, v0
	v_mov_b32_e32 v69, v0
	v_mov_b32_e32 v70, v0
	v_mov_b32_e32 v71, v0
	v_mov_b32_e32 v80, v0
	v_mov_b32_e32 v81, v0
	v_mov_b32_e32 v82, v0
	v_mov_b32_e32 v83, v0
	v_mov_b32_e32 v84, v0
	v_mov_b32_e32 v85, v0
	v_mov_b32_e32 v86, v0
	v_mov_b32_e32 v87, v0
	v_mov_b32_e32 v96, v0
	v_mov_b32_e32 v97, v0
	v_mov_b32_e32 v98, v0
	v_mov_b32_e32 v99, v0
	v_mov_b32_e32 v100, v0
	v_mov_b32_e32 v101, v0
	v_mov_b32_e32 v102, v0
	v_mov_b32_e32 v103, v0
	v_mov_b32_e32 v112, v0
	v_mov_b32_e32 v113, v0
	v_mov_b32_e32 v114, v0
	v_mov_b32_e32 v115, v0
	v_mov_b32_e32 v116, v0
	v_mov_b32_e32 v117, v0
	v_mov_b32_e32 v118, v0
	v_mov_b32_e32 v119, v0
	v_mov_b32_e32 v72, v0
	v_mov_b32_e32 v73, v0
	v_mov_b32_e32 v74, v0
	v_mov_b32_e32 v75, v0
	v_mov_b32_e32 v76, v0
	v_mov_b32_e32 v77, v0
	v_mov_b32_e32 v78, v0
	v_mov_b32_e32 v79, v0
	v_mov_b32_e32 v88, v0
	v_mov_b32_e32 v89, v0
	v_mov_b32_e32 v90, v0
	v_mov_b32_e32 v91, v0
	v_mov_b32_e32 v92, v0
	v_mov_b32_e32 v93, v0
	v_mov_b32_e32 v94, v0
	v_mov_b32_e32 v95, v0
	v_mov_b32_e32 v104, v0
	v_mov_b32_e32 v105, v0
	v_mov_b32_e32 v106, v0
	v_mov_b32_e32 v107, v0
	v_mov_b32_e32 v108, v0
	v_mov_b32_e32 v109, v0
	v_mov_b32_e32 v110, v0
	v_mov_b32_e32 v111, v0
	v_mov_b32_e32 v124, v0
	v_mov_b32_e32 v125, v0
	v_mov_b32_e32 v126, v0
	v_mov_b32_e32 v127, v0
	v_mov_b32_e32 v120, v0
	v_mov_b32_e32 v121, v0
	v_mov_b32_e32 v122, v0
	v_mov_b32_e32 v123, v0
	v_readfirstlane_b32 s100, v238
	s_cmp_lt_u32 s100, 0x100
	s_cbranch_scc1 .Lgp_642
	s_setprio 1
; #define PG8_STAGE(bufoff, gbase, voff) do { _Pragma("unroll") for (int _i = 0; _i < 2; ++_i) \
;         __builtin_amdgcn_global_load_lds((const unsigned*)((const char*)(gbase) + (voff)[_i]), (LAS unsigned*)(lds + (bufoff) + ldsw + _i * 8192), 16, 0, 0); } while (0)
; #define PG8_LDA(dst, b, h) do { _Pragma("unroll") for (int m = 0; m < 4; ++m) _Pragma("unroll") for (int k = 0; k < 2; ++k) dst[m][k] = *(const LAS bf16x8*)(lds + PG8_SA(b, h) + aoff + m * 2048 + k * 1024); } while (0)
; #define PG8_LDB(dst, b, h) do { _Pragma("unroll") for (int n = 0; n < 2; ++n) _Pragma("unroll") for (int k = 0; k < 2; ++k) dst[n][k] = *(const LAS bf16x8*)(lds + PG8_SB(b, h) + boff + n * 2048 + k * 1024); } while (0)
; #define PG8_MMA(ai, bj, At, Bt) do { __builtin_amdgcn_s_setprio(1); _Pragma("unroll") for (int m = 0; m < 4; ++m) _Pragma("unroll") for (int n = 0; n < 2; ++n) _Pragma("unroll") for (int k = 0; k < 2; ++k) \
;         acc[ai][bj][m][n] = __builtin_amdgcn_mfma_f32_16x16x32_bf16(Bt[n][k], At[m][k], acc[ai][bj][m][n], 0, 0, 0); __builtin_amdgcn_s_setprio(0); } while (0)
; #define PG8_BAR __builtin_amdgcn_s_barrier()
; template <class Epi, bool ALIGN_EPI = PG8_ALIGN>
; __device__ __forceinline__ void gemm_phase(LAS unsigned char* lds, const Gemm g, const StaticOrder& S, const Epi& E) {
;     ...
;         const bool has_next = S.next(ui + 1, nxt);
;         const char* nA = has_next ? (const char*)g.A + (size_t)nxt.pm * tstepA : cA; const char* nB = has_next ? (const char*)g.Bt + (size_t)nxt.pn * tstepB : cB;
;         for (int t = 0; t < nt; t += 2) {
;             const bool last = (t == nt - 2);
;             const char* a1 = cA + (size_t)(t + 1) * kstep;
;             const char* a2 = last ? nA : cA + (size_t)(t + 2) * kstep; const char* b2 = last ? nB : cB + (size_t)(t + 2) * kstep;
;             const char* a3 = a2 + kstep; const char* b3 = b2 + kstep;
;             PG8_LDB(B0, 0, 0); PG8_LDB(B1, 0, 1); PG8_SCHED; PG8_LDA(At, 0, 0); PG8_STAGE(PG8_SA(1, 1), a1 + hstepA, voffA);
;             PG8_WAIT_V(8); PG8_WAIT_L(0); PG8_BAR; PG8_MMA(0, 0, At, B0); PG8_MMA(0, 1, At, B1); PG8_BAR; PG8_SCHED;
;             PG8_LDA(At, 0, 1); PG8_STAGE(PG8_SB(0, 0), b2, voffB); PG8_STAGE(PG8_SB(0, 1), b2 + hstepB, voffB); PG8_STAGE(PG8_SA(0, 0), a2, voffA);
;             PG8_WAIT_V(8); PG8_WAIT_L(0); PG8_BAR; PG8_MMA(1, 0, At, B0); PG8_MMA(1, 1, At, B1); PG8_BAR; PG8_SCHED;
.Lgp_642:
.LBB0_642:
	s_add_i32 s53, s38, 2
	s_add_u32 s36, s24, 0x100
	s_addc_u32 s37, s25, 0
	s_add_i32 s20, 16, 0x10000
	s_cmp_eq_u32 s48, s38
	s_cselect_b32 s39, s3, s37
	s_cselect_b32 s38, s2, s36
	v_add_u32_e32 v142, s20, v149
	s_cselect_b32 s55, s17, s52
	s_cselect_b32 s54, s16, s51
	s_add_i32 s21, 16, 0x14000
	ds_read_b128 v[138:141], v142
	ds_read_b128 v[152:155], v142 offset:1024
	ds_read_b128 v[156:159], v142 offset:2048
	ds_read_b128 v[160:163], v142 offset:3072
	v_add_u32_e32 v142, s21, v149
	ds_read_b128 v[164:167], v142
	ds_read_b128 v[168:171], v142 offset:1024
	ds_read_b128 v[172:175], v142 offset:2048
	ds_read_b128 v[184:187], v142 offset:3072
	v_lshl_add_u64 v[142:143], s[24:25], 0, v[134:135]
	s_add_i32 m0, s31, 0xc000
	ds_read_b128 v[188:191], v151
	ds_read_b128 v[192:195], v151 offset:1024
	ds_read_b128 v[196:199], v151 offset:2048
	ds_read_b128 v[200:203], v151 offset:3072
	ds_read_b128 v[204:207], v151 offset:4096
	ds_read_b128 v[208:211], v151 offset:5120
	ds_read_b128 v[212:215], v151 offset:6144
	ds_read_b128 v[216:219], v151 offset:7168
	global_load_lds_dwordx4 v[142:143], off
	v_lshl_add_u64 v[142:143], s[24:25], 0, v[136:137]
	s_add_i32 m0, s31, 0xe000
	s_nop 0
	global_load_lds_dwordx4 v[142:143], off
	s_waitcnt vmcnt(8)
	s_waitcnt lgkmcnt(0)
	s_barrier
	s_waitcnt lgkmcnt(0)
	v_mfma_f32_16x16x32_bf16 v[120:123], v[138:141], v[188:191], v[120:123]
	v_mfma_f32_16x16x32_bf16 v[124:127], v[156:159], v[188:191], v[124:127]
	v_mfma_f32_16x16x32_bf16 v[108:111], v[138:141], v[196:199], v[108:111]
	v_mfma_f32_16x16x32_bf16 v[104:107], v[156:159], v[196:199], v[104:107]
	v_mfma_f32_16x16x32_bf16 v[92:95], v[138:141], v[204:207], v[92:95]
	v_mfma_f32_16x16x32_bf16 v[88:91], v[156:159], v[204:207], v[88:91]
	v_mfma_f32_16x16x32_bf16 v[76:79], v[138:141], v[212:215], v[76:79]
	v_mfma_f32_16x16x32_bf16 v[72:75], v[156:159], v[212:215], v[72:75]
	v_mfma_f32_16x16x32_bf16 v[120:123], v[152:155], v[192:195], v[120:123]
	v_mfma_f32_16x16x32_bf16 v[124:127], v[160:163], v[192:195], v[124:127]
	v_mfma_f32_16x16x32_bf16 v[108:111], v[152:155], v[200:203], v[108:111]
	v_mfma_f32_16x16x32_bf16 v[104:107], v[160:163], v[200:203], v[104:107]
	v_mfma_f32_16x16x32_bf16 v[92:95], v[152:155], v[208:211], v[92:95]
	v_mfma_f32_16x16x32_bf16 v[88:91], v[160:163], v[208:211], v[88:91]
	v_mfma_f32_16x16x32_bf16 v[76:79], v[152:155], v[216:219], v[76:79]
	v_mfma_f32_16x16x32_bf16 v[72:75], v[160:163], v[216:219], v[72:75]
	v_mfma_f32_16x16x32_bf16 v[116:119], v[164:167], v[188:191], v[116:119]
	v_mfma_f32_16x16x32_bf16 v[112:115], v[172:175], v[188:191], v[112:115]
	v_mfma_f32_16x16x32_bf16 v[100:103], v[164:167], v[196:199], v[100:103]
	v_mfma_f32_16x16x32_bf16 v[96:99], v[172:175], v[196:199], v[96:99]
	v_mfma_f32_16x16x32_bf16 v[84:87], v[164:167], v[204:207], v[84:87]
	v_mfma_f32_16x16x32_bf16 v[80:83], v[172:175], v[204:207], v[80:83]
	v_mfma_f32_16x16x32_bf16 v[68:71], v[164:167], v[212:215], v[68:71]
	v_mfma_f32_16x16x32_bf16 v[64:67], v[172:175], v[212:215], v[64:67]
	v_mfma_f32_16x16x32_bf16 v[116:119], v[168:171], v[192:195], v[116:119]
	v_mfma_f32_16x16x32_bf16 v[112:115], v[184:187], v[192:195], v[112:115]
	v_mfma_f32_16x16x32_bf16 v[100:103], v[168:171], v[200:203], v[100:103]
	v_mfma_f32_16x16x32_bf16 v[96:99], v[184:187], v[200:203], v[96:99]
	v_mfma_f32_16x16x32_bf16 v[84:87], v[168:171], v[208:211], v[84:87]
	v_mfma_f32_16x16x32_bf16 v[80:83], v[184:187], v[208:211], v[80:83]
	v_mfma_f32_16x16x32_bf16 v[68:71], v[168:171], v[216:219], v[68:71]
	v_mfma_f32_16x16x32_bf16 v[64:67], v[184:187], v[216:219], v[64:67]
	s_barrier
	s_add_i32 s20, s20, s30
	v_lshl_add_u64 v[142:143], s[54:55], 0, v[176:177]
	s_mov_b32 m0, s20
	ds_read_b128 v[188:191], v151 offset:16384
	ds_read_b128 v[192:195], v151 offset:17408
	ds_read_b128 v[196:199], v151 offset:18432
	ds_read_b128 v[200:203], v151 offset:19456
	ds_read_b128 v[204:207], v151 offset:20480
	ds_read_b128 v[208:211], v151 offset:21504
	ds_read_b128 v[212:215], v151 offset:22528
	ds_read_b128 v[216:219], v151 offset:23552
	global_load_lds_dwordx4 v[142:143], off
	s_add_i32 m0, s20, 0x2000
	s_add_u32 s24, s54, s6
	v_lshl_add_u64 v[146:147], s[54:55], 0, v[128:129]
	s_addc_u32 s25, s55, s7
	s_add_i32 s20, s21, s30
	global_load_lds_dwordx4 v[146:147], off
	v_lshl_add_u64 v[220:221], s[24:25], 0, v[176:177]
	s_mov_b32 m0, s20
	v_lshl_add_u64 v[222:223], s[24:25], 0, v[128:129]
	global_load_lds_dwordx4 v[220:221], off
	s_add_i32 m0, s20, 0x2000
	v_lshl_add_u64 v[224:225], s[38:39], 0, v[132:133]
	global_load_lds_dwordx4 v[222:223], off
	s_mov_b32 m0, s31
	v_lshl_add_u64 v[226:227], s[38:39], 0, v[130:131]
	global_load_lds_dwordx4 v[224:225], off
	s_mov_b32 m0, s40
	s_nop 0
	global_load_lds_dwordx4 v[226:227], off
	s_waitcnt vmcnt(8)
	s_waitcnt lgkmcnt(0)
	s_barrier
; #define PG8_STAGE(bufoff, gbase, voff) do { _Pragma("unroll") for (int _i = 0; _i < 2; ++_i) \
;         __builtin_amdgcn_global_load_lds((const unsigned*)((const char*)(gbase) + (voff)[_i]), (LAS unsigned*)(lds + (bufoff) + ldsw + _i * 8192), 16, 0, 0); } while (0)
; #define PG8_LDA(dst, b, h) do { _Pragma("unroll") for (int m = 0; m < 4; ++m) _Pragma("unroll") for (int k = 0; k < 2; ++k) dst[m][k] = *(const LAS bf16x8*)(lds + PG8_SA(b, h) + aoff + m * 2048 + k * 1024); } while (0)
; #define PG8_LDB(dst, b, h) do { _Pragma("unroll") for (int n = 0; n < 2; ++n) _Pragma("unroll") for (int k = 0; k < 2; ++k) dst[n][k] = *(const LAS bf16x8*)(lds + PG8_SB(b, h) + boff + n * 2048 + k * 1024); } while (0)
; #define PG8_MMA(ai, bj, At, Bt) do { __builtin_amdgcn_s_setprio(1); _Pragma("unroll") for (int m = 0; m < 4; ++m) _Pragma("unroll") for (int n = 0; n < 2; ++n) _Pragma("unroll") for (int k = 0; k < 2; ++k) \
;         acc[ai][bj][m][n] = __builtin_amdgcn_mfma_f32_16x16x32_bf16(Bt[n][k], At[m][k], acc[ai][bj][m][n], 0, 0, 0); __builtin_amdgcn_s_setprio(0); } while (0)
; #define PG8_WAIT_V(n) asm volatile("s_waitcnt vmcnt(" #n ")" ::: "memory")
; #define PG8_WAIT_L(n) asm volatile("s_waitcnt lgkmcnt(" #n ")" ::: "memory")
; #define PG8_BAR __builtin_amdgcn_s_barrier()
; #define PG8_SCHED __builtin_amdgcn_sched_barrier(0)
; template <class Epi, bool ALIGN_EPI = PG8_ALIGN>
; __device__ __forceinline__ void gemm_phase(LAS unsigned char* lds, const Gemm g, const StaticOrder& S, const Epi& E) {
;     ...
;             PG8_WAIT_V(8); PG8_WAIT_L(0); PG8_BAR; PG8_MMA(1, 0, At, B0); PG8_MMA(1, 1, At, B1); PG8_BAR; PG8_SCHED;
;             PG8_LDB(B0, 1, 0); PG8_LDB(B1, 1, 1); PG8_SCHED; PG8_LDA(At, 1, 0); PG8_STAGE(PG8_SA(0, 1), a2 + hstepA, voffA);
;             PG8_WAIT_V(8); PG8_WAIT_L(0); PG8_BAR; PG8_MMA(0, 0, At, B0); PG8_MMA(0, 1, At, B1); PG8_BAR; PG8_SCHED;
;             PG8_LDA(At, 1, 1); PG8_STAGE(PG8_SB(1, 0), b3, voffB); PG8_STAGE(PG8_SB(1, 1), b3 + hstepB, voffB); PG8_STAGE(PG8_SA(1, 0), a3, voffA);
;             PG8_WAIT_V(8); PG8_WAIT_L(0); PG8_BAR; PG8_MMA(1, 0, At, B0); PG8_MMA(1, 1, At, B1); PG8_BAR; PG8_SCHED;
	s_waitcnt lgkmcnt(0)
	v_mfma_f32_16x16x32_bf16 v[60:63], v[138:141], v[188:191], v[60:63]
	v_mfma_f32_16x16x32_bf16 v[56:59], v[156:159], v[188:191], v[56:59]
	v_mfma_f32_16x16x32_bf16 v[44:47], v[138:141], v[196:199], v[44:47]
	v_mfma_f32_16x16x32_bf16 v[40:43], v[156:159], v[196:199], v[40:43]
	v_mfma_f32_16x16x32_bf16 v[28:31], v[138:141], v[204:207], v[28:31]
	v_mfma_f32_16x16x32_bf16 v[24:27], v[156:159], v[204:207], v[24:27]
	v_mfma_f32_16x16x32_bf16 v[12:15], v[138:141], v[212:215], v[12:15]
	v_mfma_f32_16x16x32_bf16 v[8:11], v[156:159], v[212:215], v[8:11]
	v_mfma_f32_16x16x32_bf16 v[60:63], v[152:155], v[192:195], v[60:63]
	v_mfma_f32_16x16x32_bf16 v[56:59], v[160:163], v[192:195], v[56:59]
	v_mfma_f32_16x16x32_bf16 v[44:47], v[152:155], v[200:203], v[44:47]
	v_mfma_f32_16x16x32_bf16 v[40:43], v[160:163], v[200:203], v[40:43]
	v_mfma_f32_16x16x32_bf16 v[28:31], v[152:155], v[208:211], v[28:31]
	v_mfma_f32_16x16x32_bf16 v[24:27], v[160:163], v[208:211], v[24:27]
	v_mfma_f32_16x16x32_bf16 v[12:15], v[152:155], v[216:219], v[12:15]
	v_mfma_f32_16x16x32_bf16 v[8:11], v[160:163], v[216:219], v[8:11]
	v_mfma_f32_16x16x32_bf16 v[52:55], v[164:167], v[188:191], v[52:55]
	v_mfma_f32_16x16x32_bf16 v[48:51], v[172:175], v[188:191], v[48:51]
	v_mfma_f32_16x16x32_bf16 v[36:39], v[164:167], v[196:199], v[36:39]
	v_mfma_f32_16x16x32_bf16 v[32:35], v[172:175], v[196:199], v[32:35]
	v_mfma_f32_16x16x32_bf16 v[20:23], v[164:167], v[204:207], v[20:23]
	v_mfma_f32_16x16x32_bf16 v[16:19], v[172:175], v[204:207], v[16:19]
	v_mfma_f32_16x16x32_bf16 v[4:7], v[164:167], v[212:215], v[4:7]
	v_mfma_f32_16x16x32_bf16 v[0:3], v[172:175], v[212:215], v[0:3]
	v_mfma_f32_16x16x32_bf16 v[52:55], v[168:171], v[192:195], v[52:55]
	v_mfma_f32_16x16x32_bf16 v[48:51], v[184:187], v[192:195], v[48:51]
	v_mfma_f32_16x16x32_bf16 v[36:39], v[168:171], v[200:203], v[36:39]
	v_mfma_f32_16x16x32_bf16 v[32:35], v[184:187], v[200:203], v[32:35]
	v_mfma_f32_16x16x32_bf16 v[20:23], v[168:171], v[208:211], v[20:23]
	v_mfma_f32_16x16x32_bf16 v[16:19], v[184:187], v[208:211], v[16:19]
	v_mfma_f32_16x16x32_bf16 v[4:7], v[168:171], v[216:219], v[4:7]
	v_mfma_f32_16x16x32_bf16 v[0:3], v[184:187], v[216:219], v[0:3]
	s_barrier
	s_add_i32 s20, 16, 0x18000
	v_add_u32_e32 v144, s20, v149
	s_add_i32 s21, 16, 0x1c000
	ds_read_b128 v[138:141], v144
	ds_read_b128 v[152:155], v144 offset:1024
	ds_read_b128 v[156:159], v144 offset:2048
	ds_read_b128 v[160:163], v144 offset:3072
	v_add_u32_e32 v144, s21, v149
	ds_read_b128 v[164:167], v144
	ds_read_b128 v[168:171], v144 offset:1024
	ds_read_b128 v[172:175], v144 offset:2048
	ds_read_b128 v[184:187], v144 offset:3072
	s_add_u32 s24, s38, 0x110000
	s_addc_u32 s25, s39, 0
	s_mov_b32 m0, s41
	v_lshl_add_u64 v[228:229], s[24:25], 0, v[132:133]
	ds_read_b128 v[188:191], v151 offset:32768
	ds_read_b128 v[192:195], v151 offset:33792
	ds_read_b128 v[196:199], v151 offset:34816
	ds_read_b128 v[200:203], v151 offset:35840
	ds_read_b128 v[204:207], v151 offset:36864
	ds_read_b128 v[208:211], v151 offset:37888
	ds_read_b128 v[212:215], v151 offset:38912
	ds_read_b128 v[216:219], v151 offset:39936
	global_load_lds_dwordx4 v[228:229], off
	v_lshl_add_u64 v[228:229], s[24:25], 0, v[130:131]
	s_mov_b32 m0, s44
	s_nop 0
	global_load_lds_dwordx4 v[228:229], off
	s_waitcnt vmcnt(8)
	s_waitcnt lgkmcnt(0)
	s_barrier
	s_waitcnt lgkmcnt(0)
	v_mfma_f32_16x16x32_bf16 v[120:123], v[138:141], v[188:191], v[120:123]
	v_mfma_f32_16x16x32_bf16 v[124:127], v[156:159], v[188:191], v[124:127]
	v_mfma_f32_16x16x32_bf16 v[108:111], v[138:141], v[196:199], v[108:111]
	v_mfma_f32_16x16x32_bf16 v[104:107], v[156:159], v[196:199], v[104:107]
	v_mfma_f32_16x16x32_bf16 v[92:95], v[138:141], v[204:207], v[92:95]
	v_mfma_f32_16x16x32_bf16 v[88:91], v[156:159], v[204:207], v[88:91]
	v_mfma_f32_16x16x32_bf16 v[76:79], v[138:141], v[212:215], v[76:79]
	v_mfma_f32_16x16x32_bf16 v[72:75], v[156:159], v[212:215], v[72:75]
	v_mfma_f32_16x16x32_bf16 v[120:123], v[152:155], v[192:195], v[120:123]
	v_mfma_f32_16x16x32_bf16 v[124:127], v[160:163], v[192:195], v[124:127]
	v_mfma_f32_16x16x32_bf16 v[108:111], v[152:155], v[200:203], v[108:111]
	v_mfma_f32_16x16x32_bf16 v[104:107], v[160:163], v[200:203], v[104:107]
	v_mfma_f32_16x16x32_bf16 v[92:95], v[152:155], v[208:211], v[92:95]
	v_mfma_f32_16x16x32_bf16 v[88:91], v[160:163], v[208:211], v[88:91]
	v_mfma_f32_16x16x32_bf16 v[76:79], v[152:155], v[216:219], v[76:79]
	v_mfma_f32_16x16x32_bf16 v[72:75], v[160:163], v[216:219], v[72:75]
	v_mfma_f32_16x16x32_bf16 v[116:119], v[164:167], v[188:191], v[116:119]
	v_mfma_f32_16x16x32_bf16 v[112:115], v[172:175], v[188:191], v[112:115]
	v_mfma_f32_16x16x32_bf16 v[100:103], v[164:167], v[196:199], v[100:103]
	v_mfma_f32_16x16x32_bf16 v[96:99], v[172:175], v[196:199], v[96:99]
	v_mfma_f32_16x16x32_bf16 v[84:87], v[164:167], v[204:207], v[84:87]
	v_mfma_f32_16x16x32_bf16 v[80:83], v[172:175], v[204:207], v[80:83]
	v_mfma_f32_16x16x32_bf16 v[68:71], v[164:167], v[212:215], v[68:71]
	v_mfma_f32_16x16x32_bf16 v[64:67], v[172:175], v[212:215], v[64:67]
	v_mfma_f32_16x16x32_bf16 v[116:119], v[168:171], v[192:195], v[116:119]
	v_mfma_f32_16x16x32_bf16 v[112:115], v[184:187], v[192:195], v[112:115]
	v_mfma_f32_16x16x32_bf16 v[100:103], v[168:171], v[200:203], v[100:103]
	v_mfma_f32_16x16x32_bf16 v[96:99], v[184:187], v[200:203], v[96:99]
	v_mfma_f32_16x16x32_bf16 v[84:87], v[168:171], v[208:211], v[84:87]
	v_mfma_f32_16x16x32_bf16 v[80:83], v[184:187], v[208:211], v[80:83]
	v_mfma_f32_16x16x32_bf16 v[68:71], v[168:171], v[216:219], v[68:71]
	v_mfma_f32_16x16x32_bf16 v[64:67], v[184:187], v[216:219], v[64:67]
	s_barrier
; #define PG8_STAGE(bufoff, gbase, voff) do { _Pragma("unroll") for (int _i = 0; _i < 2; ++_i) \
;         __builtin_amdgcn_global_load_lds((const unsigned*)((const char*)(gbase) + (voff)[_i]), (LAS unsigned*)(lds + (bufoff) + ldsw + _i * 8192), 16, 0, 0); } while (0)
; #define PG8_LDA(dst, b, h) do { _Pragma("unroll") for (int m = 0; m < 4; ++m) _Pragma("unroll") for (int k = 0; k < 2; ++k) dst[m][k] = *(const LAS bf16x8*)(lds + PG8_SA(b, h) + aoff + m * 2048 + k * 1024); } while (0)
; #define PG8_LDB(dst, b, h) do { _Pragma("unroll") for (int n = 0; n < 2; ++n) _Pragma("unroll") for (int k = 0; k < 2; ++k) dst[n][k] = *(const LAS bf16x8*)(lds + PG8_SB(b, h) + boff + n * 2048 + k * 1024); } while (0)
; #define PG8_MMA(ai, bj, At, Bt) do { __builtin_amdgcn_s_setprio(1); _Pragma("unroll") for (int m = 0; m < 4; ++m) _Pragma("unroll") for (int n = 0; n < 2; ++n) _Pragma("unroll") for (int k = 0; k < 2; ++k) \
;         acc[ai][bj][m][n] = __builtin_amdgcn_mfma_f32_16x16x32_bf16(Bt[n][k], At[m][k], acc[ai][bj][m][n], 0, 0, 0); __builtin_amdgcn_s_setprio(0); } while (0)
; #define PG8_WAIT_V(n) asm volatile("s_waitcnt vmcnt(" #n ")" ::: "memory")
; #define PG8_WAIT_L(n) asm volatile("s_waitcnt lgkmcnt(" #n ")" ::: "memory")
; #define PG8_BAR __builtin_amdgcn_s_barrier()
; #define PG8_SCHED __builtin_amdgcn_sched_barrier(0)
; template <class Epi, bool ALIGN_EPI = PG8_ALIGN>
; __device__ __forceinline__ void gemm_phase(LAS unsigned char* lds, const Gemm g, const StaticOrder& S, const Epi& E) {
;     ...
;             PG8_LDB(B0, 1, 0); PG8_LDB(B1, 1, 1); PG8_SCHED; PG8_LDA(At, 1, 0); PG8_STAGE(PG8_SA(0, 1), a2 + hstepA, voffA);
;             PG8_WAIT_V(8); PG8_WAIT_L(0); PG8_BAR; PG8_MMA(0, 0, At, B0); PG8_MMA(0, 1, At, B1); PG8_BAR; PG8_SCHED;
;             PG8_LDA(At, 1, 1); PG8_STAGE(PG8_SB(1, 0), b3, voffB); PG8_STAGE(PG8_SB(1, 1), b3 + hstepB, voffB); PG8_STAGE(PG8_SA(1, 0), a3, voffA);
;             PG8_WAIT_V(8); PG8_WAIT_L(0); PG8_BAR; PG8_MMA(1, 0, At, B0); PG8_MMA(1, 1, At, B1); PG8_BAR; PG8_SCHED;
;         }
	s_add_i32 s20, s20, s30
	v_lshl_add_u64 v[142:143], v[142:143], 0, s[0:1]
	s_mov_b32 m0, s20
	ds_read_b128 v[188:191], v151 offset:49152
	ds_read_b128 v[192:195], v151 offset:50176
	ds_read_b128 v[196:199], v151 offset:51200
	ds_read_b128 v[200:203], v151 offset:52224
	ds_read_b128 v[204:207], v151 offset:53248
	ds_read_b128 v[208:211], v151 offset:54272
	ds_read_b128 v[212:215], v151 offset:55296
	ds_read_b128 v[216:219], v151 offset:56320
	global_load_lds_dwordx4 v[142:143], off
	v_lshl_add_u64 v[142:143], v[146:147], 0, s[0:1]
	s_add_i32 m0, s20, 0x2000
	s_add_i32 s20, s21, s30
	global_load_lds_dwordx4 v[142:143], off
	v_lshl_add_u64 v[142:143], v[220:221], 0, s[0:1]
	s_mov_b32 m0, s20
	s_nop 0
	global_load_lds_dwordx4 v[142:143], off
	v_lshl_add_u64 v[142:143], v[222:223], 0, s[0:1]
	s_add_i32 m0, s20, 0x2000
	s_nop 0
	global_load_lds_dwordx4 v[142:143], off
	v_lshl_add_u64 v[142:143], v[224:225], 0, s[0:1]
	s_mov_b32 m0, s45
	s_nop 0
	global_load_lds_dwordx4 v[142:143], off
	v_lshl_add_u64 v[142:143], v[226:227], 0, s[0:1]
	s_mov_b32 m0, s46
	s_nop 0
	global_load_lds_dwordx4 v[142:143], off
	s_waitcnt vmcnt(8)
	s_waitcnt lgkmcnt(0)
	s_barrier
	s_waitcnt lgkmcnt(0)
	v_mfma_f32_16x16x32_bf16 v[60:63], v[138:141], v[188:191], v[60:63]
	v_mfma_f32_16x16x32_bf16 v[56:59], v[156:159], v[188:191], v[56:59]
	v_mfma_f32_16x16x32_bf16 v[44:47], v[138:141], v[196:199], v[44:47]
	v_mfma_f32_16x16x32_bf16 v[40:43], v[156:159], v[196:199], v[40:43]
	v_mfma_f32_16x16x32_bf16 v[28:31], v[138:141], v[204:207], v[28:31]
	v_mfma_f32_16x16x32_bf16 v[24:27], v[156:159], v[204:207], v[24:27]
	v_mfma_f32_16x16x32_bf16 v[12:15], v[138:141], v[212:215], v[12:15]
	v_mfma_f32_16x16x32_bf16 v[8:11], v[156:159], v[212:215], v[8:11]
	v_mfma_f32_16x16x32_bf16 v[60:63], v[152:155], v[192:195], v[60:63]
	v_mfma_f32_16x16x32_bf16 v[56:59], v[160:163], v[192:195], v[56:59]
	v_mfma_f32_16x16x32_bf16 v[44:47], v[152:155], v[200:203], v[44:47]
	v_mfma_f32_16x16x32_bf16 v[40:43], v[160:163], v[200:203], v[40:43]
	v_mfma_f32_16x16x32_bf16 v[28:31], v[152:155], v[208:211], v[28:31]
	v_mfma_f32_16x16x32_bf16 v[24:27], v[160:163], v[208:211], v[24:27]
	v_mfma_f32_16x16x32_bf16 v[12:15], v[152:155], v[216:219], v[12:15]
	v_mfma_f32_16x16x32_bf16 v[8:11], v[160:163], v[216:219], v[8:11]
	v_mfma_f32_16x16x32_bf16 v[52:55], v[164:167], v[188:191], v[52:55]
	v_mfma_f32_16x16x32_bf16 v[48:51], v[172:175], v[188:191], v[48:51]
	v_mfma_f32_16x16x32_bf16 v[36:39], v[164:167], v[196:199], v[36:39]
	v_mfma_f32_16x16x32_bf16 v[32:35], v[172:175], v[196:199], v[32:35]
	v_mfma_f32_16x16x32_bf16 v[20:23], v[164:167], v[204:207], v[20:23]
	v_mfma_f32_16x16x32_bf16 v[16:19], v[172:175], v[204:207], v[16:19]
	v_mfma_f32_16x16x32_bf16 v[4:7], v[164:167], v[212:215], v[4:7]
	v_mfma_f32_16x16x32_bf16 v[0:3], v[172:175], v[212:215], v[0:3]
	v_mfma_f32_16x16x32_bf16 v[52:55], v[168:171], v[192:195], v[52:55]
	v_mfma_f32_16x16x32_bf16 v[48:51], v[184:187], v[192:195], v[48:51]
	v_mfma_f32_16x16x32_bf16 v[36:39], v[168:171], v[200:203], v[36:39]
	v_mfma_f32_16x16x32_bf16 v[32:35], v[184:187], v[200:203], v[32:35]
	v_mfma_f32_16x16x32_bf16 v[20:23], v[168:171], v[208:211], v[20:23]
	v_mfma_f32_16x16x32_bf16 v[16:19], v[184:187], v[208:211], v[16:19]
	v_mfma_f32_16x16x32_bf16 v[4:7], v[168:171], v[216:219], v[4:7]
	v_mfma_f32_16x16x32_bf16 v[0:3], v[184:187], v[216:219], v[0:3]
	s_barrier
	s_add_u32 s51, s51, 0x100
	s_addc_u32 s52, s52, 0
	s_cmp_ge_i32 s53, s47
	s_mov_b64 s[24:25], s[36:37]
	s_mov_b32 s38, s53
	s_cbranch_scc0 .LBB0_642
	s_setprio 0

; #define PG8_STAGE(bufoff, gbase, voff) do { _Pragma("unroll") for (int _i = 0; _i < 2; ++_i) \
;         __builtin_amdgcn_global_load_lds((const unsigned*)((const char*)(gbase) + (voff)[_i]), (LAS unsigned*)(lds + (bufoff) + ldsw + _i * 8192), 16, 0, 0); } while (0)
; #define PG8_WAIT_V(n) asm volatile("s_waitcnt vmcnt(" #n ")" ::: "memory")
; #define PG8_BAR __builtin_amdgcn_s_barrier()
; template <class Epi, bool ALIGN_EPI = PG8_ALIGN>
; __device__ __forceinline__ void gemm_phase(LAS unsigned char* lds, const Gemm g, const StaticOrder& S, const Epi& E) {
;     ...
;     f32x4 acc[2][2][4][2];
; #pragma unroll
;     for (int a = 0; a < 2; ++a)
; #pragma unroll
;         for (int b = 0; b < 2; ++b)
; #pragma unroll
;             for (int m = 0; m < 4; ++m)
; #pragma unroll
;                 for (int n = 0; n < 2; ++n) acc[a][b][m][n] = (f32x4){0.f, 0.f, 0.f, 0.f};
;     bf16x8 At[4][2], B0[2][2], B1[2][2];
;     const char* cA = (const char*)g.A + (size_t)cur.pm * tstepA; const char* cB = (const char*)g.Bt + (size_t)cur.pn * tstepB;
;     PG8_STAGE(PG8_SB(0, 0), cB, voffB); PG8_STAGE(PG8_SB(0, 1), cB + hstepB, voffB); PG8_STAGE(PG8_SA(0, 0), cA, voffA); PG8_STAGE(PG8_SA(0, 1), cA + hstepA, voffA);
;     if (wr == 1) PG8_BAR;
;     PG8_WAIT_V(2); PG8_BAR;
;     PG8_STAGE(PG8_SB(1, 0), cB + kstep, voffB); PG8_STAGE(PG8_SA(1, 0), cA + kstep, voffA); PG8_STAGE(PG8_SB(1, 1), cB + hstepB + kstep, voffB);
;     PG8_WAIT_V(6); PG8_BAR;
;     for (;;) {
;         const bool has_next = S.next(ui + 1, nxt);
;         const char* nA = has_next ? (const char*)g.A + (size_t)nxt.pm * tstepA : cA; const char* nB = has_next ? (const char*)g.Bt + (size_t)nxt.pn * tstepB : cB;
.LBB0_661:
	v_mov_b32_e32 v123, 0
	s_andn2_b64 vcc, exec, s[12:13]
	v_mov_b32_e32 v122, v123
	v_mov_b32_e32 v121, v123
	v_mov_b32_e32 v120, v123
	v_mov_b32_e32 v127, v123
	v_mov_b32_e32 v126, v123
	v_mov_b32_e32 v125, v123
	v_mov_b32_e32 v124, v123
	v_mov_b32_e32 v111, v123
	v_mov_b32_e32 v110, v123
	v_mov_b32_e32 v109, v123
	v_mov_b32_e32 v108, v123
	v_mov_b32_e32 v107, v123
	v_mov_b32_e32 v106, v123
	v_mov_b32_e32 v105, v123
	v_mov_b32_e32 v104, v123
	v_mov_b32_e32 v95, v123
	v_mov_b32_e32 v94, v123
	v_mov_b32_e32 v93, v123
	v_mov_b32_e32 v92, v123
	v_mov_b32_e32 v91, v123
	v_mov_b32_e32 v90, v123
	v_mov_b32_e32 v89, v123
	v_mov_b32_e32 v88, v123
	v_mov_b32_e32 v79, v123
	v_mov_b32_e32 v78, v123
	v_mov_b32_e32 v77, v123
	v_mov_b32_e32 v76, v123
	v_mov_b32_e32 v75, v123
	v_mov_b32_e32 v74, v123
	v_mov_b32_e32 v73, v123
	v_mov_b32_e32 v72, v123
	v_mov_b32_e32 v119, v123
	v_mov_b32_e32 v118, v123
	v_mov_b32_e32 v117, v123
	v_mov_b32_e32 v116, v123
	v_mov_b32_e32 v115, v123
	v_mov_b32_e32 v114, v123
	v_mov_b32_e32 v113, v123
	v_mov_b32_e32 v112, v123
	v_mov_b32_e32 v103, v123
	v_mov_b32_e32 v102, v123
	v_mov_b32_e32 v101, v123
	v_mov_b32_e32 v100, v123
	v_mov_b32_e32 v99, v123
	v_mov_b32_e32 v98, v123
	v_mov_b32_e32 v97, v123
	v_mov_b32_e32 v96, v123
	v_mov_b32_e32 v87, v123
	v_mov_b32_e32 v86, v123
	v_mov_b32_e32 v85, v123
	v_mov_b32_e32 v84, v123
	v_mov_b32_e32 v83, v123
	v_mov_b32_e32 v82, v123
	v_mov_b32_e32 v81, v123
	v_mov_b32_e32 v80, v123
	v_mov_b32_e32 v71, v123
	v_mov_b32_e32 v70, v123
	v_mov_b32_e32 v69, v123
	v_mov_b32_e32 v68, v123
	v_mov_b32_e32 v67, v123
	v_mov_b32_e32 v66, v123
	v_mov_b32_e32 v65, v123
	v_mov_b32_e32 v64, v123
	v_mov_b32_e32 v63, v123
	v_mov_b32_e32 v62, v123
	v_mov_b32_e32 v61, v123
	v_mov_b32_e32 v60, v123
	v_mov_b32_e32 v59, v123
	v_mov_b32_e32 v58, v123
	v_mov_b32_e32 v57, v123
	v_mov_b32_e32 v56, v123
	v_mov_b32_e32 v47, v123
	v_mov_b32_e32 v46, v123
	v_mov_b32_e32 v45, v123
	v_mov_b32_e32 v44, v123
	v_mov_b32_e32 v43, v123
	v_mov_b32_e32 v42, v123
	v_mov_b32_e32 v41, v123
	v_mov_b32_e32 v40, v123
	v_mov_b32_e32 v31, v123
	v_mov_b32_e32 v30, v123
	v_mov_b32_e32 v29, v123
	v_mov_b32_e32 v28, v123
	v_mov_b32_e32 v27, v123
	v_mov_b32_e32 v26, v123
	v_mov_b32_e32 v25, v123
	v_mov_b32_e32 v24, v123
	v_mov_b32_e32 v15, v123
	v_mov_b32_e32 v14, v123
	v_mov_b32_e32 v13, v123
	v_mov_b32_e32 v12, v123
	v_mov_b32_e32 v11, v123
	v_mov_b32_e32 v10, v123
	v_mov_b32_e32 v9, v123
	v_mov_b32_e32 v8, v123
	v_mov_b32_e32 v55, v123
	v_mov_b32_e32 v54, v123
	v_mov_b32_e32 v53, v123
	v_mov_b32_e32 v52, v123
	v_mov_b32_e32 v51, v123
	v_mov_b32_e32 v50, v123
	v_mov_b32_e32 v49, v123
	v_mov_b32_e32 v48, v123
	v_mov_b32_e32 v39, v123
	v_mov_b32_e32 v38, v123
	v_mov_b32_e32 v37, v123
	v_mov_b32_e32 v36, v123
	v_mov_b32_e32 v35, v123
	v_mov_b32_e32 v34, v123
	v_mov_b32_e32 v33, v123
	v_mov_b32_e32 v32, v123
	v_mov_b32_e32 v23, v123
	v_mov_b32_e32 v22, v123
	v_mov_b32_e32 v21, v123
	v_mov_b32_e32 v20, v123
	v_mov_b32_e32 v19, v123
	v_mov_b32_e32 v18, v123
	v_mov_b32_e32 v17, v123
	v_mov_b32_e32 v16, v123
	v_mov_b32_e32 v7, v123
	v_mov_b32_e32 v6, v123
	v_mov_b32_e32 v5, v123
	v_mov_b32_e32 v4, v123
	v_mov_b32_e32 v3, v123
	v_mov_b32_e32 v2, v123
	v_mov_b32_e32 v1, v123
	v_mov_b32_e32 v0, v123
	s_cbranch_vccnz .LBB0_664
	s_add_u32 s34, s36, 0x100
	v_mov_b32_e32 v0, 0
	s_addc_u32 s52, s37, 0
	s_mov_b32 s38, 0
	v_mov_b32_e32 v1, v0
	v_mov_b32_e32 v2, v0
	v_mov_b32_e32 v3, v0
	v_mov_b32_e32 v4, v0
	v_mov_b32_e32 v5, v0
	v_mov_b32_e32 v6, v0
	v_mov_b32_e32 v7, v0
	v_mov_b32_e32 v16, v0
	v_mov_b32_e32 v17, v0
	v_mov_b32_e32 v18, v0
	v_mov_b32_e32 v19, v0
	v_mov_b32_e32 v20, v0
	v_mov_b32_e32 v21, v0
	v_mov_b32_e32 v22, v0
	v_mov_b32_e32 v23, v0
	v_mov_b32_e32 v32, v0
	v_mov_b32_e32 v33, v0
	v_mov_b32_e32 v34, v0
	v_mov_b32_e32 v35, v0
	v_mov_b32_e32 v36, v0
	v_mov_b32_e32 v37, v0
	v_mov_b32_e32 v38, v0
	v_mov_b32_e32 v39, v0
	v_mov_b32_e32 v48, v0
	v_mov_b32_e32 v49, v0
	v_mov_b32_e32 v50, v0
	v_mov_b32_e32 v51, v0
	v_mov_b32_e32 v52, v0
	v_mov_b32_e32 v53, v0
	v_mov_b32_e32 v54, v0
	v_mov_b32_e32 v55, v0
	v_mov_b32_e32 v8, v0
	v_mov_b32_e32 v9, v0
	v_mov_b32_e32 v10, v0
	v_mov_b32_e32 v11, v0
	v_mov_b32_e32 v12, v0
	v_mov_b32_e32 v13, v0
	v_mov_b32_e32 v14, v0
	v_mov_b32_e32 v15, v0
	v_mov_b32_e32 v24, v0
	v_mov_b32_e32 v25, v0
	v_mov_b32_e32 v26, v0
	v_mov_b32_e32 v27, v0
	v_mov_b32_e32 v28, v0
	v_mov_b32_e32 v29, v0
	v_mov_b32_e32 v30, v0
	v_mov_b32_e32 v31, v0
	v_mov_b32_e32 v40, v0
	v_mov_b32_e32 v41, v0
	v_mov_b32_e32 v42, v0
	v_mov_b32_e32 v43, v0
	v_mov_b32_e32 v44, v0
	v_mov_b32_e32 v45, v0
	v_mov_b32_e32 v46, v0
	v_mov_b32_e32 v47, v0
	v_mov_b32_e32 v56, v0
	v_mov_b32_e32 v57, v0
	v_mov_b32_e32 v58, v0
	v_mov_b32_e32 v59, v0
	v_mov_b32_e32 v60, v0
	v_mov_b32_e32 v61, v0
	v_mov_b32_e32 v62, v0
	v_mov_b32_e32 v63, v0
	v_mov_b32_e32 v64, v0
	v_mov_b32_e32 v65, v0
	v_mov_b32_e32 v66, v0
	v_mov_b32_e32 v67, v0
	v_mov_b32_e32 v68, v0
	v_mov_b32_e32 v69, v0
	v_mov_b32_e32 v70, v0
	v_mov_b32_e32 v71, v0
	v_mov_b32_e32 v80, v0
	v_mov_b32_e32 v81, v0
	v_mov_b32_e32 v82, v0
	v_mov_b32_e32 v83, v0
	v_mov_b32_e32 v84, v0
	v_mov_b32_e32 v85, v0
	v_mov_b32_e32 v86, v0
	v_mov_b32_e32 v87, v0
	v_mov_b32_e32 v96, v0
	v_mov_b32_e32 v97, v0
	v_mov_b32_e32 v98, v0
	v_mov_b32_e32 v99, v0
	v_mov_b32_e32 v100, v0
	v_mov_b32_e32 v101, v0
	v_mov_b32_e32 v102, v0
	v_mov_b32_e32 v103, v0
	v_mov_b32_e32 v112, v0
	v_mov_b32_e32 v113, v0
	v_mov_b32_e32 v114, v0
	v_mov_b32_e32 v115, v0
	v_mov_b32_e32 v116, v0
	v_mov_b32_e32 v117, v0
	v_mov_b32_e32 v118, v0
	v_mov_b32_e32 v119, v0
	v_mov_b32_e32 v72, v0
	v_mov_b32_e32 v73, v0
	v_mov_b32_e32 v74, v0
	v_mov_b32_e32 v75, v0
	v_mov_b32_e32 v76, v0
	v_mov_b32_e32 v77, v0
	v_mov_b32_e32 v78, v0
	v_mov_b32_e32 v79, v0
	v_mov_b32_e32 v88, v0
	v_mov_b32_e32 v89, v0
	v_mov_b32_e32 v90, v0
	v_mov_b32_e32 v91, v0
	v_mov_b32_e32 v92, v0
	v_mov_b32_e32 v93, v0
	v_mov_b32_e32 v94, v0
	v_mov_b32_e32 v95, v0
	v_mov_b32_e32 v104, v0
	v_mov_b32_e32 v105, v0
	v_mov_b32_e32 v106, v0
	v_mov_b32_e32 v107, v0
	v_mov_b32_e32 v108, v0
	v_mov_b32_e32 v109, v0
	v_mov_b32_e32 v110, v0
	v_mov_b32_e32 v111, v0
	v_mov_b32_e32 v124, v0
	v_mov_b32_e32 v125, v0
	v_mov_b32_e32 v126, v0
	v_mov_b32_e32 v127, v0
	v_mov_b32_e32 v120, v0
	v_mov_b32_e32 v121, v0
	v_mov_b32_e32 v122, v0
	v_mov_b32_e32 v123, v0
	v_readfirstlane_b32 s100, v238
	s_cmp_lt_u32 s100, 0x100
	s_cbranch_scc1 .Lgp_663
	s_setprio 1
; #define PG8_STAGE(bufoff, gbase, voff) do { _Pragma("unroll") for (int _i = 0; _i < 2; ++_i) \
;         __builtin_amdgcn_global_load_lds((const unsigned*)((const char*)(gbase) + (voff)[_i]), (LAS unsigned*)(lds + (bufoff) + ldsw + _i * 8192), 16, 0, 0); } while (0)
; #define PG8_LDA(dst, b, h) do { _Pragma("unroll") for (int m = 0; m < 4; ++m) _Pragma("unroll") for (int k = 0; k < 2; ++k) dst[m][k] = *(const LAS bf16x8*)(lds + PG8_SA(b, h) + aoff + m * 2048 + k * 1024); } while (0)
; #define PG8_LDB(dst, b, h) do { _Pragma("unroll") for (int n = 0; n < 2; ++n) _Pragma("unroll") for (int k = 0; k < 2; ++k) dst[n][k] = *(const LAS bf16x8*)(lds + PG8_SB(b, h) + boff + n * 2048 + k * 1024); } while (0)
; #define PG8_MMA(ai, bj, At, Bt) do { __builtin_amdgcn_s_setprio(1); _Pragma("unroll") for (int m = 0; m < 4; ++m) _Pragma("unroll") for (int n = 0; n < 2; ++n) _Pragma("unroll") for (int k = 0; k < 2; ++k) \
;         acc[ai][bj][m][n] = __builtin_amdgcn_mfma_f32_16x16x32_bf16(Bt[n][k], At[m][k], acc[ai][bj][m][n], 0, 0, 0); __builtin_amdgcn_s_setprio(0); } while (0)
; #define PG8_BAR __builtin_amdgcn_s_barrier()
; template <class Epi, bool ALIGN_EPI = PG8_ALIGN>
; __device__ __forceinline__ void gemm_phase(LAS unsigned char* lds, const Gemm g, const StaticOrder& S, const Epi& E) {
;     ...
;         const bool has_next = S.next(ui + 1, nxt);
;         const char* nA = has_next ? (const char*)g.A + (size_t)nxt.pm * tstepA : cA; const char* nB = has_next ? (const char*)g.Bt + (size_t)nxt.pn * tstepB : cB;
;         for (int t = 0; t < nt; t += 2) {
;             const bool last = (t == nt - 2);
;             const char* a1 = cA + (size_t)(t + 1) * kstep;
;             const char* a2 = last ? nA : cA + (size_t)(t + 2) * kstep; const char* b2 = last ? nB : cB + (size_t)(t + 2) * kstep;
;             const char* a3 = a2 + kstep; const char* b3 = b2 + kstep;
;             PG8_LDB(B0, 0, 0); PG8_LDB(B1, 0, 1); PG8_SCHED; PG8_LDA(At, 0, 0); PG8_STAGE(PG8_SA(1, 1), a1 + hstepA, voffA);
;             PG8_WAIT_V(8); PG8_WAIT_L(0); PG8_BAR; PG8_MMA(0, 0, At, B0); PG8_MMA(0, 1, At, B1); PG8_BAR; PG8_SCHED;
;             PG8_LDA(At, 0, 1); PG8_STAGE(PG8_SB(0, 0), b2, voffB); PG8_STAGE(PG8_SB(0, 1), b2 + hstepB, voffB); PG8_STAGE(PG8_SA(0, 0), a2, voffA);
;             PG8_WAIT_V(8); PG8_WAIT_L(0); PG8_BAR; PG8_MMA(1, 0, At, B0); PG8_MMA(1, 1, At, B1); PG8_BAR; PG8_SCHED;
.Lgp_663:
.LBB0_663:
	s_add_i32 s53, s38, 2
	s_add_u32 s36, s24, 0x100
	s_addc_u32 s37, s25, 0
	s_add_i32 s20, 16, 0x10000
	s_cmp_eq_u32 s48, s38
	s_cselect_b32 s39, s3, s37
	s_cselect_b32 s38, s2, s36
	v_add_u32_e32 v138, s20, v143
	s_cselect_b32 s55, s17, s52
	s_cselect_b32 s54, s16, s34
	s_add_i32 s21, 16, 0x14000
	ds_read_b128 v[152:155], v138
	ds_read_b128 v[156:159], v138 offset:1024
	ds_read_b128 v[160:163], v138 offset:2048
	ds_read_b128 v[164:167], v138 offset:3072
	v_add_u32_e32 v138, s21, v143
	ds_read_b128 v[168:171], v138
	ds_read_b128 v[172:175], v138 offset:1024
	ds_read_b128 v[184:187], v138 offset:2048
	ds_read_b128 v[188:191], v138 offset:3072
	v_lshl_add_u64 v[140:141], s[24:25], 0, v[134:135]
	s_add_i32 m0, s31, 0xc000
	ds_read_b128 v[192:195], v151
	ds_read_b128 v[196:199], v151 offset:1024
	ds_read_b128 v[200:203], v151 offset:2048
	ds_read_b128 v[204:207], v151 offset:3072
	ds_read_b128 v[208:211], v151 offset:4096
	ds_read_b128 v[212:215], v151 offset:5120
	ds_read_b128 v[216:219], v151 offset:6144
	ds_read_b128 v[220:223], v151 offset:7168
	global_load_lds_dwordx4 v[140:141], off
	v_lshl_add_u64 v[140:141], s[24:25], 0, v[136:137]
	s_add_i32 m0, s31, 0xe000
	s_nop 0
	global_load_lds_dwordx4 v[140:141], off
	s_waitcnt vmcnt(8)
	s_waitcnt lgkmcnt(0)
	s_barrier
	s_waitcnt lgkmcnt(0)
	v_mfma_f32_16x16x32_bf16 v[120:123], v[152:155], v[192:195], v[120:123]
	v_mfma_f32_16x16x32_bf16 v[124:127], v[160:163], v[192:195], v[124:127]
	v_mfma_f32_16x16x32_bf16 v[108:111], v[152:155], v[200:203], v[108:111]
	v_mfma_f32_16x16x32_bf16 v[104:107], v[160:163], v[200:203], v[104:107]
	v_mfma_f32_16x16x32_bf16 v[92:95], v[152:155], v[208:211], v[92:95]
	v_mfma_f32_16x16x32_bf16 v[88:91], v[160:163], v[208:211], v[88:91]
	v_mfma_f32_16x16x32_bf16 v[76:79], v[152:155], v[216:219], v[76:79]
	v_mfma_f32_16x16x32_bf16 v[72:75], v[160:163], v[216:219], v[72:75]
	v_mfma_f32_16x16x32_bf16 v[120:123], v[156:159], v[196:199], v[120:123]
	v_mfma_f32_16x16x32_bf16 v[124:127], v[164:167], v[196:199], v[124:127]
	v_mfma_f32_16x16x32_bf16 v[108:111], v[156:159], v[204:207], v[108:111]
	v_mfma_f32_16x16x32_bf16 v[104:107], v[164:167], v[204:207], v[104:107]
	v_mfma_f32_16x16x32_bf16 v[92:95], v[156:159], v[212:215], v[92:95]
	v_mfma_f32_16x16x32_bf16 v[88:91], v[164:167], v[212:215], v[88:91]
	v_mfma_f32_16x16x32_bf16 v[76:79], v[156:159], v[220:223], v[76:79]
	v_mfma_f32_16x16x32_bf16 v[72:75], v[164:167], v[220:223], v[72:75]
	v_mfma_f32_16x16x32_bf16 v[116:119], v[168:171], v[192:195], v[116:119]
	v_mfma_f32_16x16x32_bf16 v[112:115], v[184:187], v[192:195], v[112:115]
	v_mfma_f32_16x16x32_bf16 v[100:103], v[168:171], v[200:203], v[100:103]
	v_mfma_f32_16x16x32_bf16 v[96:99], v[184:187], v[200:203], v[96:99]
	v_mfma_f32_16x16x32_bf16 v[84:87], v[168:171], v[208:211], v[84:87]
	v_mfma_f32_16x16x32_bf16 v[80:83], v[184:187], v[208:211], v[80:83]
	v_mfma_f32_16x16x32_bf16 v[68:71], v[168:171], v[216:219], v[68:71]
	v_mfma_f32_16x16x32_bf16 v[64:67], v[184:187], v[216:219], v[64:67]
	v_mfma_f32_16x16x32_bf16 v[116:119], v[172:175], v[196:199], v[116:119]
	v_mfma_f32_16x16x32_bf16 v[112:115], v[188:191], v[196:199], v[112:115]
	v_mfma_f32_16x16x32_bf16 v[100:103], v[172:175], v[204:207], v[100:103]
	v_mfma_f32_16x16x32_bf16 v[96:99], v[188:191], v[204:207], v[96:99]
	v_mfma_f32_16x16x32_bf16 v[84:87], v[172:175], v[212:215], v[84:87]
	v_mfma_f32_16x16x32_bf16 v[80:83], v[188:191], v[212:215], v[80:83]
	v_mfma_f32_16x16x32_bf16 v[68:71], v[172:175], v[220:223], v[68:71]
	v_mfma_f32_16x16x32_bf16 v[64:67], v[188:191], v[220:223], v[64:67]
	s_barrier
	s_add_i32 s20, s20, s30
	v_lshl_add_u64 v[140:141], s[54:55], 0, v[176:177]
	s_mov_b32 m0, s20
	ds_read_b128 v[192:195], v151 offset:16384
	ds_read_b128 v[196:199], v151 offset:17408
	ds_read_b128 v[200:203], v151 offset:18432
	ds_read_b128 v[204:207], v151 offset:19456
	ds_read_b128 v[208:211], v151 offset:20480
	ds_read_b128 v[212:215], v151 offset:21504
	ds_read_b128 v[216:219], v151 offset:22528
	ds_read_b128 v[220:223], v151 offset:23552
	global_load_lds_dwordx4 v[140:141], off
	s_add_i32 m0, s20, 0x2000
	s_add_u32 s24, s54, s6
	v_lshl_add_u64 v[144:145], s[54:55], 0, v[128:129]
	s_addc_u32 s25, s55, s7
	s_add_i32 s20, s21, s30
	global_load_lds_dwordx4 v[144:145], off
	v_lshl_add_u64 v[148:149], s[24:25], 0, v[176:177]
	s_mov_b32 m0, s20
	v_lshl_add_u64 v[224:225], s[24:25], 0, v[128:129]
	global_load_lds_dwordx4 v[148:149], off
	s_add_i32 m0, s20, 0x2000
	v_lshl_add_u64 v[226:227], s[38:39], 0, v[132:133]
	global_load_lds_dwordx4 v[224:225], off
	s_mov_b32 m0, s31
	v_lshl_add_u64 v[228:229], s[38:39], 0, v[130:131]
	global_load_lds_dwordx4 v[226:227], off
	s_mov_b32 m0, s40
	s_nop 0
	global_load_lds_dwordx4 v[228:229], off
	s_waitcnt vmcnt(8)
	s_waitcnt lgkmcnt(0)
	s_barrier
; #define PG8_STAGE(bufoff, gbase, voff) do { _Pragma("unroll") for (int _i = 0; _i < 2; ++_i) \
;         __builtin_amdgcn_global_load_lds((const unsigned*)((const char*)(gbase) + (voff)[_i]), (LAS unsigned*)(lds + (bufoff) + ldsw + _i * 8192), 16, 0, 0); } while (0)
; #define PG8_LDA(dst, b, h) do { _Pragma("unroll") for (int m = 0; m < 4; ++m) _Pragma("unroll") for (int k = 0; k < 2; ++k) dst[m][k] = *(const LAS bf16x8*)(lds + PG8_SA(b, h) + aoff + m * 2048 + k * 1024); } while (0)
; #define PG8_LDB(dst, b, h) do { _Pragma("unroll") for (int n = 0; n < 2; ++n) _Pragma("unroll") for (int k = 0; k < 2; ++k) dst[n][k] = *(const LAS bf16x8*)(lds + PG8_SB(b, h) + boff + n * 2048 + k * 1024); } while (0)
; #define PG8_MMA(ai, bj, At, Bt) do { __builtin_amdgcn_s_setprio(1); _Pragma("unroll") for (int m = 0; m < 4; ++m) _Pragma("unroll") for (int n = 0; n < 2; ++n) _Pragma("unroll") for (int k = 0; k < 2; ++k) \
;         acc[ai][bj][m][n] = __builtin_amdgcn_mfma_f32_16x16x32_bf16(Bt[n][k], At[m][k], acc[ai][bj][m][n], 0, 0, 0); __builtin_amdgcn_s_setprio(0); } while (0)
; #define PG8_WAIT_V(n) asm volatile("s_waitcnt vmcnt(" #n ")" ::: "memory")
; #define PG8_WAIT_L(n) asm volatile("s_waitcnt lgkmcnt(" #n ")" ::: "memory")
; #define PG8_BAR __builtin_amdgcn_s_barrier()
; #define PG8_SCHED __builtin_amdgcn_sched_barrier(0)
; template <class Epi, bool ALIGN_EPI = PG8_ALIGN>
; __device__ __forceinline__ void gemm_phase(LAS unsigned char* lds, const Gemm g, const StaticOrder& S, const Epi& E) {
;     ...
;             PG8_WAIT_V(8); PG8_WAIT_L(0); PG8_BAR; PG8_MMA(1, 0, At, B0); PG8_MMA(1, 1, At, B1); PG8_BAR; PG8_SCHED;
;             PG8_LDB(B0, 1, 0); PG8_LDB(B1, 1, 1); PG8_SCHED; PG8_LDA(At, 1, 0); PG8_STAGE(PG8_SA(0, 1), a2 + hstepA, voffA);
;             PG8_WAIT_V(8); PG8_WAIT_L(0); PG8_BAR; PG8_MMA(0, 0, At, B0); PG8_MMA(0, 1, At, B1); PG8_BAR; PG8_SCHED;
;             PG8_LDA(At, 1, 1); PG8_STAGE(PG8_SB(1, 0), b3, voffB); PG8_STAGE(PG8_SB(1, 1), b3 + hstepB, voffB); PG8_STAGE(PG8_SA(1, 0), a3, voffA);
;             PG8_WAIT_V(8); PG8_WAIT_L(0); PG8_BAR; PG8_MMA(1, 0, At, B0); PG8_MMA(1, 1, At, B1); PG8_BAR; PG8_SCHED;
	s_waitcnt lgkmcnt(0)
	v_mfma_f32_16x16x32_bf16 v[60:63], v[152:155], v[192:195], v[60:63]
	v_mfma_f32_16x16x32_bf16 v[56:59], v[160:163], v[192:195], v[56:59]
	v_mfma_f32_16x16x32_bf16 v[44:47], v[152:155], v[200:203], v[44:47]
	v_mfma_f32_16x16x32_bf16 v[40:43], v[160:163], v[200:203], v[40:43]
	v_mfma_f32_16x16x32_bf16 v[28:31], v[152:155], v[208:211], v[28:31]
	v_mfma_f32_16x16x32_bf16 v[24:27], v[160:163], v[208:211], v[24:27]
	v_mfma_f32_16x16x32_bf16 v[12:15], v[152:155], v[216:219], v[12:15]
	v_mfma_f32_16x16x32_bf16 v[8:11], v[160:163], v[216:219], v[8:11]
	v_mfma_f32_16x16x32_bf16 v[60:63], v[156:159], v[196:199], v[60:63]
	v_mfma_f32_16x16x32_bf16 v[56:59], v[164:167], v[196:199], v[56:59]
	v_mfma_f32_16x16x32_bf16 v[44:47], v[156:159], v[204:207], v[44:47]
	v_mfma_f32_16x16x32_bf16 v[40:43], v[164:167], v[204:207], v[40:43]
	v_mfma_f32_16x16x32_bf16 v[28:31], v[156:159], v[212:215], v[28:31]
	v_mfma_f32_16x16x32_bf16 v[24:27], v[164:167], v[212:215], v[24:27]
	v_mfma_f32_16x16x32_bf16 v[12:15], v[156:159], v[220:223], v[12:15]
	v_mfma_f32_16x16x32_bf16 v[8:11], v[164:167], v[220:223], v[8:11]
	v_mfma_f32_16x16x32_bf16 v[52:55], v[168:171], v[192:195], v[52:55]
	v_mfma_f32_16x16x32_bf16 v[48:51], v[184:187], v[192:195], v[48:51]
	v_mfma_f32_16x16x32_bf16 v[36:39], v[168:171], v[200:203], v[36:39]
	v_mfma_f32_16x16x32_bf16 v[32:35], v[184:187], v[200:203], v[32:35]
	v_mfma_f32_16x16x32_bf16 v[20:23], v[168:171], v[208:211], v[20:23]
	v_mfma_f32_16x16x32_bf16 v[16:19], v[184:187], v[208:211], v[16:19]
	v_mfma_f32_16x16x32_bf16 v[4:7], v[168:171], v[216:219], v[4:7]
	v_mfma_f32_16x16x32_bf16 v[0:3], v[184:187], v[216:219], v[0:3]
	v_mfma_f32_16x16x32_bf16 v[52:55], v[172:175], v[196:199], v[52:55]
	v_mfma_f32_16x16x32_bf16 v[48:51], v[188:191], v[196:199], v[48:51]
	v_mfma_f32_16x16x32_bf16 v[36:39], v[172:175], v[204:207], v[36:39]
	v_mfma_f32_16x16x32_bf16 v[32:35], v[188:191], v[204:207], v[32:35]
	v_mfma_f32_16x16x32_bf16 v[20:23], v[172:175], v[212:215], v[20:23]
	v_mfma_f32_16x16x32_bf16 v[16:19], v[188:191], v[212:215], v[16:19]
	v_mfma_f32_16x16x32_bf16 v[4:7], v[172:175], v[220:223], v[4:7]
	v_mfma_f32_16x16x32_bf16 v[0:3], v[188:191], v[220:223], v[0:3]
	s_barrier
	s_add_i32 s20, 16, 0x18000
	v_add_u32_e32 v138, s20, v143
	s_add_i32 s21, 16, 0x1c000
	ds_read_b128 v[152:155], v138
	ds_read_b128 v[156:159], v138 offset:1024
	ds_read_b128 v[160:163], v138 offset:2048
	ds_read_b128 v[164:167], v138 offset:3072
	v_add_u32_e32 v138, s21, v143
	ds_read_b128 v[168:171], v138
	ds_read_b128 v[172:175], v138 offset:1024
	ds_read_b128 v[184:187], v138 offset:2048
	ds_read_b128 v[188:191], v138 offset:3072
	s_add_u32 s24, s38, 0x110000
	s_addc_u32 s25, s39, 0
	s_mov_b32 m0, s41
	v_lshl_add_u64 v[230:231], s[24:25], 0, v[132:133]
	ds_read_b128 v[192:195], v151 offset:32768
	ds_read_b128 v[196:199], v151 offset:33792
	ds_read_b128 v[200:203], v151 offset:34816
	ds_read_b128 v[204:207], v151 offset:35840
	ds_read_b128 v[208:211], v151 offset:36864
	ds_read_b128 v[212:215], v151 offset:37888
	ds_read_b128 v[216:219], v151 offset:38912
	ds_read_b128 v[220:223], v151 offset:39936
	global_load_lds_dwordx4 v[230:231], off
	v_lshl_add_u64 v[230:231], s[24:25], 0, v[130:131]
	s_mov_b32 m0, s44
	s_nop 0
	global_load_lds_dwordx4 v[230:231], off
	s_waitcnt vmcnt(8)
	s_waitcnt lgkmcnt(0)
	s_barrier
	s_waitcnt lgkmcnt(0)
	v_mfma_f32_16x16x32_bf16 v[120:123], v[152:155], v[192:195], v[120:123]
	v_mfma_f32_16x16x32_bf16 v[124:127], v[160:163], v[192:195], v[124:127]
	v_mfma_f32_16x16x32_bf16 v[108:111], v[152:155], v[200:203], v[108:111]
	v_mfma_f32_16x16x32_bf16 v[104:107], v[160:163], v[200:203], v[104:107]
	v_mfma_f32_16x16x32_bf16 v[92:95], v[152:155], v[208:211], v[92:95]
	v_mfma_f32_16x16x32_bf16 v[88:91], v[160:163], v[208:211], v[88:91]
	v_mfma_f32_16x16x32_bf16 v[76:79], v[152:155], v[216:219], v[76:79]
	v_mfma_f32_16x16x32_bf16 v[72:75], v[160:163], v[216:219], v[72:75]
	v_mfma_f32_16x16x32_bf16 v[120:123], v[156:159], v[196:199], v[120:123]
	v_mfma_f32_16x16x32_bf16 v[124:127], v[164:167], v[196:199], v[124:127]
	v_mfma_f32_16x16x32_bf16 v[108:111], v[156:159], v[204:207], v[108:111]
	v_mfma_f32_16x16x32_bf16 v[104:107], v[164:167], v[204:207], v[104:107]
	v_mfma_f32_16x16x32_bf16 v[92:95], v[156:159], v[212:215], v[92:95]
	v_mfma_f32_16x16x32_bf16 v[88:91], v[164:167], v[212:215], v[88:91]
	v_mfma_f32_16x16x32_bf16 v[76:79], v[156:159], v[220:223], v[76:79]
	v_mfma_f32_16x16x32_bf16 v[72:75], v[164:167], v[220:223], v[72:75]
	v_mfma_f32_16x16x32_bf16 v[116:119], v[168:171], v[192:195], v[116:119]
	v_mfma_f32_16x16x32_bf16 v[112:115], v[184:187], v[192:195], v[112:115]
	v_mfma_f32_16x16x32_bf16 v[100:103], v[168:171], v[200:203], v[100:103]
	v_mfma_f32_16x16x32_bf16 v[96:99], v[184:187], v[200:203], v[96:99]
	v_mfma_f32_16x16x32_bf16 v[84:87], v[168:171], v[208:211], v[84:87]
	v_mfma_f32_16x16x32_bf16 v[80:83], v[184:187], v[208:211], v[80:83]
	v_mfma_f32_16x16x32_bf16 v[68:71], v[168:171], v[216:219], v[68:71]
	v_mfma_f32_16x16x32_bf16 v[64:67], v[184:187], v[216:219], v[64:67]
	v_mfma_f32_16x16x32_bf16 v[116:119], v[172:175], v[196:199], v[116:119]
	v_mfma_f32_16x16x32_bf16 v[112:115], v[188:191], v[196:199], v[112:115]
	v_mfma_f32_16x16x32_bf16 v[100:103], v[172:175], v[204:207], v[100:103]
	v_mfma_f32_16x16x32_bf16 v[96:99], v[188:191], v[204:207], v[96:99]
	v_mfma_f32_16x16x32_bf16 v[84:87], v[172:175], v[212:215], v[84:87]
	v_mfma_f32_16x16x32_bf16 v[80:83], v[188:191], v[212:215], v[80:83]
	v_mfma_f32_16x16x32_bf16 v[68:71], v[172:175], v[220:223], v[68:71]
	v_mfma_f32_16x16x32_bf16 v[64:67], v[188:191], v[220:223], v[64:67]
	s_barrier
; #define PG8_STAGE(bufoff, gbase, voff) do { _Pragma("unroll") for (int _i = 0; _i < 2; ++_i) \
;         __builtin_amdgcn_global_load_lds((const unsigned*)((const char*)(gbase) + (voff)[_i]), (LAS unsigned*)(lds + (bufoff) + ldsw + _i * 8192), 16, 0, 0); } while (0)
; #define PG8_LDA(dst, b, h) do { _Pragma("unroll") for (int m = 0; m < 4; ++m) _Pragma("unroll") for (int k = 0; k < 2; ++k) dst[m][k] = *(const LAS bf16x8*)(lds + PG8_SA(b, h) + aoff + m * 2048 + k * 1024); } while (0)
; #define PG8_LDB(dst, b, h) do { _Pragma("unroll") for (int n = 0; n < 2; ++n) _Pragma("unroll") for (int k = 0; k < 2; ++k) dst[n][k] = *(const LAS bf16x8*)(lds + PG8_SB(b, h) + boff + n * 2048 + k * 1024); } while (0)
; #define PG8_MMA(ai, bj, At, Bt) do { __builtin_amdgcn_s_setprio(1); _Pragma("unroll") for (int m = 0; m < 4; ++m) _Pragma("unroll") for (int n = 0; n < 2; ++n) _Pragma("unroll") for (int k = 0; k < 2; ++k) \
;         acc[ai][bj][m][n] = __builtin_amdgcn_mfma_f32_16x16x32_bf16(Bt[n][k], At[m][k], acc[ai][bj][m][n], 0, 0, 0); __builtin_amdgcn_s_setprio(0); } while (0)
; #define PG8_WAIT_V(n) asm volatile("s_waitcnt vmcnt(" #n ")" ::: "memory")
; #define PG8_WAIT_L(n) asm volatile("s_waitcnt lgkmcnt(" #n ")" ::: "memory")
; #define PG8_BAR __builtin_amdgcn_s_barrier()
; #define PG8_SCHED __builtin_amdgcn_sched_barrier(0)
; template <class Epi, bool ALIGN_EPI = PG8_ALIGN>
; __device__ __forceinline__ void gemm_phase(LAS unsigned char* lds, const Gemm g, const StaticOrder& S, const Epi& E) {
;     ...
;             PG8_LDB(B0, 1, 0); PG8_LDB(B1, 1, 1); PG8_SCHED; PG8_LDA(At, 1, 0); PG8_STAGE(PG8_SA(0, 1), a2 + hstepA, voffA);
;             PG8_WAIT_V(8); PG8_WAIT_L(0); PG8_BAR; PG8_MMA(0, 0, At, B0); PG8_MMA(0, 1, At, B1); PG8_BAR; PG8_SCHED;
;             PG8_LDA(At, 1, 1); PG8_STAGE(PG8_SB(1, 0), b3, voffB); PG8_STAGE(PG8_SB(1, 1), b3 + hstepB, voffB); PG8_STAGE(PG8_SA(1, 0), a3, voffA);
;             PG8_WAIT_V(8); PG8_WAIT_L(0); PG8_BAR; PG8_MMA(1, 0, At, B0); PG8_MMA(1, 1, At, B1); PG8_BAR; PG8_SCHED;
;         }
	s_add_i32 s20, s20, s30
	v_lshl_add_u64 v[140:141], v[140:141], 0, s[0:1]
	s_mov_b32 m0, s20
	ds_read_b128 v[192:195], v151 offset:49152
	ds_read_b128 v[196:199], v151 offset:50176
	ds_read_b128 v[200:203], v151 offset:51200
	ds_read_b128 v[204:207], v151 offset:52224
	ds_read_b128 v[208:211], v151 offset:53248
	ds_read_b128 v[212:215], v151 offset:54272
	ds_read_b128 v[216:219], v151 offset:55296
	ds_read_b128 v[220:223], v151 offset:56320
	global_load_lds_dwordx4 v[140:141], off
	v_lshl_add_u64 v[140:141], v[144:145], 0, s[0:1]
	s_add_i32 m0, s20, 0x2000
	s_add_i32 s20, s21, s30
	global_load_lds_dwordx4 v[140:141], off
	v_lshl_add_u64 v[140:141], v[148:149], 0, s[0:1]
	s_mov_b32 m0, s20
	s_nop 0
	global_load_lds_dwordx4 v[140:141], off
	v_lshl_add_u64 v[140:141], v[224:225], 0, s[0:1]
	s_add_i32 m0, s20, 0x2000
	s_nop 0
	global_load_lds_dwordx4 v[140:141], off
	v_lshl_add_u64 v[140:141], v[226:227], 0, s[0:1]
	s_mov_b32 m0, s45
	s_nop 0
	global_load_lds_dwordx4 v[140:141], off
	v_lshl_add_u64 v[140:141], v[228:229], 0, s[0:1]
	s_mov_b32 m0, s46
	s_nop 0
	global_load_lds_dwordx4 v[140:141], off
	s_waitcnt vmcnt(8)
	s_waitcnt lgkmcnt(0)
	s_barrier
	s_waitcnt lgkmcnt(0)
	v_mfma_f32_16x16x32_bf16 v[60:63], v[152:155], v[192:195], v[60:63]
	v_mfma_f32_16x16x32_bf16 v[56:59], v[160:163], v[192:195], v[56:59]
	v_mfma_f32_16x16x32_bf16 v[44:47], v[152:155], v[200:203], v[44:47]
	v_mfma_f32_16x16x32_bf16 v[40:43], v[160:163], v[200:203], v[40:43]
	v_mfma_f32_16x16x32_bf16 v[28:31], v[152:155], v[208:211], v[28:31]
	v_mfma_f32_16x16x32_bf16 v[24:27], v[160:163], v[208:211], v[24:27]
	v_mfma_f32_16x16x32_bf16 v[12:15], v[152:155], v[216:219], v[12:15]
	v_mfma_f32_16x16x32_bf16 v[8:11], v[160:163], v[216:219], v[8:11]
	v_mfma_f32_16x16x32_bf16 v[60:63], v[156:159], v[196:199], v[60:63]
	v_mfma_f32_16x16x32_bf16 v[56:59], v[164:167], v[196:199], v[56:59]
	v_mfma_f32_16x16x32_bf16 v[44:47], v[156:159], v[204:207], v[44:47]
	v_mfma_f32_16x16x32_bf16 v[40:43], v[164:167], v[204:207], v[40:43]
	v_mfma_f32_16x16x32_bf16 v[28:31], v[156:159], v[212:215], v[28:31]
	v_mfma_f32_16x16x32_bf16 v[24:27], v[164:167], v[212:215], v[24:27]
	v_mfma_f32_16x16x32_bf16 v[12:15], v[156:159], v[220:223], v[12:15]
	v_mfma_f32_16x16x32_bf16 v[8:11], v[164:167], v[220:223], v[8:11]
	v_mfma_f32_16x16x32_bf16 v[52:55], v[168:171], v[192:195], v[52:55]
	v_mfma_f32_16x16x32_bf16 v[48:51], v[184:187], v[192:195], v[48:51]
	v_mfma_f32_16x16x32_bf16 v[36:39], v[168:171], v[200:203], v[36:39]
	v_mfma_f32_16x16x32_bf16 v[32:35], v[184:187], v[200:203], v[32:35]
	v_mfma_f32_16x16x32_bf16 v[20:23], v[168:171], v[208:211], v[20:23]
	v_mfma_f32_16x16x32_bf16 v[16:19], v[184:187], v[208:211], v[16:19]
	v_mfma_f32_16x16x32_bf16 v[4:7], v[168:171], v[216:219], v[4:7]
	v_mfma_f32_16x16x32_bf16 v[0:3], v[184:187], v[216:219], v[0:3]
	v_mfma_f32_16x16x32_bf16 v[52:55], v[172:175], v[196:199], v[52:55]
	v_mfma_f32_16x16x32_bf16 v[48:51], v[188:191], v[196:199], v[48:51]
	v_mfma_f32_16x16x32_bf16 v[36:39], v[172:175], v[204:207], v[36:39]
	v_mfma_f32_16x16x32_bf16 v[32:35], v[188:191], v[204:207], v[32:35]
	v_mfma_f32_16x16x32_bf16 v[20:23], v[172:175], v[212:215], v[20:23]
	v_mfma_f32_16x16x32_bf16 v[16:19], v[188:191], v[212:215], v[16:19]
	v_mfma_f32_16x16x32_bf16 v[4:7], v[172:175], v[220:223], v[4:7]
	v_mfma_f32_16x16x32_bf16 v[0:3], v[188:191], v[220:223], v[0:3]
	s_barrier
	s_add_u32 s34, s34, 0x100
	s_addc_u32 s52, s52, 0
	s_cmp_ge_i32 s53, s47
	s_mov_b64 s[24:25], s[36:37]
	s_mov_b32 s38, s53
	s_cbranch_scc0 .LBB0_663
	s_setprio 0

; #define PG8_STAGE(bufoff, gbase, voff) do { _Pragma("unroll") for (int _i = 0; _i < 2; ++_i) \
;         __builtin_amdgcn_global_load_lds((const unsigned*)((const char*)(gbase) + (voff)[_i]), (LAS unsigned*)(lds + (bufoff) + ldsw + _i * 8192), 16, 0, 0); } while (0)
; #define PG8_WAIT_V(n) asm volatile("s_waitcnt vmcnt(" #n ")" ::: "memory")
; #define PG8_BAR __builtin_amdgcn_s_barrier()
; template <class Epi, bool ALIGN_EPI = PG8_ALIGN>
; __device__ __forceinline__ void gemm_phase(LAS unsigned char* lds, const Gemm g, const StaticOrder& S, const Epi& E) {
;     ...
;     f32x4 acc[2][2][4][2];
; #pragma unroll
;     for (int a = 0; a < 2; ++a)
; #pragma unroll
;         for (int b = 0; b < 2; ++b)
; #pragma unroll
;             for (int m = 0; m < 4; ++m)
; #pragma unroll
;                 for (int n = 0; n < 2; ++n) acc[a][b][m][n] = (f32x4){0.f, 0.f, 0.f, 0.f};
;     bf16x8 At[4][2], B0[2][2], B1[2][2];
;     const char* cA = (const char*)g.A + (size_t)cur.pm * tstepA; const char* cB = (const char*)g.Bt + (size_t)cur.pn * tstepB;
;     PG8_STAGE(PG8_SB(0, 0), cB, voffB); PG8_STAGE(PG8_SB(0, 1), cB + hstepB, voffB); PG8_STAGE(PG8_SA(0, 0), cA, voffA); PG8_STAGE(PG8_SA(0, 1), cA + hstepA, voffA);
;     if (wr == 1) PG8_BAR;
;     PG8_WAIT_V(2); PG8_BAR;
;     PG8_STAGE(PG8_SB(1, 0), cB + kstep, voffB); PG8_STAGE(PG8_SA(1, 0), cA + kstep, voffA); PG8_STAGE(PG8_SB(1, 1), cB + hstepB + kstep, voffB);
;     PG8_WAIT_V(6); PG8_BAR;
;     for (;;) {
;         const bool has_next = S.next(ui + 1, nxt);
;         const char* nA = has_next ? (const char*)g.A + (size_t)nxt.pm * tstepA : cA; const char* nB = has_next ? (const char*)g.Bt + (size_t)nxt.pn * tstepB : cB;
.LBB0_899:
	s_ashr_i32 s25, s24, 31
	s_lshl_b64 s[20:21], s[24:25], 20
	s_add_u32 s38, s64, s20
	v_mov_b32_e32 v123, 0
	s_addc_u32 s39, s65, s21
	s_andn2_b64 vcc, exec, s[14:15]
	v_mov_b32_e32 v122, v123
	v_mov_b32_e32 v121, v123
	v_mov_b32_e32 v120, v123
	v_mov_b32_e32 v127, v123
	v_mov_b32_e32 v126, v123
	v_mov_b32_e32 v125, v123
	v_mov_b32_e32 v124, v123
	v_mov_b32_e32 v111, v123
	v_mov_b32_e32 v110, v123
	v_mov_b32_e32 v109, v123
	v_mov_b32_e32 v108, v123
	v_mov_b32_e32 v107, v123
	v_mov_b32_e32 v106, v123
	v_mov_b32_e32 v105, v123
	v_mov_b32_e32 v104, v123
	v_mov_b32_e32 v95, v123
	v_mov_b32_e32 v94, v123
	v_mov_b32_e32 v93, v123
	v_mov_b32_e32 v92, v123
	v_mov_b32_e32 v91, v123
	v_mov_b32_e32 v90, v123
	v_mov_b32_e32 v89, v123
	v_mov_b32_e32 v88, v123
	v_mov_b32_e32 v79, v123
	v_mov_b32_e32 v78, v123
	v_mov_b32_e32 v77, v123
	v_mov_b32_e32 v76, v123
	v_mov_b32_e32 v75, v123
	v_mov_b32_e32 v74, v123
	v_mov_b32_e32 v73, v123
	v_mov_b32_e32 v72, v123
	v_mov_b32_e32 v119, v123
	v_mov_b32_e32 v118, v123
	v_mov_b32_e32 v117, v123
	v_mov_b32_e32 v116, v123
	v_mov_b32_e32 v115, v123
	v_mov_b32_e32 v114, v123
	v_mov_b32_e32 v113, v123
	v_mov_b32_e32 v112, v123
	v_mov_b32_e32 v103, v123
	v_mov_b32_e32 v102, v123
	v_mov_b32_e32 v101, v123
	v_mov_b32_e32 v100, v123
	v_mov_b32_e32 v99, v123
	v_mov_b32_e32 v98, v123
	v_mov_b32_e32 v97, v123
	v_mov_b32_e32 v96, v123
	v_mov_b32_e32 v87, v123
	v_mov_b32_e32 v86, v123
	v_mov_b32_e32 v85, v123
	v_mov_b32_e32 v84, v123
	v_mov_b32_e32 v83, v123
	v_mov_b32_e32 v82, v123
	v_mov_b32_e32 v81, v123
	v_mov_b32_e32 v80, v123
	v_mov_b32_e32 v71, v123
	v_mov_b32_e32 v70, v123
	v_mov_b32_e32 v69, v123
	v_mov_b32_e32 v68, v123
	v_mov_b32_e32 v67, v123
	v_mov_b32_e32 v66, v123
	v_mov_b32_e32 v65, v123
	v_mov_b32_e32 v64, v123
	v_mov_b32_e32 v63, v123
	v_mov_b32_e32 v62, v123
	v_mov_b32_e32 v61, v123
	v_mov_b32_e32 v60, v123
	v_mov_b32_e32 v59, v123
	v_mov_b32_e32 v58, v123
	v_mov_b32_e32 v57, v123
	v_mov_b32_e32 v56, v123
	v_mov_b32_e32 v47, v123
	v_mov_b32_e32 v46, v123
	v_mov_b32_e32 v45, v123
	v_mov_b32_e32 v44, v123
	v_mov_b32_e32 v43, v123
	v_mov_b32_e32 v42, v123
	v_mov_b32_e32 v41, v123
	v_mov_b32_e32 v40, v123
	v_mov_b32_e32 v31, v123
	v_mov_b32_e32 v30, v123
	v_mov_b32_e32 v29, v123
	v_mov_b32_e32 v28, v123
	v_mov_b32_e32 v27, v123
	v_mov_b32_e32 v26, v123
	v_mov_b32_e32 v25, v123
	v_mov_b32_e32 v24, v123
	v_mov_b32_e32 v15, v123
	v_mov_b32_e32 v14, v123
	v_mov_b32_e32 v13, v123
	v_mov_b32_e32 v12, v123
	v_mov_b32_e32 v11, v123
	v_mov_b32_e32 v10, v123
	v_mov_b32_e32 v9, v123
	v_mov_b32_e32 v8, v123
	v_mov_b32_e32 v55, v123
	v_mov_b32_e32 v54, v123
	v_mov_b32_e32 v53, v123
	v_mov_b32_e32 v52, v123
	v_mov_b32_e32 v51, v123
	v_mov_b32_e32 v50, v123
	v_mov_b32_e32 v49, v123
	v_mov_b32_e32 v48, v123
	v_mov_b32_e32 v39, v123
	v_mov_b32_e32 v38, v123
	v_mov_b32_e32 v37, v123
	v_mov_b32_e32 v36, v123
	v_mov_b32_e32 v35, v123
	v_mov_b32_e32 v34, v123
	v_mov_b32_e32 v33, v123
	v_mov_b32_e32 v32, v123
	v_mov_b32_e32 v23, v123
	v_mov_b32_e32 v22, v123
	v_mov_b32_e32 v21, v123
	v_mov_b32_e32 v20, v123
	v_mov_b32_e32 v19, v123
	v_mov_b32_e32 v18, v123
	v_mov_b32_e32 v17, v123
	v_mov_b32_e32 v16, v123
	v_mov_b32_e32 v7, v123
	v_mov_b32_e32 v6, v123
	v_mov_b32_e32 v5, v123
	v_mov_b32_e32 v4, v123
	v_mov_b32_e32 v3, v123
	v_mov_b32_e32 v2, v123
	v_mov_b32_e32 v1, v123
	v_mov_b32_e32 v0, v123
	s_cbranch_vccnz .LBB0_902
	s_and_b64 s[4:5], s[4:5], exec
	s_cselect_b32 s25, s39, s43
	s_cselect_b32 s52, s38, s42
	s_add_u32 s4, s42, 0x80080
	s_addc_u32 s5, s43, 0
	s_add_u32 s42, s40, 0x100
	v_mov_b32_e32 v0, 0
	s_addc_u32 s43, s41, 0
	s_mov_b32 s40, 0
	v_mov_b32_e32 v1, v0
	v_mov_b32_e32 v2, v0
	v_mov_b32_e32 v3, v0
	v_mov_b32_e32 v4, v0
	v_mov_b32_e32 v5, v0
	v_mov_b32_e32 v6, v0
	v_mov_b32_e32 v7, v0
	v_mov_b32_e32 v16, v0
	v_mov_b32_e32 v17, v0
	v_mov_b32_e32 v18, v0
	v_mov_b32_e32 v19, v0
	v_mov_b32_e32 v20, v0
	v_mov_b32_e32 v21, v0
	v_mov_b32_e32 v22, v0
	v_mov_b32_e32 v23, v0
	v_mov_b32_e32 v32, v0
	v_mov_b32_e32 v33, v0
	v_mov_b32_e32 v34, v0
	v_mov_b32_e32 v35, v0
	v_mov_b32_e32 v36, v0
	v_mov_b32_e32 v37, v0
	v_mov_b32_e32 v38, v0
	v_mov_b32_e32 v39, v0
	v_mov_b32_e32 v48, v0
	v_mov_b32_e32 v49, v0
	v_mov_b32_e32 v50, v0
	v_mov_b32_e32 v51, v0
	v_mov_b32_e32 v52, v0
	v_mov_b32_e32 v53, v0
	v_mov_b32_e32 v54, v0
	v_mov_b32_e32 v55, v0
	v_mov_b32_e32 v8, v0
	v_mov_b32_e32 v9, v0
	v_mov_b32_e32 v10, v0
	v_mov_b32_e32 v11, v0
	v_mov_b32_e32 v12, v0
	v_mov_b32_e32 v13, v0
	v_mov_b32_e32 v14, v0
	v_mov_b32_e32 v15, v0
	v_mov_b32_e32 v24, v0
	v_mov_b32_e32 v25, v0
	v_mov_b32_e32 v26, v0
	v_mov_b32_e32 v27, v0
	v_mov_b32_e32 v28, v0
	v_mov_b32_e32 v29, v0
	v_mov_b32_e32 v30, v0
	v_mov_b32_e32 v31, v0
	v_mov_b32_e32 v40, v0
	v_mov_b32_e32 v41, v0
	v_mov_b32_e32 v42, v0
	v_mov_b32_e32 v43, v0
	v_mov_b32_e32 v44, v0
	v_mov_b32_e32 v45, v0
	v_mov_b32_e32 v46, v0
	v_mov_b32_e32 v47, v0
	v_mov_b32_e32 v56, v0
	v_mov_b32_e32 v57, v0
	v_mov_b32_e32 v58, v0
	v_mov_b32_e32 v59, v0
	v_mov_b32_e32 v60, v0
	v_mov_b32_e32 v61, v0
	v_mov_b32_e32 v62, v0
	v_mov_b32_e32 v63, v0
	v_mov_b32_e32 v64, v0
	v_mov_b32_e32 v65, v0
	v_mov_b32_e32 v66, v0
	v_mov_b32_e32 v67, v0
	v_mov_b32_e32 v68, v0
	v_mov_b32_e32 v69, v0
	v_mov_b32_e32 v70, v0
	v_mov_b32_e32 v71, v0
	v_mov_b32_e32 v80, v0
	v_mov_b32_e32 v81, v0
	v_mov_b32_e32 v82, v0
	v_mov_b32_e32 v83, v0
	v_mov_b32_e32 v84, v0
	v_mov_b32_e32 v85, v0
	v_mov_b32_e32 v86, v0
	v_mov_b32_e32 v87, v0
	v_mov_b32_e32 v96, v0
	v_mov_b32_e32 v97, v0
	v_mov_b32_e32 v98, v0
	v_mov_b32_e32 v99, v0
	v_mov_b32_e32 v100, v0
	v_mov_b32_e32 v101, v0
	v_mov_b32_e32 v102, v0
	v_mov_b32_e32 v103, v0
	v_mov_b32_e32 v112, v0
	v_mov_b32_e32 v113, v0
	v_mov_b32_e32 v114, v0
	v_mov_b32_e32 v115, v0
	v_mov_b32_e32 v116, v0
	v_mov_b32_e32 v117, v0
	v_mov_b32_e32 v118, v0
	v_mov_b32_e32 v119, v0
	v_mov_b32_e32 v72, v0
	v_mov_b32_e32 v73, v0
	v_mov_b32_e32 v74, v0
	v_mov_b32_e32 v75, v0
	v_mov_b32_e32 v76, v0
	v_mov_b32_e32 v77, v0
	v_mov_b32_e32 v78, v0
	v_mov_b32_e32 v79, v0
	v_mov_b32_e32 v88, v0
	v_mov_b32_e32 v89, v0
	v_mov_b32_e32 v90, v0
	v_mov_b32_e32 v91, v0
	v_mov_b32_e32 v92, v0
	v_mov_b32_e32 v93, v0
	v_mov_b32_e32 v94, v0
	v_mov_b32_e32 v95, v0
	v_mov_b32_e32 v104, v0
	v_mov_b32_e32 v105, v0
	v_mov_b32_e32 v106, v0
	v_mov_b32_e32 v107, v0
	v_mov_b32_e32 v108, v0
	v_mov_b32_e32 v109, v0
	v_mov_b32_e32 v110, v0
	v_mov_b32_e32 v111, v0
	v_mov_b32_e32 v124, v0
	v_mov_b32_e32 v125, v0
	v_mov_b32_e32 v126, v0
	v_mov_b32_e32 v127, v0
	v_mov_b32_e32 v120, v0
	v_mov_b32_e32 v121, v0
	v_mov_b32_e32 v122, v0
	v_mov_b32_e32 v123, v0
	v_readfirstlane_b32 s100, v238
	s_cmp_lt_u32 s100, 0x100
	s_cbranch_scc1 .Lgp_901
	s_setprio 1
; #define PG8_STAGE(bufoff, gbase, voff) do { _Pragma("unroll") for (int _i = 0; _i < 2; ++_i) \
;         __builtin_amdgcn_global_load_lds((const unsigned*)((const char*)(gbase) + (voff)[_i]), (LAS unsigned*)(lds + (bufoff) + ldsw + _i * 8192), 16, 0, 0); } while (0)
; #define PG8_LDA(dst, b, h) do { _Pragma("unroll") for (int m = 0; m < 4; ++m) _Pragma("unroll") for (int k = 0; k < 2; ++k) dst[m][k] = *(const LAS bf16x8*)(lds + PG8_SA(b, h) + aoff + m * 2048 + k * 1024); } while (0)
; #define PG8_LDB(dst, b, h) do { _Pragma("unroll") for (int n = 0; n < 2; ++n) _Pragma("unroll") for (int k = 0; k < 2; ++k) dst[n][k] = *(const LAS bf16x8*)(lds + PG8_SB(b, h) + boff + n * 2048 + k * 1024); } while (0)
; #define PG8_MMA(ai, bj, At, Bt) do { __builtin_amdgcn_s_setprio(1); _Pragma("unroll") for (int m = 0; m < 4; ++m) _Pragma("unroll") for (int n = 0; n < 2; ++n) _Pragma("unroll") for (int k = 0; k < 2; ++k) \
;         acc[ai][bj][m][n] = __builtin_amdgcn_mfma_f32_16x16x32_bf16(Bt[n][k], At[m][k], acc[ai][bj][m][n], 0, 0, 0); __builtin_amdgcn_s_setprio(0); } while (0)
; #define PG8_BAR __builtin_amdgcn_s_barrier()
; template <class Epi, bool ALIGN_EPI = PG8_ALIGN>
; __device__ __forceinline__ void gemm_phase(LAS unsigned char* lds, const Gemm g, const StaticOrder& S, const Epi& E) {
;     ...
;         const bool has_next = S.next(ui + 1, nxt);
;         const char* nA = has_next ? (const char*)g.A + (size_t)nxt.pm * tstepA : cA; const char* nB = has_next ? (const char*)g.Bt + (size_t)nxt.pn * tstepB : cB;
;         for (int t = 0; t < nt; t += 2) {
;             const bool last = (t == nt - 2);
;             const char* a1 = cA + (size_t)(t + 1) * kstep;
;             const char* a2 = last ? nA : cA + (size_t)(t + 2) * kstep; const char* b2 = last ? nB : cB + (size_t)(t + 2) * kstep;
;             const char* a3 = a2 + kstep; const char* b3 = b2 + kstep;
;             PG8_LDB(B0, 0, 0); PG8_LDB(B1, 0, 1); PG8_SCHED; PG8_LDA(At, 0, 0); PG8_STAGE(PG8_SA(1, 1), a1 + hstepA, voffA);
;             PG8_WAIT_V(8); PG8_WAIT_L(0); PG8_BAR; PG8_MMA(0, 0, At, B0); PG8_MMA(0, 1, At, B1); PG8_BAR; PG8_SCHED;
;             PG8_LDA(At, 0, 1); PG8_STAGE(PG8_SB(0, 0), b2, voffB); PG8_STAGE(PG8_SB(0, 1), b2 + hstepB, voffB); PG8_STAGE(PG8_SA(0, 0), a2, voffA);
;             PG8_WAIT_V(8); PG8_WAIT_L(0); PG8_BAR; PG8_MMA(1, 0, At, B0); PG8_MMA(1, 1, At, B1); PG8_BAR; PG8_SCHED;
.Lgp_901:
.LBB0_901:
	s_add_i32 s53, s40, 2
	s_add_u32 s20, s4, 0xfff80080
	s_addc_u32 s21, s5, -1
	s_add_i32 s22, 16, 0x10000
	s_cmp_eq_u32 s47, s40
	s_cselect_b32 s41, s25, s21
	s_cselect_b32 s40, s52, s20
	s_cselect_b32 s21, s37, s43
	s_cselect_b32 s20, s36, s42
	s_add_i32 s23, 16, 0x14000
	v_add_u32_e32 v154, s22, v139
	v_add_u32_e32 v170, s23, v139
	ds_read_b128 v[142:145], v154
	ds_read_b128 v[146:149], v154 offset:1024
	ds_read_b128 v[150:153], v154 offset:2048
	ds_read_b128 v[154:157], v154 offset:3072
	ds_read_b128 v[158:161], v170
	ds_read_b128 v[162:165], v170 offset:1024
	ds_read_b128 v[166:169], v170 offset:2048
	ds_read_b128 v[170:173], v170 offset:3072
	v_lshl_add_u64 v[174:175], s[4:5], 0, v[134:135]
	s_add_i32 m0, s29, 0xc000
	ds_read_b128 v[184:187], v141
	ds_read_b128 v[188:191], v141 offset:1024
	ds_read_b128 v[192:195], v141 offset:2048
	ds_read_b128 v[196:199], v141 offset:3072
	ds_read_b128 v[200:203], v141 offset:4096
	ds_read_b128 v[204:207], v141 offset:5120
	ds_read_b128 v[208:211], v141 offset:6144
	ds_read_b128 v[212:215], v141 offset:7168
	global_load_lds_dwordx4 v[174:175], off
	v_lshl_add_u64 v[174:175], s[4:5], 0, v[136:137]
	s_add_i32 m0, s29, 0xe000
	s_nop 0
	global_load_lds_dwordx4 v[174:175], off
	s_waitcnt vmcnt(8)
	s_waitcnt lgkmcnt(0)
	s_barrier
	s_waitcnt lgkmcnt(0)
	v_mfma_f32_16x16x32_bf16 v[120:123], v[142:145], v[184:187], v[120:123]
	v_mfma_f32_16x16x32_bf16 v[124:127], v[150:153], v[184:187], v[124:127]
	v_mfma_f32_16x16x32_bf16 v[108:111], v[142:145], v[192:195], v[108:111]
	v_mfma_f32_16x16x32_bf16 v[104:107], v[150:153], v[192:195], v[104:107]
	v_mfma_f32_16x16x32_bf16 v[92:95], v[142:145], v[200:203], v[92:95]
	v_mfma_f32_16x16x32_bf16 v[88:91], v[150:153], v[200:203], v[88:91]
	v_mfma_f32_16x16x32_bf16 v[76:79], v[142:145], v[208:211], v[76:79]
	v_mfma_f32_16x16x32_bf16 v[72:75], v[150:153], v[208:211], v[72:75]
	v_mfma_f32_16x16x32_bf16 v[120:123], v[146:149], v[188:191], v[120:123]
	v_mfma_f32_16x16x32_bf16 v[124:127], v[154:157], v[188:191], v[124:127]
	v_mfma_f32_16x16x32_bf16 v[108:111], v[146:149], v[196:199], v[108:111]
	v_mfma_f32_16x16x32_bf16 v[104:107], v[154:157], v[196:199], v[104:107]
	v_mfma_f32_16x16x32_bf16 v[92:95], v[146:149], v[204:207], v[92:95]
	v_mfma_f32_16x16x32_bf16 v[88:91], v[154:157], v[204:207], v[88:91]
	v_mfma_f32_16x16x32_bf16 v[76:79], v[146:149], v[212:215], v[76:79]
	v_mfma_f32_16x16x32_bf16 v[72:75], v[154:157], v[212:215], v[72:75]
	v_mfma_f32_16x16x32_bf16 v[116:119], v[158:161], v[184:187], v[116:119]
	v_mfma_f32_16x16x32_bf16 v[112:115], v[166:169], v[184:187], v[112:115]
	v_mfma_f32_16x16x32_bf16 v[100:103], v[158:161], v[192:195], v[100:103]
	v_mfma_f32_16x16x32_bf16 v[96:99], v[166:169], v[192:195], v[96:99]
	v_mfma_f32_16x16x32_bf16 v[84:87], v[158:161], v[200:203], v[84:87]
	v_mfma_f32_16x16x32_bf16 v[80:83], v[166:169], v[200:203], v[80:83]
	v_mfma_f32_16x16x32_bf16 v[68:71], v[158:161], v[208:211], v[68:71]
	v_mfma_f32_16x16x32_bf16 v[64:67], v[166:169], v[208:211], v[64:67]
	v_mfma_f32_16x16x32_bf16 v[116:119], v[162:165], v[188:191], v[116:119]
	v_mfma_f32_16x16x32_bf16 v[112:115], v[170:173], v[188:191], v[112:115]
	v_mfma_f32_16x16x32_bf16 v[100:103], v[162:165], v[196:199], v[100:103]
	v_mfma_f32_16x16x32_bf16 v[96:99], v[170:173], v[196:199], v[96:99]
	v_mfma_f32_16x16x32_bf16 v[84:87], v[162:165], v[204:207], v[84:87]
	v_mfma_f32_16x16x32_bf16 v[80:83], v[170:173], v[204:207], v[80:83]
	v_mfma_f32_16x16x32_bf16 v[68:71], v[162:165], v[212:215], v[68:71]
	v_mfma_f32_16x16x32_bf16 v[64:67], v[170:173], v[212:215], v[64:67]
	s_barrier
	s_add_i32 s22, s22, s18
	v_lshl_add_u64 v[174:175], s[20:21], 0, v[176:177]
	s_mov_b32 m0, s22
	ds_read_b128 v[184:187], v141 offset:16384
	ds_read_b128 v[188:191], v141 offset:17408
	ds_read_b128 v[192:195], v141 offset:18432
	ds_read_b128 v[196:199], v141 offset:19456
	ds_read_b128 v[200:203], v141 offset:20480
	ds_read_b128 v[204:207], v141 offset:21504
	ds_read_b128 v[208:211], v141 offset:22528
	ds_read_b128 v[212:215], v141 offset:23552
	global_load_lds_dwordx4 v[174:175], off
	s_add_i32 m0, s22, 0x2000
	v_lshl_add_u64 v[180:181], s[20:21], 0, v[128:129]
	s_add_u32 s20, s20, s8
	s_addc_u32 s21, s21, s9
	s_add_i32 s22, s23, s18
	global_load_lds_dwordx4 v[180:181], off
	v_lshl_add_u64 v[182:183], s[20:21], 0, v[176:177]
	s_mov_b32 m0, s22
	v_lshl_add_u64 v[216:217], s[20:21], 0, v[128:129]
	global_load_lds_dwordx4 v[182:183], off
	s_add_i32 m0, s22, 0x2000
	v_lshl_add_u64 v[218:219], s[40:41], 0, v[132:133]
	global_load_lds_dwordx4 v[216:217], off
	s_mov_b32 m0, s29
	v_lshl_add_u64 v[220:221], s[40:41], 0, v[130:131]
	global_load_lds_dwordx4 v[218:219], off
	s_mov_b32 m0, s30
	s_nop 0
	global_load_lds_dwordx4 v[220:221], off
	s_waitcnt vmcnt(8)
	s_waitcnt lgkmcnt(0)
	s_barrier
; #define PG8_STAGE(bufoff, gbase, voff) do { _Pragma("unroll") for (int _i = 0; _i < 2; ++_i) \
;         __builtin_amdgcn_global_load_lds((const unsigned*)((const char*)(gbase) + (voff)[_i]), (LAS unsigned*)(lds + (bufoff) + ldsw + _i * 8192), 16, 0, 0); } while (0)
; #define PG8_LDA(dst, b, h) do { _Pragma("unroll") for (int m = 0; m < 4; ++m) _Pragma("unroll") for (int k = 0; k < 2; ++k) dst[m][k] = *(const LAS bf16x8*)(lds + PG8_SA(b, h) + aoff + m * 2048 + k * 1024); } while (0)
; #define PG8_LDB(dst, b, h) do { _Pragma("unroll") for (int n = 0; n < 2; ++n) _Pragma("unroll") for (int k = 0; k < 2; ++k) dst[n][k] = *(const LAS bf16x8*)(lds + PG8_SB(b, h) + boff + n * 2048 + k * 1024); } while (0)
; #define PG8_MMA(ai, bj, At, Bt) do { __builtin_amdgcn_s_setprio(1); _Pragma("unroll") for (int m = 0; m < 4; ++m) _Pragma("unroll") for (int n = 0; n < 2; ++n) _Pragma("unroll") for (int k = 0; k < 2; ++k) \
;         acc[ai][bj][m][n] = __builtin_amdgcn_mfma_f32_16x16x32_bf16(Bt[n][k], At[m][k], acc[ai][bj][m][n], 0, 0, 0); __builtin_amdgcn_s_setprio(0); } while (0)
; #define PG8_WAIT_V(n) asm volatile("s_waitcnt vmcnt(" #n ")" ::: "memory")
; #define PG8_WAIT_L(n) asm volatile("s_waitcnt lgkmcnt(" #n ")" ::: "memory")
; #define PG8_BAR __builtin_amdgcn_s_barrier()
; #define PG8_SCHED __builtin_amdgcn_sched_barrier(0)
; template <class Epi, bool ALIGN_EPI = PG8_ALIGN>
; __device__ __forceinline__ void gemm_phase(LAS unsigned char* lds, const Gemm g, const StaticOrder& S, const Epi& E) {
;     ...
;             PG8_WAIT_V(8); PG8_WAIT_L(0); PG8_BAR; PG8_MMA(1, 0, At, B0); PG8_MMA(1, 1, At, B1); PG8_BAR; PG8_SCHED;
;             PG8_LDB(B0, 1, 0); PG8_LDB(B1, 1, 1); PG8_SCHED; PG8_LDA(At, 1, 0); PG8_STAGE(PG8_SA(0, 1), a2 + hstepA, voffA);
;             PG8_WAIT_V(8); PG8_WAIT_L(0); PG8_BAR; PG8_MMA(0, 0, At, B0); PG8_MMA(0, 1, At, B1); PG8_BAR; PG8_SCHED;
	s_waitcnt lgkmcnt(0)
	v_mfma_f32_16x16x32_bf16 v[60:63], v[142:145], v[184:187], v[60:63]
	v_mfma_f32_16x16x32_bf16 v[56:59], v[150:153], v[184:187], v[56:59]
	v_mfma_f32_16x16x32_bf16 v[44:47], v[142:145], v[192:195], v[44:47]
	v_mfma_f32_16x16x32_bf16 v[40:43], v[150:153], v[192:195], v[40:43]
	v_mfma_f32_16x16x32_bf16 v[28:31], v[142:145], v[200:203], v[28:31]
	v_mfma_f32_16x16x32_bf16 v[24:27], v[150:153], v[200:203], v[24:27]
	v_mfma_f32_16x16x32_bf16 v[12:15], v[142:145], v[208:211], v[12:15]
	v_mfma_f32_16x16x32_bf16 v[8:11], v[150:153], v[208:211], v[8:11]
	v_mfma_f32_16x16x32_bf16 v[60:63], v[146:149], v[188:191], v[60:63]
	v_mfma_f32_16x16x32_bf16 v[56:59], v[154:157], v[188:191], v[56:59]
	v_mfma_f32_16x16x32_bf16 v[44:47], v[146:149], v[196:199], v[44:47]
	v_mfma_f32_16x16x32_bf16 v[40:43], v[154:157], v[196:199], v[40:43]
	v_mfma_f32_16x16x32_bf16 v[28:31], v[146:149], v[204:207], v[28:31]
	v_mfma_f32_16x16x32_bf16 v[24:27], v[154:157], v[204:207], v[24:27]
	v_mfma_f32_16x16x32_bf16 v[12:15], v[146:149], v[212:215], v[12:15]
	v_mfma_f32_16x16x32_bf16 v[8:11], v[154:157], v[212:215], v[8:11]
	v_mfma_f32_16x16x32_bf16 v[52:55], v[158:161], v[184:187], v[52:55]
	v_mfma_f32_16x16x32_bf16 v[48:51], v[166:169], v[184:187], v[48:51]
	v_mfma_f32_16x16x32_bf16 v[36:39], v[158:161], v[192:195], v[36:39]
	v_mfma_f32_16x16x32_bf16 v[32:35], v[166:169], v[192:195], v[32:35]
	v_mfma_f32_16x16x32_bf16 v[20:23], v[158:161], v[200:203], v[20:23]
	v_mfma_f32_16x16x32_bf16 v[16:19], v[166:169], v[200:203], v[16:19]
	v_mfma_f32_16x16x32_bf16 v[4:7], v[158:161], v[208:211], v[4:7]
	v_mfma_f32_16x16x32_bf16 v[0:3], v[166:169], v[208:211], v[0:3]
	v_mfma_f32_16x16x32_bf16 v[52:55], v[162:165], v[188:191], v[52:55]
	v_mfma_f32_16x16x32_bf16 v[48:51], v[170:173], v[188:191], v[48:51]
	v_mfma_f32_16x16x32_bf16 v[36:39], v[162:165], v[196:199], v[36:39]
	v_mfma_f32_16x16x32_bf16 v[32:35], v[170:173], v[196:199], v[32:35]
	v_mfma_f32_16x16x32_bf16 v[20:23], v[162:165], v[204:207], v[20:23]
	v_mfma_f32_16x16x32_bf16 v[16:19], v[170:173], v[204:207], v[16:19]
	v_mfma_f32_16x16x32_bf16 v[4:7], v[162:165], v[212:215], v[4:7]
	v_mfma_f32_16x16x32_bf16 v[0:3], v[170:173], v[212:215], v[0:3]
	s_barrier
	s_add_i32 s22, 16, 0x18000
	s_add_i32 s23, 16, 0x1c000
	v_add_u32_e32 v154, s22, v139
	v_add_u32_e32 v170, s23, v139
	ds_read_b128 v[142:145], v154
	ds_read_b128 v[146:149], v154 offset:1024
	ds_read_b128 v[150:153], v154 offset:2048
	ds_read_b128 v[154:157], v154 offset:3072
	ds_read_b128 v[158:161], v170
	ds_read_b128 v[162:165], v170 offset:1024
	ds_read_b128 v[166:169], v170 offset:2048
	ds_read_b128 v[170:173], v170 offset:3072
	s_add_u32 s20, s40, 0x80000
	s_addc_u32 s21, s41, 0
	s_mov_b32 m0, s31
	v_lshl_add_u64 v[222:223], s[20:21], 0, v[132:133]
	ds_read_b128 v[184:187], v141 offset:32768
	ds_read_b128 v[188:191], v141 offset:33792
	ds_read_b128 v[192:195], v141 offset:34816
	ds_read_b128 v[196:199], v141 offset:35840
	ds_read_b128 v[200:203], v141 offset:36864
	ds_read_b128 v[204:207], v141 offset:37888
	ds_read_b128 v[208:211], v141 offset:38912
	ds_read_b128 v[212:215], v141 offset:39936
	global_load_lds_dwordx4 v[222:223], off
	v_lshl_add_u64 v[222:223], s[20:21], 0, v[130:131]
	s_mov_b32 m0, s44
	s_nop 0
	global_load_lds_dwordx4 v[222:223], off
	s_waitcnt vmcnt(8)
	s_waitcnt lgkmcnt(0)
	s_barrier
	s_waitcnt lgkmcnt(0)
	v_mfma_f32_16x16x32_bf16 v[120:123], v[142:145], v[184:187], v[120:123]
	v_mfma_f32_16x16x32_bf16 v[124:127], v[150:153], v[184:187], v[124:127]
	v_mfma_f32_16x16x32_bf16 v[108:111], v[142:145], v[192:195], v[108:111]
	v_mfma_f32_16x16x32_bf16 v[104:107], v[150:153], v[192:195], v[104:107]
	v_mfma_f32_16x16x32_bf16 v[92:95], v[142:145], v[200:203], v[92:95]
	v_mfma_f32_16x16x32_bf16 v[88:91], v[150:153], v[200:203], v[88:91]
	v_mfma_f32_16x16x32_bf16 v[76:79], v[142:145], v[208:211], v[76:79]
	v_mfma_f32_16x16x32_bf16 v[72:75], v[150:153], v[208:211], v[72:75]
	v_mfma_f32_16x16x32_bf16 v[120:123], v[146:149], v[188:191], v[120:123]
	v_mfma_f32_16x16x32_bf16 v[124:127], v[154:157], v[188:191], v[124:127]
	v_mfma_f32_16x16x32_bf16 v[108:111], v[146:149], v[196:199], v[108:111]
	v_mfma_f32_16x16x32_bf16 v[104:107], v[154:157], v[196:199], v[104:107]
	v_mfma_f32_16x16x32_bf16 v[92:95], v[146:149], v[204:207], v[92:95]
	v_mfma_f32_16x16x32_bf16 v[88:91], v[154:157], v[204:207], v[88:91]
	v_mfma_f32_16x16x32_bf16 v[76:79], v[146:149], v[212:215], v[76:79]
	v_mfma_f32_16x16x32_bf16 v[72:75], v[154:157], v[212:215], v[72:75]
	v_mfma_f32_16x16x32_bf16 v[116:119], v[158:161], v[184:187], v[116:119]
	v_mfma_f32_16x16x32_bf16 v[112:115], v[166:169], v[184:187], v[112:115]
	v_mfma_f32_16x16x32_bf16 v[100:103], v[158:161], v[192:195], v[100:103]
	v_mfma_f32_16x16x32_bf16 v[96:99], v[166:169], v[192:195], v[96:99]
	v_mfma_f32_16x16x32_bf16 v[84:87], v[158:161], v[200:203], v[84:87]
	v_mfma_f32_16x16x32_bf16 v[80:83], v[166:169], v[200:203], v[80:83]
	v_mfma_f32_16x16x32_bf16 v[68:71], v[158:161], v[208:211], v[68:71]
	v_mfma_f32_16x16x32_bf16 v[64:67], v[166:169], v[208:211], v[64:67]
	v_mfma_f32_16x16x32_bf16 v[116:119], v[162:165], v[188:191], v[116:119]
	v_mfma_f32_16x16x32_bf16 v[112:115], v[170:173], v[188:191], v[112:115]
	v_mfma_f32_16x16x32_bf16 v[100:103], v[162:165], v[196:199], v[100:103]
	v_mfma_f32_16x16x32_bf16 v[96:99], v[170:173], v[196:199], v[96:99]
	v_mfma_f32_16x16x32_bf16 v[84:87], v[162:165], v[204:207], v[84:87]
	v_mfma_f32_16x16x32_bf16 v[80:83], v[170:173], v[204:207], v[80:83]
	v_mfma_f32_16x16x32_bf16 v[68:71], v[162:165], v[212:215], v[68:71]
	v_mfma_f32_16x16x32_bf16 v[64:67], v[170:173], v[212:215], v[64:67]
	s_barrier
; #define PG8_STAGE(bufoff, gbase, voff) do { _Pragma("unroll") for (int _i = 0; _i < 2; ++_i) \
;         __builtin_amdgcn_global_load_lds((const unsigned*)((const char*)(gbase) + (voff)[_i]), (LAS unsigned*)(lds + (bufoff) + ldsw + _i * 8192), 16, 0, 0); } while (0)
; #define PG8_LDA(dst, b, h) do { _Pragma("unroll") for (int m = 0; m < 4; ++m) _Pragma("unroll") for (int k = 0; k < 2; ++k) dst[m][k] = *(const LAS bf16x8*)(lds + PG8_SA(b, h) + aoff + m * 2048 + k * 1024); } while (0)
; #define PG8_MMA(ai, bj, At, Bt) do { __builtin_amdgcn_s_setprio(1); _Pragma("unroll") for (int m = 0; m < 4; ++m) _Pragma("unroll") for (int n = 0; n < 2; ++n) _Pragma("unroll") for (int k = 0; k < 2; ++k) \
;         acc[ai][bj][m][n] = __builtin_amdgcn_mfma_f32_16x16x32_bf16(Bt[n][k], At[m][k], acc[ai][bj][m][n], 0, 0, 0); __builtin_amdgcn_s_setprio(0); } while (0)
; #define PG8_WAIT_V(n) asm volatile("s_waitcnt vmcnt(" #n ")" ::: "memory")
; #define PG8_WAIT_L(n) asm volatile("s_waitcnt lgkmcnt(" #n ")" ::: "memory")
; #define PG8_BAR __builtin_amdgcn_s_barrier()
; #define PG8_SCHED __builtin_amdgcn_sched_barrier(0)
; template <class Epi, bool ALIGN_EPI = PG8_ALIGN>
; __device__ __forceinline__ void gemm_phase(LAS unsigned char* lds, const Gemm g, const StaticOrder& S, const Epi& E) {
;     ...
;             PG8_LDA(At, 1, 1); PG8_STAGE(PG8_SB(1, 0), b3, voffB); PG8_STAGE(PG8_SB(1, 1), b3 + hstepB, voffB); PG8_STAGE(PG8_SA(1, 0), a3, voffA);
;             PG8_WAIT_V(8); PG8_WAIT_L(0); PG8_BAR; PG8_MMA(1, 0, At, B0); PG8_MMA(1, 1, At, B1); PG8_BAR; PG8_SCHED;
;         }
	s_add_i32 s20, s22, s18
	v_lshl_add_u64 v[174:175], v[174:175], 0, s[0:1]
	s_mov_b32 m0, s20
	ds_read_b128 v[184:187], v141 offset:49152
	ds_read_b128 v[188:191], v141 offset:50176
	ds_read_b128 v[192:195], v141 offset:51200
	ds_read_b128 v[196:199], v141 offset:52224
	ds_read_b128 v[200:203], v141 offset:53248
	ds_read_b128 v[204:207], v141 offset:54272
	ds_read_b128 v[208:211], v141 offset:55296
	ds_read_b128 v[212:215], v141 offset:56320
	global_load_lds_dwordx4 v[174:175], off
	v_lshl_add_u64 v[174:175], v[180:181], 0, s[0:1]
	s_add_i32 m0, s20, 0x2000
	s_add_i32 s20, s23, s18
	global_load_lds_dwordx4 v[174:175], off
	v_lshl_add_u64 v[174:175], v[182:183], 0, s[0:1]
	s_mov_b32 m0, s20
	s_nop 0
	global_load_lds_dwordx4 v[174:175], off
	v_lshl_add_u64 v[174:175], v[216:217], 0, s[0:1]
	s_add_i32 m0, s20, 0x2000
	s_nop 0
	global_load_lds_dwordx4 v[174:175], off
	v_lshl_add_u64 v[174:175], v[218:219], 0, s[0:1]
	s_mov_b32 m0, s45
	s_nop 0
	global_load_lds_dwordx4 v[174:175], off
	v_lshl_add_u64 v[174:175], v[220:221], 0, s[0:1]
	s_mov_b32 m0, s46
	s_nop 0
	global_load_lds_dwordx4 v[174:175], off
	s_waitcnt vmcnt(8)
	s_waitcnt lgkmcnt(0)
	s_barrier
	s_waitcnt lgkmcnt(0)
	v_mfma_f32_16x16x32_bf16 v[60:63], v[142:145], v[184:187], v[60:63]
	v_mfma_f32_16x16x32_bf16 v[56:59], v[150:153], v[184:187], v[56:59]
	v_mfma_f32_16x16x32_bf16 v[44:47], v[142:145], v[192:195], v[44:47]
	v_mfma_f32_16x16x32_bf16 v[40:43], v[150:153], v[192:195], v[40:43]
	v_mfma_f32_16x16x32_bf16 v[28:31], v[142:145], v[200:203], v[28:31]
	v_mfma_f32_16x16x32_bf16 v[24:27], v[150:153], v[200:203], v[24:27]
	v_mfma_f32_16x16x32_bf16 v[12:15], v[142:145], v[208:211], v[12:15]
	v_mfma_f32_16x16x32_bf16 v[8:11], v[150:153], v[208:211], v[8:11]
	v_mfma_f32_16x16x32_bf16 v[60:63], v[146:149], v[188:191], v[60:63]
	v_mfma_f32_16x16x32_bf16 v[56:59], v[154:157], v[188:191], v[56:59]
	v_mfma_f32_16x16x32_bf16 v[44:47], v[146:149], v[196:199], v[44:47]
	v_mfma_f32_16x16x32_bf16 v[40:43], v[154:157], v[196:199], v[40:43]
	v_mfma_f32_16x16x32_bf16 v[28:31], v[146:149], v[204:207], v[28:31]
	v_mfma_f32_16x16x32_bf16 v[24:27], v[154:157], v[204:207], v[24:27]
	v_mfma_f32_16x16x32_bf16 v[12:15], v[146:149], v[212:215], v[12:15]
	v_mfma_f32_16x16x32_bf16 v[8:11], v[154:157], v[212:215], v[8:11]
	v_mfma_f32_16x16x32_bf16 v[52:55], v[158:161], v[184:187], v[52:55]
	v_mfma_f32_16x16x32_bf16 v[48:51], v[166:169], v[184:187], v[48:51]
	v_mfma_f32_16x16x32_bf16 v[36:39], v[158:161], v[192:195], v[36:39]
	v_mfma_f32_16x16x32_bf16 v[32:35], v[166:169], v[192:195], v[32:35]
	v_mfma_f32_16x16x32_bf16 v[20:23], v[158:161], v[200:203], v[20:23]
	v_mfma_f32_16x16x32_bf16 v[16:19], v[166:169], v[200:203], v[16:19]
	v_mfma_f32_16x16x32_bf16 v[4:7], v[158:161], v[208:211], v[4:7]
	v_mfma_f32_16x16x32_bf16 v[0:3], v[166:169], v[208:211], v[0:3]
	v_mfma_f32_16x16x32_bf16 v[52:55], v[162:165], v[188:191], v[52:55]
	v_mfma_f32_16x16x32_bf16 v[48:51], v[170:173], v[188:191], v[48:51]
	v_mfma_f32_16x16x32_bf16 v[36:39], v[162:165], v[196:199], v[36:39]
	v_mfma_f32_16x16x32_bf16 v[32:35], v[170:173], v[196:199], v[32:35]
	v_mfma_f32_16x16x32_bf16 v[20:23], v[162:165], v[204:207], v[20:23]
	v_mfma_f32_16x16x32_bf16 v[16:19], v[170:173], v[204:207], v[16:19]
	v_mfma_f32_16x16x32_bf16 v[4:7], v[162:165], v[212:215], v[4:7]
	v_mfma_f32_16x16x32_bf16 v[0:3], v[170:173], v[212:215], v[0:3]
	s_barrier
	s_add_u32 s4, s4, 0x100
	s_addc_u32 s5, s5, 0
	s_add_u32 s42, s42, 0x100
	s_addc_u32 s43, s43, 0
	s_cmp_ge_i32 s53, s34
	s_mov_b32 s40, s53
	s_cbranch_scc0 .LBB0_901
	s_setprio 0

; #define PG8_STAGE(bufoff, gbase, voff) do { _Pragma("unroll") for (int _i = 0; _i < 2; ++_i) \
;         __builtin_amdgcn_global_load_lds((const unsigned*)((const char*)(gbase) + (voff)[_i]), (LAS unsigned*)(lds + (bufoff) + ldsw + _i * 8192), 16, 0, 0); } while (0)
; #define PG8_WAIT_V(n) asm volatile("s_waitcnt vmcnt(" #n ")" ::: "memory")
; #define PG8_BAR __builtin_amdgcn_s_barrier()
; template <class Epi, bool ALIGN_EPI = PG8_ALIGN>
; __device__ __forceinline__ void gemm_phase(LAS unsigned char* lds, const Gemm g, const StaticOrder& S, const Epi& E) {
;     ...
;     f32x4 acc[2][2][4][2];
; #pragma unroll
;     for (int a = 0; a < 2; ++a)
; #pragma unroll
;         for (int b = 0; b < 2; ++b)
; #pragma unroll
;             for (int m = 0; m < 4; ++m)
; #pragma unroll
;                 for (int n = 0; n < 2; ++n) acc[a][b][m][n] = (f32x4){0.f, 0.f, 0.f, 0.f};
;     bf16x8 At[4][2], B0[2][2], B1[2][2];
;     const char* cA = (const char*)g.A + (size_t)cur.pm * tstepA; const char* cB = (const char*)g.Bt + (size_t)cur.pn * tstepB;
;     PG8_STAGE(PG8_SB(0, 0), cB, voffB); PG8_STAGE(PG8_SB(0, 1), cB + hstepB, voffB); PG8_STAGE(PG8_SA(0, 0), cA, voffA); PG8_STAGE(PG8_SA(0, 1), cA + hstepA, voffA);
;     if (wr == 1) PG8_BAR;
;     PG8_WAIT_V(2); PG8_BAR;
;     PG8_STAGE(PG8_SB(1, 0), cB + kstep, voffB); PG8_STAGE(PG8_SA(1, 0), cA + kstep, voffA); PG8_STAGE(PG8_SB(1, 1), cB + hstepB + kstep, voffB);
;     PG8_WAIT_V(6); PG8_BAR;
;     for (;;) {
;         const bool has_next = S.next(ui + 1, nxt);
;         const char* nA = has_next ? (const char*)g.A + (size_t)nxt.pm * tstepA : cA; const char* nB = has_next ? (const char*)g.Bt + (size_t)nxt.pn * tstepB : cB;
.LBB0_1026:
	s_ashr_i32 s17, s16, 31
	s_lshl_b64 s[20:21], s[16:17], 20
	s_add_u32 s42, s58, s20
	v_mov_b32_e32 v127, 0
	s_addc_u32 s43, s59, s21
	s_andn2_b64 vcc, exec, s[12:13]
	v_mov_b32_e32 v126, v127
	v_mov_b32_e32 v125, v127
	v_mov_b32_e32 v124, v127
	v_mov_b32_e32 v119, v127
	v_mov_b32_e32 v118, v127
	v_mov_b32_e32 v117, v127
	v_mov_b32_e32 v116, v127
	v_mov_b32_e32 v111, v127
	v_mov_b32_e32 v110, v127
	v_mov_b32_e32 v109, v127
	v_mov_b32_e32 v108, v127
	v_mov_b32_e32 v103, v127
	v_mov_b32_e32 v102, v127
	v_mov_b32_e32 v101, v127
	v_mov_b32_e32 v100, v127
	v_mov_b32_e32 v95, v127
	v_mov_b32_e32 v94, v127
	v_mov_b32_e32 v93, v127
	v_mov_b32_e32 v92, v127
	v_mov_b32_e32 v87, v127
	v_mov_b32_e32 v86, v127
	v_mov_b32_e32 v85, v127
	v_mov_b32_e32 v84, v127
	v_mov_b32_e32 v79, v127
	v_mov_b32_e32 v78, v127
	v_mov_b32_e32 v77, v127
	v_mov_b32_e32 v76, v127
	v_mov_b32_e32 v71, v127
	v_mov_b32_e32 v70, v127
	v_mov_b32_e32 v69, v127
	v_mov_b32_e32 v68, v127
	v_mov_b32_e32 v123, v127
	v_mov_b32_e32 v122, v127
	v_mov_b32_e32 v121, v127
	v_mov_b32_e32 v120, v127
	v_mov_b32_e32 v115, v127
	v_mov_b32_e32 v114, v127
	v_mov_b32_e32 v113, v127
	v_mov_b32_e32 v112, v127
	v_mov_b32_e32 v107, v127
	v_mov_b32_e32 v106, v127
	v_mov_b32_e32 v105, v127
	v_mov_b32_e32 v104, v127
	v_mov_b32_e32 v99, v127
	v_mov_b32_e32 v98, v127
	v_mov_b32_e32 v97, v127
	v_mov_b32_e32 v96, v127
	v_mov_b32_e32 v91, v127
	v_mov_b32_e32 v90, v127
	v_mov_b32_e32 v89, v127
	v_mov_b32_e32 v88, v127
	v_mov_b32_e32 v83, v127
	v_mov_b32_e32 v82, v127
	v_mov_b32_e32 v81, v127
	v_mov_b32_e32 v80, v127
	v_mov_b32_e32 v75, v127
	v_mov_b32_e32 v74, v127
	v_mov_b32_e32 v73, v127
	v_mov_b32_e32 v72, v127
	v_mov_b32_e32 v67, v127
	v_mov_b32_e32 v66, v127
	v_mov_b32_e32 v65, v127
	v_mov_b32_e32 v64, v127
	v_mov_b32_e32 v63, v127
	v_mov_b32_e32 v62, v127
	v_mov_b32_e32 v61, v127
	v_mov_b32_e32 v60, v127
	v_mov_b32_e32 v55, v127
	v_mov_b32_e32 v54, v127
	v_mov_b32_e32 v53, v127
	v_mov_b32_e32 v52, v127
	v_mov_b32_e32 v47, v127
	v_mov_b32_e32 v46, v127
	v_mov_b32_e32 v45, v127
	v_mov_b32_e32 v44, v127
	v_mov_b32_e32 v39, v127
	v_mov_b32_e32 v38, v127
	v_mov_b32_e32 v37, v127
	v_mov_b32_e32 v36, v127
	v_mov_b32_e32 v31, v127
	v_mov_b32_e32 v30, v127
	v_mov_b32_e32 v29, v127
	v_mov_b32_e32 v28, v127
	v_mov_b32_e32 v23, v127
	v_mov_b32_e32 v22, v127
	v_mov_b32_e32 v21, v127
	v_mov_b32_e32 v20, v127
	v_mov_b32_e32 v15, v127
	v_mov_b32_e32 v14, v127
	v_mov_b32_e32 v13, v127
	v_mov_b32_e32 v12, v127
	v_mov_b32_e32 v7, v127
	v_mov_b32_e32 v6, v127
	v_mov_b32_e32 v5, v127
	v_mov_b32_e32 v4, v127
	v_mov_b32_e32 v59, v127
	v_mov_b32_e32 v58, v127
	v_mov_b32_e32 v57, v127
	v_mov_b32_e32 v56, v127
	v_mov_b32_e32 v51, v127
	v_mov_b32_e32 v50, v127
	v_mov_b32_e32 v49, v127
	v_mov_b32_e32 v48, v127
	v_mov_b32_e32 v43, v127
	v_mov_b32_e32 v42, v127
	v_mov_b32_e32 v41, v127
	v_mov_b32_e32 v40, v127
	v_mov_b32_e32 v35, v127
	v_mov_b32_e32 v34, v127
	v_mov_b32_e32 v33, v127
	v_mov_b32_e32 v32, v127
	v_mov_b32_e32 v27, v127
	v_mov_b32_e32 v26, v127
	v_mov_b32_e32 v25, v127
	v_mov_b32_e32 v24, v127
	v_mov_b32_e32 v19, v127
	v_mov_b32_e32 v18, v127
	v_mov_b32_e32 v17, v127
	v_mov_b32_e32 v16, v127
	v_mov_b32_e32 v11, v127
	v_mov_b32_e32 v10, v127
	v_mov_b32_e32 v9, v127
	v_mov_b32_e32 v8, v127
	v_mov_b32_e32 v3, v127
	v_mov_b32_e32 v2, v127
	v_mov_b32_e32 v1, v127
	v_mov_b32_e32 v0, v127
	s_cbranch_vccnz .LBB0_1029
	s_and_b64 s[2:3], s[2:3], exec
	s_cselect_b32 s17, s43, s37
	s_cselect_b32 s27, s42, s36
	s_add_u32 s2, s36, 0x80080
	s_addc_u32 s3, s37, 0
	s_add_u32 s29, s24, 0x100
	v_mov_b32_e32 v0, 0
	s_addc_u32 s30, s25, 0
	s_mov_b32 s24, 0
	v_mov_b32_e32 v1, v0
	v_mov_b32_e32 v2, v0
	v_mov_b32_e32 v3, v0
	v_mov_b32_e32 v8, v0
	v_mov_b32_e32 v9, v0
	v_mov_b32_e32 v10, v0
	v_mov_b32_e32 v11, v0
	v_mov_b32_e32 v16, v0
	v_mov_b32_e32 v17, v0
	v_mov_b32_e32 v18, v0
	v_mov_b32_e32 v19, v0
	v_mov_b32_e32 v24, v0
	v_mov_b32_e32 v25, v0
	v_mov_b32_e32 v26, v0
	v_mov_b32_e32 v27, v0
	v_mov_b32_e32 v32, v0
	v_mov_b32_e32 v33, v0
	v_mov_b32_e32 v34, v0
	v_mov_b32_e32 v35, v0
	v_mov_b32_e32 v40, v0
	v_mov_b32_e32 v41, v0
	v_mov_b32_e32 v42, v0
	v_mov_b32_e32 v43, v0
	v_mov_b32_e32 v48, v0
	v_mov_b32_e32 v49, v0
	v_mov_b32_e32 v50, v0
	v_mov_b32_e32 v51, v0
	v_mov_b32_e32 v56, v0
	v_mov_b32_e32 v57, v0
	v_mov_b32_e32 v58, v0
	v_mov_b32_e32 v59, v0
	v_mov_b32_e32 v4, v0
	v_mov_b32_e32 v5, v0
	v_mov_b32_e32 v6, v0
	v_mov_b32_e32 v7, v0
	v_mov_b32_e32 v12, v0
	v_mov_b32_e32 v13, v0
	v_mov_b32_e32 v14, v0
	v_mov_b32_e32 v15, v0
	v_mov_b32_e32 v20, v0
	v_mov_b32_e32 v21, v0
	v_mov_b32_e32 v22, v0
	v_mov_b32_e32 v23, v0
	v_mov_b32_e32 v28, v0
	v_mov_b32_e32 v29, v0
	v_mov_b32_e32 v30, v0
	v_mov_b32_e32 v31, v0
	v_mov_b32_e32 v36, v0
	v_mov_b32_e32 v37, v0
	v_mov_b32_e32 v38, v0
	v_mov_b32_e32 v39, v0
	v_mov_b32_e32 v44, v0
	v_mov_b32_e32 v45, v0
	v_mov_b32_e32 v46, v0
	v_mov_b32_e32 v47, v0
	v_mov_b32_e32 v52, v0
	v_mov_b32_e32 v53, v0
	v_mov_b32_e32 v54, v0
	v_mov_b32_e32 v55, v0
	v_mov_b32_e32 v60, v0
	v_mov_b32_e32 v61, v0
	v_mov_b32_e32 v62, v0
	v_mov_b32_e32 v63, v0
	v_mov_b32_e32 v64, v0
	v_mov_b32_e32 v65, v0
	v_mov_b32_e32 v66, v0
	v_mov_b32_e32 v67, v0
	v_mov_b32_e32 v72, v0
	v_mov_b32_e32 v73, v0
	v_mov_b32_e32 v74, v0
	v_mov_b32_e32 v75, v0
	v_mov_b32_e32 v80, v0
	v_mov_b32_e32 v81, v0
	v_mov_b32_e32 v82, v0
	v_mov_b32_e32 v83, v0
	v_mov_b32_e32 v88, v0
	v_mov_b32_e32 v89, v0
	v_mov_b32_e32 v90, v0
	v_mov_b32_e32 v91, v0
	v_mov_b32_e32 v96, v0
	v_mov_b32_e32 v97, v0
	v_mov_b32_e32 v98, v0
	v_mov_b32_e32 v99, v0
	v_mov_b32_e32 v104, v0
	v_mov_b32_e32 v105, v0
	v_mov_b32_e32 v106, v0
	v_mov_b32_e32 v107, v0
	v_mov_b32_e32 v112, v0
	v_mov_b32_e32 v113, v0
	v_mov_b32_e32 v114, v0
	v_mov_b32_e32 v115, v0
	v_mov_b32_e32 v120, v0
	v_mov_b32_e32 v121, v0
	v_mov_b32_e32 v122, v0
	v_mov_b32_e32 v123, v0
	v_mov_b32_e32 v68, v0
	v_mov_b32_e32 v69, v0
	v_mov_b32_e32 v70, v0
	v_mov_b32_e32 v71, v0
	v_mov_b32_e32 v76, v0
	v_mov_b32_e32 v77, v0
	v_mov_b32_e32 v78, v0
	v_mov_b32_e32 v79, v0
	v_mov_b32_e32 v84, v0
	v_mov_b32_e32 v85, v0
	v_mov_b32_e32 v86, v0
	v_mov_b32_e32 v87, v0
	v_mov_b32_e32 v92, v0
	v_mov_b32_e32 v93, v0
	v_mov_b32_e32 v94, v0
	v_mov_b32_e32 v95, v0
	v_mov_b32_e32 v100, v0
	v_mov_b32_e32 v101, v0
	v_mov_b32_e32 v102, v0
	v_mov_b32_e32 v103, v0
	v_mov_b32_e32 v108, v0
	v_mov_b32_e32 v109, v0
	v_mov_b32_e32 v110, v0
	v_mov_b32_e32 v111, v0
	v_mov_b32_e32 v116, v0
	v_mov_b32_e32 v117, v0
	v_mov_b32_e32 v118, v0
	v_mov_b32_e32 v119, v0
	v_mov_b32_e32 v124, v0
	v_mov_b32_e32 v125, v0
	v_mov_b32_e32 v126, v0
	v_mov_b32_e32 v127, v0
	v_readfirstlane_b32 s100, v238
	s_cmp_lt_u32 s100, 0x100
	s_cbranch_scc1 .Lgp_1028
	s_setprio 1
; #define PG8_STAGE(bufoff, gbase, voff) do { _Pragma("unroll") for (int _i = 0; _i < 2; ++_i) \
;         __builtin_amdgcn_global_load_lds((const unsigned*)((const char*)(gbase) + (voff)[_i]), (LAS unsigned*)(lds + (bufoff) + ldsw + _i * 8192), 16, 0, 0); } while (0)
; #define PG8_LDA(dst, b, h) do { _Pragma("unroll") for (int m = 0; m < 4; ++m) _Pragma("unroll") for (int k = 0; k < 2; ++k) dst[m][k] = *(const LAS bf16x8*)(lds + PG8_SA(b, h) + aoff + m * 2048 + k * 1024); } while (0)
; #define PG8_LDB(dst, b, h) do { _Pragma("unroll") for (int n = 0; n < 2; ++n) _Pragma("unroll") for (int k = 0; k < 2; ++k) dst[n][k] = *(const LAS bf16x8*)(lds + PG8_SB(b, h) + boff + n * 2048 + k * 1024); } while (0)
; #define PG8_MMA(ai, bj, At, Bt) do { __builtin_amdgcn_s_setprio(1); _Pragma("unroll") for (int m = 0; m < 4; ++m) _Pragma("unroll") for (int n = 0; n < 2; ++n) _Pragma("unroll") for (int k = 0; k < 2; ++k) \
;         acc[ai][bj][m][n] = __builtin_amdgcn_mfma_f32_16x16x32_bf16(Bt[n][k], At[m][k], acc[ai][bj][m][n], 0, 0, 0); __builtin_amdgcn_s_setprio(0); } while (0)
; #define PG8_BAR __builtin_amdgcn_s_barrier()
; template <class Epi, bool ALIGN_EPI = PG8_ALIGN>
; __device__ __forceinline__ void gemm_phase(LAS unsigned char* lds, const Gemm g, const StaticOrder& S, const Epi& E) {
;     ...
;         const bool has_next = S.next(ui + 1, nxt);
;         const char* nA = has_next ? (const char*)g.A + (size_t)nxt.pm * tstepA : cA; const char* nB = has_next ? (const char*)g.Bt + (size_t)nxt.pn * tstepB : cB;
;         for (int t = 0; t < nt; t += 2) {
;             const bool last = (t == nt - 2);
;             const char* a1 = cA + (size_t)(t + 1) * kstep;
;             const char* a2 = last ? nA : cA + (size_t)(t + 2) * kstep; const char* b2 = last ? nB : cB + (size_t)(t + 2) * kstep;
;             const char* a3 = a2 + kstep; const char* b3 = b2 + kstep;
;             PG8_LDB(B0, 0, 0); PG8_LDB(B1, 0, 1); PG8_SCHED; PG8_LDA(At, 0, 0); PG8_STAGE(PG8_SA(1, 1), a1 + hstepA, voffA);
;             PG8_WAIT_V(8); PG8_WAIT_L(0); PG8_BAR; PG8_MMA(0, 0, At, B0); PG8_MMA(0, 1, At, B1); PG8_BAR; PG8_SCHED;
;             PG8_LDA(At, 0, 1); PG8_STAGE(PG8_SB(0, 0), b2, voffB); PG8_STAGE(PG8_SB(0, 1), b2 + hstepB, voffB); PG8_STAGE(PG8_SA(0, 0), a2, voffA);
;             PG8_WAIT_V(8); PG8_WAIT_L(0); PG8_BAR; PG8_MMA(1, 0, At, B0); PG8_MMA(1, 1, At, B1); PG8_BAR; PG8_SCHED;
.Lgp_1028:
.LBB0_1028:
	s_add_i32 s31, s24, 2
	s_add_u32 s20, s2, 0xfff80080
	s_addc_u32 s21, s3, -1
	s_add_i32 s22, 16, 0x10000
	s_cmp_eq_u32 s53, s24
	s_cselect_b32 s25, s17, s21
	s_cselect_b32 s24, s27, s20
	s_cselect_b32 s21, s39, s30
	s_cselect_b32 s20, s38, s29
	s_add_i32 s23, 16, 0x14000
	v_add_u32_e32 v140, s22, v220
	v_add_u32_e32 v156, s23, v220
	ds_read_b128 v[128:131], v140
	ds_read_b128 v[132:135], v140 offset:1024
	ds_read_b128 v[136:139], v140 offset:2048
	ds_read_b128 v[140:143], v140 offset:3072
	ds_read_b128 v[144:147], v156
	ds_read_b128 v[148:151], v156 offset:1024
	ds_read_b128 v[152:155], v156 offset:2048
	ds_read_b128 v[156:159], v156 offset:3072
	v_lshl_add_u64 v[180:181], s[2:3], 0, v[192:193]
	s_add_i32 m0, s47, 0xc000
	ds_read_b128 v[160:163], v223
	ds_read_b128 v[164:167], v223 offset:1024
	ds_read_b128 v[168:171], v223 offset:2048
	ds_read_b128 v[172:175], v223 offset:3072
	ds_read_b128 v[196:199], v223 offset:4096
	ds_read_b128 v[200:203], v223 offset:5120
	ds_read_b128 v[204:207], v223 offset:6144
	ds_read_b128 v[208:211], v223 offset:7168
	global_load_lds_dwordx4 v[180:181], off
	v_lshl_add_u64 v[180:181], s[2:3], 0, v[194:195]
	s_add_i32 m0, s47, 0xe000
	s_nop 0
	global_load_lds_dwordx4 v[180:181], off
	s_waitcnt vmcnt(8)
	s_waitcnt lgkmcnt(0)
	s_barrier
	s_waitcnt lgkmcnt(0)
	v_mfma_f32_16x16x32_bf16 v[124:127], v[128:131], v[160:163], v[124:127]
	v_mfma_f32_16x16x32_bf16 v[116:119], v[136:139], v[160:163], v[116:119]
	v_mfma_f32_16x16x32_bf16 v[108:111], v[128:131], v[168:171], v[108:111]
	v_mfma_f32_16x16x32_bf16 v[100:103], v[136:139], v[168:171], v[100:103]
	v_mfma_f32_16x16x32_bf16 v[92:95], v[128:131], v[196:199], v[92:95]
	v_mfma_f32_16x16x32_bf16 v[84:87], v[136:139], v[196:199], v[84:87]
	v_mfma_f32_16x16x32_bf16 v[76:79], v[128:131], v[204:207], v[76:79]
	v_mfma_f32_16x16x32_bf16 v[68:71], v[136:139], v[204:207], v[68:71]
	v_mfma_f32_16x16x32_bf16 v[124:127], v[132:135], v[164:167], v[124:127]
	v_mfma_f32_16x16x32_bf16 v[116:119], v[140:143], v[164:167], v[116:119]
	v_mfma_f32_16x16x32_bf16 v[108:111], v[132:135], v[172:175], v[108:111]
	v_mfma_f32_16x16x32_bf16 v[100:103], v[140:143], v[172:175], v[100:103]
	v_mfma_f32_16x16x32_bf16 v[92:95], v[132:135], v[200:203], v[92:95]
	v_mfma_f32_16x16x32_bf16 v[84:87], v[140:143], v[200:203], v[84:87]
	v_mfma_f32_16x16x32_bf16 v[76:79], v[132:135], v[208:211], v[76:79]
	v_mfma_f32_16x16x32_bf16 v[68:71], v[140:143], v[208:211], v[68:71]
	v_mfma_f32_16x16x32_bf16 v[120:123], v[144:147], v[160:163], v[120:123]
	v_mfma_f32_16x16x32_bf16 v[112:115], v[152:155], v[160:163], v[112:115]
	v_mfma_f32_16x16x32_bf16 v[104:107], v[144:147], v[168:171], v[104:107]
	v_mfma_f32_16x16x32_bf16 v[96:99], v[152:155], v[168:171], v[96:99]
	v_mfma_f32_16x16x32_bf16 v[88:91], v[144:147], v[196:199], v[88:91]
	v_mfma_f32_16x16x32_bf16 v[80:83], v[152:155], v[196:199], v[80:83]
	v_mfma_f32_16x16x32_bf16 v[72:75], v[144:147], v[204:207], v[72:75]
	v_mfma_f32_16x16x32_bf16 v[64:67], v[152:155], v[204:207], v[64:67]
	v_mfma_f32_16x16x32_bf16 v[120:123], v[148:151], v[164:167], v[120:123]
	v_mfma_f32_16x16x32_bf16 v[112:115], v[156:159], v[164:167], v[112:115]
	v_mfma_f32_16x16x32_bf16 v[104:107], v[148:151], v[172:175], v[104:107]
	v_mfma_f32_16x16x32_bf16 v[96:99], v[156:159], v[172:175], v[96:99]
	v_mfma_f32_16x16x32_bf16 v[88:91], v[148:151], v[200:203], v[88:91]
	v_mfma_f32_16x16x32_bf16 v[80:83], v[156:159], v[200:203], v[80:83]
	v_mfma_f32_16x16x32_bf16 v[72:75], v[148:151], v[208:211], v[72:75]
	v_mfma_f32_16x16x32_bf16 v[64:67], v[156:159], v[208:211], v[64:67]
	s_barrier
	s_add_i32 s22, s22, s46
	v_lshl_add_u64 v[180:181], s[20:21], 0, v[188:189]
	s_mov_b32 m0, s22
	ds_read_b128 v[160:163], v223 offset:16384
	ds_read_b128 v[164:167], v223 offset:17408
	ds_read_b128 v[168:171], v223 offset:18432
	ds_read_b128 v[172:175], v223 offset:19456
	ds_read_b128 v[196:199], v223 offset:20480
	ds_read_b128 v[200:203], v223 offset:21504
	ds_read_b128 v[204:207], v223 offset:22528
	ds_read_b128 v[208:211], v223 offset:23552
	global_load_lds_dwordx4 v[180:181], off
	s_add_i32 m0, s22, 0x2000
	v_lshl_add_u64 v[182:183], s[20:21], 0, v[184:185]
	s_add_u32 s20, s20, s4
	s_addc_u32 s21, s21, s5
	s_add_i32 s22, s23, s46
	global_load_lds_dwordx4 v[182:183], off
	v_lshl_add_u64 v[212:213], s[20:21], 0, v[188:189]
	s_mov_b32 m0, s22
	v_lshl_add_u64 v[214:215], s[20:21], 0, v[184:185]
	global_load_lds_dwordx4 v[212:213], off
	s_add_i32 m0, s22, 0x2000
	v_lshl_add_u64 v[216:217], s[24:25], 0, v[190:191]
	global_load_lds_dwordx4 v[214:215], off
	s_mov_b32 m0, s47
	v_lshl_add_u64 v[218:219], s[24:25], 0, v[186:187]
	global_load_lds_dwordx4 v[216:217], off
	s_mov_b32 m0, s48
	s_nop 0
	global_load_lds_dwordx4 v[218:219], off
	s_waitcnt vmcnt(8)
	s_waitcnt lgkmcnt(0)
	s_barrier
; #define PG8_STAGE(bufoff, gbase, voff) do { _Pragma("unroll") for (int _i = 0; _i < 2; ++_i) \
;         __builtin_amdgcn_global_load_lds((const unsigned*)((const char*)(gbase) + (voff)[_i]), (LAS unsigned*)(lds + (bufoff) + ldsw + _i * 8192), 16, 0, 0); } while (0)
; #define PG8_LDA(dst, b, h) do { _Pragma("unroll") for (int m = 0; m < 4; ++m) _Pragma("unroll") for (int k = 0; k < 2; ++k) dst[m][k] = *(const LAS bf16x8*)(lds + PG8_SA(b, h) + aoff + m * 2048 + k * 1024); } while (0)
; #define PG8_LDB(dst, b, h) do { _Pragma("unroll") for (int n = 0; n < 2; ++n) _Pragma("unroll") for (int k = 0; k < 2; ++k) dst[n][k] = *(const LAS bf16x8*)(lds + PG8_SB(b, h) + boff + n * 2048 + k * 1024); } while (0)
; #define PG8_MMA(ai, bj, At, Bt) do { __builtin_amdgcn_s_setprio(1); _Pragma("unroll") for (int m = 0; m < 4; ++m) _Pragma("unroll") for (int n = 0; n < 2; ++n) _Pragma("unroll") for (int k = 0; k < 2; ++k) \
;         acc[ai][bj][m][n] = __builtin_amdgcn_mfma_f32_16x16x32_bf16(Bt[n][k], At[m][k], acc[ai][bj][m][n], 0, 0, 0); __builtin_amdgcn_s_setprio(0); } while (0)
; #define PG8_WAIT_V(n) asm volatile("s_waitcnt vmcnt(" #n ")" ::: "memory")
; #define PG8_WAIT_L(n) asm volatile("s_waitcnt lgkmcnt(" #n ")" ::: "memory")
; #define PG8_BAR __builtin_amdgcn_s_barrier()
; #define PG8_SCHED __builtin_amdgcn_sched_barrier(0)
; template <class Epi, bool ALIGN_EPI = PG8_ALIGN>
; __device__ __forceinline__ void gemm_phase(LAS unsigned char* lds, const Gemm g, const StaticOrder& S, const Epi& E) {
;     ...
;             PG8_WAIT_V(8); PG8_WAIT_L(0); PG8_BAR; PG8_MMA(1, 0, At, B0); PG8_MMA(1, 1, At, B1); PG8_BAR; PG8_SCHED;
;             PG8_LDB(B0, 1, 0); PG8_LDB(B1, 1, 1); PG8_SCHED; PG8_LDA(At, 1, 0); PG8_STAGE(PG8_SA(0, 1), a2 + hstepA, voffA);
;             PG8_WAIT_V(8); PG8_WAIT_L(0); PG8_BAR; PG8_MMA(0, 0, At, B0); PG8_MMA(0, 1, At, B1); PG8_BAR; PG8_SCHED;
	s_waitcnt lgkmcnt(0)
	v_mfma_f32_16x16x32_bf16 v[60:63], v[128:131], v[160:163], v[60:63]
	v_mfma_f32_16x16x32_bf16 v[52:55], v[136:139], v[160:163], v[52:55]
	v_mfma_f32_16x16x32_bf16 v[44:47], v[128:131], v[168:171], v[44:47]
	v_mfma_f32_16x16x32_bf16 v[36:39], v[136:139], v[168:171], v[36:39]
	v_mfma_f32_16x16x32_bf16 v[28:31], v[128:131], v[196:199], v[28:31]
	v_mfma_f32_16x16x32_bf16 v[20:23], v[136:139], v[196:199], v[20:23]
	v_mfma_f32_16x16x32_bf16 v[12:15], v[128:131], v[204:207], v[12:15]
	v_mfma_f32_16x16x32_bf16 v[4:7], v[136:139], v[204:207], v[4:7]
	v_mfma_f32_16x16x32_bf16 v[60:63], v[132:135], v[164:167], v[60:63]
	v_mfma_f32_16x16x32_bf16 v[52:55], v[140:143], v[164:167], v[52:55]
	v_mfma_f32_16x16x32_bf16 v[44:47], v[132:135], v[172:175], v[44:47]
	v_mfma_f32_16x16x32_bf16 v[36:39], v[140:143], v[172:175], v[36:39]
	v_mfma_f32_16x16x32_bf16 v[28:31], v[132:135], v[200:203], v[28:31]
	v_mfma_f32_16x16x32_bf16 v[20:23], v[140:143], v[200:203], v[20:23]
	v_mfma_f32_16x16x32_bf16 v[12:15], v[132:135], v[208:211], v[12:15]
	v_mfma_f32_16x16x32_bf16 v[4:7], v[140:143], v[208:211], v[4:7]
	v_mfma_f32_16x16x32_bf16 v[56:59], v[144:147], v[160:163], v[56:59]
	v_mfma_f32_16x16x32_bf16 v[48:51], v[152:155], v[160:163], v[48:51]
	v_mfma_f32_16x16x32_bf16 v[40:43], v[144:147], v[168:171], v[40:43]
	v_mfma_f32_16x16x32_bf16 v[32:35], v[152:155], v[168:171], v[32:35]
	v_mfma_f32_16x16x32_bf16 v[24:27], v[144:147], v[196:199], v[24:27]
	v_mfma_f32_16x16x32_bf16 v[16:19], v[152:155], v[196:199], v[16:19]
	v_mfma_f32_16x16x32_bf16 v[8:11], v[144:147], v[204:207], v[8:11]
	v_mfma_f32_16x16x32_bf16 v[0:3], v[152:155], v[204:207], v[0:3]
	v_mfma_f32_16x16x32_bf16 v[56:59], v[148:151], v[164:167], v[56:59]
	v_mfma_f32_16x16x32_bf16 v[48:51], v[156:159], v[164:167], v[48:51]
	v_mfma_f32_16x16x32_bf16 v[40:43], v[148:151], v[172:175], v[40:43]
	v_mfma_f32_16x16x32_bf16 v[32:35], v[156:159], v[172:175], v[32:35]
	v_mfma_f32_16x16x32_bf16 v[24:27], v[148:151], v[200:203], v[24:27]
	v_mfma_f32_16x16x32_bf16 v[16:19], v[156:159], v[200:203], v[16:19]
	v_mfma_f32_16x16x32_bf16 v[8:11], v[148:151], v[208:211], v[8:11]
	v_mfma_f32_16x16x32_bf16 v[0:3], v[156:159], v[208:211], v[0:3]
	s_barrier
	s_add_i32 s22, 16, 0x18000
	s_add_i32 s23, 16, 0x1c000
	v_add_u32_e32 v140, s22, v220
	v_add_u32_e32 v156, s23, v220
	ds_read_b128 v[128:131], v140
	ds_read_b128 v[132:135], v140 offset:1024
	ds_read_b128 v[136:139], v140 offset:2048
	ds_read_b128 v[140:143], v140 offset:3072
	ds_read_b128 v[144:147], v156
	ds_read_b128 v[148:151], v156 offset:1024
	ds_read_b128 v[152:155], v156 offset:2048
	ds_read_b128 v[156:159], v156 offset:3072
	s_add_u32 s20, s24, 0x80000
	s_addc_u32 s21, s25, 0
	s_mov_b32 m0, s49
	v_lshl_add_u64 v[224:225], s[20:21], 0, v[190:191]
	ds_read_b128 v[160:163], v223 offset:32768
	ds_read_b128 v[164:167], v223 offset:33792
	ds_read_b128 v[168:171], v223 offset:34816
	ds_read_b128 v[172:175], v223 offset:35840
	ds_read_b128 v[196:199], v223 offset:36864
	ds_read_b128 v[200:203], v223 offset:37888
	ds_read_b128 v[204:207], v223 offset:38912
	ds_read_b128 v[208:211], v223 offset:39936
	global_load_lds_dwordx4 v[224:225], off
	v_lshl_add_u64 v[224:225], s[20:21], 0, v[186:187]
	s_mov_b32 m0, s50
	s_nop 0
	global_load_lds_dwordx4 v[224:225], off
	s_waitcnt vmcnt(8)
	s_waitcnt lgkmcnt(0)
	s_barrier
	s_waitcnt lgkmcnt(0)
	v_mfma_f32_16x16x32_bf16 v[124:127], v[128:131], v[160:163], v[124:127]
	v_mfma_f32_16x16x32_bf16 v[116:119], v[136:139], v[160:163], v[116:119]
	v_mfma_f32_16x16x32_bf16 v[108:111], v[128:131], v[168:171], v[108:111]
	v_mfma_f32_16x16x32_bf16 v[100:103], v[136:139], v[168:171], v[100:103]
	v_mfma_f32_16x16x32_bf16 v[92:95], v[128:131], v[196:199], v[92:95]
	v_mfma_f32_16x16x32_bf16 v[84:87], v[136:139], v[196:199], v[84:87]
	v_mfma_f32_16x16x32_bf16 v[76:79], v[128:131], v[204:207], v[76:79]
	v_mfma_f32_16x16x32_bf16 v[68:71], v[136:139], v[204:207], v[68:71]
	v_mfma_f32_16x16x32_bf16 v[124:127], v[132:135], v[164:167], v[124:127]
	v_mfma_f32_16x16x32_bf16 v[116:119], v[140:143], v[164:167], v[116:119]
	v_mfma_f32_16x16x32_bf16 v[108:111], v[132:135], v[172:175], v[108:111]
	v_mfma_f32_16x16x32_bf16 v[100:103], v[140:143], v[172:175], v[100:103]
	v_mfma_f32_16x16x32_bf16 v[92:95], v[132:135], v[200:203], v[92:95]
	v_mfma_f32_16x16x32_bf16 v[84:87], v[140:143], v[200:203], v[84:87]
	v_mfma_f32_16x16x32_bf16 v[76:79], v[132:135], v[208:211], v[76:79]
	v_mfma_f32_16x16x32_bf16 v[68:71], v[140:143], v[208:211], v[68:71]
	v_mfma_f32_16x16x32_bf16 v[120:123], v[144:147], v[160:163], v[120:123]
	v_mfma_f32_16x16x32_bf16 v[112:115], v[152:155], v[160:163], v[112:115]
	v_mfma_f32_16x16x32_bf16 v[104:107], v[144:147], v[168:171], v[104:107]
	v_mfma_f32_16x16x32_bf16 v[96:99], v[152:155], v[168:171], v[96:99]
	v_mfma_f32_16x16x32_bf16 v[88:91], v[144:147], v[196:199], v[88:91]
	v_mfma_f32_16x16x32_bf16 v[80:83], v[152:155], v[196:199], v[80:83]
	v_mfma_f32_16x16x32_bf16 v[72:75], v[144:147], v[204:207], v[72:75]
	v_mfma_f32_16x16x32_bf16 v[64:67], v[152:155], v[204:207], v[64:67]
	v_mfma_f32_16x16x32_bf16 v[120:123], v[148:151], v[164:167], v[120:123]
	v_mfma_f32_16x16x32_bf16 v[112:115], v[156:159], v[164:167], v[112:115]
	v_mfma_f32_16x16x32_bf16 v[104:107], v[148:151], v[172:175], v[104:107]
	v_mfma_f32_16x16x32_bf16 v[96:99], v[156:159], v[172:175], v[96:99]
	v_mfma_f32_16x16x32_bf16 v[88:91], v[148:151], v[200:203], v[88:91]
	v_mfma_f32_16x16x32_bf16 v[80:83], v[156:159], v[200:203], v[80:83]
	v_mfma_f32_16x16x32_bf16 v[72:75], v[148:151], v[208:211], v[72:75]
	v_mfma_f32_16x16x32_bf16 v[64:67], v[156:159], v[208:211], v[64:67]
	s_barrier
; #define PG8_STAGE(bufoff, gbase, voff) do { _Pragma("unroll") for (int _i = 0; _i < 2; ++_i) \
;         __builtin_amdgcn_global_load_lds((const unsigned*)((const char*)(gbase) + (voff)[_i]), (LAS unsigned*)(lds + (bufoff) + ldsw + _i * 8192), 16, 0, 0); } while (0)
; #define PG8_LDA(dst, b, h) do { _Pragma("unroll") for (int m = 0; m < 4; ++m) _Pragma("unroll") for (int k = 0; k < 2; ++k) dst[m][k] = *(const LAS bf16x8*)(lds + PG8_SA(b, h) + aoff + m * 2048 + k * 1024); } while (0)
; #define PG8_MMA(ai, bj, At, Bt) do { __builtin_amdgcn_s_setprio(1); _Pragma("unroll") for (int m = 0; m < 4; ++m) _Pragma("unroll") for (int n = 0; n < 2; ++n) _Pragma("unroll") for (int k = 0; k < 2; ++k) \
;         acc[ai][bj][m][n] = __builtin_amdgcn_mfma_f32_16x16x32_bf16(Bt[n][k], At[m][k], acc[ai][bj][m][n], 0, 0, 0); __builtin_amdgcn_s_setprio(0); } while (0)
; #define PG8_WAIT_V(n) asm volatile("s_waitcnt vmcnt(" #n ")" ::: "memory")
; #define PG8_WAIT_L(n) asm volatile("s_waitcnt lgkmcnt(" #n ")" ::: "memory")
; #define PG8_BAR __builtin_amdgcn_s_barrier()
; #define PG8_SCHED __builtin_amdgcn_sched_barrier(0)
; template <class Epi, bool ALIGN_EPI = PG8_ALIGN>
; __device__ __forceinline__ void gemm_phase(LAS unsigned char* lds, const Gemm g, const StaticOrder& S, const Epi& E) {
;     ...
;             PG8_LDA(At, 1, 1); PG8_STAGE(PG8_SB(1, 0), b3, voffB); PG8_STAGE(PG8_SB(1, 1), b3 + hstepB, voffB); PG8_STAGE(PG8_SA(1, 0), a3, voffA);
;             PG8_WAIT_V(8); PG8_WAIT_L(0); PG8_BAR; PG8_MMA(1, 0, At, B0); PG8_MMA(1, 1, At, B1); PG8_BAR; PG8_SCHED;
;         }
	s_add_i32 s20, s22, s46
	v_lshl_add_u64 v[180:181], v[180:181], 0, s[0:1]
	s_mov_b32 m0, s20
	ds_read_b128 v[160:163], v223 offset:49152
	ds_read_b128 v[164:167], v223 offset:50176
	ds_read_b128 v[168:171], v223 offset:51200
	ds_read_b128 v[172:175], v223 offset:52224
	ds_read_b128 v[196:199], v223 offset:53248
	ds_read_b128 v[200:203], v223 offset:54272
	ds_read_b128 v[204:207], v223 offset:55296
	ds_read_b128 v[208:211], v223 offset:56320
	global_load_lds_dwordx4 v[180:181], off
	v_lshl_add_u64 v[180:181], v[182:183], 0, s[0:1]
	s_add_i32 m0, s20, 0x2000
	s_add_i32 s20, s23, s46
	global_load_lds_dwordx4 v[180:181], off
	v_lshl_add_u64 v[180:181], v[212:213], 0, s[0:1]
	s_mov_b32 m0, s20
	s_nop 0
	global_load_lds_dwordx4 v[180:181], off
	v_lshl_add_u64 v[180:181], v[214:215], 0, s[0:1]
	s_add_i32 m0, s20, 0x2000
	s_nop 0
	global_load_lds_dwordx4 v[180:181], off
	v_lshl_add_u64 v[180:181], v[216:217], 0, s[0:1]
	s_mov_b32 m0, s18
	s_nop 0
	global_load_lds_dwordx4 v[180:181], off
	v_lshl_add_u64 v[180:181], v[218:219], 0, s[0:1]
	s_mov_b32 m0, s51
	s_nop 0
	global_load_lds_dwordx4 v[180:181], off
	s_waitcnt vmcnt(8)
	s_waitcnt lgkmcnt(0)
	s_barrier
	s_waitcnt lgkmcnt(0)
	v_mfma_f32_16x16x32_bf16 v[60:63], v[128:131], v[160:163], v[60:63]
	v_mfma_f32_16x16x32_bf16 v[52:55], v[136:139], v[160:163], v[52:55]
	v_mfma_f32_16x16x32_bf16 v[44:47], v[128:131], v[168:171], v[44:47]
	v_mfma_f32_16x16x32_bf16 v[36:39], v[136:139], v[168:171], v[36:39]
	v_mfma_f32_16x16x32_bf16 v[28:31], v[128:131], v[196:199], v[28:31]
	v_mfma_f32_16x16x32_bf16 v[20:23], v[136:139], v[196:199], v[20:23]
	v_mfma_f32_16x16x32_bf16 v[12:15], v[128:131], v[204:207], v[12:15]
	v_mfma_f32_16x16x32_bf16 v[4:7], v[136:139], v[204:207], v[4:7]
	v_mfma_f32_16x16x32_bf16 v[60:63], v[132:135], v[164:167], v[60:63]
	v_mfma_f32_16x16x32_bf16 v[52:55], v[140:143], v[164:167], v[52:55]
	v_mfma_f32_16x16x32_bf16 v[44:47], v[132:135], v[172:175], v[44:47]
	v_mfma_f32_16x16x32_bf16 v[36:39], v[140:143], v[172:175], v[36:39]
	v_mfma_f32_16x16x32_bf16 v[28:31], v[132:135], v[200:203], v[28:31]
	v_mfma_f32_16x16x32_bf16 v[20:23], v[140:143], v[200:203], v[20:23]
	v_mfma_f32_16x16x32_bf16 v[12:15], v[132:135], v[208:211], v[12:15]
	v_mfma_f32_16x16x32_bf16 v[4:7], v[140:143], v[208:211], v[4:7]
	v_mfma_f32_16x16x32_bf16 v[56:59], v[144:147], v[160:163], v[56:59]
	v_mfma_f32_16x16x32_bf16 v[48:51], v[152:155], v[160:163], v[48:51]
	v_mfma_f32_16x16x32_bf16 v[40:43], v[144:147], v[168:171], v[40:43]
	v_mfma_f32_16x16x32_bf16 v[32:35], v[152:155], v[168:171], v[32:35]
	v_mfma_f32_16x16x32_bf16 v[24:27], v[144:147], v[196:199], v[24:27]
	v_mfma_f32_16x16x32_bf16 v[16:19], v[152:155], v[196:199], v[16:19]
	v_mfma_f32_16x16x32_bf16 v[8:11], v[144:147], v[204:207], v[8:11]
	v_mfma_f32_16x16x32_bf16 v[0:3], v[152:155], v[204:207], v[0:3]
	v_mfma_f32_16x16x32_bf16 v[56:59], v[148:151], v[164:167], v[56:59]
	v_mfma_f32_16x16x32_bf16 v[48:51], v[156:159], v[164:167], v[48:51]
	v_mfma_f32_16x16x32_bf16 v[40:43], v[148:151], v[172:175], v[40:43]
	v_mfma_f32_16x16x32_bf16 v[32:35], v[156:159], v[172:175], v[32:35]
	v_mfma_f32_16x16x32_bf16 v[24:27], v[148:151], v[200:203], v[24:27]
	v_mfma_f32_16x16x32_bf16 v[16:19], v[156:159], v[200:203], v[16:19]
	v_mfma_f32_16x16x32_bf16 v[8:11], v[148:151], v[208:211], v[8:11]
	v_mfma_f32_16x16x32_bf16 v[0:3], v[156:159], v[208:211], v[0:3]
	s_barrier
	s_add_u32 s2, s2, 0x100
	s_addc_u32 s3, s3, 0
	s_add_u32 s29, s29, 0x100
	s_addc_u32 s30, s30, 0
	s_cmp_ge_i32 s31, s52
	s_mov_b32 s24, s31
	s_cbranch_scc0 .LBB0_1028
	s_setprio 0

; #define PG8_STAGE(bufoff, gbase, voff) do { _Pragma("unroll") for (int _i = 0; _i < 2; ++_i) \
;         __builtin_amdgcn_global_load_lds((const unsigned*)((const char*)(gbase) + (voff)[_i]), (LAS unsigned*)(lds + (bufoff) + ldsw + _i * 8192), 16, 0, 0); } while (0)
; #define PG8_WAIT_V(n) asm volatile("s_waitcnt vmcnt(" #n ")" ::: "memory")
; #define PG8_BAR __builtin_amdgcn_s_barrier()
; template <class Epi, bool ALIGN_EPI = PG8_ALIGN>
; __device__ __forceinline__ void gemm_phase(LAS unsigned char* lds, const Gemm g, const StaticOrder& S, const Epi& E) {
;     ...
;     f32x4 acc[2][2][4][2];
; #pragma unroll
;     for (int a = 0; a < 2; ++a)
; #pragma unroll
;         for (int b = 0; b < 2; ++b)
; #pragma unroll
;             for (int m = 0; m < 4; ++m)
; #pragma unroll
;                 for (int n = 0; n < 2; ++n) acc[a][b][m][n] = (f32x4){0.f, 0.f, 0.f, 0.f};
;     bf16x8 At[4][2], B0[2][2], B1[2][2];
;     const char* cA = (const char*)g.A + (size_t)cur.pm * tstepA; const char* cB = (const char*)g.Bt + (size_t)cur.pn * tstepB;
;     PG8_STAGE(PG8_SB(0, 0), cB, voffB); PG8_STAGE(PG8_SB(0, 1), cB + hstepB, voffB); PG8_STAGE(PG8_SA(0, 0), cA, voffA); PG8_STAGE(PG8_SA(0, 1), cA + hstepA, voffA);
;     if (wr == 1) PG8_BAR;
;     PG8_WAIT_V(2); PG8_BAR;
;     PG8_STAGE(PG8_SB(1, 0), cB + kstep, voffB); PG8_STAGE(PG8_SA(1, 0), cA + kstep, voffA); PG8_STAGE(PG8_SB(1, 1), cB + hstepB + kstep, voffB);
;     PG8_WAIT_V(6); PG8_BAR;
;     for (;;) {
;         const bool has_next = S.next(ui + 1, nxt);
;         const char* nA = has_next ? (const char*)g.A + (size_t)nxt.pm * tstepA : cA; const char* nB = has_next ? (const char*)g.Bt + (size_t)nxt.pn * tstepB : cB;
.LBB0_1106:
	v_mov_b32_e32 v127, 0
	s_andn2_b64 vcc, exec, s[12:13]
	v_mov_b32_e32 v126, 0
	v_mov_b32_e32 v125, 0
	v_mov_b32_e32 v124, 0
	v_mov_b32_e32 v123, 0
	v_mov_b32_e32 v122, 0
	v_mov_b32_e32 v121, 0
	v_mov_b32_e32 v120, 0
	v_mov_b32_e32 v101, 0
	v_mov_b32_e32 v100, 0
	v_mov_b32_e32 v103, 0
	v_mov_b32_e32 v102, 0
	v_mov_b32_e32 v109, 0
	v_mov_b32_e32 v108, 0
	v_mov_b32_e32 v111, 0
	v_mov_b32_e32 v110, 0
	v_mov_b32_e32 v85, 0
	v_mov_b32_e32 v84, 0
	v_mov_b32_e32 v87, 0
	v_mov_b32_e32 v86, 0
	v_mov_b32_e32 v93, 0
	v_mov_b32_e32 v92, 0
	v_mov_b32_e32 v95, 0
	v_mov_b32_e32 v94, 0
	v_mov_b32_e32 v73, 0
	v_mov_b32_e32 v72, 0
	v_mov_b32_e32 v75, 0
	v_mov_b32_e32 v74, 0
	v_mov_b32_e32 v77, 0
	v_mov_b32_e32 v76, 0
	v_mov_b32_e32 v79, 0
	v_mov_b32_e32 v78, 0
	v_mov_b32_e32 v139, 0
	v_mov_b32_e32 v138, 0
	v_mov_b32_e32 v141, 0
	v_mov_b32_e32 v140, 0
	v_mov_b32_e32 v143, 0
	v_mov_b32_e32 v142, 0
	v_mov_b32_e32 v145, 0
	v_mov_b32_e32 v144, 0
	v_mov_b32_e32 v113, 0
	v_mov_b32_e32 v112, 0
	v_mov_b32_e32 v115, 0
	v_mov_b32_e32 v114, 0
	v_mov_b32_e32 v117, 0
	v_mov_b32_e32 v116, 0
	v_mov_b32_e32 v119, 0
	v_mov_b32_e32 v118, 0
	v_mov_b32_e32 v97, 0
	v_mov_b32_e32 v96, 0
	v_mov_b32_e32 v99, 0
	v_mov_b32_e32 v98, 0
	v_mov_b32_e32 v105, 0
	v_mov_b32_e32 v104, 0
	v_mov_b32_e32 v107, 0
	v_mov_b32_e32 v106, 0
	v_mov_b32_e32 v71, 0
	v_mov_b32_e32 v70, 0
	v_mov_b32_e32 v69, 0
	v_mov_b32_e32 v68, 0
	v_mov_b32_e32 v67, 0
	v_mov_b32_e32 v66, 0
	v_mov_b32_e32 v65, 0
	v_mov_b32_e32 v64, 0
	v_mov_b32_e32 v63, 0
	v_mov_b32_e32 v62, 0
	v_mov_b32_e32 v61, 0
	v_mov_b32_e32 v60, 0
	v_mov_b32_e32 v59, 0
	v_mov_b32_e32 v58, 0
	v_mov_b32_e32 v57, 0
	v_mov_b32_e32 v56, 0
	v_mov_b32_e32 v37, 0
	v_mov_b32_e32 v36, 0
	v_mov_b32_e32 v39, 0
	v_mov_b32_e32 v38, 0
	v_mov_b32_e32 v45, 0
	v_mov_b32_e32 v44, 0
	v_mov_b32_e32 v47, 0
	v_mov_b32_e32 v46, 0
	v_mov_b32_e32 v21, 0
	v_mov_b32_e32 v20, 0
	v_mov_b32_e32 v23, 0
	v_mov_b32_e32 v22, 0
	v_mov_b32_e32 v29, 0
	v_mov_b32_e32 v28, 0
	v_mov_b32_e32 v31, 0
	v_mov_b32_e32 v30, 0
	v_mov_b32_e32 v9, 0
	v_mov_b32_e32 v8, 0
	v_mov_b32_e32 v11, 0
	v_mov_b32_e32 v10, 0
	v_mov_b32_e32 v13, 0
	v_mov_b32_e32 v12, 0
	v_mov_b32_e32 v15, 0
	v_mov_b32_e32 v14, 0
	v_mov_b32_e32 v81, 0
	v_mov_b32_e32 v80, 0
	v_mov_b32_e32 v83, 0
	v_mov_b32_e32 v82, 0
	v_mov_b32_e32 v89, 0
	v_mov_b32_e32 v88, 0
	v_mov_b32_e32 v91, 0
	v_mov_b32_e32 v90, 0
	v_mov_b32_e32 v49, 0
	v_mov_b32_e32 v48, 0
	v_mov_b32_e32 v51, 0
	v_mov_b32_e32 v50, 0
	v_mov_b32_e32 v53, 0
	v_mov_b32_e32 v52, 0
	v_mov_b32_e32 v55, 0
	v_mov_b32_e32 v54, 0
	v_mov_b32_e32 v33, 0
	v_mov_b32_e32 v32, 0
	v_mov_b32_e32 v35, 0
	v_mov_b32_e32 v34, 0
	v_mov_b32_e32 v41, 0
	v_mov_b32_e32 v40, 0
	v_mov_b32_e32 v43, 0
	v_mov_b32_e32 v42, 0
	v_mov_b32_e32 v7, 0
	v_mov_b32_e32 v6, 0
	v_mov_b32_e32 v5, 0
	v_mov_b32_e32 v4, 0
	v_mov_b32_e32 v3, 0
	v_mov_b32_e32 v2, 0
	v_mov_b32_e32 v1, 0
	v_mov_b32_e32 v0, 0
	s_cbranch_vccnz .LBB0_1110
	s_add_u32 s51, s36, 0x100
	v_mov_b32_e32 v0, 0
	s_addc_u32 s52, s37, 0
	s_mov_b32 s40, 0
	v_mov_b32_e32 v1, v0
	v_mov_b32_e32 v2, v0
	v_mov_b32_e32 v3, v0
	v_mov_b32_e32 v4, v0
	v_mov_b32_e32 v5, v0
	v_mov_b32_e32 v6, v0
	v_mov_b32_e32 v7, v0
	v_mov_b32_e32 v8, v0
	v_mov_b32_e32 v9, v0
	v_mov_b32_e32 v10, v0
	v_mov_b32_e32 v11, v0
	v_mov_b32_e32 v12, v0
	v_mov_b32_e32 v13, v0
	v_mov_b32_e32 v14, v0
	v_mov_b32_e32 v15, v0
	v_mov_b32_e32 v20, v0
	v_mov_b32_e32 v21, v0
	v_mov_b32_e32 v22, v0
	v_mov_b32_e32 v23, v0
	v_mov_b32_e32 v28, v0
	v_mov_b32_e32 v29, v0
	v_mov_b32_e32 v30, v0
	v_mov_b32_e32 v31, v0
	v_mov_b32_e32 v36, v0
	v_mov_b32_e32 v37, v0
	v_mov_b32_e32 v38, v0
	v_mov_b32_e32 v39, v0
	v_mov_b32_e32 v44, v0
	v_mov_b32_e32 v45, v0
	v_mov_b32_e32 v46, v0
	v_mov_b32_e32 v47, v0
	v_mov_b32_e32 v16, v0
	v_mov_b32_e32 v17, v0
	v_mov_b32_e32 v18, v0
	v_mov_b32_e32 v19, v0
	v_mov_b32_e32 v24, v0
	v_mov_b32_e32 v25, v0
	v_mov_b32_e32 v26, v0
	v_mov_b32_e32 v27, v0
	v_mov_b32_e32 v32, v0
	v_mov_b32_e32 v33, v0
	v_mov_b32_e32 v34, v0
	v_mov_b32_e32 v35, v0
	v_mov_b32_e32 v40, v0
	v_mov_b32_e32 v41, v0
	v_mov_b32_e32 v42, v0
	v_mov_b32_e32 v43, v0
	v_mov_b32_e32 v48, v0
	v_mov_b32_e32 v49, v0
	v_mov_b32_e32 v50, v0
	v_mov_b32_e32 v51, v0
	v_mov_b32_e32 v52, v0
	v_mov_b32_e32 v53, v0
	v_mov_b32_e32 v54, v0
	v_mov_b32_e32 v55, v0
	v_mov_b32_e32 v56, v0
	v_mov_b32_e32 v57, v0
	v_mov_b32_e32 v58, v0
	v_mov_b32_e32 v59, v0
	v_mov_b32_e32 v60, v0
	v_mov_b32_e32 v61, v0
	v_mov_b32_e32 v62, v0
	v_mov_b32_e32 v63, v0
	v_mov_b32_e32 v64, v0
	v_mov_b32_e32 v65, v0
	v_mov_b32_e32 v66, v0
	v_mov_b32_e32 v67, v0
	v_mov_b32_e32 v68, v0
	v_mov_b32_e32 v69, v0
	v_mov_b32_e32 v70, v0
	v_mov_b32_e32 v71, v0
	v_mov_b32_e32 v72, v0
	v_mov_b32_e32 v73, v0
	v_mov_b32_e32 v74, v0
	v_mov_b32_e32 v75, v0
	v_mov_b32_e32 v76, v0
	v_mov_b32_e32 v77, v0
	v_mov_b32_e32 v78, v0
	v_mov_b32_e32 v79, v0
	v_mov_b32_e32 v84, v0
	v_mov_b32_e32 v85, v0
	v_mov_b32_e32 v86, v0
	v_mov_b32_e32 v87, v0
	v_mov_b32_e32 v92, v0
	v_mov_b32_e32 v93, v0
	v_mov_b32_e32 v94, v0
	v_mov_b32_e32 v95, v0
	v_mov_b32_e32 v100, v0
	v_mov_b32_e32 v101, v0
	v_mov_b32_e32 v102, v0
	v_mov_b32_e32 v103, v0
	v_mov_b32_e32 v108, v0
	v_mov_b32_e32 v109, v0
	v_mov_b32_e32 v110, v0
	v_mov_b32_e32 v111, v0
	v_mov_b32_e32 v80, v0
	v_mov_b32_e32 v81, v0
	v_mov_b32_e32 v82, v0
	v_mov_b32_e32 v83, v0
	v_mov_b32_e32 v88, v0
	v_mov_b32_e32 v89, v0
	v_mov_b32_e32 v90, v0
	v_mov_b32_e32 v91, v0
	v_mov_b32_e32 v96, v0
	v_mov_b32_e32 v97, v0
	v_mov_b32_e32 v98, v0
	v_mov_b32_e32 v99, v0
	v_mov_b32_e32 v104, v0
	v_mov_b32_e32 v105, v0
	v_mov_b32_e32 v106, v0
	v_mov_b32_e32 v107, v0
	v_mov_b32_e32 v112, v0
	v_mov_b32_e32 v113, v0
	v_mov_b32_e32 v114, v0
	v_mov_b32_e32 v115, v0
	v_mov_b32_e32 v116, v0
	v_mov_b32_e32 v117, v0
	v_mov_b32_e32 v118, v0
	v_mov_b32_e32 v119, v0
	v_mov_b32_e32 v120, v0
	v_mov_b32_e32 v121, v0
	v_mov_b32_e32 v122, v0
	v_mov_b32_e32 v123, v0
	v_mov_b32_e32 v124, v0
	v_mov_b32_e32 v125, v0
	v_mov_b32_e32 v126, v0
	v_mov_b32_e32 v127, v0
	v_readfirstlane_b32 s100, v238
	s_cmp_lt_u32 s100, 0x100
	s_cbranch_scc1 .Lgp_1108
	s_setprio 1
; #define PG8_STAGE(bufoff, gbase, voff) do { _Pragma("unroll") for (int _i = 0; _i < 2; ++_i) \
;         __builtin_amdgcn_global_load_lds((const unsigned*)((const char*)(gbase) + (voff)[_i]), (LAS unsigned*)(lds + (bufoff) + ldsw + _i * 8192), 16, 0, 0); } while (0)
; #define PG8_LDA(dst, b, h) do { _Pragma("unroll") for (int m = 0; m < 4; ++m) _Pragma("unroll") for (int k = 0; k < 2; ++k) dst[m][k] = *(const LAS bf16x8*)(lds + PG8_SA(b, h) + aoff + m * 2048 + k * 1024); } while (0)
; #define PG8_LDB(dst, b, h) do { _Pragma("unroll") for (int n = 0; n < 2; ++n) _Pragma("unroll") for (int k = 0; k < 2; ++k) dst[n][k] = *(const LAS bf16x8*)(lds + PG8_SB(b, h) + boff + n * 2048 + k * 1024); } while (0)
; #define PG8_MMA(ai, bj, At, Bt) do { __builtin_amdgcn_s_setprio(1); _Pragma("unroll") for (int m = 0; m < 4; ++m) _Pragma("unroll") for (int n = 0; n < 2; ++n) _Pragma("unroll") for (int k = 0; k < 2; ++k) \
;         acc[ai][bj][m][n] = __builtin_amdgcn_mfma_f32_16x16x32_bf16(Bt[n][k], At[m][k], acc[ai][bj][m][n], 0, 0, 0); __builtin_amdgcn_s_setprio(0); } while (0)
; #define PG8_BAR __builtin_amdgcn_s_barrier()
; template <class Epi, bool ALIGN_EPI = PG8_ALIGN>
; __device__ __forceinline__ void gemm_phase(LAS unsigned char* lds, const Gemm g, const StaticOrder& S, const Epi& E) {
;     ...
;         const bool has_next = S.next(ui + 1, nxt);
;         const char* nA = has_next ? (const char*)g.A + (size_t)nxt.pm * tstepA : cA; const char* nB = has_next ? (const char*)g.Bt + (size_t)nxt.pn * tstepB : cB;
;         for (int t = 0; t < nt; t += 2) {
;             const bool last = (t == nt - 2);
;             const char* a1 = cA + (size_t)(t + 1) * kstep;
;             const char* a2 = last ? nA : cA + (size_t)(t + 2) * kstep; const char* b2 = last ? nB : cB + (size_t)(t + 2) * kstep;
;             const char* a3 = a2 + kstep; const char* b3 = b2 + kstep;
;             PG8_LDB(B0, 0, 0); PG8_LDB(B1, 0, 1); PG8_SCHED; PG8_LDA(At, 0, 0); PG8_STAGE(PG8_SA(1, 1), a1 + hstepA, voffA);
;             PG8_WAIT_V(8); PG8_WAIT_L(0); PG8_BAR; PG8_MMA(0, 0, At, B0); PG8_MMA(0, 1, At, B1); PG8_BAR; PG8_SCHED;
;             PG8_LDA(At, 0, 1); PG8_STAGE(PG8_SB(0, 0), b2, voffB); PG8_STAGE(PG8_SB(0, 1), b2 + hstepB, voffB); PG8_STAGE(PG8_SA(0, 0), a2, voffA);
;             PG8_WAIT_V(8); PG8_WAIT_L(0); PG8_BAR; PG8_MMA(1, 0, At, B0); PG8_MMA(1, 1, At, B1); PG8_BAR; PG8_SCHED;
.Lgp_1108:
.LBB0_1108:
	s_add_i32 s53, s40, 2
	s_add_u32 s36, s24, 0x100
	s_addc_u32 s37, s25, 0
	s_add_i32 s22, 16, 0x10000
	s_cmp_eq_u32 s27, s40
	s_cselect_b32 s41, s3, s37
	s_cselect_b32 s40, s2, s36
	s_cselect_b32 s21, s17, s52
	s_cselect_b32 s20, s16, s51
	s_add_i32 s23, 16, 0x14000
	v_add_u32_e32 v154, s22, v147
	v_add_u32_e32 v170, s23, v147
	ds_read_b128 v[138:141], v154
	ds_read_b128 v[142:145], v154 offset:1024
	ds_read_b128 v[150:153], v154 offset:2048
	ds_read_b128 v[154:157], v154 offset:3072
	ds_read_b128 v[158:161], v170
	ds_read_b128 v[162:165], v170 offset:1024
	ds_read_b128 v[166:169], v170 offset:2048
	ds_read_b128 v[170:173], v170 offset:3072
	v_lshl_add_u64 v[174:175], s[24:25], 0, v[134:135]
	s_add_i32 m0, s31, 0xc000
	ds_read_b128 v[184:187], v149
	ds_read_b128 v[188:191], v149 offset:1024
	ds_read_b128 v[192:195], v149 offset:2048
	ds_read_b128 v[196:199], v149 offset:3072
	ds_read_b128 v[200:203], v149 offset:4096
	ds_read_b128 v[204:207], v149 offset:5120
	ds_read_b128 v[208:211], v149 offset:6144
	ds_read_b128 v[212:215], v149 offset:7168
	global_load_lds_dwordx4 v[174:175], off
	v_lshl_add_u64 v[174:175], s[24:25], 0, v[136:137]
	s_add_i32 m0, s31, 0xe000
	s_nop 0
	global_load_lds_dwordx4 v[174:175], off
	s_waitcnt vmcnt(8)
	s_waitcnt lgkmcnt(0)
	s_barrier
	s_waitcnt lgkmcnt(0)
	v_mfma_f32_16x16x32_bf16 v[124:127], v[138:141], v[184:187], v[124:127]
	v_mfma_f32_16x16x32_bf16 v[120:123], v[150:153], v[184:187], v[120:123]
	v_mfma_f32_16x16x32_bf16 v[116:119], v[138:141], v[192:195], v[116:119]
	v_mfma_f32_16x16x32_bf16 v[112:115], v[150:153], v[192:195], v[112:115]
	v_mfma_f32_16x16x32_bf16 v[104:107], v[138:141], v[200:203], v[104:107]
	v_mfma_f32_16x16x32_bf16 v[96:99], v[150:153], v[200:203], v[96:99]
	v_mfma_f32_16x16x32_bf16 v[88:91], v[138:141], v[208:211], v[88:91]
	v_mfma_f32_16x16x32_bf16 v[80:83], v[150:153], v[208:211], v[80:83]
	v_mfma_f32_16x16x32_bf16 v[124:127], v[142:145], v[188:191], v[124:127]
	v_mfma_f32_16x16x32_bf16 v[120:123], v[154:157], v[188:191], v[120:123]
	v_mfma_f32_16x16x32_bf16 v[116:119], v[142:145], v[196:199], v[116:119]
	v_mfma_f32_16x16x32_bf16 v[112:115], v[154:157], v[196:199], v[112:115]
	v_mfma_f32_16x16x32_bf16 v[104:107], v[142:145], v[204:207], v[104:107]
	v_mfma_f32_16x16x32_bf16 v[96:99], v[154:157], v[204:207], v[96:99]
	v_mfma_f32_16x16x32_bf16 v[88:91], v[142:145], v[212:215], v[88:91]
	v_mfma_f32_16x16x32_bf16 v[80:83], v[154:157], v[212:215], v[80:83]
	v_mfma_f32_16x16x32_bf16 v[108:111], v[158:161], v[184:187], v[108:111]
	v_mfma_f32_16x16x32_bf16 v[100:103], v[166:169], v[184:187], v[100:103]
	v_mfma_f32_16x16x32_bf16 v[92:95], v[158:161], v[192:195], v[92:95]
	v_mfma_f32_16x16x32_bf16 v[84:87], v[166:169], v[192:195], v[84:87]
	v_mfma_f32_16x16x32_bf16 v[76:79], v[158:161], v[200:203], v[76:79]
	v_mfma_f32_16x16x32_bf16 v[72:75], v[166:169], v[200:203], v[72:75]
	v_mfma_f32_16x16x32_bf16 v[68:71], v[158:161], v[208:211], v[68:71]
	v_mfma_f32_16x16x32_bf16 v[64:67], v[166:169], v[208:211], v[64:67]
	v_mfma_f32_16x16x32_bf16 v[108:111], v[162:165], v[188:191], v[108:111]
	v_mfma_f32_16x16x32_bf16 v[100:103], v[170:173], v[188:191], v[100:103]
	v_mfma_f32_16x16x32_bf16 v[92:95], v[162:165], v[196:199], v[92:95]
	v_mfma_f32_16x16x32_bf16 v[84:87], v[170:173], v[196:199], v[84:87]
	v_mfma_f32_16x16x32_bf16 v[76:79], v[162:165], v[204:207], v[76:79]
	v_mfma_f32_16x16x32_bf16 v[72:75], v[170:173], v[204:207], v[72:75]
	v_mfma_f32_16x16x32_bf16 v[68:71], v[162:165], v[212:215], v[68:71]
	v_mfma_f32_16x16x32_bf16 v[64:67], v[170:173], v[212:215], v[64:67]
	s_barrier
	s_add_i32 s22, s22, s18
	v_lshl_add_u64 v[174:175], s[20:21], 0, v[176:177]
	s_mov_b32 m0, s22
	ds_read_b128 v[184:187], v149 offset:16384
	ds_read_b128 v[188:191], v149 offset:17408
	ds_read_b128 v[192:195], v149 offset:18432
	ds_read_b128 v[196:199], v149 offset:19456
	ds_read_b128 v[200:203], v149 offset:20480
	ds_read_b128 v[204:207], v149 offset:21504
	ds_read_b128 v[208:211], v149 offset:22528
	ds_read_b128 v[212:215], v149 offset:23552
	global_load_lds_dwordx4 v[174:175], off
	s_add_i32 m0, s22, 0x2000
	v_lshl_add_u64 v[180:181], s[20:21], 0, v[128:129]
	s_add_u32 s20, s20, s6
	s_addc_u32 s21, s21, s7
	s_add_i32 s22, s23, s18
	global_load_lds_dwordx4 v[180:181], off
	v_lshl_add_u64 v[182:183], s[20:21], 0, v[176:177]
	s_mov_b32 m0, s22
	v_lshl_add_u64 v[216:217], s[20:21], 0, v[128:129]
	global_load_lds_dwordx4 v[182:183], off
	s_add_i32 m0, s22, 0x2000
	v_lshl_add_u64 v[218:219], s[40:41], 0, v[132:133]
	global_load_lds_dwordx4 v[216:217], off
	s_mov_b32 m0, s31
	v_lshl_add_u64 v[220:221], s[40:41], 0, v[130:131]
	global_load_lds_dwordx4 v[218:219], off
	s_mov_b32 m0, s42
	s_nop 0
	global_load_lds_dwordx4 v[220:221], off
	s_waitcnt vmcnt(8)
	s_waitcnt lgkmcnt(0)
	s_barrier
; #define PG8_STAGE(bufoff, gbase, voff) do { _Pragma("unroll") for (int _i = 0; _i < 2; ++_i) \
;         __builtin_amdgcn_global_load_lds((const unsigned*)((const char*)(gbase) + (voff)[_i]), (LAS unsigned*)(lds + (bufoff) + ldsw + _i * 8192), 16, 0, 0); } while (0)
; #define PG8_LDA(dst, b, h) do { _Pragma("unroll") for (int m = 0; m < 4; ++m) _Pragma("unroll") for (int k = 0; k < 2; ++k) dst[m][k] = *(const LAS bf16x8*)(lds + PG8_SA(b, h) + aoff + m * 2048 + k * 1024); } while (0)
; #define PG8_LDB(dst, b, h) do { _Pragma("unroll") for (int n = 0; n < 2; ++n) _Pragma("unroll") for (int k = 0; k < 2; ++k) dst[n][k] = *(const LAS bf16x8*)(lds + PG8_SB(b, h) + boff + n * 2048 + k * 1024); } while (0)
; #define PG8_MMA(ai, bj, At, Bt) do { __builtin_amdgcn_s_setprio(1); _Pragma("unroll") for (int m = 0; m < 4; ++m) _Pragma("unroll") for (int n = 0; n < 2; ++n) _Pragma("unroll") for (int k = 0; k < 2; ++k) \
;         acc[ai][bj][m][n] = __builtin_amdgcn_mfma_f32_16x16x32_bf16(Bt[n][k], At[m][k], acc[ai][bj][m][n], 0, 0, 0); __builtin_amdgcn_s_setprio(0); } while (0)
; #define PG8_WAIT_V(n) asm volatile("s_waitcnt vmcnt(" #n ")" ::: "memory")
; #define PG8_WAIT_L(n) asm volatile("s_waitcnt lgkmcnt(" #n ")" ::: "memory")
; #define PG8_BAR __builtin_amdgcn_s_barrier()
; #define PG8_SCHED __builtin_amdgcn_sched_barrier(0)
; template <class Epi, bool ALIGN_EPI = PG8_ALIGN>
; __device__ __forceinline__ void gemm_phase(LAS unsigned char* lds, const Gemm g, const StaticOrder& S, const Epi& E) {
;     ...
;             PG8_WAIT_V(8); PG8_WAIT_L(0); PG8_BAR; PG8_MMA(1, 0, At, B0); PG8_MMA(1, 1, At, B1); PG8_BAR; PG8_SCHED;
;             PG8_LDB(B0, 1, 0); PG8_LDB(B1, 1, 1); PG8_SCHED; PG8_LDA(At, 1, 0); PG8_STAGE(PG8_SA(0, 1), a2 + hstepA, voffA);
;             PG8_WAIT_V(8); PG8_WAIT_L(0); PG8_BAR; PG8_MMA(0, 0, At, B0); PG8_MMA(0, 1, At, B1); PG8_BAR; PG8_SCHED;
	s_waitcnt lgkmcnt(0)
	v_mfma_f32_16x16x32_bf16 v[60:63], v[138:141], v[184:187], v[60:63]
	v_mfma_f32_16x16x32_bf16 v[56:59], v[150:153], v[184:187], v[56:59]
	v_mfma_f32_16x16x32_bf16 v[52:55], v[138:141], v[192:195], v[52:55]
	v_mfma_f32_16x16x32_bf16 v[48:51], v[150:153], v[192:195], v[48:51]
	v_mfma_f32_16x16x32_bf16 v[40:43], v[138:141], v[200:203], v[40:43]
	v_mfma_f32_16x16x32_bf16 v[32:35], v[150:153], v[200:203], v[32:35]
	v_mfma_f32_16x16x32_bf16 v[24:27], v[138:141], v[208:211], v[24:27]
	v_mfma_f32_16x16x32_bf16 v[16:19], v[150:153], v[208:211], v[16:19]
	v_mfma_f32_16x16x32_bf16 v[60:63], v[142:145], v[188:191], v[60:63]
	v_mfma_f32_16x16x32_bf16 v[56:59], v[154:157], v[188:191], v[56:59]
	v_mfma_f32_16x16x32_bf16 v[52:55], v[142:145], v[196:199], v[52:55]
	v_mfma_f32_16x16x32_bf16 v[48:51], v[154:157], v[196:199], v[48:51]
	v_mfma_f32_16x16x32_bf16 v[40:43], v[142:145], v[204:207], v[40:43]
	v_mfma_f32_16x16x32_bf16 v[32:35], v[154:157], v[204:207], v[32:35]
	v_mfma_f32_16x16x32_bf16 v[24:27], v[142:145], v[212:215], v[24:27]
	v_mfma_f32_16x16x32_bf16 v[16:19], v[154:157], v[212:215], v[16:19]
	v_mfma_f32_16x16x32_bf16 v[44:47], v[158:161], v[184:187], v[44:47]
	v_mfma_f32_16x16x32_bf16 v[36:39], v[166:169], v[184:187], v[36:39]
	v_mfma_f32_16x16x32_bf16 v[28:31], v[158:161], v[192:195], v[28:31]
	v_mfma_f32_16x16x32_bf16 v[20:23], v[166:169], v[192:195], v[20:23]
	v_mfma_f32_16x16x32_bf16 v[12:15], v[158:161], v[200:203], v[12:15]
	v_mfma_f32_16x16x32_bf16 v[8:11], v[166:169], v[200:203], v[8:11]
	v_mfma_f32_16x16x32_bf16 v[4:7], v[158:161], v[208:211], v[4:7]
	v_mfma_f32_16x16x32_bf16 v[0:3], v[166:169], v[208:211], v[0:3]
	v_mfma_f32_16x16x32_bf16 v[44:47], v[162:165], v[188:191], v[44:47]
	v_mfma_f32_16x16x32_bf16 v[36:39], v[170:173], v[188:191], v[36:39]
	v_mfma_f32_16x16x32_bf16 v[28:31], v[162:165], v[196:199], v[28:31]
	v_mfma_f32_16x16x32_bf16 v[20:23], v[170:173], v[196:199], v[20:23]
	v_mfma_f32_16x16x32_bf16 v[12:15], v[162:165], v[204:207], v[12:15]
	v_mfma_f32_16x16x32_bf16 v[8:11], v[170:173], v[204:207], v[8:11]
	v_mfma_f32_16x16x32_bf16 v[4:7], v[162:165], v[212:215], v[4:7]
	v_mfma_f32_16x16x32_bf16 v[0:3], v[170:173], v[212:215], v[0:3]
	s_barrier
	s_add_i32 s22, 16, 0x18000
	s_add_i32 s23, 16, 0x1c000
	v_add_u32_e32 v154, s22, v147
	v_add_u32_e32 v170, s23, v147
	ds_read_b128 v[138:141], v154
	ds_read_b128 v[142:145], v154 offset:1024
	ds_read_b128 v[150:153], v154 offset:2048
	ds_read_b128 v[154:157], v154 offset:3072
	ds_read_b128 v[158:161], v170
	ds_read_b128 v[162:165], v170 offset:1024
	ds_read_b128 v[166:169], v170 offset:2048
	ds_read_b128 v[170:173], v170 offset:3072
	s_add_u32 s20, s40, 0x160000
	s_addc_u32 s21, s41, 0
	s_mov_b32 m0, s43
	v_lshl_add_u64 v[222:223], s[20:21], 0, v[132:133]
	ds_read_b128 v[184:187], v149 offset:32768
	ds_read_b128 v[188:191], v149 offset:33792
	ds_read_b128 v[192:195], v149 offset:34816
	ds_read_b128 v[196:199], v149 offset:35840
	ds_read_b128 v[200:203], v149 offset:36864
	ds_read_b128 v[204:207], v149 offset:37888
	ds_read_b128 v[208:211], v149 offset:38912
	ds_read_b128 v[212:215], v149 offset:39936
	global_load_lds_dwordx4 v[222:223], off
	v_lshl_add_u64 v[222:223], s[20:21], 0, v[130:131]
	s_mov_b32 m0, s44
	s_nop 0
	global_load_lds_dwordx4 v[222:223], off
	s_waitcnt vmcnt(8)
	s_waitcnt lgkmcnt(0)
	s_barrier
	s_waitcnt lgkmcnt(0)
	v_mfma_f32_16x16x32_bf16 v[124:127], v[138:141], v[184:187], v[124:127]
	v_mfma_f32_16x16x32_bf16 v[120:123], v[150:153], v[184:187], v[120:123]
	v_mfma_f32_16x16x32_bf16 v[116:119], v[138:141], v[192:195], v[116:119]
	v_mfma_f32_16x16x32_bf16 v[112:115], v[150:153], v[192:195], v[112:115]
	v_mfma_f32_16x16x32_bf16 v[104:107], v[138:141], v[200:203], v[104:107]
	v_mfma_f32_16x16x32_bf16 v[96:99], v[150:153], v[200:203], v[96:99]
	v_mfma_f32_16x16x32_bf16 v[88:91], v[138:141], v[208:211], v[88:91]
	v_mfma_f32_16x16x32_bf16 v[80:83], v[150:153], v[208:211], v[80:83]
	v_mfma_f32_16x16x32_bf16 v[124:127], v[142:145], v[188:191], v[124:127]
	v_mfma_f32_16x16x32_bf16 v[120:123], v[154:157], v[188:191], v[120:123]
	v_mfma_f32_16x16x32_bf16 v[116:119], v[142:145], v[196:199], v[116:119]
	v_mfma_f32_16x16x32_bf16 v[112:115], v[154:157], v[196:199], v[112:115]
	v_mfma_f32_16x16x32_bf16 v[104:107], v[142:145], v[204:207], v[104:107]
	v_mfma_f32_16x16x32_bf16 v[96:99], v[154:157], v[204:207], v[96:99]
	v_mfma_f32_16x16x32_bf16 v[88:91], v[142:145], v[212:215], v[88:91]
	v_mfma_f32_16x16x32_bf16 v[80:83], v[154:157], v[212:215], v[80:83]
	v_mfma_f32_16x16x32_bf16 v[108:111], v[158:161], v[184:187], v[108:111]
	v_mfma_f32_16x16x32_bf16 v[100:103], v[166:169], v[184:187], v[100:103]
	v_mfma_f32_16x16x32_bf16 v[92:95], v[158:161], v[192:195], v[92:95]
	v_mfma_f32_16x16x32_bf16 v[84:87], v[166:169], v[192:195], v[84:87]
	v_mfma_f32_16x16x32_bf16 v[76:79], v[158:161], v[200:203], v[76:79]
	v_mfma_f32_16x16x32_bf16 v[72:75], v[166:169], v[200:203], v[72:75]
	v_mfma_f32_16x16x32_bf16 v[68:71], v[158:161], v[208:211], v[68:71]
	v_mfma_f32_16x16x32_bf16 v[64:67], v[166:169], v[208:211], v[64:67]
	v_mfma_f32_16x16x32_bf16 v[108:111], v[162:165], v[188:191], v[108:111]
	v_mfma_f32_16x16x32_bf16 v[100:103], v[170:173], v[188:191], v[100:103]
	v_mfma_f32_16x16x32_bf16 v[92:95], v[162:165], v[196:199], v[92:95]
	v_mfma_f32_16x16x32_bf16 v[84:87], v[170:173], v[196:199], v[84:87]
	v_mfma_f32_16x16x32_bf16 v[76:79], v[162:165], v[204:207], v[76:79]
	v_mfma_f32_16x16x32_bf16 v[72:75], v[170:173], v[204:207], v[72:75]
	v_mfma_f32_16x16x32_bf16 v[68:71], v[162:165], v[212:215], v[68:71]
	v_mfma_f32_16x16x32_bf16 v[64:67], v[170:173], v[212:215], v[64:67]
	s_barrier
; #define PG8_STAGE(bufoff, gbase, voff) do { _Pragma("unroll") for (int _i = 0; _i < 2; ++_i) \
;         __builtin_amdgcn_global_load_lds((const unsigned*)((const char*)(gbase) + (voff)[_i]), (LAS unsigned*)(lds + (bufoff) + ldsw + _i * 8192), 16, 0, 0); } while (0)
; #define PG8_LDA(dst, b, h) do { _Pragma("unroll") for (int m = 0; m < 4; ++m) _Pragma("unroll") for (int k = 0; k < 2; ++k) dst[m][k] = *(const LAS bf16x8*)(lds + PG8_SA(b, h) + aoff + m * 2048 + k * 1024); } while (0)
; #define PG8_MMA(ai, bj, At, Bt) do { __builtin_amdgcn_s_setprio(1); _Pragma("unroll") for (int m = 0; m < 4; ++m) _Pragma("unroll") for (int n = 0; n < 2; ++n) _Pragma("unroll") for (int k = 0; k < 2; ++k) \
;         acc[ai][bj][m][n] = __builtin_amdgcn_mfma_f32_16x16x32_bf16(Bt[n][k], At[m][k], acc[ai][bj][m][n], 0, 0, 0); __builtin_amdgcn_s_setprio(0); } while (0)
; #define PG8_WAIT_V(n) asm volatile("s_waitcnt vmcnt(" #n ")" ::: "memory")
; #define PG8_WAIT_L(n) asm volatile("s_waitcnt lgkmcnt(" #n ")" ::: "memory")
; #define PG8_BAR __builtin_amdgcn_s_barrier()
; #define PG8_SCHED __builtin_amdgcn_sched_barrier(0)
; template <class Epi, bool ALIGN_EPI = PG8_ALIGN>
; __device__ __forceinline__ void gemm_phase(LAS unsigned char* lds, const Gemm g, const StaticOrder& S, const Epi& E) {
;     ...
;             PG8_LDA(At, 1, 1); PG8_STAGE(PG8_SB(1, 0), b3, voffB); PG8_STAGE(PG8_SB(1, 1), b3 + hstepB, voffB); PG8_STAGE(PG8_SA(1, 0), a3, voffA);
;             PG8_WAIT_V(8); PG8_WAIT_L(0); PG8_BAR; PG8_MMA(1, 0, At, B0); PG8_MMA(1, 1, At, B1); PG8_BAR; PG8_SCHED;
;         }
	s_add_i32 s20, s22, s18
	v_lshl_add_u64 v[174:175], v[174:175], 0, s[0:1]
	s_mov_b32 m0, s20
	ds_read_b128 v[184:187], v149 offset:49152
	ds_read_b128 v[188:191], v149 offset:50176
	ds_read_b128 v[192:195], v149 offset:51200
	ds_read_b128 v[196:199], v149 offset:52224
	ds_read_b128 v[200:203], v149 offset:53248
	ds_read_b128 v[204:207], v149 offset:54272
	ds_read_b128 v[208:211], v149 offset:55296
	ds_read_b128 v[212:215], v149 offset:56320
	global_load_lds_dwordx4 v[174:175], off
	v_lshl_add_u64 v[174:175], v[180:181], 0, s[0:1]
	s_add_i32 m0, s20, 0x2000
	s_add_i32 s20, s23, s18
	global_load_lds_dwordx4 v[174:175], off
	v_lshl_add_u64 v[174:175], v[182:183], 0, s[0:1]
	s_mov_b32 m0, s20
	s_nop 0
	global_load_lds_dwordx4 v[174:175], off
	v_lshl_add_u64 v[174:175], v[216:217], 0, s[0:1]
	s_add_i32 m0, s20, 0x2000
	s_nop 0
	global_load_lds_dwordx4 v[174:175], off
	v_lshl_add_u64 v[174:175], v[218:219], 0, s[0:1]
	s_mov_b32 m0, s45
	s_nop 0
	global_load_lds_dwordx4 v[174:175], off
	v_lshl_add_u64 v[174:175], v[220:221], 0, s[0:1]
	s_mov_b32 m0, s46
	s_nop 0
	global_load_lds_dwordx4 v[174:175], off
	s_waitcnt vmcnt(8)
	s_waitcnt lgkmcnt(0)
	s_barrier
	s_waitcnt lgkmcnt(0)
	v_mfma_f32_16x16x32_bf16 v[60:63], v[138:141], v[184:187], v[60:63]
	v_mfma_f32_16x16x32_bf16 v[56:59], v[150:153], v[184:187], v[56:59]
	v_mfma_f32_16x16x32_bf16 v[52:55], v[138:141], v[192:195], v[52:55]
	v_mfma_f32_16x16x32_bf16 v[48:51], v[150:153], v[192:195], v[48:51]
	v_mfma_f32_16x16x32_bf16 v[40:43], v[138:141], v[200:203], v[40:43]
	v_mfma_f32_16x16x32_bf16 v[32:35], v[150:153], v[200:203], v[32:35]
	v_mfma_f32_16x16x32_bf16 v[24:27], v[138:141], v[208:211], v[24:27]
	v_mfma_f32_16x16x32_bf16 v[16:19], v[150:153], v[208:211], v[16:19]
	v_mfma_f32_16x16x32_bf16 v[60:63], v[142:145], v[188:191], v[60:63]
	v_mfma_f32_16x16x32_bf16 v[56:59], v[154:157], v[188:191], v[56:59]
	v_mfma_f32_16x16x32_bf16 v[52:55], v[142:145], v[196:199], v[52:55]
	v_mfma_f32_16x16x32_bf16 v[48:51], v[154:157], v[196:199], v[48:51]
	v_mfma_f32_16x16x32_bf16 v[40:43], v[142:145], v[204:207], v[40:43]
	v_mfma_f32_16x16x32_bf16 v[32:35], v[154:157], v[204:207], v[32:35]
	v_mfma_f32_16x16x32_bf16 v[24:27], v[142:145], v[212:215], v[24:27]
	v_mfma_f32_16x16x32_bf16 v[16:19], v[154:157], v[212:215], v[16:19]
	v_mfma_f32_16x16x32_bf16 v[44:47], v[158:161], v[184:187], v[44:47]
	v_mfma_f32_16x16x32_bf16 v[36:39], v[166:169], v[184:187], v[36:39]
	v_mfma_f32_16x16x32_bf16 v[28:31], v[158:161], v[192:195], v[28:31]
	v_mfma_f32_16x16x32_bf16 v[20:23], v[166:169], v[192:195], v[20:23]
	v_mfma_f32_16x16x32_bf16 v[12:15], v[158:161], v[200:203], v[12:15]
	v_mfma_f32_16x16x32_bf16 v[8:11], v[166:169], v[200:203], v[8:11]
	v_mfma_f32_16x16x32_bf16 v[4:7], v[158:161], v[208:211], v[4:7]
	v_mfma_f32_16x16x32_bf16 v[0:3], v[166:169], v[208:211], v[0:3]
	v_mfma_f32_16x16x32_bf16 v[44:47], v[162:165], v[188:191], v[44:47]
	v_mfma_f32_16x16x32_bf16 v[36:39], v[170:173], v[188:191], v[36:39]
	v_mfma_f32_16x16x32_bf16 v[28:31], v[162:165], v[196:199], v[28:31]
	v_mfma_f32_16x16x32_bf16 v[20:23], v[170:173], v[196:199], v[20:23]
	v_mfma_f32_16x16x32_bf16 v[12:15], v[162:165], v[204:207], v[12:15]
	v_mfma_f32_16x16x32_bf16 v[8:11], v[170:173], v[204:207], v[8:11]
	v_mfma_f32_16x16x32_bf16 v[4:7], v[162:165], v[212:215], v[4:7]
	v_mfma_f32_16x16x32_bf16 v[0:3], v[170:173], v[212:215], v[0:3]
	s_barrier
	s_add_u32 s51, s51, 0x100
	s_addc_u32 s52, s52, 0
	s_cmp_ge_i32 s53, s26
	s_mov_b64 s[24:25], s[36:37]
	s_mov_b32 s40, s53
	s_cbranch_scc0 .LBB0_1108
; __device__ __forceinline__ unsigned cvt_pk(float lo, float hi) { f32x2_t v = {lo, hi}; bf16x2_t b = __builtin_convertvector(v, bf16x2_t); return __builtin_bit_cast(unsigned, b); }
;     __device__ __forceinline__ void operator()(const f32x4 (&acc)[2][2][4][2], const Unit& u, int wr, int wc, int fr, int fq) const {
;         const int row0 = u.pm * BM + wr * 64 + fr, col0 = u.pn * BM + wc * 32 + 8 * fq;
;         float scv[2][4];
; #pragma unroll
;         for (int ai = 0; ai < 2; ++ai)
; #pragma unroll
;             for (int m = 0; m < 4; ++m) scv[ai][m] = rs ? rs[(size_t)(row0 + ai * HALF + m * 16) * rs_stride] * cs : cs;
; #pragma unroll
;         for (int ai = 0; ai < 2; ++ai)
; #pragma unroll
;             for (int m = 0; m < 4; ++m) {
;                 const int row = row0 + ai * HALF + m * 16; const float sc = scv[ai][m];
;                 bf16_t* rowp = O + (size_t)row * ldc + col0;
; #pragma unroll
;                 for (int bj = 0; bj < 2; ++bj) { const f32x4 v0 = acc[ai][bj][m][0] * sc, v1 = acc[ai][bj][m][1] * sc;
;                     u32x4 w; w.x = cvt_pk(v0[0], v0[1]); w.y = cvt_pk(v0[2], v0[3]); w.z = cvt_pk(v1[0], v1[1]); w.w = cvt_pk(v1[2], v1[3]);
;                     *(u32x4*)(rowp + bj * HALF) = w; }
	s_setprio 0
	v_pk_mul_f32 v[126:127], v[126:127], 0.5 op_sel_hi:[1,0]
	v_pk_mul_f32 v[124:125], v[124:125], 0.5 op_sel_hi:[1,0]
	v_pk_mul_f32 v[122:123], v[122:123], 0.5 op_sel_hi:[1,0]
	v_pk_mul_f32 v[120:121], v[120:121], 0.5 op_sel_hi:[1,0]
	v_pk_mul_f32 v[138:139], v[110:111], 0.5 op_sel_hi:[1,0]
	v_pk_mul_f32 v[140:141], v[108:109], 0.5 op_sel_hi:[1,0]
	v_pk_mul_f32 v[142:143], v[102:103], 0.5 op_sel_hi:[1,0]
	v_pk_mul_f32 v[144:145], v[100:101], 0.5 op_sel_hi:[1,0]
	v_pk_mul_f32 v[100:101], v[118:119], 0.5 op_sel_hi:[1,0]
	v_pk_mul_f32 v[102:103], v[116:117], 0.5 op_sel_hi:[1,0]
	v_pk_mul_f32 v[108:109], v[114:115], 0.5 op_sel_hi:[1,0]
	v_pk_mul_f32 v[110:111], v[112:113], 0.5 op_sel_hi:[1,0]
	v_pk_mul_f32 v[112:113], v[94:95], 0.5 op_sel_hi:[1,0]
	v_pk_mul_f32 v[114:115], v[92:93], 0.5 op_sel_hi:[1,0]
	v_pk_mul_f32 v[116:117], v[86:87], 0.5 op_sel_hi:[1,0]
	v_pk_mul_f32 v[118:119], v[84:85], 0.5 op_sel_hi:[1,0]
	v_pk_mul_f32 v[84:85], v[106:107], 0.5 op_sel_hi:[1,0]
	v_pk_mul_f32 v[86:87], v[104:105], 0.5 op_sel_hi:[1,0]
	v_pk_mul_f32 v[92:93], v[98:99], 0.5 op_sel_hi:[1,0]
	v_pk_mul_f32 v[94:95], v[96:97], 0.5 op_sel_hi:[1,0]
	v_pk_mul_f32 v[96:97], v[78:79], 0.5 op_sel_hi:[1,0]
	v_pk_mul_f32 v[98:99], v[76:77], 0.5 op_sel_hi:[1,0]
	v_pk_mul_f32 v[104:105], v[74:75], 0.5 op_sel_hi:[1,0]
	v_pk_mul_f32 v[106:107], v[72:73], 0.5 op_sel_hi:[1,0]
	v_pk_mul_f32 v[72:73], v[90:91], 0.5 op_sel_hi:[1,0]
	v_pk_mul_f32 v[74:75], v[88:89], 0.5 op_sel_hi:[1,0]
	v_pk_mul_f32 v[76:77], v[82:83], 0.5 op_sel_hi:[1,0]
	v_pk_mul_f32 v[78:79], v[80:81], 0.5 op_sel_hi:[1,0]
	v_pk_mul_f32 v[70:71], v[70:71], 0.5 op_sel_hi:[1,0]
	v_pk_mul_f32 v[68:69], v[68:69], 0.5 op_sel_hi:[1,0]
	v_pk_mul_f32 v[66:67], v[66:67], 0.5 op_sel_hi:[1,0]
	v_pk_mul_f32 v[64:65], v[64:65], 0.5 op_sel_hi:[1,0]
	v_pk_mul_f32 v[62:63], v[62:63], 0.5 op_sel_hi:[1,0]
	v_pk_mul_f32 v[60:61], v[60:61], 0.5 op_sel_hi:[1,0]
	v_pk_mul_f32 v[58:59], v[58:59], 0.5 op_sel_hi:[1,0]
	v_pk_mul_f32 v[56:57], v[56:57], 0.5 op_sel_hi:[1,0]
	v_pk_mul_f32 v[80:81], v[46:47], 0.5 op_sel_hi:[1,0]
	v_pk_mul_f32 v[82:83], v[44:45], 0.5 op_sel_hi:[1,0]
	v_pk_mul_f32 v[88:89], v[38:39], 0.5 op_sel_hi:[1,0]
	v_pk_mul_f32 v[90:91], v[36:37], 0.5 op_sel_hi:[1,0]
	v_pk_mul_f32 v[36:37], v[54:55], 0.5 op_sel_hi:[1,0]
	v_pk_mul_f32 v[38:39], v[52:53], 0.5 op_sel_hi:[1,0]
	v_pk_mul_f32 v[44:45], v[50:51], 0.5 op_sel_hi:[1,0]
	v_pk_mul_f32 v[46:47], v[48:49], 0.5 op_sel_hi:[1,0]
	v_pk_mul_f32 v[48:49], v[30:31], 0.5 op_sel_hi:[1,0]
	v_pk_mul_f32 v[50:51], v[28:29], 0.5 op_sel_hi:[1,0]
	v_pk_mul_f32 v[52:53], v[22:23], 0.5 op_sel_hi:[1,0]
	v_pk_mul_f32 v[54:55], v[20:21], 0.5 op_sel_hi:[1,0]
	v_pk_mul_f32 v[20:21], v[42:43], 0.5 op_sel_hi:[1,0]
	v_pk_mul_f32 v[22:23], v[40:41], 0.5 op_sel_hi:[1,0]
	v_pk_mul_f32 v[28:29], v[34:35], 0.5 op_sel_hi:[1,0]
	v_pk_mul_f32 v[30:31], v[32:33], 0.5 op_sel_hi:[1,0]
	v_pk_mul_f32 v[32:33], v[14:15], 0.5 op_sel_hi:[1,0]
	v_pk_mul_f32 v[34:35], v[12:13], 0.5 op_sel_hi:[1,0]
	v_pk_mul_f32 v[40:41], v[10:11], 0.5 op_sel_hi:[1,0]
	v_pk_mul_f32 v[42:43], v[8:9], 0.5 op_sel_hi:[1,0]
	v_pk_mul_f32 v[8:9], v[26:27], 0.5 op_sel_hi:[1,0]
	v_pk_mul_f32 v[10:11], v[24:25], 0.5 op_sel_hi:[1,0]
	v_pk_mul_f32 v[12:13], v[18:19], 0.5 op_sel_hi:[1,0]
	v_pk_mul_f32 v[14:15], v[16:17], 0.5 op_sel_hi:[1,0]
	v_pk_mul_f32 v[6:7], v[6:7], 0.5 op_sel_hi:[1,0]
	v_pk_mul_f32 v[4:5], v[4:5], 0.5 op_sel_hi:[1,0]
	v_pk_mul_f32 v[2:3], v[2:3], 0.5 op_sel_hi:[1,0]
	v_pk_mul_f32 v[0:1], v[0:1], 0.5 op_sel_hi:[1,0]
